# stack: v65 + no s_setprio flips in the GEMM K-loops + saddr-form LDS-DMA (leanest loop bodies)
# baseline (speedup 1.0000x reference)
; #define PG8_STAGE(bufoff, gbase, voff) do { _Pragma("unroll") for (int _i = 0; _i < 2; ++_i) \
;         __builtin_amdgcn_global_load_lds((const unsigned*)((const char*)(gbase) + (voff)[_i]), (LAS unsigned*)(lds + (bufoff) + ldsw + _i * 8192), 16, 0, 0); } while (0)
; #define PG8_LDA(dst, b, h) do { _Pragma("unroll") for (int m = 0; m < 4; ++m) _Pragma("unroll") for (int k = 0; k < 2; ++k) dst[m][k] = *(const LAS bf16x8*)(lds + PG8_SA(b, h) + aoff + m * 2048 + k * 1024); } while (0)
; #define PG8_LDB(dst, b, h) do { _Pragma("unroll") for (int n = 0; n < 2; ++n) _Pragma("unroll") for (int k = 0; k < 2; ++k) dst[n][k] = *(const LAS bf16x8*)(lds + PG8_SB(b, h) + boff + n * 2048 + k * 1024); } while (0)
; #define PG8_MMA(ai, bj, At, Bt) do { __builtin_amdgcn_s_setprio(1); _Pragma("unroll") for (int m = 0; m < 4; ++m) _Pragma("unroll") for (int n = 0; n < 2; ++n) _Pragma("unroll") for (int k = 0; k < 2; ++k) \
;         acc[ai][bj][m][n] = __builtin_amdgcn_mfma_f32_16x16x32_bf16(Bt[n][k], At[m][k], acc[ai][bj][m][n], 0, 0, 0); __builtin_amdgcn_s_setprio(0); } while (0)
; #define PG8_WAIT_V(n) asm volatile("s_waitcnt vmcnt(" #n ")" ::: "memory")
; #define PG8_WAIT_L(n) asm volatile("s_waitcnt lgkmcnt(" #n ")" ::: "memory")
; #define PG8_BAR __builtin_amdgcn_s_barrier()
; #define PG8_SCHED __builtin_amdgcn_sched_barrier(0)
; template <class Epi>
; __device__ __forceinline__ void gemm_phase(LAS unsigned char* lds, const Gemm g, const StaticOrder& S, const Epi& E) {
;     ...
;             const bool last = (t == nt - 2);
;             const char* a1 = cA + (size_t)(t + 1) * kstep;
;             const char* a2 = last ? nA : cA + (size_t)(t + 2) * kstep; const char* b2 = last ? nB : cB + (size_t)(t + 2) * kstep;
;             const char* a3 = a2 + kstep; const char* b3 = b2 + kstep;
;             PG8_LDB(B0, 0, 0); PG8_LDB(B1, 0, 1); PG8_SCHED; PG8_LDA(At, 0, 0); PG8_STAGE(PG8_SA(1, 1), a1 + hstepA, voffA);
;             PG8_WAIT_V(8); PG8_WAIT_L(0); PG8_BAR; PG8_MMA(0, 0, At, B0); PG8_MMA(0, 1, At, B1); PG8_BAR; PG8_SCHED;
;             PG8_LDA(At, 0, 1); PG8_STAGE(PG8_SB(0, 0), b2, voffB); PG8_STAGE(PG8_SB(0, 1), b2 + hstepB, voffB); PG8_STAGE(PG8_SA(0, 0), a2, voffA);
;             PG8_WAIT_V(8); PG8_WAIT_L(0); PG8_BAR; PG8_MMA(1, 0, At, B0); PG8_MMA(1, 1, At, B1); PG8_BAR; PG8_SCHED;
.LBB0_191:
	s_ashr_i32 s65, s64, 31
	s_lshl_b64 s[68:69], s[64:65], 19
	s_add_u32 s68, s24, s68
	s_addc_u32 s69, s25, s69
	s_and_b64 s[70:71], s[4:5], exec
	s_cselect_b32 s7, s69, s75
	s_cselect_b32 s65, s68, s74
	s_ashr_i32 s63, s62, 31
	s_lshl_b64 s[70:71], s[62:63], 19
	s_add_u32 s70, s10, s70
	s_addc_u32 s71, s11, s71
	s_and_b64 s[78:79], s[4:5], exec
	s_cselect_b32 s63, s71, s77
	s_cselect_b32 s73, s70, s76
	s_add_u32 s74, s74, 0x40080
	s_addc_u32 s75, s75, 0
	s_add_u32 s87, s76, 0x100
	s_addc_u32 s88, s77, 0
	s_mov_b32 s89, -2
	v_lshl_add_u32 v248, s72, 8, v150
	v_add_u32_e32 v248, s41, v248
	v_ashrrev_i32_e32 v249, 31, v248
	v_lshl_add_u64 v[248:249], v[248:249], 2, s[50:51]
	global_load_dword v240, v[248:249], off
	global_load_dword v241, v[248:249], off offset:64
	global_load_dword v242, v[248:249], off offset:128
	global_load_dword v243, v[248:249], off offset:192
	global_load_dword v244, v[248:249], off offset:512
	global_load_dword v245, v[248:249], off offset:576
	global_load_dword v246, v[248:249], off offset:640
	global_load_dword v247, v[248:249], off offset:704
	ds_read_b128 v[144:147], v153
	ds_read_b128 v[158:161], v153 offset:1024
	ds_read_b128 v[162:165], v153 offset:2048
	ds_read_b128 v[166:169], v153 offset:3072
	ds_read_b128 v[170:173], v154
	ds_read_b128 v[178:181], v154 offset:1024
	ds_read_b128 v[182:185], v154 offset:2048
	ds_read_b128 v[186:189], v154 offset:3072
	s_add_u32 s76, s74, 0xfffc0080
	s_addc_u32 s77, s75, -1
	s_cmp_eq_u32 s89, 12
	s_cselect_b32 s79, s7, s77
	s_cselect_b32 s78, s65, s76
	s_cselect_b32 s77, s63, s88
	s_cselect_b32 s76, s73, s87
	s_add_i32 m0, s19, 0xc000
	ds_read_b128 v[190:193], v155
	ds_read_b128 v[194:197], v155 offset:1024
	ds_read_b128 v[198:201], v155 offset:2048
	ds_read_b128 v[202:205], v155 offset:3072
	ds_read_b128 v[206:209], v155 offset:4096
	ds_read_b128 v[210:213], v155 offset:5120
	ds_read_b128 v[214:217], v155 offset:6144
	ds_read_b128 v[218:221], v155 offset:7168
	global_load_lds_dwordx4 v136, s[74:75]
	s_add_i32 m0, s19, 0xe000
	s_nop 0
	global_load_lds_dwordx4 v138, s[74:75]
	s_waitcnt vmcnt(8)
	s_waitcnt lgkmcnt(0)
	s_barrier
	s_waitcnt lgkmcnt(0)
	v_mfma_f32_16x16x32_bf16 v[124:127], v[144:147], v[190:193], 0
	v_mfma_f32_16x16x32_bf16 v[120:123], v[162:165], v[190:193], 0
	v_mfma_f32_16x16x32_bf16 v[108:111], v[144:147], v[198:201], 0
	v_mfma_f32_16x16x32_bf16 v[104:107], v[162:165], v[198:201], 0
	v_mfma_f32_16x16x32_bf16 v[92:95], v[144:147], v[206:209], 0
	v_mfma_f32_16x16x32_bf16 v[88:91], v[162:165], v[206:209], 0
	v_mfma_f32_16x16x32_bf16 v[76:79], v[144:147], v[214:217], 0
	v_mfma_f32_16x16x32_bf16 v[72:75], v[162:165], v[214:217], 0
	v_mfma_f32_16x16x32_bf16 v[124:127], v[158:161], v[194:197], v[124:127]
	v_mfma_f32_16x16x32_bf16 v[120:123], v[166:169], v[194:197], v[120:123]
	v_mfma_f32_16x16x32_bf16 v[108:111], v[158:161], v[202:205], v[108:111]
	v_mfma_f32_16x16x32_bf16 v[104:107], v[166:169], v[202:205], v[104:107]
	v_mfma_f32_16x16x32_bf16 v[92:95], v[158:161], v[210:213], v[92:95]
	v_mfma_f32_16x16x32_bf16 v[88:91], v[166:169], v[210:213], v[88:91]
	v_mfma_f32_16x16x32_bf16 v[76:79], v[158:161], v[218:221], v[76:79]
	v_mfma_f32_16x16x32_bf16 v[72:75], v[166:169], v[218:221], v[72:75]
	v_mfma_f32_16x16x32_bf16 v[116:119], v[170:173], v[190:193], 0
	v_mfma_f32_16x16x32_bf16 v[112:115], v[182:185], v[190:193], 0
	v_mfma_f32_16x16x32_bf16 v[100:103], v[170:173], v[198:201], 0
	v_mfma_f32_16x16x32_bf16 v[96:99], v[182:185], v[198:201], 0
	v_mfma_f32_16x16x32_bf16 v[84:87], v[170:173], v[206:209], 0
	v_mfma_f32_16x16x32_bf16 v[80:83], v[182:185], v[206:209], 0
	v_mfma_f32_16x16x32_bf16 v[68:71], v[170:173], v[214:217], 0
	v_mfma_f32_16x16x32_bf16 v[64:67], v[182:185], v[214:217], 0
	v_mfma_f32_16x16x32_bf16 v[116:119], v[178:181], v[194:197], v[116:119]
	v_mfma_f32_16x16x32_bf16 v[112:115], v[186:189], v[194:197], v[112:115]
	v_mfma_f32_16x16x32_bf16 v[100:103], v[178:181], v[202:205], v[100:103]
	v_mfma_f32_16x16x32_bf16 v[96:99], v[186:189], v[202:205], v[96:99]
	v_mfma_f32_16x16x32_bf16 v[84:87], v[178:181], v[210:213], v[84:87]
	v_mfma_f32_16x16x32_bf16 v[80:83], v[186:189], v[210:213], v[80:83]
	v_mfma_f32_16x16x32_bf16 v[68:71], v[178:181], v[218:221], v[68:71]
	v_mfma_f32_16x16x32_bf16 v[64:67], v[186:189], v[218:221], v[64:67]
	s_barrier
	s_add_i32 s90, s84, s3
	v_lshl_add_u64 v[148:149], s[76:77], 0, v[130:131]
	s_mov_b32 m0, s90
	ds_read_b128 v[190:193], v155 offset:16384
	ds_read_b128 v[194:197], v155 offset:17408
	ds_read_b128 v[198:201], v155 offset:18432
	ds_read_b128 v[202:205], v155 offset:19456
	ds_read_b128 v[206:209], v155 offset:20480
	ds_read_b128 v[210:213], v155 offset:21504
	ds_read_b128 v[214:217], v155 offset:22528
	ds_read_b128 v[218:221], v155 offset:23552
	global_load_lds_dwordx4 v[148:149], off
	s_add_i32 m0, s90, 0x2000
	s_add_u32 s90, s76, 0x40000
	v_lshl_add_u64 v[174:175], s[76:77], 0, v[134:135]
	s_addc_u32 s91, s77, 0
	s_add_i32 s92, s85, s3
	global_load_lds_dwordx4 v[174:175], off
	s_mov_b32 m0, s92
	v_lshl_add_u64 v[226:227], s[78:79], 0, v[132:133]
	global_load_lds_dwordx4 v130, s[90:91]
	s_add_i32 m0, s92, 0x2000
	s_nop 0
	global_load_lds_dwordx4 v134, s[90:91]
	v_lshl_add_u64 v[222:223], s[78:79], 0, v[128:129]
	s_mov_b32 m0, s19
	s_nop 0
	global_load_lds_dwordx4 v[222:223], off
	s_mov_b32 m0, s23
	s_nop 0
	global_load_lds_dwordx4 v[226:227], off
	s_waitcnt vmcnt(8)
	s_waitcnt lgkmcnt(0)
	s_barrier
; #define PG8_STAGE(bufoff, gbase, voff) do { _Pragma("unroll") for (int _i = 0; _i < 2; ++_i) \
;         __builtin_amdgcn_global_load_lds((const unsigned*)((const char*)(gbase) + (voff)[_i]), (LAS unsigned*)(lds + (bufoff) + ldsw + _i * 8192), 16, 0, 0); } while (0)
; #define PG8_LDA(dst, b, h) do { _Pragma("unroll") for (int m = 0; m < 4; ++m) _Pragma("unroll") for (int k = 0; k < 2; ++k) dst[m][k] = *(const LAS bf16x8*)(lds + PG8_SA(b, h) + aoff + m * 2048 + k * 1024); } while (0)
; #define PG8_LDB(dst, b, h) do { _Pragma("unroll") for (int n = 0; n < 2; ++n) _Pragma("unroll") for (int k = 0; k < 2; ++k) dst[n][k] = *(const LAS bf16x8*)(lds + PG8_SB(b, h) + boff + n * 2048 + k * 1024); } while (0)
; #define PG8_MMA(ai, bj, At, Bt) do { __builtin_amdgcn_s_setprio(1); _Pragma("unroll") for (int m = 0; m < 4; ++m) _Pragma("unroll") for (int n = 0; n < 2; ++n) _Pragma("unroll") for (int k = 0; k < 2; ++k) \
;         acc[ai][bj][m][n] = __builtin_amdgcn_mfma_f32_16x16x32_bf16(Bt[n][k], At[m][k], acc[ai][bj][m][n], 0, 0, 0); __builtin_amdgcn_s_setprio(0); } while (0)
; #define PG8_WAIT_V(n) asm volatile("s_waitcnt vmcnt(" #n ")" ::: "memory")
; #define PG8_WAIT_L(n) asm volatile("s_waitcnt lgkmcnt(" #n ")" ::: "memory")
; #define PG8_BAR __builtin_amdgcn_s_barrier()
; #define PG8_SCHED __builtin_amdgcn_sched_barrier(0)
; template <class Epi>
; __device__ __forceinline__ void gemm_phase(LAS unsigned char* lds, const Gemm g, const StaticOrder& S, const Epi& E) {
;     ...
;             PG8_WAIT_V(8); PG8_WAIT_L(0); PG8_BAR; PG8_MMA(1, 0, At, B0); PG8_MMA(1, 1, At, B1); PG8_BAR; PG8_SCHED;
;             PG8_LDB(B0, 1, 0); PG8_LDB(B1, 1, 1); PG8_SCHED; PG8_LDA(At, 1, 0); PG8_STAGE(PG8_SA(0, 1), a2 + hstepA, voffA);
;             PG8_WAIT_V(8); PG8_WAIT_L(0); PG8_BAR; PG8_MMA(0, 0, At, B0); PG8_MMA(0, 1, At, B1); PG8_BAR; PG8_SCHED;
	s_waitcnt lgkmcnt(0)
	v_mfma_f32_16x16x32_bf16 v[60:63], v[144:147], v[190:193], 0
	v_mfma_f32_16x16x32_bf16 v[56:59], v[162:165], v[190:193], 0
	v_mfma_f32_16x16x32_bf16 v[44:47], v[144:147], v[198:201], 0
	v_mfma_f32_16x16x32_bf16 v[40:43], v[162:165], v[198:201], 0
	v_mfma_f32_16x16x32_bf16 v[28:31], v[144:147], v[206:209], 0
	v_mfma_f32_16x16x32_bf16 v[24:27], v[162:165], v[206:209], 0
	v_mfma_f32_16x16x32_bf16 v[12:15], v[144:147], v[214:217], 0
	v_mfma_f32_16x16x32_bf16 v[8:11], v[162:165], v[214:217], 0
	v_mfma_f32_16x16x32_bf16 v[60:63], v[158:161], v[194:197], v[60:63]
	v_mfma_f32_16x16x32_bf16 v[56:59], v[166:169], v[194:197], v[56:59]
	v_mfma_f32_16x16x32_bf16 v[44:47], v[158:161], v[202:205], v[44:47]
	v_mfma_f32_16x16x32_bf16 v[40:43], v[166:169], v[202:205], v[40:43]
	v_mfma_f32_16x16x32_bf16 v[28:31], v[158:161], v[210:213], v[28:31]
	v_mfma_f32_16x16x32_bf16 v[24:27], v[166:169], v[210:213], v[24:27]
	v_mfma_f32_16x16x32_bf16 v[12:15], v[158:161], v[218:221], v[12:15]
	v_mfma_f32_16x16x32_bf16 v[8:11], v[166:169], v[218:221], v[8:11]
	v_mfma_f32_16x16x32_bf16 v[52:55], v[170:173], v[190:193], 0
	v_mfma_f32_16x16x32_bf16 v[48:51], v[182:185], v[190:193], 0
	v_mfma_f32_16x16x32_bf16 v[36:39], v[170:173], v[198:201], 0
	v_mfma_f32_16x16x32_bf16 v[32:35], v[182:185], v[198:201], 0
	v_mfma_f32_16x16x32_bf16 v[20:23], v[170:173], v[206:209], 0
	v_mfma_f32_16x16x32_bf16 v[16:19], v[182:185], v[206:209], 0
	v_mfma_f32_16x16x32_bf16 v[4:7], v[170:173], v[214:217], 0
	v_mfma_f32_16x16x32_bf16 v[0:3], v[182:185], v[214:217], 0
	v_mfma_f32_16x16x32_bf16 v[52:55], v[178:181], v[194:197], v[52:55]
	v_mfma_f32_16x16x32_bf16 v[48:51], v[186:189], v[194:197], v[48:51]
	v_mfma_f32_16x16x32_bf16 v[36:39], v[178:181], v[202:205], v[36:39]
	v_mfma_f32_16x16x32_bf16 v[32:35], v[186:189], v[202:205], v[32:35]
	v_mfma_f32_16x16x32_bf16 v[20:23], v[178:181], v[210:213], v[20:23]
	v_mfma_f32_16x16x32_bf16 v[16:19], v[186:189], v[210:213], v[16:19]
	v_mfma_f32_16x16x32_bf16 v[4:7], v[178:181], v[218:221], v[4:7]
	v_mfma_f32_16x16x32_bf16 v[0:3], v[186:189], v[218:221], v[0:3]
	s_barrier
	s_add_i32 s90, 0, 0x18000
	v_add_u32_e32 v157, s90, v152
	s_add_i32 s91, 0, 0x1c000
	ds_read_b128 v[144:147], v157
	ds_read_b128 v[158:161], v157 offset:1024
	ds_read_b128 v[162:165], v157 offset:2048
	ds_read_b128 v[166:169], v157 offset:3072
	v_add_u32_e32 v157, s91, v152
	ds_read_b128 v[170:173], v157
	ds_read_b128 v[178:181], v157 offset:1024
	ds_read_b128 v[182:185], v157 offset:2048
	ds_read_b128 v[186:189], v157 offset:3072
	s_add_u32 s78, s78, 0x40000
	s_addc_u32 s79, s79, 0
	s_mov_b32 m0, s33
	ds_read_b128 v[190:193], v155 offset:32768
	ds_read_b128 v[194:197], v155 offset:33792
	ds_read_b128 v[198:201], v155 offset:34816
	ds_read_b128 v[202:205], v155 offset:35840
	ds_read_b128 v[206:209], v155 offset:36864
	ds_read_b128 v[210:213], v155 offset:37888
	ds_read_b128 v[214:217], v155 offset:38912
	ds_read_b128 v[218:221], v155 offset:39936
	global_load_lds_dwordx4 v128, s[78:79]
	s_mov_b32 m0, s35
	s_nop 0
	global_load_lds_dwordx4 v132, s[78:79]
	s_waitcnt vmcnt(8)
	s_waitcnt lgkmcnt(0)
	s_barrier
	s_waitcnt lgkmcnt(0)
	v_mfma_f32_16x16x32_bf16 v[124:127], v[144:147], v[190:193], v[124:127]
	v_mfma_f32_16x16x32_bf16 v[120:123], v[162:165], v[190:193], v[120:123]
	v_mfma_f32_16x16x32_bf16 v[108:111], v[144:147], v[198:201], v[108:111]
	v_mfma_f32_16x16x32_bf16 v[104:107], v[162:165], v[198:201], v[104:107]
	v_mfma_f32_16x16x32_bf16 v[92:95], v[144:147], v[206:209], v[92:95]
	v_mfma_f32_16x16x32_bf16 v[88:91], v[162:165], v[206:209], v[88:91]
	v_mfma_f32_16x16x32_bf16 v[76:79], v[144:147], v[214:217], v[76:79]
	v_mfma_f32_16x16x32_bf16 v[72:75], v[162:165], v[214:217], v[72:75]
	v_mfma_f32_16x16x32_bf16 v[124:127], v[158:161], v[194:197], v[124:127]
	v_mfma_f32_16x16x32_bf16 v[120:123], v[166:169], v[194:197], v[120:123]
	v_mfma_f32_16x16x32_bf16 v[108:111], v[158:161], v[202:205], v[108:111]
	v_mfma_f32_16x16x32_bf16 v[104:107], v[166:169], v[202:205], v[104:107]
	v_mfma_f32_16x16x32_bf16 v[92:95], v[158:161], v[210:213], v[92:95]
	v_mfma_f32_16x16x32_bf16 v[88:91], v[166:169], v[210:213], v[88:91]
	v_mfma_f32_16x16x32_bf16 v[76:79], v[158:161], v[218:221], v[76:79]
	v_mfma_f32_16x16x32_bf16 v[72:75], v[166:169], v[218:221], v[72:75]
	v_mfma_f32_16x16x32_bf16 v[116:119], v[170:173], v[190:193], v[116:119]
	v_mfma_f32_16x16x32_bf16 v[112:115], v[182:185], v[190:193], v[112:115]
	v_mfma_f32_16x16x32_bf16 v[100:103], v[170:173], v[198:201], v[100:103]
	v_mfma_f32_16x16x32_bf16 v[96:99], v[182:185], v[198:201], v[96:99]
	v_mfma_f32_16x16x32_bf16 v[84:87], v[170:173], v[206:209], v[84:87]
	v_mfma_f32_16x16x32_bf16 v[80:83], v[182:185], v[206:209], v[80:83]
	v_mfma_f32_16x16x32_bf16 v[68:71], v[170:173], v[214:217], v[68:71]
	v_mfma_f32_16x16x32_bf16 v[64:67], v[182:185], v[214:217], v[64:67]
	v_mfma_f32_16x16x32_bf16 v[116:119], v[178:181], v[194:197], v[116:119]
	v_mfma_f32_16x16x32_bf16 v[112:115], v[186:189], v[194:197], v[112:115]
	v_mfma_f32_16x16x32_bf16 v[100:103], v[178:181], v[202:205], v[100:103]
	v_mfma_f32_16x16x32_bf16 v[96:99], v[186:189], v[202:205], v[96:99]
	v_mfma_f32_16x16x32_bf16 v[84:87], v[178:181], v[210:213], v[84:87]
	v_mfma_f32_16x16x32_bf16 v[80:83], v[186:189], v[210:213], v[80:83]
	v_mfma_f32_16x16x32_bf16 v[68:71], v[178:181], v[218:221], v[68:71]
	v_mfma_f32_16x16x32_bf16 v[64:67], v[186:189], v[218:221], v[64:67]
	s_barrier
; #define PG8_STAGE(bufoff, gbase, voff) do { _Pragma("unroll") for (int _i = 0; _i < 2; ++_i) \
;         __builtin_amdgcn_global_load_lds((const unsigned*)((const char*)(gbase) + (voff)[_i]), (LAS unsigned*)(lds + (bufoff) + ldsw + _i * 8192), 16, 0, 0); } while (0)
; #define PG8_LDA(dst, b, h) do { _Pragma("unroll") for (int m = 0; m < 4; ++m) _Pragma("unroll") for (int k = 0; k < 2; ++k) dst[m][k] = *(const LAS bf16x8*)(lds + PG8_SA(b, h) + aoff + m * 2048 + k * 1024); } while (0)
; #define PG8_LDB(dst, b, h) do { _Pragma("unroll") for (int n = 0; n < 2; ++n) _Pragma("unroll") for (int k = 0; k < 2; ++k) dst[n][k] = *(const LAS bf16x8*)(lds + PG8_SB(b, h) + boff + n * 2048 + k * 1024); } while (0)
; #define PG8_MMA(ai, bj, At, Bt) do { __builtin_amdgcn_s_setprio(1); _Pragma("unroll") for (int m = 0; m < 4; ++m) _Pragma("unroll") for (int n = 0; n < 2; ++n) _Pragma("unroll") for (int k = 0; k < 2; ++k) \
;         acc[ai][bj][m][n] = __builtin_amdgcn_mfma_f32_16x16x32_bf16(Bt[n][k], At[m][k], acc[ai][bj][m][n], 0, 0, 0); __builtin_amdgcn_s_setprio(0); } while (0)
; #define PG8_WAIT_V(n) asm volatile("s_waitcnt vmcnt(" #n ")" ::: "memory")
; #define PG8_WAIT_L(n) asm volatile("s_waitcnt lgkmcnt(" #n ")" ::: "memory")
; #define PG8_BAR __builtin_amdgcn_s_barrier()
; #define PG8_SCHED __builtin_amdgcn_sched_barrier(0)
; template <class Epi>
; __device__ __forceinline__ void gemm_phase(LAS unsigned char* lds, const Gemm g, const StaticOrder& S, const Epi& E) {
;     ...
;             PG8_LDB(B0, 0, 0); PG8_LDB(B1, 0, 1); PG8_SCHED; PG8_LDA(At, 0, 0); PG8_STAGE(PG8_SA(1, 1), a1 + hstepA, voffA);
;     ...
;             PG8_LDA(At, 1, 1); PG8_STAGE(PG8_SB(1, 0), b3, voffB); PG8_STAGE(PG8_SB(1, 1), b3 + hstepB, voffB); PG8_STAGE(PG8_SA(1, 0), a3, voffA);
;             PG8_WAIT_V(8); PG8_WAIT_L(0); PG8_BAR; PG8_MMA(1, 0, At, B0); PG8_MMA(1, 1, At, B1); PG8_BAR; PG8_SCHED;
	s_add_i32 s78, s90, s3
	v_lshl_add_u64 v[148:149], v[148:149], 0, s[12:13]
	s_mov_b32 m0, s78
	ds_read_b128 v[190:193], v155 offset:49152
	ds_read_b128 v[194:197], v155 offset:50176
	ds_read_b128 v[198:201], v155 offset:51200
	ds_read_b128 v[202:205], v155 offset:52224
	ds_read_b128 v[206:209], v155 offset:53248
	ds_read_b128 v[210:213], v155 offset:54272
	ds_read_b128 v[214:217], v155 offset:55296
	ds_read_b128 v[218:221], v155 offset:56320
	global_load_lds_dwordx4 v[148:149], off
	s_add_i32 m0, s78, 0x2000
	s_add_u32 s76, s76, 0x40080
	v_lshl_add_u64 v[148:149], v[174:175], 0, s[12:13]
	s_addc_u32 s77, s77, 0
	s_add_i32 s78, s91, s3
	global_load_lds_dwordx4 v[148:149], off
	s_mov_b32 m0, s78
	s_nop 0
	global_load_lds_dwordx4 v130, s[76:77]
	s_add_i32 m0, s78, 0x2000
	s_nop 0
	global_load_lds_dwordx4 v134, s[76:77]
	v_lshl_add_u64 v[148:149], v[222:223], 0, s[12:13]
	s_mov_b32 m0, s57
	s_nop 0
	global_load_lds_dwordx4 v[148:149], off
	v_lshl_add_u64 v[148:149], v[226:227], 0, s[12:13]
	s_mov_b32 m0, s80
	s_nop 0
	global_load_lds_dwordx4 v[148:149], off
	s_waitcnt vmcnt(8)
	s_waitcnt lgkmcnt(0)
	s_barrier
	s_waitcnt lgkmcnt(0)
	v_mfma_f32_16x16x32_bf16 v[60:63], v[144:147], v[190:193], v[60:63]
	v_mfma_f32_16x16x32_bf16 v[56:59], v[162:165], v[190:193], v[56:59]
	v_mfma_f32_16x16x32_bf16 v[44:47], v[144:147], v[198:201], v[44:47]
	v_mfma_f32_16x16x32_bf16 v[40:43], v[162:165], v[198:201], v[40:43]
	v_mfma_f32_16x16x32_bf16 v[28:31], v[144:147], v[206:209], v[28:31]
	v_mfma_f32_16x16x32_bf16 v[24:27], v[162:165], v[206:209], v[24:27]
	v_mfma_f32_16x16x32_bf16 v[12:15], v[144:147], v[214:217], v[12:15]
	v_mfma_f32_16x16x32_bf16 v[8:11], v[162:165], v[214:217], v[8:11]
	v_mfma_f32_16x16x32_bf16 v[60:63], v[158:161], v[194:197], v[60:63]
	v_mfma_f32_16x16x32_bf16 v[56:59], v[166:169], v[194:197], v[56:59]
	v_mfma_f32_16x16x32_bf16 v[44:47], v[158:161], v[202:205], v[44:47]
	v_mfma_f32_16x16x32_bf16 v[40:43], v[166:169], v[202:205], v[40:43]
	v_mfma_f32_16x16x32_bf16 v[28:31], v[158:161], v[210:213], v[28:31]
	v_mfma_f32_16x16x32_bf16 v[24:27], v[166:169], v[210:213], v[24:27]
	v_mfma_f32_16x16x32_bf16 v[12:15], v[158:161], v[218:221], v[12:15]
	v_mfma_f32_16x16x32_bf16 v[8:11], v[166:169], v[218:221], v[8:11]
	v_mfma_f32_16x16x32_bf16 v[52:55], v[170:173], v[190:193], v[52:55]
	v_mfma_f32_16x16x32_bf16 v[48:51], v[182:185], v[190:193], v[48:51]
	v_mfma_f32_16x16x32_bf16 v[36:39], v[170:173], v[198:201], v[36:39]
	v_mfma_f32_16x16x32_bf16 v[32:35], v[182:185], v[198:201], v[32:35]
	v_mfma_f32_16x16x32_bf16 v[20:23], v[170:173], v[206:209], v[20:23]
	v_mfma_f32_16x16x32_bf16 v[16:19], v[182:185], v[206:209], v[16:19]
	v_mfma_f32_16x16x32_bf16 v[4:7], v[170:173], v[214:217], v[4:7]
	v_mfma_f32_16x16x32_bf16 v[0:3], v[182:185], v[214:217], v[0:3]
	v_mfma_f32_16x16x32_bf16 v[52:55], v[178:181], v[194:197], v[52:55]
	v_mfma_f32_16x16x32_bf16 v[48:51], v[186:189], v[194:197], v[48:51]
	v_mfma_f32_16x16x32_bf16 v[36:39], v[178:181], v[202:205], v[36:39]
	v_mfma_f32_16x16x32_bf16 v[32:35], v[186:189], v[202:205], v[32:35]
	v_mfma_f32_16x16x32_bf16 v[20:23], v[178:181], v[210:213], v[20:23]
	v_mfma_f32_16x16x32_bf16 v[16:19], v[186:189], v[210:213], v[16:19]
	v_mfma_f32_16x16x32_bf16 v[4:7], v[178:181], v[218:221], v[4:7]
	v_mfma_f32_16x16x32_bf16 v[0:3], v[186:189], v[218:221], v[0:3]
	s_barrier
	s_add_i32 s89, s89, 2
	s_add_u32 s74, s74, 0x100
	s_addc_u32 s75, s75, 0
	s_add_u32 s87, s87, 0x100
	s_addc_u32 s88, s88, 0
	s_cmp_gt_u32 s89, 13
.LBB0_192:
	ds_read_b128 v[144:147], v153
	ds_read_b128 v[158:161], v153 offset:1024
	ds_read_b128 v[162:165], v153 offset:2048
	ds_read_b128 v[166:169], v153 offset:3072
	ds_read_b128 v[170:173], v154
	ds_read_b128 v[178:181], v154 offset:1024
	ds_read_b128 v[182:185], v154 offset:2048
	ds_read_b128 v[186:189], v154 offset:3072
	s_add_u32 s76, s74, 0xfffc0080
	s_addc_u32 s77, s75, -1
	s_cmp_eq_u32 s89, 12
	s_cselect_b32 s79, s7, s77
	s_cselect_b32 s78, s65, s76
	s_cselect_b32 s77, s63, s88
	s_cselect_b32 s76, s73, s87
	s_add_i32 m0, s19, 0xc000
	ds_read_b128 v[190:193], v155
	ds_read_b128 v[194:197], v155 offset:1024
	ds_read_b128 v[198:201], v155 offset:2048
	ds_read_b128 v[202:205], v155 offset:3072
	ds_read_b128 v[206:209], v155 offset:4096
	ds_read_b128 v[210:213], v155 offset:5120
	ds_read_b128 v[214:217], v155 offset:6144
	ds_read_b128 v[218:221], v155 offset:7168
	global_load_lds_dwordx4 v136, s[74:75]
	s_add_i32 m0, s19, 0xe000
	s_nop 0
	global_load_lds_dwordx4 v138, s[74:75]
	s_waitcnt vmcnt(8)
	s_waitcnt lgkmcnt(0)
	s_barrier
; #define PG8_STAGE(bufoff, gbase, voff) do { _Pragma("unroll") for (int _i = 0; _i < 2; ++_i) \
;         __builtin_amdgcn_global_load_lds((const unsigned*)((const char*)(gbase) + (voff)[_i]), (LAS unsigned*)(lds + (bufoff) + ldsw + _i * 8192), 16, 0, 0); } while (0)
; #define PG8_LDA(dst, b, h) do { _Pragma("unroll") for (int m = 0; m < 4; ++m) _Pragma("unroll") for (int k = 0; k < 2; ++k) dst[m][k] = *(const LAS bf16x8*)(lds + PG8_SA(b, h) + aoff + m * 2048 + k * 1024); } while (0)
; #define PG8_LDB(dst, b, h) do { _Pragma("unroll") for (int n = 0; n < 2; ++n) _Pragma("unroll") for (int k = 0; k < 2; ++k) dst[n][k] = *(const LAS bf16x8*)(lds + PG8_SB(b, h) + boff + n * 2048 + k * 1024); } while (0)
; #define PG8_MMA(ai, bj, At, Bt) do { __builtin_amdgcn_s_setprio(1); _Pragma("unroll") for (int m = 0; m < 4; ++m) _Pragma("unroll") for (int n = 0; n < 2; ++n) _Pragma("unroll") for (int k = 0; k < 2; ++k) \
;         acc[ai][bj][m][n] = __builtin_amdgcn_mfma_f32_16x16x32_bf16(Bt[n][k], At[m][k], acc[ai][bj][m][n], 0, 0, 0); __builtin_amdgcn_s_setprio(0); } while (0)
; #define PG8_WAIT_V(n) asm volatile("s_waitcnt vmcnt(" #n ")" ::: "memory")
; #define PG8_WAIT_L(n) asm volatile("s_waitcnt lgkmcnt(" #n ")" ::: "memory")
; #define PG8_BAR __builtin_amdgcn_s_barrier()
; #define PG8_SCHED __builtin_amdgcn_sched_barrier(0)
; template <class Epi>
; __device__ __forceinline__ void gemm_phase(LAS unsigned char* lds, const Gemm g, const StaticOrder& S, const Epi& E) {
;     ...
;             PG8_LDB(B0, 0, 0); PG8_LDB(B1, 0, 1); PG8_SCHED; PG8_LDA(At, 0, 0); PG8_STAGE(PG8_SA(1, 1), a1 + hstepA, voffA);
;             PG8_WAIT_V(8); PG8_WAIT_L(0); PG8_BAR; PG8_MMA(0, 0, At, B0); PG8_MMA(0, 1, At, B1); PG8_BAR; PG8_SCHED;
;             PG8_LDA(At, 0, 1); PG8_STAGE(PG8_SB(0, 0), b2, voffB); PG8_STAGE(PG8_SB(0, 1), b2 + hstepB, voffB); PG8_STAGE(PG8_SA(0, 0), a2, voffA);
;             PG8_WAIT_V(8); PG8_WAIT_L(0); PG8_BAR; PG8_MMA(1, 0, At, B0); PG8_MMA(1, 1, At, B1); PG8_BAR; PG8_SCHED;
	s_waitcnt lgkmcnt(0)
	v_mfma_f32_16x16x32_bf16 v[124:127], v[144:147], v[190:193], v[124:127]
	v_mfma_f32_16x16x32_bf16 v[120:123], v[162:165], v[190:193], v[120:123]
	v_mfma_f32_16x16x32_bf16 v[108:111], v[144:147], v[198:201], v[108:111]
	v_mfma_f32_16x16x32_bf16 v[104:107], v[162:165], v[198:201], v[104:107]
	v_mfma_f32_16x16x32_bf16 v[92:95], v[144:147], v[206:209], v[92:95]
	v_mfma_f32_16x16x32_bf16 v[88:91], v[162:165], v[206:209], v[88:91]
	v_mfma_f32_16x16x32_bf16 v[76:79], v[144:147], v[214:217], v[76:79]
	v_mfma_f32_16x16x32_bf16 v[72:75], v[162:165], v[214:217], v[72:75]
	v_mfma_f32_16x16x32_bf16 v[124:127], v[158:161], v[194:197], v[124:127]
	v_mfma_f32_16x16x32_bf16 v[120:123], v[166:169], v[194:197], v[120:123]
	v_mfma_f32_16x16x32_bf16 v[108:111], v[158:161], v[202:205], v[108:111]
	v_mfma_f32_16x16x32_bf16 v[104:107], v[166:169], v[202:205], v[104:107]
	v_mfma_f32_16x16x32_bf16 v[92:95], v[158:161], v[210:213], v[92:95]
	v_mfma_f32_16x16x32_bf16 v[88:91], v[166:169], v[210:213], v[88:91]
	v_mfma_f32_16x16x32_bf16 v[76:79], v[158:161], v[218:221], v[76:79]
	v_mfma_f32_16x16x32_bf16 v[72:75], v[166:169], v[218:221], v[72:75]
	v_mfma_f32_16x16x32_bf16 v[116:119], v[170:173], v[190:193], v[116:119]
	v_mfma_f32_16x16x32_bf16 v[112:115], v[182:185], v[190:193], v[112:115]
	v_mfma_f32_16x16x32_bf16 v[100:103], v[170:173], v[198:201], v[100:103]
	v_mfma_f32_16x16x32_bf16 v[96:99], v[182:185], v[198:201], v[96:99]
	v_mfma_f32_16x16x32_bf16 v[84:87], v[170:173], v[206:209], v[84:87]
	v_mfma_f32_16x16x32_bf16 v[80:83], v[182:185], v[206:209], v[80:83]
	v_mfma_f32_16x16x32_bf16 v[68:71], v[170:173], v[214:217], v[68:71]
	v_mfma_f32_16x16x32_bf16 v[64:67], v[182:185], v[214:217], v[64:67]
	v_mfma_f32_16x16x32_bf16 v[116:119], v[178:181], v[194:197], v[116:119]
	v_mfma_f32_16x16x32_bf16 v[112:115], v[186:189], v[194:197], v[112:115]
	v_mfma_f32_16x16x32_bf16 v[100:103], v[178:181], v[202:205], v[100:103]
	v_mfma_f32_16x16x32_bf16 v[96:99], v[186:189], v[202:205], v[96:99]
	v_mfma_f32_16x16x32_bf16 v[84:87], v[178:181], v[210:213], v[84:87]
	v_mfma_f32_16x16x32_bf16 v[80:83], v[186:189], v[210:213], v[80:83]
	v_mfma_f32_16x16x32_bf16 v[68:71], v[178:181], v[218:221], v[68:71]
	v_mfma_f32_16x16x32_bf16 v[64:67], v[186:189], v[218:221], v[64:67]
	s_barrier
	s_add_i32 s90, s84, s3
	v_lshl_add_u64 v[148:149], s[76:77], 0, v[130:131]
	s_mov_b32 m0, s90
	ds_read_b128 v[190:193], v155 offset:16384
	ds_read_b128 v[194:197], v155 offset:17408
	ds_read_b128 v[198:201], v155 offset:18432
	ds_read_b128 v[202:205], v155 offset:19456
	ds_read_b128 v[206:209], v155 offset:20480
	ds_read_b128 v[210:213], v155 offset:21504
	ds_read_b128 v[214:217], v155 offset:22528
	ds_read_b128 v[218:221], v155 offset:23552
	global_load_lds_dwordx4 v[148:149], off
	s_add_i32 m0, s90, 0x2000
	s_add_u32 s90, s76, 0x40000
	v_lshl_add_u64 v[174:175], s[76:77], 0, v[134:135]
	s_addc_u32 s91, s77, 0
	s_add_i32 s92, s85, s3
	global_load_lds_dwordx4 v[174:175], off
	s_mov_b32 m0, s92
	v_lshl_add_u64 v[226:227], s[78:79], 0, v[132:133]
	global_load_lds_dwordx4 v130, s[90:91]
	s_add_i32 m0, s92, 0x2000
	s_nop 0
	global_load_lds_dwordx4 v134, s[90:91]
	v_lshl_add_u64 v[222:223], s[78:79], 0, v[128:129]
	s_mov_b32 m0, s19
	s_nop 0
	global_load_lds_dwordx4 v[222:223], off
	s_mov_b32 m0, s23
	s_nop 0
	global_load_lds_dwordx4 v[226:227], off
	s_waitcnt vmcnt(8)
	s_waitcnt lgkmcnt(0)
	s_barrier
	s_waitcnt lgkmcnt(0)
	v_mfma_f32_16x16x32_bf16 v[60:63], v[144:147], v[190:193], v[60:63]
	v_mfma_f32_16x16x32_bf16 v[56:59], v[162:165], v[190:193], v[56:59]
	v_mfma_f32_16x16x32_bf16 v[44:47], v[144:147], v[198:201], v[44:47]
	v_mfma_f32_16x16x32_bf16 v[40:43], v[162:165], v[198:201], v[40:43]
	v_mfma_f32_16x16x32_bf16 v[28:31], v[144:147], v[206:209], v[28:31]
	v_mfma_f32_16x16x32_bf16 v[24:27], v[162:165], v[206:209], v[24:27]
	v_mfma_f32_16x16x32_bf16 v[12:15], v[144:147], v[214:217], v[12:15]
	v_mfma_f32_16x16x32_bf16 v[8:11], v[162:165], v[214:217], v[8:11]
	v_mfma_f32_16x16x32_bf16 v[60:63], v[158:161], v[194:197], v[60:63]
	v_mfma_f32_16x16x32_bf16 v[56:59], v[166:169], v[194:197], v[56:59]
	v_mfma_f32_16x16x32_bf16 v[44:47], v[158:161], v[202:205], v[44:47]
	v_mfma_f32_16x16x32_bf16 v[40:43], v[166:169], v[202:205], v[40:43]
	v_mfma_f32_16x16x32_bf16 v[28:31], v[158:161], v[210:213], v[28:31]
	v_mfma_f32_16x16x32_bf16 v[24:27], v[166:169], v[210:213], v[24:27]
	v_mfma_f32_16x16x32_bf16 v[12:15], v[158:161], v[218:221], v[12:15]
	v_mfma_f32_16x16x32_bf16 v[8:11], v[166:169], v[218:221], v[8:11]
	v_mfma_f32_16x16x32_bf16 v[52:55], v[170:173], v[190:193], v[52:55]
	v_mfma_f32_16x16x32_bf16 v[48:51], v[182:185], v[190:193], v[48:51]
	v_mfma_f32_16x16x32_bf16 v[36:39], v[170:173], v[198:201], v[36:39]
	v_mfma_f32_16x16x32_bf16 v[32:35], v[182:185], v[198:201], v[32:35]
	v_mfma_f32_16x16x32_bf16 v[20:23], v[170:173], v[206:209], v[20:23]
	v_mfma_f32_16x16x32_bf16 v[16:19], v[182:185], v[206:209], v[16:19]
	v_mfma_f32_16x16x32_bf16 v[4:7], v[170:173], v[214:217], v[4:7]
	v_mfma_f32_16x16x32_bf16 v[0:3], v[182:185], v[214:217], v[0:3]
	v_mfma_f32_16x16x32_bf16 v[52:55], v[178:181], v[194:197], v[52:55]
	v_mfma_f32_16x16x32_bf16 v[48:51], v[186:189], v[194:197], v[48:51]
	v_mfma_f32_16x16x32_bf16 v[36:39], v[178:181], v[202:205], v[36:39]
	v_mfma_f32_16x16x32_bf16 v[32:35], v[186:189], v[202:205], v[32:35]
	v_mfma_f32_16x16x32_bf16 v[20:23], v[178:181], v[210:213], v[20:23]
	v_mfma_f32_16x16x32_bf16 v[16:19], v[186:189], v[210:213], v[16:19]
	v_mfma_f32_16x16x32_bf16 v[4:7], v[178:181], v[218:221], v[4:7]
	v_mfma_f32_16x16x32_bf16 v[0:3], v[186:189], v[218:221], v[0:3]
	s_barrier
; #define PG8_STAGE(bufoff, gbase, voff) do { _Pragma("unroll") for (int _i = 0; _i < 2; ++_i) \
;         __builtin_amdgcn_global_load_lds((const unsigned*)((const char*)(gbase) + (voff)[_i]), (LAS unsigned*)(lds + (bufoff) + ldsw + _i * 8192), 16, 0, 0); } while (0)
; #define PG8_LDA(dst, b, h) do { _Pragma("unroll") for (int m = 0; m < 4; ++m) _Pragma("unroll") for (int k = 0; k < 2; ++k) dst[m][k] = *(const LAS bf16x8*)(lds + PG8_SA(b, h) + aoff + m * 2048 + k * 1024); } while (0)
; #define PG8_LDB(dst, b, h) do { _Pragma("unroll") for (int n = 0; n < 2; ++n) _Pragma("unroll") for (int k = 0; k < 2; ++k) dst[n][k] = *(const LAS bf16x8*)(lds + PG8_SB(b, h) + boff + n * 2048 + k * 1024); } while (0)
; #define PG8_MMA(ai, bj, At, Bt) do { __builtin_amdgcn_s_setprio(1); _Pragma("unroll") for (int m = 0; m < 4; ++m) _Pragma("unroll") for (int n = 0; n < 2; ++n) _Pragma("unroll") for (int k = 0; k < 2; ++k) \
;         acc[ai][bj][m][n] = __builtin_amdgcn_mfma_f32_16x16x32_bf16(Bt[n][k], At[m][k], acc[ai][bj][m][n], 0, 0, 0); __builtin_amdgcn_s_setprio(0); } while (0)
; #define PG8_WAIT_V(n) asm volatile("s_waitcnt vmcnt(" #n ")" ::: "memory")
; #define PG8_WAIT_L(n) asm volatile("s_waitcnt lgkmcnt(" #n ")" ::: "memory")
; #define PG8_BAR __builtin_amdgcn_s_barrier()
; #define PG8_SCHED __builtin_amdgcn_sched_barrier(0)
; template <class Epi>
; __device__ __forceinline__ void gemm_phase(LAS unsigned char* lds, const Gemm g, const StaticOrder& S, const Epi& E) {
;     ...
;             PG8_LDB(B0, 1, 0); PG8_LDB(B1, 1, 1); PG8_SCHED; PG8_LDA(At, 1, 0); PG8_STAGE(PG8_SA(0, 1), a2 + hstepA, voffA);
;             PG8_WAIT_V(8); PG8_WAIT_L(0); PG8_BAR; PG8_MMA(0, 0, At, B0); PG8_MMA(0, 1, At, B1); PG8_BAR; PG8_SCHED;
;             PG8_LDA(At, 1, 1); PG8_STAGE(PG8_SB(1, 0), b3, voffB); PG8_STAGE(PG8_SB(1, 1), b3 + hstepB, voffB); PG8_STAGE(PG8_SA(1, 0), a3, voffA);
;             PG8_WAIT_V(8); PG8_WAIT_L(0); PG8_BAR; PG8_MMA(1, 0, At, B0); PG8_MMA(1, 1, At, B1); PG8_BAR; PG8_SCHED;
;         }
	s_add_i32 s90, 0, 0x18000
	v_add_u32_e32 v157, s90, v152
	s_add_i32 s91, 0, 0x1c000
	ds_read_b128 v[144:147], v157
	ds_read_b128 v[158:161], v157 offset:1024
	ds_read_b128 v[162:165], v157 offset:2048
	ds_read_b128 v[166:169], v157 offset:3072
	v_add_u32_e32 v157, s91, v152
	ds_read_b128 v[170:173], v157
	ds_read_b128 v[178:181], v157 offset:1024
	ds_read_b128 v[182:185], v157 offset:2048
	ds_read_b128 v[186:189], v157 offset:3072
	s_add_u32 s78, s78, 0x40000
	s_addc_u32 s79, s79, 0
	s_mov_b32 m0, s33
	ds_read_b128 v[190:193], v155 offset:32768
	ds_read_b128 v[194:197], v155 offset:33792
	ds_read_b128 v[198:201], v155 offset:34816
	ds_read_b128 v[202:205], v155 offset:35840
	ds_read_b128 v[206:209], v155 offset:36864
	ds_read_b128 v[210:213], v155 offset:37888
	ds_read_b128 v[214:217], v155 offset:38912
	ds_read_b128 v[218:221], v155 offset:39936
	global_load_lds_dwordx4 v128, s[78:79]
	s_mov_b32 m0, s35
	s_nop 0
	global_load_lds_dwordx4 v132, s[78:79]
	s_waitcnt vmcnt(8)
	s_waitcnt lgkmcnt(0)
	s_barrier
	s_waitcnt lgkmcnt(0)
	v_mfma_f32_16x16x32_bf16 v[124:127], v[144:147], v[190:193], v[124:127]
	v_mfma_f32_16x16x32_bf16 v[120:123], v[162:165], v[190:193], v[120:123]
	v_mfma_f32_16x16x32_bf16 v[108:111], v[144:147], v[198:201], v[108:111]
	v_mfma_f32_16x16x32_bf16 v[104:107], v[162:165], v[198:201], v[104:107]
	v_mfma_f32_16x16x32_bf16 v[92:95], v[144:147], v[206:209], v[92:95]
	v_mfma_f32_16x16x32_bf16 v[88:91], v[162:165], v[206:209], v[88:91]
	v_mfma_f32_16x16x32_bf16 v[76:79], v[144:147], v[214:217], v[76:79]
	v_mfma_f32_16x16x32_bf16 v[72:75], v[162:165], v[214:217], v[72:75]
	v_mfma_f32_16x16x32_bf16 v[124:127], v[158:161], v[194:197], v[124:127]
	v_mfma_f32_16x16x32_bf16 v[120:123], v[166:169], v[194:197], v[120:123]
	v_mfma_f32_16x16x32_bf16 v[108:111], v[158:161], v[202:205], v[108:111]
	v_mfma_f32_16x16x32_bf16 v[104:107], v[166:169], v[202:205], v[104:107]
	v_mfma_f32_16x16x32_bf16 v[92:95], v[158:161], v[210:213], v[92:95]
	v_mfma_f32_16x16x32_bf16 v[88:91], v[166:169], v[210:213], v[88:91]
	v_mfma_f32_16x16x32_bf16 v[76:79], v[158:161], v[218:221], v[76:79]
	v_mfma_f32_16x16x32_bf16 v[72:75], v[166:169], v[218:221], v[72:75]
	v_mfma_f32_16x16x32_bf16 v[116:119], v[170:173], v[190:193], v[116:119]
	v_mfma_f32_16x16x32_bf16 v[112:115], v[182:185], v[190:193], v[112:115]
	v_mfma_f32_16x16x32_bf16 v[100:103], v[170:173], v[198:201], v[100:103]
	v_mfma_f32_16x16x32_bf16 v[96:99], v[182:185], v[198:201], v[96:99]
	v_mfma_f32_16x16x32_bf16 v[84:87], v[170:173], v[206:209], v[84:87]
	v_mfma_f32_16x16x32_bf16 v[80:83], v[182:185], v[206:209], v[80:83]
	v_mfma_f32_16x16x32_bf16 v[68:71], v[170:173], v[214:217], v[68:71]
	v_mfma_f32_16x16x32_bf16 v[64:67], v[182:185], v[214:217], v[64:67]
	v_mfma_f32_16x16x32_bf16 v[116:119], v[178:181], v[194:197], v[116:119]
	v_mfma_f32_16x16x32_bf16 v[112:115], v[186:189], v[194:197], v[112:115]
	v_mfma_f32_16x16x32_bf16 v[100:103], v[178:181], v[202:205], v[100:103]
	v_mfma_f32_16x16x32_bf16 v[96:99], v[186:189], v[202:205], v[96:99]
	v_mfma_f32_16x16x32_bf16 v[84:87], v[178:181], v[210:213], v[84:87]
	v_mfma_f32_16x16x32_bf16 v[80:83], v[186:189], v[210:213], v[80:83]
	v_mfma_f32_16x16x32_bf16 v[68:71], v[178:181], v[218:221], v[68:71]
	v_mfma_f32_16x16x32_bf16 v[64:67], v[186:189], v[218:221], v[64:67]
	s_barrier
	s_add_i32 s78, s90, s3
	v_lshl_add_u64 v[148:149], v[148:149], 0, s[12:13]
	s_mov_b32 m0, s78
	ds_read_b128 v[190:193], v155 offset:49152
	ds_read_b128 v[194:197], v155 offset:50176
	ds_read_b128 v[198:201], v155 offset:51200
	ds_read_b128 v[202:205], v155 offset:52224
	ds_read_b128 v[206:209], v155 offset:53248
	ds_read_b128 v[210:213], v155 offset:54272
	ds_read_b128 v[214:217], v155 offset:55296
	ds_read_b128 v[218:221], v155 offset:56320
	global_load_lds_dwordx4 v[148:149], off
	s_add_i32 m0, s78, 0x2000
	s_add_u32 s76, s76, 0x40080
	v_lshl_add_u64 v[148:149], v[174:175], 0, s[12:13]
	s_addc_u32 s77, s77, 0
	s_add_i32 s78, s91, s3
	global_load_lds_dwordx4 v[148:149], off
	s_mov_b32 m0, s78
	s_nop 0
	global_load_lds_dwordx4 v130, s[76:77]
	s_add_i32 m0, s78, 0x2000
	s_nop 0
	global_load_lds_dwordx4 v134, s[76:77]
	v_lshl_add_u64 v[148:149], v[222:223], 0, s[12:13]
	s_mov_b32 m0, s57
	s_nop 0
	global_load_lds_dwordx4 v[148:149], off
	v_lshl_add_u64 v[148:149], v[226:227], 0, s[12:13]
	s_mov_b32 m0, s80
	s_nop 0
	global_load_lds_dwordx4 v[148:149], off
	s_waitcnt vmcnt(8)
	s_waitcnt lgkmcnt(0)
	s_barrier
	s_waitcnt lgkmcnt(0)
	v_mfma_f32_16x16x32_bf16 v[60:63], v[144:147], v[190:193], v[60:63]
	v_mfma_f32_16x16x32_bf16 v[56:59], v[162:165], v[190:193], v[56:59]
	v_mfma_f32_16x16x32_bf16 v[44:47], v[144:147], v[198:201], v[44:47]
	v_mfma_f32_16x16x32_bf16 v[40:43], v[162:165], v[198:201], v[40:43]
	v_mfma_f32_16x16x32_bf16 v[28:31], v[144:147], v[206:209], v[28:31]
	v_mfma_f32_16x16x32_bf16 v[24:27], v[162:165], v[206:209], v[24:27]
	v_mfma_f32_16x16x32_bf16 v[12:15], v[144:147], v[214:217], v[12:15]
	v_mfma_f32_16x16x32_bf16 v[8:11], v[162:165], v[214:217], v[8:11]
	v_mfma_f32_16x16x32_bf16 v[60:63], v[158:161], v[194:197], v[60:63]
	v_mfma_f32_16x16x32_bf16 v[56:59], v[166:169], v[194:197], v[56:59]
	v_mfma_f32_16x16x32_bf16 v[44:47], v[158:161], v[202:205], v[44:47]
	v_mfma_f32_16x16x32_bf16 v[40:43], v[166:169], v[202:205], v[40:43]
	v_mfma_f32_16x16x32_bf16 v[28:31], v[158:161], v[210:213], v[28:31]
	v_mfma_f32_16x16x32_bf16 v[24:27], v[166:169], v[210:213], v[24:27]
	v_mfma_f32_16x16x32_bf16 v[12:15], v[158:161], v[218:221], v[12:15]
	v_mfma_f32_16x16x32_bf16 v[8:11], v[166:169], v[218:221], v[8:11]
	v_mfma_f32_16x16x32_bf16 v[52:55], v[170:173], v[190:193], v[52:55]
	v_mfma_f32_16x16x32_bf16 v[48:51], v[182:185], v[190:193], v[48:51]
	v_mfma_f32_16x16x32_bf16 v[36:39], v[170:173], v[198:201], v[36:39]
	v_mfma_f32_16x16x32_bf16 v[32:35], v[182:185], v[198:201], v[32:35]
	v_mfma_f32_16x16x32_bf16 v[20:23], v[170:173], v[206:209], v[20:23]
	v_mfma_f32_16x16x32_bf16 v[16:19], v[182:185], v[206:209], v[16:19]
	v_mfma_f32_16x16x32_bf16 v[4:7], v[170:173], v[214:217], v[4:7]
	v_mfma_f32_16x16x32_bf16 v[0:3], v[182:185], v[214:217], v[0:3]
	v_mfma_f32_16x16x32_bf16 v[52:55], v[178:181], v[194:197], v[52:55]
	v_mfma_f32_16x16x32_bf16 v[48:51], v[186:189], v[194:197], v[48:51]
	v_mfma_f32_16x16x32_bf16 v[36:39], v[178:181], v[202:205], v[36:39]
	v_mfma_f32_16x16x32_bf16 v[32:35], v[186:189], v[202:205], v[32:35]
	v_mfma_f32_16x16x32_bf16 v[20:23], v[178:181], v[210:213], v[20:23]
	v_mfma_f32_16x16x32_bf16 v[16:19], v[186:189], v[210:213], v[16:19]
	v_mfma_f32_16x16x32_bf16 v[4:7], v[178:181], v[218:221], v[4:7]
	v_mfma_f32_16x16x32_bf16 v[0:3], v[186:189], v[218:221], v[0:3]
	s_barrier
	s_add_i32 s89, s89, 2
	s_add_u32 s74, s74, 0x100
	s_addc_u32 s75, s75, 0
	s_add_u32 s87, s87, 0x100
	s_addc_u32 s88, s88, 0
	s_cmp_gt_u32 s89, 13
	s_cbranch_scc0 .LBB0_192
	s_and_b64 vcc, exec, s[14:15]
	s_cbranch_vccz .LBB0_195
	s_barrier

; #define PG8_STAGE(bufoff, gbase, voff) do { _Pragma("unroll") for (int _i = 0; _i < 2; ++_i) \
;         __builtin_amdgcn_global_load_lds((const unsigned*)((const char*)(gbase) + (voff)[_i]), (LAS unsigned*)(lds + (bufoff) + ldsw + _i * 8192), 16, 0, 0); } while (0)
; #define PG8_LDA(dst, b, h) do { _Pragma("unroll") for (int m = 0; m < 4; ++m) _Pragma("unroll") for (int k = 0; k < 2; ++k) dst[m][k] = *(const LAS bf16x8*)(lds + PG8_SA(b, h) + aoff + m * 2048 + k * 1024); } while (0)
; #define PG8_LDB(dst, b, h) do { _Pragma("unroll") for (int n = 0; n < 2; ++n) _Pragma("unroll") for (int k = 0; k < 2; ++k) dst[n][k] = *(const LAS bf16x8*)(lds + PG8_SB(b, h) + boff + n * 2048 + k * 1024); } while (0)
; #define PG8_MMA(ai, bj, At, Bt) do { __builtin_amdgcn_s_setprio(1); _Pragma("unroll") for (int m = 0; m < 4; ++m) _Pragma("unroll") for (int n = 0; n < 2; ++n) _Pragma("unroll") for (int k = 0; k < 2; ++k) \
;         acc[ai][bj][m][n] = __builtin_amdgcn_mfma_f32_16x16x32_bf16(Bt[n][k], At[m][k], acc[ai][bj][m][n], 0, 0, 0); __builtin_amdgcn_s_setprio(0); } while (0)
; #define PG8_BAR __builtin_amdgcn_s_barrier()
; template <class Epi>
; __device__ __forceinline__ void gemm_phase(LAS unsigned char* lds, const Gemm g, const StaticOrder& S, const Epi& E) {
;     ...
;         const bool has_next = S.next(ui + 1, nxt);
;         const char* nA = has_next ? (const char*)g.A + (size_t)nxt.pm * tstepA : cA; const char* nB = has_next ? (const char*)g.Bt + (size_t)nxt.pn * tstepB : cB;
; #pragma nounroll
;         for (int t = 0; t < nt; t += 2) {
;             const bool last = (t == nt - 2);
;             const char* a1 = cA + (size_t)(t + 1) * kstep;
;             const char* a2 = last ? nA : cA + (size_t)(t + 2) * kstep; const char* b2 = last ? nB : cB + (size_t)(t + 2) * kstep;
;             const char* a3 = a2 + kstep; const char* b3 = b2 + kstep;
;             PG8_LDB(B0, 0, 0); PG8_LDB(B1, 0, 1); PG8_SCHED; PG8_LDA(At, 0, 0); PG8_STAGE(PG8_SA(1, 1), a1 + hstepA, voffA);
;             PG8_WAIT_V(8); PG8_WAIT_L(0); PG8_BAR; PG8_MMA(0, 0, At, B0); PG8_MMA(0, 1, At, B1); PG8_BAR; PG8_SCHED;
;             PG8_LDA(At, 0, 1); PG8_STAGE(PG8_SB(0, 0), b2, voffB); PG8_STAGE(PG8_SB(0, 1), b2 + hstepB, voffB); PG8_STAGE(PG8_SA(0, 0), a2, voffA);
;             PG8_WAIT_V(8); PG8_WAIT_L(0); PG8_BAR; PG8_MMA(1, 0, At, B0); PG8_MMA(1, 1, At, B1); PG8_BAR; PG8_SCHED;
.LBB0_456:
	s_ashr_i32 s23, s22, 31
	s_lshl_b64 s[28:29], s[22:23], 19
	s_add_u32 s28, s40, s28
	s_addc_u32 s29, s41, s29
	s_and_b64 s[30:31], s[4:5], exec
	s_cselect_b32 s1, s29, s39
	s_cselect_b32 s23, s28, s38
	s_ashr_i32 s19, s18, 31
	s_lshl_b64 s[30:31], s[18:19], 19
	s_add_u32 s30, s3, s30
	s_addc_u32 s31, s33, s31
	s_and_b64 s[52:53], s[4:5], exec
	s_cselect_b32 s19, s31, s43
	s_cselect_b32 s74, s30, s42
	s_add_u32 s38, s38, 0x40080
	s_addc_u32 s39, s39, 0
	s_add_u32 s75, s42, 0x100
	s_addc_u32 s76, s43, 0
	s_mov_b32 s77, -2
	s_waitcnt lgkmcnt(0)
	s_nop 0
	ds_read_b128 v[128:131], v173
	ds_read_b128 v[132:135], v173 offset:1024
	ds_read_b128 v[136:139], v173 offset:2048
	ds_read_b128 v[140:143], v173 offset:3072
	ds_read_b128 v[160:163], v174
	ds_read_b128 v[164:167], v174 offset:1024
	ds_read_b128 v[178:181], v174 offset:2048
	ds_read_b128 v[182:185], v174 offset:3072
	s_add_u32 s42, s38, 0xfffc0080
	s_addc_u32 s43, s39, -1
	s_cmp_eq_u32 s77, 12
	s_cselect_b32 s53, s1, s43
	s_cselect_b32 s52, s23, s42
	s_cselect_b32 s43, s19, s76
	s_cselect_b32 s42, s74, s75
	s_add_i32 m0, s35, 0xc000
	ds_read_b128 v[186:189], v175
	ds_read_b128 v[190:193], v175 offset:1024
	ds_read_b128 v[194:197], v175 offset:2048
	ds_read_b128 v[198:201], v175 offset:3072
	ds_read_b128 v[202:205], v175 offset:4096
	ds_read_b128 v[206:209], v175 offset:5120
	ds_read_b128 v[210:213], v175 offset:6144
	ds_read_b128 v[214:217], v175 offset:7168
	global_load_lds_dwordx4 v152, s[38:39]
	s_add_i32 m0, s35, 0xe000
	s_nop 0
	global_load_lds_dwordx4 v154, s[38:39]
	s_waitcnt vmcnt(8)
	s_waitcnt lgkmcnt(0)
	s_barrier
	s_waitcnt lgkmcnt(0)
	v_mfma_f32_16x16x32_bf16 v[124:127], v[128:131], v[186:189], 0
	v_mfma_f32_16x16x32_bf16 v[120:123], v[136:139], v[186:189], 0
	v_mfma_f32_16x16x32_bf16 v[108:111], v[128:131], v[194:197], 0
	v_mfma_f32_16x16x32_bf16 v[104:107], v[136:139], v[194:197], 0
	v_mfma_f32_16x16x32_bf16 v[92:95], v[128:131], v[202:205], 0
	v_mfma_f32_16x16x32_bf16 v[88:91], v[136:139], v[202:205], 0
	v_mfma_f32_16x16x32_bf16 v[76:79], v[128:131], v[210:213], 0
	v_mfma_f32_16x16x32_bf16 v[72:75], v[136:139], v[210:213], 0
	v_mfma_f32_16x16x32_bf16 v[124:127], v[132:135], v[190:193], v[124:127]
	v_mfma_f32_16x16x32_bf16 v[120:123], v[140:143], v[190:193], v[120:123]
	v_mfma_f32_16x16x32_bf16 v[108:111], v[132:135], v[198:201], v[108:111]
	v_mfma_f32_16x16x32_bf16 v[104:107], v[140:143], v[198:201], v[104:107]
	v_mfma_f32_16x16x32_bf16 v[92:95], v[132:135], v[206:209], v[92:95]
	v_mfma_f32_16x16x32_bf16 v[88:91], v[140:143], v[206:209], v[88:91]
	v_mfma_f32_16x16x32_bf16 v[76:79], v[132:135], v[214:217], v[76:79]
	v_mfma_f32_16x16x32_bf16 v[72:75], v[140:143], v[214:217], v[72:75]
	v_mfma_f32_16x16x32_bf16 v[116:119], v[160:163], v[186:189], 0
	v_mfma_f32_16x16x32_bf16 v[112:115], v[178:181], v[186:189], 0
	v_mfma_f32_16x16x32_bf16 v[100:103], v[160:163], v[194:197], 0
	v_mfma_f32_16x16x32_bf16 v[96:99], v[178:181], v[194:197], 0
	v_mfma_f32_16x16x32_bf16 v[84:87], v[160:163], v[202:205], 0
	v_mfma_f32_16x16x32_bf16 v[80:83], v[178:181], v[202:205], 0
	v_mfma_f32_16x16x32_bf16 v[68:71], v[160:163], v[210:213], 0
	v_mfma_f32_16x16x32_bf16 v[64:67], v[178:181], v[210:213], 0
	v_mfma_f32_16x16x32_bf16 v[116:119], v[164:167], v[190:193], v[116:119]
	v_mfma_f32_16x16x32_bf16 v[112:115], v[182:185], v[190:193], v[112:115]
	v_mfma_f32_16x16x32_bf16 v[100:103], v[164:167], v[198:201], v[100:103]
	v_mfma_f32_16x16x32_bf16 v[96:99], v[182:185], v[198:201], v[96:99]
	v_mfma_f32_16x16x32_bf16 v[84:87], v[164:167], v[206:209], v[84:87]
	v_mfma_f32_16x16x32_bf16 v[80:83], v[182:185], v[206:209], v[80:83]
	v_mfma_f32_16x16x32_bf16 v[68:71], v[164:167], v[214:217], v[68:71]
	v_mfma_f32_16x16x32_bf16 v[64:67], v[182:185], v[214:217], v[64:67]
	s_barrier
	s_add_i32 s78, s72, s54
	v_lshl_add_u64 v[168:169], s[42:43], 0, v[146:147]
	s_mov_b32 m0, s78
	ds_read_b128 v[186:189], v175 offset:16384
	ds_read_b128 v[190:193], v175 offset:17408
	ds_read_b128 v[194:197], v175 offset:18432
	ds_read_b128 v[198:201], v175 offset:19456
	ds_read_b128 v[202:205], v175 offset:20480
	ds_read_b128 v[206:209], v175 offset:21504
	ds_read_b128 v[210:213], v175 offset:22528
	ds_read_b128 v[214:217], v175 offset:23552
	global_load_lds_dwordx4 v[168:169], off
	s_add_i32 m0, s78, 0x2000
	s_add_u32 s78, s42, 0x40000
	v_lshl_add_u64 v[218:219], s[42:43], 0, v[150:151]
	s_addc_u32 s79, s43, 0
	s_add_i32 s80, s73, s54
	global_load_lds_dwordx4 v[218:219], off
	s_mov_b32 m0, s80
	v_lshl_add_u64 v[222:223], s[52:53], 0, v[148:149]
	global_load_lds_dwordx4 v146, s[78:79]
	s_add_i32 m0, s80, 0x2000
	s_nop 0
	global_load_lds_dwordx4 v150, s[78:79]
	v_lshl_add_u64 v[220:221], s[52:53], 0, v[144:145]
	s_mov_b32 m0, s35
	s_nop 0
	global_load_lds_dwordx4 v[220:221], off
	s_mov_b32 m0, s55
	s_nop 0
	global_load_lds_dwordx4 v[222:223], off
	s_waitcnt vmcnt(8)
	s_waitcnt lgkmcnt(0)
	s_barrier
; #define PG8_STAGE(bufoff, gbase, voff) do { _Pragma("unroll") for (int _i = 0; _i < 2; ++_i) \
;         __builtin_amdgcn_global_load_lds((const unsigned*)((const char*)(gbase) + (voff)[_i]), (LAS unsigned*)(lds + (bufoff) + ldsw + _i * 8192), 16, 0, 0); } while (0)
; #define PG8_LDA(dst, b, h) do { _Pragma("unroll") for (int m = 0; m < 4; ++m) _Pragma("unroll") for (int k = 0; k < 2; ++k) dst[m][k] = *(const LAS bf16x8*)(lds + PG8_SA(b, h) + aoff + m * 2048 + k * 1024); } while (0)
; #define PG8_LDB(dst, b, h) do { _Pragma("unroll") for (int n = 0; n < 2; ++n) _Pragma("unroll") for (int k = 0; k < 2; ++k) dst[n][k] = *(const LAS bf16x8*)(lds + PG8_SB(b, h) + boff + n * 2048 + k * 1024); } while (0)
; #define PG8_MMA(ai, bj, At, Bt) do { __builtin_amdgcn_s_setprio(1); _Pragma("unroll") for (int m = 0; m < 4; ++m) _Pragma("unroll") for (int n = 0; n < 2; ++n) _Pragma("unroll") for (int k = 0; k < 2; ++k) \
;         acc[ai][bj][m][n] = __builtin_amdgcn_mfma_f32_16x16x32_bf16(Bt[n][k], At[m][k], acc[ai][bj][m][n], 0, 0, 0); __builtin_amdgcn_s_setprio(0); } while (0)
; #define PG8_WAIT_V(n) asm volatile("s_waitcnt vmcnt(" #n ")" ::: "memory")
; #define PG8_WAIT_L(n) asm volatile("s_waitcnt lgkmcnt(" #n ")" ::: "memory")
; #define PG8_BAR __builtin_amdgcn_s_barrier()
; #define PG8_SCHED __builtin_amdgcn_sched_barrier(0)
; template <class Epi>
; __device__ __forceinline__ void gemm_phase(LAS unsigned char* lds, const Gemm g, const StaticOrder& S, const Epi& E) {
;     ...
;             PG8_WAIT_V(8); PG8_WAIT_L(0); PG8_BAR; PG8_MMA(1, 0, At, B0); PG8_MMA(1, 1, At, B1); PG8_BAR; PG8_SCHED;
;             PG8_LDB(B0, 1, 0); PG8_LDB(B1, 1, 1); PG8_SCHED; PG8_LDA(At, 1, 0); PG8_STAGE(PG8_SA(0, 1), a2 + hstepA, voffA);
;             PG8_WAIT_V(8); PG8_WAIT_L(0); PG8_BAR; PG8_MMA(0, 0, At, B0); PG8_MMA(0, 1, At, B1); PG8_BAR; PG8_SCHED;
	s_waitcnt lgkmcnt(0)
	v_mfma_f32_16x16x32_bf16 v[60:63], v[128:131], v[186:189], 0
	v_mfma_f32_16x16x32_bf16 v[56:59], v[136:139], v[186:189], 0
	v_mfma_f32_16x16x32_bf16 v[44:47], v[128:131], v[194:197], 0
	v_mfma_f32_16x16x32_bf16 v[40:43], v[136:139], v[194:197], 0
	v_mfma_f32_16x16x32_bf16 v[28:31], v[128:131], v[202:205], 0
	v_mfma_f32_16x16x32_bf16 v[24:27], v[136:139], v[202:205], 0
	v_mfma_f32_16x16x32_bf16 v[12:15], v[128:131], v[210:213], 0
	v_mfma_f32_16x16x32_bf16 v[8:11], v[136:139], v[210:213], 0
	v_mfma_f32_16x16x32_bf16 v[60:63], v[132:135], v[190:193], v[60:63]
	v_mfma_f32_16x16x32_bf16 v[56:59], v[140:143], v[190:193], v[56:59]
	v_mfma_f32_16x16x32_bf16 v[44:47], v[132:135], v[198:201], v[44:47]
	v_mfma_f32_16x16x32_bf16 v[40:43], v[140:143], v[198:201], v[40:43]
	v_mfma_f32_16x16x32_bf16 v[28:31], v[132:135], v[206:209], v[28:31]
	v_mfma_f32_16x16x32_bf16 v[24:27], v[140:143], v[206:209], v[24:27]
	v_mfma_f32_16x16x32_bf16 v[12:15], v[132:135], v[214:217], v[12:15]
	v_mfma_f32_16x16x32_bf16 v[8:11], v[140:143], v[214:217], v[8:11]
	v_mfma_f32_16x16x32_bf16 v[52:55], v[160:163], v[186:189], 0
	v_mfma_f32_16x16x32_bf16 v[48:51], v[178:181], v[186:189], 0
	v_mfma_f32_16x16x32_bf16 v[36:39], v[160:163], v[194:197], 0
	v_mfma_f32_16x16x32_bf16 v[32:35], v[178:181], v[194:197], 0
	v_mfma_f32_16x16x32_bf16 v[20:23], v[160:163], v[202:205], 0
	v_mfma_f32_16x16x32_bf16 v[16:19], v[178:181], v[202:205], 0
	v_mfma_f32_16x16x32_bf16 v[4:7], v[160:163], v[210:213], 0
	v_mfma_f32_16x16x32_bf16 v[0:3], v[178:181], v[210:213], 0
	v_mfma_f32_16x16x32_bf16 v[52:55], v[164:167], v[190:193], v[52:55]
	v_mfma_f32_16x16x32_bf16 v[48:51], v[182:185], v[190:193], v[48:51]
	v_mfma_f32_16x16x32_bf16 v[36:39], v[164:167], v[198:201], v[36:39]
	v_mfma_f32_16x16x32_bf16 v[32:35], v[182:185], v[198:201], v[32:35]
	v_mfma_f32_16x16x32_bf16 v[20:23], v[164:167], v[206:209], v[20:23]
	v_mfma_f32_16x16x32_bf16 v[16:19], v[182:185], v[206:209], v[16:19]
	v_mfma_f32_16x16x32_bf16 v[4:7], v[164:167], v[214:217], v[4:7]
	v_mfma_f32_16x16x32_bf16 v[0:3], v[182:185], v[214:217], v[0:3]
	s_barrier
	s_add_i32 s78, 0, 0x18000
	s_add_i32 s79, 0, 0x1c000
	v_add_u32_e32 v140, s78, v172
	v_add_u32_e32 v182, s79, v172
	ds_read_b128 v[128:131], v140
	ds_read_b128 v[132:135], v140 offset:1024
	ds_read_b128 v[136:139], v140 offset:2048
	ds_read_b128 v[140:143], v140 offset:3072
	ds_read_b128 v[160:163], v182
	ds_read_b128 v[164:167], v182 offset:1024
	ds_read_b128 v[178:181], v182 offset:2048
	ds_read_b128 v[182:185], v182 offset:3072
	s_add_u32 s52, s52, 0x40000
	s_addc_u32 s53, s53, 0
	s_mov_b32 m0, s56
	ds_read_b128 v[186:189], v175 offset:32768
	ds_read_b128 v[190:193], v175 offset:33792
	ds_read_b128 v[194:197], v175 offset:34816
	ds_read_b128 v[198:201], v175 offset:35840
	ds_read_b128 v[202:205], v175 offset:36864
	ds_read_b128 v[206:209], v175 offset:37888
	ds_read_b128 v[210:213], v175 offset:38912
	ds_read_b128 v[214:217], v175 offset:39936
	global_load_lds_dwordx4 v144, s[52:53]
	s_mov_b32 m0, s57
	s_nop 0
	global_load_lds_dwordx4 v148, s[52:53]
	s_waitcnt vmcnt(8)
	s_waitcnt lgkmcnt(0)
	s_barrier
	s_waitcnt lgkmcnt(0)
	v_mfma_f32_16x16x32_bf16 v[124:127], v[128:131], v[186:189], v[124:127]
	v_mfma_f32_16x16x32_bf16 v[120:123], v[136:139], v[186:189], v[120:123]
	v_mfma_f32_16x16x32_bf16 v[108:111], v[128:131], v[194:197], v[108:111]
	v_mfma_f32_16x16x32_bf16 v[104:107], v[136:139], v[194:197], v[104:107]
	v_mfma_f32_16x16x32_bf16 v[92:95], v[128:131], v[202:205], v[92:95]
	v_mfma_f32_16x16x32_bf16 v[88:91], v[136:139], v[202:205], v[88:91]
	v_mfma_f32_16x16x32_bf16 v[76:79], v[128:131], v[210:213], v[76:79]
	v_mfma_f32_16x16x32_bf16 v[72:75], v[136:139], v[210:213], v[72:75]
	v_mfma_f32_16x16x32_bf16 v[124:127], v[132:135], v[190:193], v[124:127]
	v_mfma_f32_16x16x32_bf16 v[120:123], v[140:143], v[190:193], v[120:123]
	v_mfma_f32_16x16x32_bf16 v[108:111], v[132:135], v[198:201], v[108:111]
	v_mfma_f32_16x16x32_bf16 v[104:107], v[140:143], v[198:201], v[104:107]
	v_mfma_f32_16x16x32_bf16 v[92:95], v[132:135], v[206:209], v[92:95]
	v_mfma_f32_16x16x32_bf16 v[88:91], v[140:143], v[206:209], v[88:91]
	v_mfma_f32_16x16x32_bf16 v[76:79], v[132:135], v[214:217], v[76:79]
	v_mfma_f32_16x16x32_bf16 v[72:75], v[140:143], v[214:217], v[72:75]
	v_mfma_f32_16x16x32_bf16 v[116:119], v[160:163], v[186:189], v[116:119]
	v_mfma_f32_16x16x32_bf16 v[112:115], v[178:181], v[186:189], v[112:115]
	v_mfma_f32_16x16x32_bf16 v[100:103], v[160:163], v[194:197], v[100:103]
	v_mfma_f32_16x16x32_bf16 v[96:99], v[178:181], v[194:197], v[96:99]
	v_mfma_f32_16x16x32_bf16 v[84:87], v[160:163], v[202:205], v[84:87]
	v_mfma_f32_16x16x32_bf16 v[80:83], v[178:181], v[202:205], v[80:83]
	v_mfma_f32_16x16x32_bf16 v[68:71], v[160:163], v[210:213], v[68:71]
	v_mfma_f32_16x16x32_bf16 v[64:67], v[178:181], v[210:213], v[64:67]
	v_mfma_f32_16x16x32_bf16 v[116:119], v[164:167], v[190:193], v[116:119]
	v_mfma_f32_16x16x32_bf16 v[112:115], v[182:185], v[190:193], v[112:115]
	v_mfma_f32_16x16x32_bf16 v[100:103], v[164:167], v[198:201], v[100:103]
	v_mfma_f32_16x16x32_bf16 v[96:99], v[182:185], v[198:201], v[96:99]
	v_mfma_f32_16x16x32_bf16 v[84:87], v[164:167], v[206:209], v[84:87]
	v_mfma_f32_16x16x32_bf16 v[80:83], v[182:185], v[206:209], v[80:83]
	v_mfma_f32_16x16x32_bf16 v[68:71], v[164:167], v[214:217], v[68:71]
	v_mfma_f32_16x16x32_bf16 v[64:67], v[182:185], v[214:217], v[64:67]
	s_barrier
; #define PG8_STAGE(bufoff, gbase, voff) do { _Pragma("unroll") for (int _i = 0; _i < 2; ++_i) \
;         __builtin_amdgcn_global_load_lds((const unsigned*)((const char*)(gbase) + (voff)[_i]), (LAS unsigned*)(lds + (bufoff) + ldsw + _i * 8192), 16, 0, 0); } while (0)
; #define PG8_LDA(dst, b, h) do { _Pragma("unroll") for (int m = 0; m < 4; ++m) _Pragma("unroll") for (int k = 0; k < 2; ++k) dst[m][k] = *(const LAS bf16x8*)(lds + PG8_SA(b, h) + aoff + m * 2048 + k * 1024); } while (0)
; #define PG8_LDB(dst, b, h) do { _Pragma("unroll") for (int n = 0; n < 2; ++n) _Pragma("unroll") for (int k = 0; k < 2; ++k) dst[n][k] = *(const LAS bf16x8*)(lds + PG8_SB(b, h) + boff + n * 2048 + k * 1024); } while (0)
; #define PG8_MMA(ai, bj, At, Bt) do { __builtin_amdgcn_s_setprio(1); _Pragma("unroll") for (int m = 0; m < 4; ++m) _Pragma("unroll") for (int n = 0; n < 2; ++n) _Pragma("unroll") for (int k = 0; k < 2; ++k) \
;         acc[ai][bj][m][n] = __builtin_amdgcn_mfma_f32_16x16x32_bf16(Bt[n][k], At[m][k], acc[ai][bj][m][n], 0, 0, 0); __builtin_amdgcn_s_setprio(0); } while (0)
; #define PG8_WAIT_V(n) asm volatile("s_waitcnt vmcnt(" #n ")" ::: "memory")
; #define PG8_BAR __builtin_amdgcn_s_barrier()
; template <class Epi>
; __device__ __forceinline__ void gemm_phase(LAS unsigned char* lds, const Gemm g, const StaticOrder& S, const Epi& E) {
;     ...
;             PG8_LDB(B0, 0, 0); PG8_LDB(B1, 0, 1); PG8_SCHED; PG8_LDA(At, 0, 0); PG8_STAGE(PG8_SA(1, 1), a1 + hstepA, voffA);
;             PG8_WAIT_V(8); PG8_WAIT_L(0); PG8_BAR; PG8_MMA(0, 0, At, B0); PG8_MMA(0, 1, At, B1); PG8_BAR; PG8_SCHED;
;             PG8_LDA(At, 0, 1); PG8_STAGE(PG8_SB(0, 0), b2, voffB); PG8_STAGE(PG8_SB(0, 1), b2 + hstepB, voffB); PG8_STAGE(PG8_SA(0, 0), a2, voffA);
;             PG8_WAIT_V(8); PG8_WAIT_L(0); PG8_BAR; PG8_MMA(1, 0, At, B0); PG8_MMA(1, 1, At, B1); PG8_BAR; PG8_SCHED;
;             PG8_LDB(B0, 1, 0); PG8_LDB(B1, 1, 1); PG8_SCHED; PG8_LDA(At, 1, 0); PG8_STAGE(PG8_SA(0, 1), a2 + hstepA, voffA);
;             PG8_WAIT_V(8); PG8_WAIT_L(0); PG8_BAR; PG8_MMA(0, 0, At, B0); PG8_MMA(0, 1, At, B1); PG8_BAR; PG8_SCHED;
;             PG8_LDA(At, 1, 1); PG8_STAGE(PG8_SB(1, 0), b3, voffB); PG8_STAGE(PG8_SB(1, 1), b3 + hstepB, voffB); PG8_STAGE(PG8_SA(1, 0), a3, voffA);
;             PG8_WAIT_V(8); PG8_WAIT_L(0); PG8_BAR; PG8_MMA(1, 0, At, B0); PG8_MMA(1, 1, At, B1); PG8_BAR; PG8_SCHED;
	s_add_i32 s52, s78, s54
	v_lshl_add_u64 v[168:169], v[168:169], 0, s[12:13]
	s_mov_b32 m0, s52
	ds_read_b128 v[186:189], v175 offset:49152
	ds_read_b128 v[190:193], v175 offset:50176
	ds_read_b128 v[194:197], v175 offset:51200
	ds_read_b128 v[198:201], v175 offset:52224
	ds_read_b128 v[202:205], v175 offset:53248
	ds_read_b128 v[206:209], v175 offset:54272
	ds_read_b128 v[210:213], v175 offset:55296
	ds_read_b128 v[214:217], v175 offset:56320
	global_load_lds_dwordx4 v[168:169], off
	s_add_i32 m0, s52, 0x2000
	s_add_u32 s42, s42, 0x40080
	v_lshl_add_u64 v[168:169], v[218:219], 0, s[12:13]
	s_addc_u32 s43, s43, 0
	s_add_i32 s52, s79, s54
	global_load_lds_dwordx4 v[168:169], off
	s_mov_b32 m0, s52
	s_nop 0
	global_load_lds_dwordx4 v146, s[42:43]
	s_add_i32 m0, s52, 0x2000
	s_nop 0
	global_load_lds_dwordx4 v150, s[42:43]
	v_lshl_add_u64 v[168:169], v[220:221], 0, s[12:13]
	s_mov_b32 m0, s65
	s_nop 0
	global_load_lds_dwordx4 v[168:169], off
	v_lshl_add_u64 v[168:169], v[222:223], 0, s[12:13]
	s_mov_b32 m0, s68
	s_nop 0
	global_load_lds_dwordx4 v[168:169], off
	s_waitcnt vmcnt(8)
	s_waitcnt lgkmcnt(0)
	s_barrier
	s_waitcnt lgkmcnt(0)
	v_mfma_f32_16x16x32_bf16 v[60:63], v[128:131], v[186:189], v[60:63]
	v_mfma_f32_16x16x32_bf16 v[56:59], v[136:139], v[186:189], v[56:59]
	v_mfma_f32_16x16x32_bf16 v[44:47], v[128:131], v[194:197], v[44:47]
	v_mfma_f32_16x16x32_bf16 v[40:43], v[136:139], v[194:197], v[40:43]
	v_mfma_f32_16x16x32_bf16 v[28:31], v[128:131], v[202:205], v[28:31]
	v_mfma_f32_16x16x32_bf16 v[24:27], v[136:139], v[202:205], v[24:27]
	v_mfma_f32_16x16x32_bf16 v[12:15], v[128:131], v[210:213], v[12:15]
	v_mfma_f32_16x16x32_bf16 v[8:11], v[136:139], v[210:213], v[8:11]
	v_mfma_f32_16x16x32_bf16 v[60:63], v[132:135], v[190:193], v[60:63]
	v_mfma_f32_16x16x32_bf16 v[56:59], v[140:143], v[190:193], v[56:59]
	v_mfma_f32_16x16x32_bf16 v[44:47], v[132:135], v[198:201], v[44:47]
	v_mfma_f32_16x16x32_bf16 v[40:43], v[140:143], v[198:201], v[40:43]
	v_mfma_f32_16x16x32_bf16 v[28:31], v[132:135], v[206:209], v[28:31]
	v_mfma_f32_16x16x32_bf16 v[24:27], v[140:143], v[206:209], v[24:27]
	v_mfma_f32_16x16x32_bf16 v[12:15], v[132:135], v[214:217], v[12:15]
	v_mfma_f32_16x16x32_bf16 v[8:11], v[140:143], v[214:217], v[8:11]
	v_mfma_f32_16x16x32_bf16 v[52:55], v[160:163], v[186:189], v[52:55]
	v_mfma_f32_16x16x32_bf16 v[48:51], v[178:181], v[186:189], v[48:51]
	v_mfma_f32_16x16x32_bf16 v[36:39], v[160:163], v[194:197], v[36:39]
	v_mfma_f32_16x16x32_bf16 v[32:35], v[178:181], v[194:197], v[32:35]
	v_mfma_f32_16x16x32_bf16 v[20:23], v[160:163], v[202:205], v[20:23]
	v_mfma_f32_16x16x32_bf16 v[16:19], v[178:181], v[202:205], v[16:19]
	v_mfma_f32_16x16x32_bf16 v[4:7], v[160:163], v[210:213], v[4:7]
	v_mfma_f32_16x16x32_bf16 v[0:3], v[178:181], v[210:213], v[0:3]
	v_mfma_f32_16x16x32_bf16 v[52:55], v[164:167], v[190:193], v[52:55]
	v_mfma_f32_16x16x32_bf16 v[48:51], v[182:185], v[190:193], v[48:51]
	v_mfma_f32_16x16x32_bf16 v[36:39], v[164:167], v[198:201], v[36:39]
	v_mfma_f32_16x16x32_bf16 v[32:35], v[182:185], v[198:201], v[32:35]
	v_mfma_f32_16x16x32_bf16 v[20:23], v[164:167], v[206:209], v[20:23]
	v_mfma_f32_16x16x32_bf16 v[16:19], v[182:185], v[206:209], v[16:19]
	v_mfma_f32_16x16x32_bf16 v[4:7], v[164:167], v[214:217], v[4:7]
	v_mfma_f32_16x16x32_bf16 v[0:3], v[182:185], v[214:217], v[0:3]
	s_barrier
	s_add_i32 s77, s77, 2
	s_add_u32 s38, s38, 0x100
	s_addc_u32 s39, s39, 0
	s_add_u32 s75, s75, 0x100
	s_addc_u32 s76, s76, 0
	s_cmp_gt_u32 s77, 13
.LBB0_457:
	ds_read_b128 v[128:131], v173
	ds_read_b128 v[132:135], v173 offset:1024
	ds_read_b128 v[136:139], v173 offset:2048
	ds_read_b128 v[140:143], v173 offset:3072
	ds_read_b128 v[160:163], v174
	ds_read_b128 v[164:167], v174 offset:1024
	ds_read_b128 v[178:181], v174 offset:2048
	ds_read_b128 v[182:185], v174 offset:3072
	s_add_u32 s42, s38, 0xfffc0080
	s_addc_u32 s43, s39, -1
	s_cmp_eq_u32 s77, 12
	s_cselect_b32 s53, s1, s43
	s_cselect_b32 s52, s23, s42
	s_cselect_b32 s43, s19, s76
	s_cselect_b32 s42, s74, s75
	s_add_i32 m0, s35, 0xc000
	ds_read_b128 v[186:189], v175
	ds_read_b128 v[190:193], v175 offset:1024
	ds_read_b128 v[194:197], v175 offset:2048
	ds_read_b128 v[198:201], v175 offset:3072
	ds_read_b128 v[202:205], v175 offset:4096
	ds_read_b128 v[206:209], v175 offset:5120
	ds_read_b128 v[210:213], v175 offset:6144
	ds_read_b128 v[214:217], v175 offset:7168
	global_load_lds_dwordx4 v152, s[38:39]
	s_add_i32 m0, s35, 0xe000
	s_nop 0
	global_load_lds_dwordx4 v154, s[38:39]
	s_waitcnt vmcnt(8)
	s_waitcnt lgkmcnt(0)
	s_barrier
; #define PG8_STAGE(bufoff, gbase, voff) do { _Pragma("unroll") for (int _i = 0; _i < 2; ++_i) \
;         __builtin_amdgcn_global_load_lds((const unsigned*)((const char*)(gbase) + (voff)[_i]), (LAS unsigned*)(lds + (bufoff) + ldsw + _i * 8192), 16, 0, 0); } while (0)
; #define PG8_LDA(dst, b, h) do { _Pragma("unroll") for (int m = 0; m < 4; ++m) _Pragma("unroll") for (int k = 0; k < 2; ++k) dst[m][k] = *(const LAS bf16x8*)(lds + PG8_SA(b, h) + aoff + m * 2048 + k * 1024); } while (0)
; #define PG8_MMA(ai, bj, At, Bt) do { __builtin_amdgcn_s_setprio(1); _Pragma("unroll") for (int m = 0; m < 4; ++m) _Pragma("unroll") for (int n = 0; n < 2; ++n) _Pragma("unroll") for (int k = 0; k < 2; ++k) \
;         acc[ai][bj][m][n] = __builtin_amdgcn_mfma_f32_16x16x32_bf16(Bt[n][k], At[m][k], acc[ai][bj][m][n], 0, 0, 0); __builtin_amdgcn_s_setprio(0); } while (0)
; #define PG8_WAIT_V(n) asm volatile("s_waitcnt vmcnt(" #n ")" ::: "memory")
; #define PG8_WAIT_L(n) asm volatile("s_waitcnt lgkmcnt(" #n ")" ::: "memory")
; #define PG8_BAR __builtin_amdgcn_s_barrier()
; #define PG8_SCHED __builtin_amdgcn_sched_barrier(0)
; template <class Epi>
; __device__ __forceinline__ void gemm_phase(LAS unsigned char* lds, const Gemm g, const StaticOrder& S, const Epi& E) {
;     ...
;             PG8_WAIT_V(8); PG8_WAIT_L(0); PG8_BAR; PG8_MMA(0, 0, At, B0); PG8_MMA(0, 1, At, B1); PG8_BAR; PG8_SCHED;
;             PG8_LDA(At, 0, 1); PG8_STAGE(PG8_SB(0, 0), b2, voffB); PG8_STAGE(PG8_SB(0, 1), b2 + hstepB, voffB); PG8_STAGE(PG8_SA(0, 0), a2, voffA);
;             PG8_WAIT_V(8); PG8_WAIT_L(0); PG8_BAR; PG8_MMA(1, 0, At, B0); PG8_MMA(1, 1, At, B1); PG8_BAR; PG8_SCHED;
	s_waitcnt lgkmcnt(0)
	v_mfma_f32_16x16x32_bf16 v[124:127], v[128:131], v[186:189], v[124:127]
	v_mfma_f32_16x16x32_bf16 v[120:123], v[136:139], v[186:189], v[120:123]
	v_mfma_f32_16x16x32_bf16 v[108:111], v[128:131], v[194:197], v[108:111]
	v_mfma_f32_16x16x32_bf16 v[104:107], v[136:139], v[194:197], v[104:107]
	v_mfma_f32_16x16x32_bf16 v[92:95], v[128:131], v[202:205], v[92:95]
	v_mfma_f32_16x16x32_bf16 v[88:91], v[136:139], v[202:205], v[88:91]
	v_mfma_f32_16x16x32_bf16 v[76:79], v[128:131], v[210:213], v[76:79]
	v_mfma_f32_16x16x32_bf16 v[72:75], v[136:139], v[210:213], v[72:75]
	v_mfma_f32_16x16x32_bf16 v[124:127], v[132:135], v[190:193], v[124:127]
	v_mfma_f32_16x16x32_bf16 v[120:123], v[140:143], v[190:193], v[120:123]
	v_mfma_f32_16x16x32_bf16 v[108:111], v[132:135], v[198:201], v[108:111]
	v_mfma_f32_16x16x32_bf16 v[104:107], v[140:143], v[198:201], v[104:107]
	v_mfma_f32_16x16x32_bf16 v[92:95], v[132:135], v[206:209], v[92:95]
	v_mfma_f32_16x16x32_bf16 v[88:91], v[140:143], v[206:209], v[88:91]
	v_mfma_f32_16x16x32_bf16 v[76:79], v[132:135], v[214:217], v[76:79]
	v_mfma_f32_16x16x32_bf16 v[72:75], v[140:143], v[214:217], v[72:75]
	v_mfma_f32_16x16x32_bf16 v[116:119], v[160:163], v[186:189], v[116:119]
	v_mfma_f32_16x16x32_bf16 v[112:115], v[178:181], v[186:189], v[112:115]
	v_mfma_f32_16x16x32_bf16 v[100:103], v[160:163], v[194:197], v[100:103]
	v_mfma_f32_16x16x32_bf16 v[96:99], v[178:181], v[194:197], v[96:99]
	v_mfma_f32_16x16x32_bf16 v[84:87], v[160:163], v[202:205], v[84:87]
	v_mfma_f32_16x16x32_bf16 v[80:83], v[178:181], v[202:205], v[80:83]
	v_mfma_f32_16x16x32_bf16 v[68:71], v[160:163], v[210:213], v[68:71]
	v_mfma_f32_16x16x32_bf16 v[64:67], v[178:181], v[210:213], v[64:67]
	v_mfma_f32_16x16x32_bf16 v[116:119], v[164:167], v[190:193], v[116:119]
	v_mfma_f32_16x16x32_bf16 v[112:115], v[182:185], v[190:193], v[112:115]
	v_mfma_f32_16x16x32_bf16 v[100:103], v[164:167], v[198:201], v[100:103]
	v_mfma_f32_16x16x32_bf16 v[96:99], v[182:185], v[198:201], v[96:99]
	v_mfma_f32_16x16x32_bf16 v[84:87], v[164:167], v[206:209], v[84:87]
	v_mfma_f32_16x16x32_bf16 v[80:83], v[182:185], v[206:209], v[80:83]
	v_mfma_f32_16x16x32_bf16 v[68:71], v[164:167], v[214:217], v[68:71]
	v_mfma_f32_16x16x32_bf16 v[64:67], v[182:185], v[214:217], v[64:67]
	s_barrier
	s_add_i32 s78, s72, s54
	v_lshl_add_u64 v[168:169], s[42:43], 0, v[146:147]
	s_mov_b32 m0, s78
	ds_read_b128 v[186:189], v175 offset:16384
	ds_read_b128 v[190:193], v175 offset:17408
	ds_read_b128 v[194:197], v175 offset:18432
	ds_read_b128 v[198:201], v175 offset:19456
	ds_read_b128 v[202:205], v175 offset:20480
	ds_read_b128 v[206:209], v175 offset:21504
	ds_read_b128 v[210:213], v175 offset:22528
	ds_read_b128 v[214:217], v175 offset:23552
	global_load_lds_dwordx4 v[168:169], off
	s_add_i32 m0, s78, 0x2000
	s_add_u32 s78, s42, 0x40000
	v_lshl_add_u64 v[218:219], s[42:43], 0, v[150:151]
	s_addc_u32 s79, s43, 0
	s_add_i32 s80, s73, s54
	global_load_lds_dwordx4 v[218:219], off
	s_mov_b32 m0, s80
	v_lshl_add_u64 v[222:223], s[52:53], 0, v[148:149]
	global_load_lds_dwordx4 v146, s[78:79]
	s_add_i32 m0, s80, 0x2000
	s_nop 0
	global_load_lds_dwordx4 v150, s[78:79]
	v_lshl_add_u64 v[220:221], s[52:53], 0, v[144:145]
	s_mov_b32 m0, s35
	s_nop 0
	global_load_lds_dwordx4 v[220:221], off
	s_mov_b32 m0, s55
	s_nop 0
	global_load_lds_dwordx4 v[222:223], off
	s_waitcnt vmcnt(8)
	s_waitcnt lgkmcnt(0)
	s_barrier
	s_waitcnt lgkmcnt(0)
	v_mfma_f32_16x16x32_bf16 v[60:63], v[128:131], v[186:189], v[60:63]
	v_mfma_f32_16x16x32_bf16 v[56:59], v[136:139], v[186:189], v[56:59]
	v_mfma_f32_16x16x32_bf16 v[44:47], v[128:131], v[194:197], v[44:47]
	v_mfma_f32_16x16x32_bf16 v[40:43], v[136:139], v[194:197], v[40:43]
	v_mfma_f32_16x16x32_bf16 v[28:31], v[128:131], v[202:205], v[28:31]
	v_mfma_f32_16x16x32_bf16 v[24:27], v[136:139], v[202:205], v[24:27]
	v_mfma_f32_16x16x32_bf16 v[12:15], v[128:131], v[210:213], v[12:15]
	v_mfma_f32_16x16x32_bf16 v[8:11], v[136:139], v[210:213], v[8:11]
	v_mfma_f32_16x16x32_bf16 v[60:63], v[132:135], v[190:193], v[60:63]
	v_mfma_f32_16x16x32_bf16 v[56:59], v[140:143], v[190:193], v[56:59]
	v_mfma_f32_16x16x32_bf16 v[44:47], v[132:135], v[198:201], v[44:47]
	v_mfma_f32_16x16x32_bf16 v[40:43], v[140:143], v[198:201], v[40:43]
	v_mfma_f32_16x16x32_bf16 v[28:31], v[132:135], v[206:209], v[28:31]
	v_mfma_f32_16x16x32_bf16 v[24:27], v[140:143], v[206:209], v[24:27]
	v_mfma_f32_16x16x32_bf16 v[12:15], v[132:135], v[214:217], v[12:15]
	v_mfma_f32_16x16x32_bf16 v[8:11], v[140:143], v[214:217], v[8:11]
	v_mfma_f32_16x16x32_bf16 v[52:55], v[160:163], v[186:189], v[52:55]
	v_mfma_f32_16x16x32_bf16 v[48:51], v[178:181], v[186:189], v[48:51]
	v_mfma_f32_16x16x32_bf16 v[36:39], v[160:163], v[194:197], v[36:39]
	v_mfma_f32_16x16x32_bf16 v[32:35], v[178:181], v[194:197], v[32:35]
	v_mfma_f32_16x16x32_bf16 v[20:23], v[160:163], v[202:205], v[20:23]
	v_mfma_f32_16x16x32_bf16 v[16:19], v[178:181], v[202:205], v[16:19]
	v_mfma_f32_16x16x32_bf16 v[4:7], v[160:163], v[210:213], v[4:7]
	v_mfma_f32_16x16x32_bf16 v[0:3], v[178:181], v[210:213], v[0:3]
	v_mfma_f32_16x16x32_bf16 v[52:55], v[164:167], v[190:193], v[52:55]
	v_mfma_f32_16x16x32_bf16 v[48:51], v[182:185], v[190:193], v[48:51]
	v_mfma_f32_16x16x32_bf16 v[36:39], v[164:167], v[198:201], v[36:39]
	v_mfma_f32_16x16x32_bf16 v[32:35], v[182:185], v[198:201], v[32:35]
	v_mfma_f32_16x16x32_bf16 v[20:23], v[164:167], v[206:209], v[20:23]
	v_mfma_f32_16x16x32_bf16 v[16:19], v[182:185], v[206:209], v[16:19]
	v_mfma_f32_16x16x32_bf16 v[4:7], v[164:167], v[214:217], v[4:7]
	v_mfma_f32_16x16x32_bf16 v[0:3], v[182:185], v[214:217], v[0:3]
	s_barrier
; #define PG8_STAGE(bufoff, gbase, voff) do { _Pragma("unroll") for (int _i = 0; _i < 2; ++_i) \
;         __builtin_amdgcn_global_load_lds((const unsigned*)((const char*)(gbase) + (voff)[_i]), (LAS unsigned*)(lds + (bufoff) + ldsw + _i * 8192), 16, 0, 0); } while (0)
; #define PG8_LDA(dst, b, h) do { _Pragma("unroll") for (int m = 0; m < 4; ++m) _Pragma("unroll") for (int k = 0; k < 2; ++k) dst[m][k] = *(const LAS bf16x8*)(lds + PG8_SA(b, h) + aoff + m * 2048 + k * 1024); } while (0)
; #define PG8_LDB(dst, b, h) do { _Pragma("unroll") for (int n = 0; n < 2; ++n) _Pragma("unroll") for (int k = 0; k < 2; ++k) dst[n][k] = *(const LAS bf16x8*)(lds + PG8_SB(b, h) + boff + n * 2048 + k * 1024); } while (0)
; #define PG8_MMA(ai, bj, At, Bt) do { __builtin_amdgcn_s_setprio(1); _Pragma("unroll") for (int m = 0; m < 4; ++m) _Pragma("unroll") for (int n = 0; n < 2; ++n) _Pragma("unroll") for (int k = 0; k < 2; ++k) \
;         acc[ai][bj][m][n] = __builtin_amdgcn_mfma_f32_16x16x32_bf16(Bt[n][k], At[m][k], acc[ai][bj][m][n], 0, 0, 0); __builtin_amdgcn_s_setprio(0); } while (0)
; #define PG8_WAIT_V(n) asm volatile("s_waitcnt vmcnt(" #n ")" ::: "memory")
; #define PG8_WAIT_L(n) asm volatile("s_waitcnt lgkmcnt(" #n ")" ::: "memory")
; #define PG8_BAR __builtin_amdgcn_s_barrier()
; #define PG8_SCHED __builtin_amdgcn_sched_barrier(0)
; template <class Epi>
; __device__ __forceinline__ void gemm_phase(LAS unsigned char* lds, const Gemm g, const StaticOrder& S, const Epi& E) {
;     ...
;             PG8_LDB(B0, 1, 0); PG8_LDB(B1, 1, 1); PG8_SCHED; PG8_LDA(At, 1, 0); PG8_STAGE(PG8_SA(0, 1), a2 + hstepA, voffA);
;             PG8_WAIT_V(8); PG8_WAIT_L(0); PG8_BAR; PG8_MMA(0, 0, At, B0); PG8_MMA(0, 1, At, B1); PG8_BAR; PG8_SCHED;
;             PG8_LDA(At, 1, 1); PG8_STAGE(PG8_SB(1, 0), b3, voffB); PG8_STAGE(PG8_SB(1, 1), b3 + hstepB, voffB); PG8_STAGE(PG8_SA(1, 0), a3, voffA);
;             PG8_WAIT_V(8); PG8_WAIT_L(0); PG8_BAR; PG8_MMA(1, 0, At, B0); PG8_MMA(1, 1, At, B1); PG8_BAR; PG8_SCHED;
;         }
	s_add_i32 s78, 0, 0x18000
	s_add_i32 s79, 0, 0x1c000
	v_add_u32_e32 v140, s78, v172
	v_add_u32_e32 v182, s79, v172
	ds_read_b128 v[128:131], v140
	ds_read_b128 v[132:135], v140 offset:1024
	ds_read_b128 v[136:139], v140 offset:2048
	ds_read_b128 v[140:143], v140 offset:3072
	ds_read_b128 v[160:163], v182
	ds_read_b128 v[164:167], v182 offset:1024
	ds_read_b128 v[178:181], v182 offset:2048
	ds_read_b128 v[182:185], v182 offset:3072
	s_add_u32 s52, s52, 0x40000
	s_addc_u32 s53, s53, 0
	s_mov_b32 m0, s56
	ds_read_b128 v[186:189], v175 offset:32768
	ds_read_b128 v[190:193], v175 offset:33792
	ds_read_b128 v[194:197], v175 offset:34816
	ds_read_b128 v[198:201], v175 offset:35840
	ds_read_b128 v[202:205], v175 offset:36864
	ds_read_b128 v[206:209], v175 offset:37888
	ds_read_b128 v[210:213], v175 offset:38912
	ds_read_b128 v[214:217], v175 offset:39936
	global_load_lds_dwordx4 v144, s[52:53]
	s_mov_b32 m0, s57
	s_nop 0
	global_load_lds_dwordx4 v148, s[52:53]
	s_waitcnt vmcnt(8)
	s_waitcnt lgkmcnt(0)
	s_barrier
	s_waitcnt lgkmcnt(0)
	v_mfma_f32_16x16x32_bf16 v[124:127], v[128:131], v[186:189], v[124:127]
	v_mfma_f32_16x16x32_bf16 v[120:123], v[136:139], v[186:189], v[120:123]
	v_mfma_f32_16x16x32_bf16 v[108:111], v[128:131], v[194:197], v[108:111]
	v_mfma_f32_16x16x32_bf16 v[104:107], v[136:139], v[194:197], v[104:107]
	v_mfma_f32_16x16x32_bf16 v[92:95], v[128:131], v[202:205], v[92:95]
	v_mfma_f32_16x16x32_bf16 v[88:91], v[136:139], v[202:205], v[88:91]
	v_mfma_f32_16x16x32_bf16 v[76:79], v[128:131], v[210:213], v[76:79]
	v_mfma_f32_16x16x32_bf16 v[72:75], v[136:139], v[210:213], v[72:75]
	v_mfma_f32_16x16x32_bf16 v[124:127], v[132:135], v[190:193], v[124:127]
	v_mfma_f32_16x16x32_bf16 v[120:123], v[140:143], v[190:193], v[120:123]
	v_mfma_f32_16x16x32_bf16 v[108:111], v[132:135], v[198:201], v[108:111]
	v_mfma_f32_16x16x32_bf16 v[104:107], v[140:143], v[198:201], v[104:107]
	v_mfma_f32_16x16x32_bf16 v[92:95], v[132:135], v[206:209], v[92:95]
	v_mfma_f32_16x16x32_bf16 v[88:91], v[140:143], v[206:209], v[88:91]
	v_mfma_f32_16x16x32_bf16 v[76:79], v[132:135], v[214:217], v[76:79]
	v_mfma_f32_16x16x32_bf16 v[72:75], v[140:143], v[214:217], v[72:75]
	v_mfma_f32_16x16x32_bf16 v[116:119], v[160:163], v[186:189], v[116:119]
	v_mfma_f32_16x16x32_bf16 v[112:115], v[178:181], v[186:189], v[112:115]
	v_mfma_f32_16x16x32_bf16 v[100:103], v[160:163], v[194:197], v[100:103]
	v_mfma_f32_16x16x32_bf16 v[96:99], v[178:181], v[194:197], v[96:99]
	v_mfma_f32_16x16x32_bf16 v[84:87], v[160:163], v[202:205], v[84:87]
	v_mfma_f32_16x16x32_bf16 v[80:83], v[178:181], v[202:205], v[80:83]
	v_mfma_f32_16x16x32_bf16 v[68:71], v[160:163], v[210:213], v[68:71]
	v_mfma_f32_16x16x32_bf16 v[64:67], v[178:181], v[210:213], v[64:67]
	v_mfma_f32_16x16x32_bf16 v[116:119], v[164:167], v[190:193], v[116:119]
	v_mfma_f32_16x16x32_bf16 v[112:115], v[182:185], v[190:193], v[112:115]
	v_mfma_f32_16x16x32_bf16 v[100:103], v[164:167], v[198:201], v[100:103]
	v_mfma_f32_16x16x32_bf16 v[96:99], v[182:185], v[198:201], v[96:99]
	v_mfma_f32_16x16x32_bf16 v[84:87], v[164:167], v[206:209], v[84:87]
	v_mfma_f32_16x16x32_bf16 v[80:83], v[182:185], v[206:209], v[80:83]
	v_mfma_f32_16x16x32_bf16 v[68:71], v[164:167], v[214:217], v[68:71]
	v_mfma_f32_16x16x32_bf16 v[64:67], v[182:185], v[214:217], v[64:67]
	s_barrier
	s_add_i32 s52, s78, s54
	v_lshl_add_u64 v[168:169], v[168:169], 0, s[12:13]
	s_mov_b32 m0, s52
	ds_read_b128 v[186:189], v175 offset:49152
	ds_read_b128 v[190:193], v175 offset:50176
	ds_read_b128 v[194:197], v175 offset:51200
	ds_read_b128 v[198:201], v175 offset:52224
	ds_read_b128 v[202:205], v175 offset:53248
	ds_read_b128 v[206:209], v175 offset:54272
	ds_read_b128 v[210:213], v175 offset:55296
	ds_read_b128 v[214:217], v175 offset:56320
	global_load_lds_dwordx4 v[168:169], off
	s_add_i32 m0, s52, 0x2000
	s_add_u32 s42, s42, 0x40080
	v_lshl_add_u64 v[168:169], v[218:219], 0, s[12:13]
	s_addc_u32 s43, s43, 0
	s_add_i32 s52, s79, s54
	global_load_lds_dwordx4 v[168:169], off
	s_mov_b32 m0, s52
	s_nop 0
	global_load_lds_dwordx4 v146, s[42:43]
	s_add_i32 m0, s52, 0x2000
	s_nop 0
	global_load_lds_dwordx4 v150, s[42:43]
	v_lshl_add_u64 v[168:169], v[220:221], 0, s[12:13]
	s_mov_b32 m0, s65
	s_nop 0
	global_load_lds_dwordx4 v[168:169], off
	v_lshl_add_u64 v[168:169], v[222:223], 0, s[12:13]
	s_mov_b32 m0, s68
	s_nop 0
	global_load_lds_dwordx4 v[168:169], off
	s_waitcnt vmcnt(8)
	s_waitcnt lgkmcnt(0)
	s_barrier
	s_waitcnt lgkmcnt(0)
	v_mfma_f32_16x16x32_bf16 v[60:63], v[128:131], v[186:189], v[60:63]
	v_mfma_f32_16x16x32_bf16 v[56:59], v[136:139], v[186:189], v[56:59]
	v_mfma_f32_16x16x32_bf16 v[44:47], v[128:131], v[194:197], v[44:47]
	v_mfma_f32_16x16x32_bf16 v[40:43], v[136:139], v[194:197], v[40:43]
	v_mfma_f32_16x16x32_bf16 v[28:31], v[128:131], v[202:205], v[28:31]
	v_mfma_f32_16x16x32_bf16 v[24:27], v[136:139], v[202:205], v[24:27]
	v_mfma_f32_16x16x32_bf16 v[12:15], v[128:131], v[210:213], v[12:15]
	v_mfma_f32_16x16x32_bf16 v[8:11], v[136:139], v[210:213], v[8:11]
	v_mfma_f32_16x16x32_bf16 v[60:63], v[132:135], v[190:193], v[60:63]
	v_mfma_f32_16x16x32_bf16 v[56:59], v[140:143], v[190:193], v[56:59]
	v_mfma_f32_16x16x32_bf16 v[44:47], v[132:135], v[198:201], v[44:47]
	v_mfma_f32_16x16x32_bf16 v[40:43], v[140:143], v[198:201], v[40:43]
	v_mfma_f32_16x16x32_bf16 v[28:31], v[132:135], v[206:209], v[28:31]
	v_mfma_f32_16x16x32_bf16 v[24:27], v[140:143], v[206:209], v[24:27]
	v_mfma_f32_16x16x32_bf16 v[12:15], v[132:135], v[214:217], v[12:15]
	v_mfma_f32_16x16x32_bf16 v[8:11], v[140:143], v[214:217], v[8:11]
	v_mfma_f32_16x16x32_bf16 v[52:55], v[160:163], v[186:189], v[52:55]
	v_mfma_f32_16x16x32_bf16 v[48:51], v[178:181], v[186:189], v[48:51]
	v_mfma_f32_16x16x32_bf16 v[36:39], v[160:163], v[194:197], v[36:39]
	v_mfma_f32_16x16x32_bf16 v[32:35], v[178:181], v[194:197], v[32:35]
	v_mfma_f32_16x16x32_bf16 v[20:23], v[160:163], v[202:205], v[20:23]
	v_mfma_f32_16x16x32_bf16 v[16:19], v[178:181], v[202:205], v[16:19]
	v_mfma_f32_16x16x32_bf16 v[4:7], v[160:163], v[210:213], v[4:7]
	v_mfma_f32_16x16x32_bf16 v[0:3], v[178:181], v[210:213], v[0:3]
	v_mfma_f32_16x16x32_bf16 v[52:55], v[164:167], v[190:193], v[52:55]
	v_mfma_f32_16x16x32_bf16 v[48:51], v[182:185], v[190:193], v[48:51]
	v_mfma_f32_16x16x32_bf16 v[36:39], v[164:167], v[198:201], v[36:39]
	v_mfma_f32_16x16x32_bf16 v[32:35], v[182:185], v[198:201], v[32:35]
	v_mfma_f32_16x16x32_bf16 v[20:23], v[164:167], v[206:209], v[20:23]
	v_mfma_f32_16x16x32_bf16 v[16:19], v[182:185], v[206:209], v[16:19]
	v_mfma_f32_16x16x32_bf16 v[4:7], v[164:167], v[214:217], v[4:7]
	v_mfma_f32_16x16x32_bf16 v[0:3], v[182:185], v[214:217], v[0:3]
	s_barrier
	s_add_i32 s77, s77, 2
	s_add_u32 s38, s38, 0x100
	s_addc_u32 s39, s39, 0
	s_add_u32 s75, s75, 0x100
	s_addc_u32 s76, s76, 0
	s_cmp_gt_u32 s77, 13
	s_cbranch_scc0 .LBB0_457
	s_and_b64 vcc, exec, s[14:15]
	s_cbranch_vccz .LBB0_460
	s_barrier

; #define PG8_STAGE(bufoff, gbase, voff) do { _Pragma("unroll") for (int _i = 0; _i < 2; ++_i) \
;         __builtin_amdgcn_global_load_lds((const unsigned*)((const char*)(gbase) + (voff)[_i]), (LAS unsigned*)(lds + (bufoff) + ldsw + _i * 8192), 16, 0, 0); } while (0)
; #define PG8_LDA(dst, b, h) do { _Pragma("unroll") for (int m = 0; m < 4; ++m) _Pragma("unroll") for (int k = 0; k < 2; ++k) dst[m][k] = *(const LAS bf16x8*)(lds + PG8_SA(b, h) + aoff + m * 2048 + k * 1024); } while (0)
; #define PG8_LDB(dst, b, h) do { _Pragma("unroll") for (int n = 0; n < 2; ++n) _Pragma("unroll") for (int k = 0; k < 2; ++k) dst[n][k] = *(const LAS bf16x8*)(lds + PG8_SB(b, h) + boff + n * 2048 + k * 1024); } while (0)
; #define PG8_MMA(ai, bj, At, Bt) do { __builtin_amdgcn_s_setprio(1); _Pragma("unroll") for (int m = 0; m < 4; ++m) _Pragma("unroll") for (int n = 0; n < 2; ++n) _Pragma("unroll") for (int k = 0; k < 2; ++k) \
;         acc[ai][bj][m][n] = __builtin_amdgcn_mfma_f32_16x16x32_bf16(Bt[n][k], At[m][k], acc[ai][bj][m][n], 0, 0, 0); __builtin_amdgcn_s_setprio(0); } while (0)
; #define PG8_BAR __builtin_amdgcn_s_barrier()
; template <class Epi>
; __device__ __forceinline__ void gemm_phase(LAS unsigned char* lds, const Gemm g, const StaticOrder& S, const Epi& E) {
;     ...
;         const bool has_next = S.next(ui + 1, nxt);
;         const char* nA = has_next ? (const char*)g.A + (size_t)nxt.pm * tstepA : cA; const char* nB = has_next ? (const char*)g.Bt + (size_t)nxt.pn * tstepB : cB;
; #pragma nounroll
;         for (int t = 0; t < nt; t += 2) {
;             const bool last = (t == nt - 2);
;             const char* a1 = cA + (size_t)(t + 1) * kstep;
;             const char* a2 = last ? nA : cA + (size_t)(t + 2) * kstep; const char* b2 = last ? nB : cB + (size_t)(t + 2) * kstep;
;             const char* a3 = a2 + kstep; const char* b3 = b2 + kstep;
;             PG8_LDB(B0, 0, 0); PG8_LDB(B1, 0, 1); PG8_SCHED; PG8_LDA(At, 0, 0); PG8_STAGE(PG8_SA(1, 1), a1 + hstepA, voffA);
;             PG8_WAIT_V(8); PG8_WAIT_L(0); PG8_BAR; PG8_MMA(0, 0, At, B0); PG8_MMA(0, 1, At, B1); PG8_BAR; PG8_SCHED;
;             PG8_LDA(At, 0, 1); PG8_STAGE(PG8_SB(0, 0), b2, voffB); PG8_STAGE(PG8_SB(0, 1), b2 + hstepB, voffB); PG8_STAGE(PG8_SA(0, 0), a2, voffA);
;             PG8_WAIT_V(8); PG8_WAIT_L(0); PG8_BAR; PG8_MMA(1, 0, At, B0); PG8_MMA(1, 1, At, B1); PG8_BAR; PG8_SCHED;
.LBB0_545:
	s_ashr_i32 s71, s70, 31
	s_lshl_b64 s[12:13], s[70:71], 19
	s_add_u32 s72, s24, s12
	s_addc_u32 s73, s25, s13
	s_and_b64 s[12:13], s[4:5], exec
	s_cselect_b32 s1, s73, s9
	s_cselect_b32 s7, s72, s8
	s_ashr_i32 s69, s68, 31
	s_lshl_b64 s[12:13], s[68:69], 19
	s_add_u32 s74, s3, s12
	s_addc_u32 s75, s33, s13
	s_and_b64 s[12:13], s[4:5], exec
	s_cselect_b32 s69, s75, s11
	s_cselect_b32 s71, s74, s10
	s_add_u32 s8, s8, 0x40080
	s_addc_u32 s9, s9, 0
	s_add_u32 s76, s10, 0x100
	s_addc_u32 s77, s11, 0
	s_mov_b32 s89, -2
	s_nop 0
	v_lshl_add_u32 v248, s6, 8, v151
	v_add_u32_e32 v248, s65, v248
	v_ashrrev_i32_e32 v249, 31, v248
	v_lshl_add_u64 v[248:249], v[248:249], 2, s[22:23]
	global_load_dword v240, v[248:249], off
	global_load_dword v241, v[248:249], off offset:64
	global_load_dword v242, v[248:249], off offset:128
	global_load_dword v243, v[248:249], off offset:192
	global_load_dword v244, v[248:249], off offset:512
	global_load_dword v245, v[248:249], off offset:576
	global_load_dword v246, v[248:249], off offset:640
	global_load_dword v247, v[248:249], off offset:704
	ds_read_b128 v[146:149], v162
	ds_read_b128 v[166:169], v162 offset:1024
	ds_read_b128 v[170:173], v162 offset:2048
	ds_read_b128 v[178:181], v162 offset:3072
	ds_read_b128 v[182:185], v163
	ds_read_b128 v[186:189], v163 offset:1024
	ds_read_b128 v[190:193], v163 offset:2048
	ds_read_b128 v[194:197], v163 offset:3072
	s_add_u32 s10, s8, 0xfffc0080
	s_addc_u32 s11, s9, -1
	s_cmp_eq_u32 s89, 12
	s_cselect_b32 s13, s1, s11
	s_cselect_b32 s12, s7, s10
	s_cselect_b32 s11, s69, s77
	s_cselect_b32 s10, s71, s76
	s_add_i32 m0, s43, 0xc000
	ds_read_b128 v[198:201], v164
	ds_read_b128 v[202:205], v164 offset:1024
	ds_read_b128 v[206:209], v164 offset:2048
	ds_read_b128 v[210:213], v164 offset:3072
	ds_read_b128 v[214:217], v164 offset:4096
	ds_read_b128 v[218:221], v164 offset:5120
	ds_read_b128 v[226:229], v164 offset:6144
	ds_read_b128 v[230:233], v164 offset:7168
	global_load_lds_dwordx4 v138, s[8:9]
	s_add_i32 m0, s43, 0xe000
	s_nop 0
	global_load_lds_dwordx4 v140, s[8:9]
	s_waitcnt vmcnt(8)
	s_waitcnt lgkmcnt(0)
	s_barrier
	s_waitcnt lgkmcnt(0)
	v_mfma_f32_16x16x32_bf16 v[124:127], v[146:149], v[198:201], 0
	v_mfma_f32_16x16x32_bf16 v[120:123], v[170:173], v[198:201], 0
	v_mfma_f32_16x16x32_bf16 v[112:115], v[146:149], v[206:209], 0
	v_mfma_f32_16x16x32_bf16 v[104:107], v[170:173], v[206:209], 0
	v_mfma_f32_16x16x32_bf16 v[100:103], v[146:149], v[214:217], 0
	v_mfma_f32_16x16x32_bf16 v[92:95], v[170:173], v[214:217], 0
	v_mfma_f32_16x16x32_bf16 v[84:87], v[146:149], v[226:229], 0
	v_mfma_f32_16x16x32_bf16 v[76:79], v[170:173], v[226:229], 0
	v_mfma_f32_16x16x32_bf16 v[124:127], v[166:169], v[202:205], v[124:127]
	v_mfma_f32_16x16x32_bf16 v[120:123], v[178:181], v[202:205], v[120:123]
	v_mfma_f32_16x16x32_bf16 v[112:115], v[166:169], v[210:213], v[112:115]
	v_mfma_f32_16x16x32_bf16 v[104:107], v[178:181], v[210:213], v[104:107]
	v_mfma_f32_16x16x32_bf16 v[100:103], v[166:169], v[218:221], v[100:103]
	v_mfma_f32_16x16x32_bf16 v[92:95], v[178:181], v[218:221], v[92:95]
	v_mfma_f32_16x16x32_bf16 v[84:87], v[166:169], v[230:233], v[84:87]
	v_mfma_f32_16x16x32_bf16 v[76:79], v[178:181], v[230:233], v[76:79]
	v_mfma_f32_16x16x32_bf16 v[116:119], v[182:185], v[198:201], 0
	v_mfma_f32_16x16x32_bf16 v[108:111], v[190:193], v[198:201], 0
	v_mfma_f32_16x16x32_bf16 v[96:99], v[182:185], v[206:209], 0
	v_mfma_f32_16x16x32_bf16 v[88:91], v[190:193], v[206:209], 0
	v_mfma_f32_16x16x32_bf16 v[80:83], v[182:185], v[214:217], 0
	v_mfma_f32_16x16x32_bf16 v[72:75], v[190:193], v[214:217], 0
	v_mfma_f32_16x16x32_bf16 v[68:71], v[182:185], v[226:229], 0
	v_mfma_f32_16x16x32_bf16 v[64:67], v[190:193], v[226:229], 0
	v_mfma_f32_16x16x32_bf16 v[116:119], v[186:189], v[202:205], v[116:119]
	v_mfma_f32_16x16x32_bf16 v[108:111], v[194:197], v[202:205], v[108:111]
	v_mfma_f32_16x16x32_bf16 v[96:99], v[186:189], v[210:213], v[96:99]
	v_mfma_f32_16x16x32_bf16 v[88:91], v[194:197], v[210:213], v[88:91]
	v_mfma_f32_16x16x32_bf16 v[80:83], v[186:189], v[218:221], v[80:83]
	v_mfma_f32_16x16x32_bf16 v[72:75], v[194:197], v[218:221], v[72:75]
	v_mfma_f32_16x16x32_bf16 v[68:71], v[186:189], v[230:233], v[68:71]
	v_mfma_f32_16x16x32_bf16 v[64:67], v[194:197], v[230:233], v[64:67]
	s_barrier
	s_add_i32 s90, s85, s39
	v_lshl_add_u64 v[174:175], s[10:11], 0, v[130:131]
	s_mov_b32 m0, s90
	ds_read_b128 v[198:201], v164 offset:16384
	ds_read_b128 v[202:205], v164 offset:17408
	ds_read_b128 v[206:209], v164 offset:18432
	ds_read_b128 v[210:213], v164 offset:19456
	ds_read_b128 v[214:217], v164 offset:20480
	ds_read_b128 v[218:221], v164 offset:21504
	ds_read_b128 v[226:229], v164 offset:22528
	ds_read_b128 v[230:233], v164 offset:23552
	global_load_lds_dwordx4 v[174:175], off
	s_add_i32 m0, s90, 0x2000
	s_add_u32 s90, s10, 0x40000
	v_lshl_add_u64 v[222:223], s[10:11], 0, v[134:135]
	s_addc_u32 s91, s11, 0
	s_add_i32 s92, s86, s39
	global_load_lds_dwordx4 v[222:223], off
	s_mov_b32 m0, s92
	v_lshl_add_u64 v[236:237], s[12:13], 0, v[132:133]
	global_load_lds_dwordx4 v130, s[90:91]
	s_add_i32 m0, s92, 0x2000
	s_nop 0
	global_load_lds_dwordx4 v134, s[90:91]
	v_lshl_add_u64 v[234:235], s[12:13], 0, v[128:129]
	s_mov_b32 m0, s43
	s_nop 0
	global_load_lds_dwordx4 v[234:235], off
	s_mov_b32 m0, s53
	s_nop 0
	global_load_lds_dwordx4 v[236:237], off
	s_waitcnt vmcnt(8)
	s_waitcnt lgkmcnt(0)
	s_barrier
; #define PG8_STAGE(bufoff, gbase, voff) do { _Pragma("unroll") for (int _i = 0; _i < 2; ++_i) \
;         __builtin_amdgcn_global_load_lds((const unsigned*)((const char*)(gbase) + (voff)[_i]), (LAS unsigned*)(lds + (bufoff) + ldsw + _i * 8192), 16, 0, 0); } while (0)
; #define PG8_LDA(dst, b, h) do { _Pragma("unroll") for (int m = 0; m < 4; ++m) _Pragma("unroll") for (int k = 0; k < 2; ++k) dst[m][k] = *(const LAS bf16x8*)(lds + PG8_SA(b, h) + aoff + m * 2048 + k * 1024); } while (0)
; #define PG8_LDB(dst, b, h) do { _Pragma("unroll") for (int n = 0; n < 2; ++n) _Pragma("unroll") for (int k = 0; k < 2; ++k) dst[n][k] = *(const LAS bf16x8*)(lds + PG8_SB(b, h) + boff + n * 2048 + k * 1024); } while (0)
; #define PG8_MMA(ai, bj, At, Bt) do { __builtin_amdgcn_s_setprio(1); _Pragma("unroll") for (int m = 0; m < 4; ++m) _Pragma("unroll") for (int n = 0; n < 2; ++n) _Pragma("unroll") for (int k = 0; k < 2; ++k) \
;         acc[ai][bj][m][n] = __builtin_amdgcn_mfma_f32_16x16x32_bf16(Bt[n][k], At[m][k], acc[ai][bj][m][n], 0, 0, 0); __builtin_amdgcn_s_setprio(0); } while (0)
; #define PG8_WAIT_V(n) asm volatile("s_waitcnt vmcnt(" #n ")" ::: "memory")
; #define PG8_WAIT_L(n) asm volatile("s_waitcnt lgkmcnt(" #n ")" ::: "memory")
; #define PG8_BAR __builtin_amdgcn_s_barrier()
; #define PG8_SCHED __builtin_amdgcn_sched_barrier(0)
; template <class Epi>
; __device__ __forceinline__ void gemm_phase(LAS unsigned char* lds, const Gemm g, const StaticOrder& S, const Epi& E) {
;     ...
;             PG8_WAIT_V(8); PG8_WAIT_L(0); PG8_BAR; PG8_MMA(1, 0, At, B0); PG8_MMA(1, 1, At, B1); PG8_BAR; PG8_SCHED;
;             PG8_LDB(B0, 1, 0); PG8_LDB(B1, 1, 1); PG8_SCHED; PG8_LDA(At, 1, 0); PG8_STAGE(PG8_SA(0, 1), a2 + hstepA, voffA);
;             PG8_WAIT_V(8); PG8_WAIT_L(0); PG8_BAR; PG8_MMA(0, 0, At, B0); PG8_MMA(0, 1, At, B1); PG8_BAR; PG8_SCHED;
	s_waitcnt lgkmcnt(0)
	v_mfma_f32_16x16x32_bf16 v[60:63], v[146:149], v[198:201], 0
	v_mfma_f32_16x16x32_bf16 v[56:59], v[170:173], v[198:201], 0
	v_mfma_f32_16x16x32_bf16 v[52:55], v[146:149], v[206:209], 0
	v_mfma_f32_16x16x32_bf16 v[44:47], v[170:173], v[206:209], 0
	v_mfma_f32_16x16x32_bf16 v[36:39], v[146:149], v[214:217], 0
	v_mfma_f32_16x16x32_bf16 v[28:31], v[170:173], v[214:217], 0
	v_mfma_f32_16x16x32_bf16 v[20:23], v[146:149], v[226:229], 0
	v_mfma_f32_16x16x32_bf16 v[12:15], v[170:173], v[226:229], 0
	v_mfma_f32_16x16x32_bf16 v[60:63], v[166:169], v[202:205], v[60:63]
	v_mfma_f32_16x16x32_bf16 v[56:59], v[178:181], v[202:205], v[56:59]
	v_mfma_f32_16x16x32_bf16 v[52:55], v[166:169], v[210:213], v[52:55]
	v_mfma_f32_16x16x32_bf16 v[44:47], v[178:181], v[210:213], v[44:47]
	v_mfma_f32_16x16x32_bf16 v[36:39], v[166:169], v[218:221], v[36:39]
	v_mfma_f32_16x16x32_bf16 v[28:31], v[178:181], v[218:221], v[28:31]
	v_mfma_f32_16x16x32_bf16 v[20:23], v[166:169], v[230:233], v[20:23]
	v_mfma_f32_16x16x32_bf16 v[12:15], v[178:181], v[230:233], v[12:15]
	v_mfma_f32_16x16x32_bf16 v[48:51], v[182:185], v[198:201], 0
	v_mfma_f32_16x16x32_bf16 v[40:43], v[190:193], v[198:201], 0
	v_mfma_f32_16x16x32_bf16 v[32:35], v[182:185], v[206:209], 0
	v_mfma_f32_16x16x32_bf16 v[24:27], v[190:193], v[206:209], 0
	v_mfma_f32_16x16x32_bf16 v[16:19], v[182:185], v[214:217], 0
	v_mfma_f32_16x16x32_bf16 v[8:11], v[190:193], v[214:217], 0
	v_mfma_f32_16x16x32_bf16 v[4:7], v[182:185], v[226:229], 0
	v_mfma_f32_16x16x32_bf16 v[0:3], v[190:193], v[226:229], 0
	v_mfma_f32_16x16x32_bf16 v[48:51], v[186:189], v[202:205], v[48:51]
	v_mfma_f32_16x16x32_bf16 v[40:43], v[194:197], v[202:205], v[40:43]
	v_mfma_f32_16x16x32_bf16 v[32:35], v[186:189], v[210:213], v[32:35]
	v_mfma_f32_16x16x32_bf16 v[24:27], v[194:197], v[210:213], v[24:27]
	v_mfma_f32_16x16x32_bf16 v[16:19], v[186:189], v[218:221], v[16:19]
	v_mfma_f32_16x16x32_bf16 v[8:11], v[194:197], v[218:221], v[8:11]
	v_mfma_f32_16x16x32_bf16 v[4:7], v[186:189], v[230:233], v[4:7]
	v_mfma_f32_16x16x32_bf16 v[0:3], v[194:197], v[230:233], v[0:3]
	s_barrier
	s_add_i32 s90, 0, 0x18000
	v_add_u32_e32 v136, s90, v161
	s_add_i32 s91, 0, 0x1c000
	ds_read_b128 v[146:149], v136
	ds_read_b128 v[166:169], v136 offset:1024
	ds_read_b128 v[170:173], v136 offset:2048
	ds_read_b128 v[178:181], v136 offset:3072
	v_add_u32_e32 v136, s91, v161
	ds_read_b128 v[182:185], v136
	ds_read_b128 v[186:189], v136 offset:1024
	ds_read_b128 v[190:193], v136 offset:2048
	ds_read_b128 v[194:197], v136 offset:3072
	s_add_u32 s12, s12, 0x40000
	s_addc_u32 s13, s13, 0
	s_mov_b32 m0, s55
	ds_read_b128 v[198:201], v164 offset:32768
	ds_read_b128 v[202:205], v164 offset:33792
	ds_read_b128 v[206:209], v164 offset:34816
	ds_read_b128 v[210:213], v164 offset:35840
	ds_read_b128 v[214:217], v164 offset:36864
	ds_read_b128 v[218:221], v164 offset:37888
	ds_read_b128 v[226:229], v164 offset:38912
	ds_read_b128 v[230:233], v164 offset:39936
	global_load_lds_dwordx4 v128, s[12:13]
	s_mov_b32 m0, s57
	s_nop 0
	global_load_lds_dwordx4 v132, s[12:13]
	s_waitcnt vmcnt(8)
	s_waitcnt lgkmcnt(0)
	s_barrier
	s_waitcnt lgkmcnt(0)
	v_mfma_f32_16x16x32_bf16 v[124:127], v[146:149], v[198:201], v[124:127]
	v_mfma_f32_16x16x32_bf16 v[120:123], v[170:173], v[198:201], v[120:123]
	v_mfma_f32_16x16x32_bf16 v[112:115], v[146:149], v[206:209], v[112:115]
	v_mfma_f32_16x16x32_bf16 v[104:107], v[170:173], v[206:209], v[104:107]
	v_mfma_f32_16x16x32_bf16 v[100:103], v[146:149], v[214:217], v[100:103]
	v_mfma_f32_16x16x32_bf16 v[92:95], v[170:173], v[214:217], v[92:95]
	v_mfma_f32_16x16x32_bf16 v[84:87], v[146:149], v[226:229], v[84:87]
	v_mfma_f32_16x16x32_bf16 v[76:79], v[170:173], v[226:229], v[76:79]
	v_mfma_f32_16x16x32_bf16 v[124:127], v[166:169], v[202:205], v[124:127]
	v_mfma_f32_16x16x32_bf16 v[120:123], v[178:181], v[202:205], v[120:123]
	v_mfma_f32_16x16x32_bf16 v[112:115], v[166:169], v[210:213], v[112:115]
	v_mfma_f32_16x16x32_bf16 v[104:107], v[178:181], v[210:213], v[104:107]
	v_mfma_f32_16x16x32_bf16 v[100:103], v[166:169], v[218:221], v[100:103]
	v_mfma_f32_16x16x32_bf16 v[92:95], v[178:181], v[218:221], v[92:95]
	v_mfma_f32_16x16x32_bf16 v[84:87], v[166:169], v[230:233], v[84:87]
	v_mfma_f32_16x16x32_bf16 v[76:79], v[178:181], v[230:233], v[76:79]
	v_mfma_f32_16x16x32_bf16 v[116:119], v[182:185], v[198:201], v[116:119]
	v_mfma_f32_16x16x32_bf16 v[108:111], v[190:193], v[198:201], v[108:111]
	v_mfma_f32_16x16x32_bf16 v[96:99], v[182:185], v[206:209], v[96:99]
	v_mfma_f32_16x16x32_bf16 v[88:91], v[190:193], v[206:209], v[88:91]
	v_mfma_f32_16x16x32_bf16 v[80:83], v[182:185], v[214:217], v[80:83]
	v_mfma_f32_16x16x32_bf16 v[72:75], v[190:193], v[214:217], v[72:75]
	v_mfma_f32_16x16x32_bf16 v[68:71], v[182:185], v[226:229], v[68:71]
	v_mfma_f32_16x16x32_bf16 v[64:67], v[190:193], v[226:229], v[64:67]
	v_mfma_f32_16x16x32_bf16 v[116:119], v[186:189], v[202:205], v[116:119]
	v_mfma_f32_16x16x32_bf16 v[108:111], v[194:197], v[202:205], v[108:111]
	v_mfma_f32_16x16x32_bf16 v[96:99], v[186:189], v[210:213], v[96:99]
	v_mfma_f32_16x16x32_bf16 v[88:91], v[194:197], v[210:213], v[88:91]
	v_mfma_f32_16x16x32_bf16 v[80:83], v[186:189], v[218:221], v[80:83]
	v_mfma_f32_16x16x32_bf16 v[72:75], v[194:197], v[218:221], v[72:75]
	v_mfma_f32_16x16x32_bf16 v[68:71], v[186:189], v[230:233], v[68:71]
	v_mfma_f32_16x16x32_bf16 v[64:67], v[194:197], v[230:233], v[64:67]
	s_barrier
; #define PG8_STAGE(bufoff, gbase, voff) do { _Pragma("unroll") for (int _i = 0; _i < 2; ++_i) \
;         __builtin_amdgcn_global_load_lds((const unsigned*)((const char*)(gbase) + (voff)[_i]), (LAS unsigned*)(lds + (bufoff) + ldsw + _i * 8192), 16, 0, 0); } while (0)
; #define PG8_LDA(dst, b, h) do { _Pragma("unroll") for (int m = 0; m < 4; ++m) _Pragma("unroll") for (int k = 0; k < 2; ++k) dst[m][k] = *(const LAS bf16x8*)(lds + PG8_SA(b, h) + aoff + m * 2048 + k * 1024); } while (0)
; #define PG8_LDB(dst, b, h) do { _Pragma("unroll") for (int n = 0; n < 2; ++n) _Pragma("unroll") for (int k = 0; k < 2; ++k) dst[n][k] = *(const LAS bf16x8*)(lds + PG8_SB(b, h) + boff + n * 2048 + k * 1024); } while (0)
; #define PG8_MMA(ai, bj, At, Bt) do { __builtin_amdgcn_s_setprio(1); _Pragma("unroll") for (int m = 0; m < 4; ++m) _Pragma("unroll") for (int n = 0; n < 2; ++n) _Pragma("unroll") for (int k = 0; k < 2; ++k) \
;         acc[ai][bj][m][n] = __builtin_amdgcn_mfma_f32_16x16x32_bf16(Bt[n][k], At[m][k], acc[ai][bj][m][n], 0, 0, 0); __builtin_amdgcn_s_setprio(0); } while (0)
; #define PG8_WAIT_V(n) asm volatile("s_waitcnt vmcnt(" #n ")" ::: "memory")
; #define PG8_BAR __builtin_amdgcn_s_barrier()
; template <class Epi>
; __device__ __forceinline__ void gemm_phase(LAS unsigned char* lds, const Gemm g, const StaticOrder& S, const Epi& E) {
;     ...
;             PG8_LDB(B0, 0, 0); PG8_LDB(B1, 0, 1); PG8_SCHED; PG8_LDA(At, 0, 0); PG8_STAGE(PG8_SA(1, 1), a1 + hstepA, voffA);
;             PG8_WAIT_V(8); PG8_WAIT_L(0); PG8_BAR; PG8_MMA(0, 0, At, B0); PG8_MMA(0, 1, At, B1); PG8_BAR; PG8_SCHED;
;             PG8_LDA(At, 0, 1); PG8_STAGE(PG8_SB(0, 0), b2, voffB); PG8_STAGE(PG8_SB(0, 1), b2 + hstepB, voffB); PG8_STAGE(PG8_SA(0, 0), a2, voffA);
;             PG8_WAIT_V(8); PG8_WAIT_L(0); PG8_BAR; PG8_MMA(1, 0, At, B0); PG8_MMA(1, 1, At, B1); PG8_BAR; PG8_SCHED;
;             PG8_LDB(B0, 1, 0); PG8_LDB(B1, 1, 1); PG8_SCHED; PG8_LDA(At, 1, 0); PG8_STAGE(PG8_SA(0, 1), a2 + hstepA, voffA);
;             PG8_WAIT_V(8); PG8_WAIT_L(0); PG8_BAR; PG8_MMA(0, 0, At, B0); PG8_MMA(0, 1, At, B1); PG8_BAR; PG8_SCHED;
;             PG8_LDA(At, 1, 1); PG8_STAGE(PG8_SB(1, 0), b3, voffB); PG8_STAGE(PG8_SB(1, 1), b3 + hstepB, voffB); PG8_STAGE(PG8_SA(1, 0), a3, voffA);
;             PG8_WAIT_V(8); PG8_WAIT_L(0); PG8_BAR; PG8_MMA(1, 0, At, B0); PG8_MMA(1, 1, At, B1); PG8_BAR; PG8_SCHED;
	s_add_i32 s12, s90, s39
	v_lshl_add_u64 v[174:175], v[174:175], 0, s[30:31]
	s_mov_b32 m0, s12
	ds_read_b128 v[198:201], v164 offset:49152
	ds_read_b128 v[202:205], v164 offset:50176
	ds_read_b128 v[206:209], v164 offset:51200
	ds_read_b128 v[210:213], v164 offset:52224
	ds_read_b128 v[214:217], v164 offset:53248
	ds_read_b128 v[218:221], v164 offset:54272
	ds_read_b128 v[226:229], v164 offset:55296
	ds_read_b128 v[230:233], v164 offset:56320
	global_load_lds_dwordx4 v[174:175], off
	s_add_i32 m0, s12, 0x2000
	s_add_u32 s10, s10, 0x40080
	v_lshl_add_u64 v[174:175], v[222:223], 0, s[30:31]
	s_addc_u32 s11, s11, 0
	s_add_i32 s12, s91, s39
	global_load_lds_dwordx4 v[174:175], off
	s_mov_b32 m0, s12
	s_nop 0
	global_load_lds_dwordx4 v130, s[10:11]
	s_add_i32 m0, s12, 0x2000
	s_nop 0
	global_load_lds_dwordx4 v134, s[10:11]
	v_lshl_add_u64 v[174:175], v[234:235], 0, s[30:31]
	s_mov_b32 m0, s79
	s_nop 0
	global_load_lds_dwordx4 v[174:175], off
	v_lshl_add_u64 v[174:175], v[236:237], 0, s[30:31]
	s_mov_b32 m0, s80
	s_nop 0
	global_load_lds_dwordx4 v[174:175], off
	s_waitcnt vmcnt(8)
	s_waitcnt lgkmcnt(0)
	s_barrier
	s_waitcnt lgkmcnt(0)
	v_mfma_f32_16x16x32_bf16 v[60:63], v[146:149], v[198:201], v[60:63]
	v_mfma_f32_16x16x32_bf16 v[56:59], v[170:173], v[198:201], v[56:59]
	v_mfma_f32_16x16x32_bf16 v[52:55], v[146:149], v[206:209], v[52:55]
	v_mfma_f32_16x16x32_bf16 v[44:47], v[170:173], v[206:209], v[44:47]
	v_mfma_f32_16x16x32_bf16 v[36:39], v[146:149], v[214:217], v[36:39]
	v_mfma_f32_16x16x32_bf16 v[28:31], v[170:173], v[214:217], v[28:31]
	v_mfma_f32_16x16x32_bf16 v[20:23], v[146:149], v[226:229], v[20:23]
	v_mfma_f32_16x16x32_bf16 v[12:15], v[170:173], v[226:229], v[12:15]
	v_mfma_f32_16x16x32_bf16 v[60:63], v[166:169], v[202:205], v[60:63]
	v_mfma_f32_16x16x32_bf16 v[56:59], v[178:181], v[202:205], v[56:59]
	v_mfma_f32_16x16x32_bf16 v[52:55], v[166:169], v[210:213], v[52:55]
	v_mfma_f32_16x16x32_bf16 v[44:47], v[178:181], v[210:213], v[44:47]
	v_mfma_f32_16x16x32_bf16 v[36:39], v[166:169], v[218:221], v[36:39]
	v_mfma_f32_16x16x32_bf16 v[28:31], v[178:181], v[218:221], v[28:31]
	v_mfma_f32_16x16x32_bf16 v[20:23], v[166:169], v[230:233], v[20:23]
	v_mfma_f32_16x16x32_bf16 v[12:15], v[178:181], v[230:233], v[12:15]
	v_mfma_f32_16x16x32_bf16 v[48:51], v[182:185], v[198:201], v[48:51]
	v_mfma_f32_16x16x32_bf16 v[40:43], v[190:193], v[198:201], v[40:43]
	v_mfma_f32_16x16x32_bf16 v[32:35], v[182:185], v[206:209], v[32:35]
	v_mfma_f32_16x16x32_bf16 v[24:27], v[190:193], v[206:209], v[24:27]
	v_mfma_f32_16x16x32_bf16 v[16:19], v[182:185], v[214:217], v[16:19]
	v_mfma_f32_16x16x32_bf16 v[8:11], v[190:193], v[214:217], v[8:11]
	v_mfma_f32_16x16x32_bf16 v[4:7], v[182:185], v[226:229], v[4:7]
	v_mfma_f32_16x16x32_bf16 v[0:3], v[190:193], v[226:229], v[0:3]
	v_mfma_f32_16x16x32_bf16 v[48:51], v[186:189], v[202:205], v[48:51]
	v_mfma_f32_16x16x32_bf16 v[40:43], v[194:197], v[202:205], v[40:43]
	v_mfma_f32_16x16x32_bf16 v[32:35], v[186:189], v[210:213], v[32:35]
	v_mfma_f32_16x16x32_bf16 v[24:27], v[194:197], v[210:213], v[24:27]
	v_mfma_f32_16x16x32_bf16 v[16:19], v[186:189], v[218:221], v[16:19]
	v_mfma_f32_16x16x32_bf16 v[8:11], v[194:197], v[218:221], v[8:11]
	v_mfma_f32_16x16x32_bf16 v[4:7], v[186:189], v[230:233], v[4:7]
	v_mfma_f32_16x16x32_bf16 v[0:3], v[194:197], v[230:233], v[0:3]
	s_barrier
	s_add_i32 s89, s89, 2
	s_add_u32 s8, s8, 0x100
	s_addc_u32 s9, s9, 0
	s_add_u32 s76, s76, 0x100
	s_addc_u32 s77, s77, 0
	s_cmp_gt_u32 s89, 13
.LBB0_546:
	ds_read_b128 v[146:149], v162
	ds_read_b128 v[166:169], v162 offset:1024
	ds_read_b128 v[170:173], v162 offset:2048
	ds_read_b128 v[178:181], v162 offset:3072
	ds_read_b128 v[182:185], v163
	ds_read_b128 v[186:189], v163 offset:1024
	ds_read_b128 v[190:193], v163 offset:2048
	ds_read_b128 v[194:197], v163 offset:3072
	s_add_u32 s10, s8, 0xfffc0080
	s_addc_u32 s11, s9, -1
	s_cmp_eq_u32 s89, 12
	s_cselect_b32 s13, s1, s11
	s_cselect_b32 s12, s7, s10
	s_cselect_b32 s11, s69, s77
	s_cselect_b32 s10, s71, s76
	s_add_i32 m0, s43, 0xc000
	ds_read_b128 v[198:201], v164
	ds_read_b128 v[202:205], v164 offset:1024
	ds_read_b128 v[206:209], v164 offset:2048
	ds_read_b128 v[210:213], v164 offset:3072
	ds_read_b128 v[214:217], v164 offset:4096
	ds_read_b128 v[218:221], v164 offset:5120
	ds_read_b128 v[226:229], v164 offset:6144
	ds_read_b128 v[230:233], v164 offset:7168
	global_load_lds_dwordx4 v138, s[8:9]
	s_add_i32 m0, s43, 0xe000
	s_nop 0
	global_load_lds_dwordx4 v140, s[8:9]
	s_waitcnt vmcnt(8)
	s_waitcnt lgkmcnt(0)
	s_barrier
; #define PG8_STAGE(bufoff, gbase, voff) do { _Pragma("unroll") for (int _i = 0; _i < 2; ++_i) \
;         __builtin_amdgcn_global_load_lds((const unsigned*)((const char*)(gbase) + (voff)[_i]), (LAS unsigned*)(lds + (bufoff) + ldsw + _i * 8192), 16, 0, 0); } while (0)
; #define PG8_LDA(dst, b, h) do { _Pragma("unroll") for (int m = 0; m < 4; ++m) _Pragma("unroll") for (int k = 0; k < 2; ++k) dst[m][k] = *(const LAS bf16x8*)(lds + PG8_SA(b, h) + aoff + m * 2048 + k * 1024); } while (0)
; #define PG8_MMA(ai, bj, At, Bt) do { __builtin_amdgcn_s_setprio(1); _Pragma("unroll") for (int m = 0; m < 4; ++m) _Pragma("unroll") for (int n = 0; n < 2; ++n) _Pragma("unroll") for (int k = 0; k < 2; ++k) \
;         acc[ai][bj][m][n] = __builtin_amdgcn_mfma_f32_16x16x32_bf16(Bt[n][k], At[m][k], acc[ai][bj][m][n], 0, 0, 0); __builtin_amdgcn_s_setprio(0); } while (0)
; #define PG8_WAIT_V(n) asm volatile("s_waitcnt vmcnt(" #n ")" ::: "memory")
; #define PG8_WAIT_L(n) asm volatile("s_waitcnt lgkmcnt(" #n ")" ::: "memory")
; #define PG8_BAR __builtin_amdgcn_s_barrier()
; #define PG8_SCHED __builtin_amdgcn_sched_barrier(0)
; template <class Epi>
; __device__ __forceinline__ void gemm_phase(LAS unsigned char* lds, const Gemm g, const StaticOrder& S, const Epi& E) {
;     ...
;             PG8_WAIT_V(8); PG8_WAIT_L(0); PG8_BAR; PG8_MMA(0, 0, At, B0); PG8_MMA(0, 1, At, B1); PG8_BAR; PG8_SCHED;
;             PG8_LDA(At, 0, 1); PG8_STAGE(PG8_SB(0, 0), b2, voffB); PG8_STAGE(PG8_SB(0, 1), b2 + hstepB, voffB); PG8_STAGE(PG8_SA(0, 0), a2, voffA);
;             PG8_WAIT_V(8); PG8_WAIT_L(0); PG8_BAR; PG8_MMA(1, 0, At, B0); PG8_MMA(1, 1, At, B1); PG8_BAR; PG8_SCHED;
	s_waitcnt lgkmcnt(0)
	v_mfma_f32_16x16x32_bf16 v[124:127], v[146:149], v[198:201], v[124:127]
	v_mfma_f32_16x16x32_bf16 v[120:123], v[170:173], v[198:201], v[120:123]
	v_mfma_f32_16x16x32_bf16 v[112:115], v[146:149], v[206:209], v[112:115]
	v_mfma_f32_16x16x32_bf16 v[104:107], v[170:173], v[206:209], v[104:107]
	v_mfma_f32_16x16x32_bf16 v[100:103], v[146:149], v[214:217], v[100:103]
	v_mfma_f32_16x16x32_bf16 v[92:95], v[170:173], v[214:217], v[92:95]
	v_mfma_f32_16x16x32_bf16 v[84:87], v[146:149], v[226:229], v[84:87]
	v_mfma_f32_16x16x32_bf16 v[76:79], v[170:173], v[226:229], v[76:79]
	v_mfma_f32_16x16x32_bf16 v[124:127], v[166:169], v[202:205], v[124:127]
	v_mfma_f32_16x16x32_bf16 v[120:123], v[178:181], v[202:205], v[120:123]
	v_mfma_f32_16x16x32_bf16 v[112:115], v[166:169], v[210:213], v[112:115]
	v_mfma_f32_16x16x32_bf16 v[104:107], v[178:181], v[210:213], v[104:107]
	v_mfma_f32_16x16x32_bf16 v[100:103], v[166:169], v[218:221], v[100:103]
	v_mfma_f32_16x16x32_bf16 v[92:95], v[178:181], v[218:221], v[92:95]
	v_mfma_f32_16x16x32_bf16 v[84:87], v[166:169], v[230:233], v[84:87]
	v_mfma_f32_16x16x32_bf16 v[76:79], v[178:181], v[230:233], v[76:79]
	v_mfma_f32_16x16x32_bf16 v[116:119], v[182:185], v[198:201], v[116:119]
	v_mfma_f32_16x16x32_bf16 v[108:111], v[190:193], v[198:201], v[108:111]
	v_mfma_f32_16x16x32_bf16 v[96:99], v[182:185], v[206:209], v[96:99]
	v_mfma_f32_16x16x32_bf16 v[88:91], v[190:193], v[206:209], v[88:91]
	v_mfma_f32_16x16x32_bf16 v[80:83], v[182:185], v[214:217], v[80:83]
	v_mfma_f32_16x16x32_bf16 v[72:75], v[190:193], v[214:217], v[72:75]
	v_mfma_f32_16x16x32_bf16 v[68:71], v[182:185], v[226:229], v[68:71]
	v_mfma_f32_16x16x32_bf16 v[64:67], v[190:193], v[226:229], v[64:67]
	v_mfma_f32_16x16x32_bf16 v[116:119], v[186:189], v[202:205], v[116:119]
	v_mfma_f32_16x16x32_bf16 v[108:111], v[194:197], v[202:205], v[108:111]
	v_mfma_f32_16x16x32_bf16 v[96:99], v[186:189], v[210:213], v[96:99]
	v_mfma_f32_16x16x32_bf16 v[88:91], v[194:197], v[210:213], v[88:91]
	v_mfma_f32_16x16x32_bf16 v[80:83], v[186:189], v[218:221], v[80:83]
	v_mfma_f32_16x16x32_bf16 v[72:75], v[194:197], v[218:221], v[72:75]
	v_mfma_f32_16x16x32_bf16 v[68:71], v[186:189], v[230:233], v[68:71]
	v_mfma_f32_16x16x32_bf16 v[64:67], v[194:197], v[230:233], v[64:67]
	s_barrier
	s_add_i32 s90, s85, s39
	v_lshl_add_u64 v[174:175], s[10:11], 0, v[130:131]
	s_mov_b32 m0, s90
	ds_read_b128 v[198:201], v164 offset:16384
	ds_read_b128 v[202:205], v164 offset:17408
	ds_read_b128 v[206:209], v164 offset:18432
	ds_read_b128 v[210:213], v164 offset:19456
	ds_read_b128 v[214:217], v164 offset:20480
	ds_read_b128 v[218:221], v164 offset:21504
	ds_read_b128 v[226:229], v164 offset:22528
	ds_read_b128 v[230:233], v164 offset:23552
	global_load_lds_dwordx4 v[174:175], off
	s_add_i32 m0, s90, 0x2000
	s_add_u32 s90, s10, 0x40000
	v_lshl_add_u64 v[222:223], s[10:11], 0, v[134:135]
	s_addc_u32 s91, s11, 0
	s_add_i32 s92, s86, s39
	global_load_lds_dwordx4 v[222:223], off
	s_mov_b32 m0, s92
	v_lshl_add_u64 v[236:237], s[12:13], 0, v[132:133]
	global_load_lds_dwordx4 v130, s[90:91]
	s_add_i32 m0, s92, 0x2000
	s_nop 0
	global_load_lds_dwordx4 v134, s[90:91]
	v_lshl_add_u64 v[234:235], s[12:13], 0, v[128:129]
	s_mov_b32 m0, s43
	s_nop 0
	global_load_lds_dwordx4 v[234:235], off
	s_mov_b32 m0, s53
	s_nop 0
	global_load_lds_dwordx4 v[236:237], off
	s_waitcnt vmcnt(8)
	s_waitcnt lgkmcnt(0)
	s_barrier
	s_waitcnt lgkmcnt(0)
	v_mfma_f32_16x16x32_bf16 v[60:63], v[146:149], v[198:201], v[60:63]
	v_mfma_f32_16x16x32_bf16 v[56:59], v[170:173], v[198:201], v[56:59]
	v_mfma_f32_16x16x32_bf16 v[52:55], v[146:149], v[206:209], v[52:55]
	v_mfma_f32_16x16x32_bf16 v[44:47], v[170:173], v[206:209], v[44:47]
	v_mfma_f32_16x16x32_bf16 v[36:39], v[146:149], v[214:217], v[36:39]
	v_mfma_f32_16x16x32_bf16 v[28:31], v[170:173], v[214:217], v[28:31]
	v_mfma_f32_16x16x32_bf16 v[20:23], v[146:149], v[226:229], v[20:23]
	v_mfma_f32_16x16x32_bf16 v[12:15], v[170:173], v[226:229], v[12:15]
	v_mfma_f32_16x16x32_bf16 v[60:63], v[166:169], v[202:205], v[60:63]
	v_mfma_f32_16x16x32_bf16 v[56:59], v[178:181], v[202:205], v[56:59]
	v_mfma_f32_16x16x32_bf16 v[52:55], v[166:169], v[210:213], v[52:55]
	v_mfma_f32_16x16x32_bf16 v[44:47], v[178:181], v[210:213], v[44:47]
	v_mfma_f32_16x16x32_bf16 v[36:39], v[166:169], v[218:221], v[36:39]
	v_mfma_f32_16x16x32_bf16 v[28:31], v[178:181], v[218:221], v[28:31]
	v_mfma_f32_16x16x32_bf16 v[20:23], v[166:169], v[230:233], v[20:23]
	v_mfma_f32_16x16x32_bf16 v[12:15], v[178:181], v[230:233], v[12:15]
	v_mfma_f32_16x16x32_bf16 v[48:51], v[182:185], v[198:201], v[48:51]
	v_mfma_f32_16x16x32_bf16 v[40:43], v[190:193], v[198:201], v[40:43]
	v_mfma_f32_16x16x32_bf16 v[32:35], v[182:185], v[206:209], v[32:35]
	v_mfma_f32_16x16x32_bf16 v[24:27], v[190:193], v[206:209], v[24:27]
	v_mfma_f32_16x16x32_bf16 v[16:19], v[182:185], v[214:217], v[16:19]
	v_mfma_f32_16x16x32_bf16 v[8:11], v[190:193], v[214:217], v[8:11]
	v_mfma_f32_16x16x32_bf16 v[4:7], v[182:185], v[226:229], v[4:7]
	v_mfma_f32_16x16x32_bf16 v[0:3], v[190:193], v[226:229], v[0:3]
	v_mfma_f32_16x16x32_bf16 v[48:51], v[186:189], v[202:205], v[48:51]
	v_mfma_f32_16x16x32_bf16 v[40:43], v[194:197], v[202:205], v[40:43]
	v_mfma_f32_16x16x32_bf16 v[32:35], v[186:189], v[210:213], v[32:35]
	v_mfma_f32_16x16x32_bf16 v[24:27], v[194:197], v[210:213], v[24:27]
	v_mfma_f32_16x16x32_bf16 v[16:19], v[186:189], v[218:221], v[16:19]
	v_mfma_f32_16x16x32_bf16 v[8:11], v[194:197], v[218:221], v[8:11]
	v_mfma_f32_16x16x32_bf16 v[4:7], v[186:189], v[230:233], v[4:7]
	v_mfma_f32_16x16x32_bf16 v[0:3], v[194:197], v[230:233], v[0:3]
	s_barrier
; #define PG8_STAGE(bufoff, gbase, voff) do { _Pragma("unroll") for (int _i = 0; _i < 2; ++_i) \
;         __builtin_amdgcn_global_load_lds((const unsigned*)((const char*)(gbase) + (voff)[_i]), (LAS unsigned*)(lds + (bufoff) + ldsw + _i * 8192), 16, 0, 0); } while (0)
; #define PG8_LDA(dst, b, h) do { _Pragma("unroll") for (int m = 0; m < 4; ++m) _Pragma("unroll") for (int k = 0; k < 2; ++k) dst[m][k] = *(const LAS bf16x8*)(lds + PG8_SA(b, h) + aoff + m * 2048 + k * 1024); } while (0)
; #define PG8_LDB(dst, b, h) do { _Pragma("unroll") for (int n = 0; n < 2; ++n) _Pragma("unroll") for (int k = 0; k < 2; ++k) dst[n][k] = *(const LAS bf16x8*)(lds + PG8_SB(b, h) + boff + n * 2048 + k * 1024); } while (0)
; #define PG8_MMA(ai, bj, At, Bt) do { __builtin_amdgcn_s_setprio(1); _Pragma("unroll") for (int m = 0; m < 4; ++m) _Pragma("unroll") for (int n = 0; n < 2; ++n) _Pragma("unroll") for (int k = 0; k < 2; ++k) \
;         acc[ai][bj][m][n] = __builtin_amdgcn_mfma_f32_16x16x32_bf16(Bt[n][k], At[m][k], acc[ai][bj][m][n], 0, 0, 0); __builtin_amdgcn_s_setprio(0); } while (0)
; #define PG8_WAIT_V(n) asm volatile("s_waitcnt vmcnt(" #n ")" ::: "memory")
; #define PG8_WAIT_L(n) asm volatile("s_waitcnt lgkmcnt(" #n ")" ::: "memory")
; #define PG8_BAR __builtin_amdgcn_s_barrier()
; #define PG8_SCHED __builtin_amdgcn_sched_barrier(0)
; template <class Epi>
; __device__ __forceinline__ void gemm_phase(LAS unsigned char* lds, const Gemm g, const StaticOrder& S, const Epi& E) {
;     ...
;             PG8_LDB(B0, 1, 0); PG8_LDB(B1, 1, 1); PG8_SCHED; PG8_LDA(At, 1, 0); PG8_STAGE(PG8_SA(0, 1), a2 + hstepA, voffA);
;             PG8_WAIT_V(8); PG8_WAIT_L(0); PG8_BAR; PG8_MMA(0, 0, At, B0); PG8_MMA(0, 1, At, B1); PG8_BAR; PG8_SCHED;
;             PG8_LDA(At, 1, 1); PG8_STAGE(PG8_SB(1, 0), b3, voffB); PG8_STAGE(PG8_SB(1, 1), b3 + hstepB, voffB); PG8_STAGE(PG8_SA(1, 0), a3, voffA);
;             PG8_WAIT_V(8); PG8_WAIT_L(0); PG8_BAR; PG8_MMA(1, 0, At, B0); PG8_MMA(1, 1, At, B1); PG8_BAR; PG8_SCHED;
;         }
	s_add_i32 s90, 0, 0x18000
	v_add_u32_e32 v136, s90, v161
	s_add_i32 s91, 0, 0x1c000
	ds_read_b128 v[146:149], v136
	ds_read_b128 v[166:169], v136 offset:1024
	ds_read_b128 v[170:173], v136 offset:2048
	ds_read_b128 v[178:181], v136 offset:3072
	v_add_u32_e32 v136, s91, v161
	ds_read_b128 v[182:185], v136
	ds_read_b128 v[186:189], v136 offset:1024
	ds_read_b128 v[190:193], v136 offset:2048
	ds_read_b128 v[194:197], v136 offset:3072
	s_add_u32 s12, s12, 0x40000
	s_addc_u32 s13, s13, 0
	s_mov_b32 m0, s55
	ds_read_b128 v[198:201], v164 offset:32768
	ds_read_b128 v[202:205], v164 offset:33792
	ds_read_b128 v[206:209], v164 offset:34816
	ds_read_b128 v[210:213], v164 offset:35840
	ds_read_b128 v[214:217], v164 offset:36864
	ds_read_b128 v[218:221], v164 offset:37888
	ds_read_b128 v[226:229], v164 offset:38912
	ds_read_b128 v[230:233], v164 offset:39936
	global_load_lds_dwordx4 v128, s[12:13]
	s_mov_b32 m0, s57
	s_nop 0
	global_load_lds_dwordx4 v132, s[12:13]
	s_waitcnt vmcnt(8)
	s_waitcnt lgkmcnt(0)
	s_barrier
	s_waitcnt lgkmcnt(0)
	v_mfma_f32_16x16x32_bf16 v[124:127], v[146:149], v[198:201], v[124:127]
	v_mfma_f32_16x16x32_bf16 v[120:123], v[170:173], v[198:201], v[120:123]
	v_mfma_f32_16x16x32_bf16 v[112:115], v[146:149], v[206:209], v[112:115]
	v_mfma_f32_16x16x32_bf16 v[104:107], v[170:173], v[206:209], v[104:107]
	v_mfma_f32_16x16x32_bf16 v[100:103], v[146:149], v[214:217], v[100:103]
	v_mfma_f32_16x16x32_bf16 v[92:95], v[170:173], v[214:217], v[92:95]
	v_mfma_f32_16x16x32_bf16 v[84:87], v[146:149], v[226:229], v[84:87]
	v_mfma_f32_16x16x32_bf16 v[76:79], v[170:173], v[226:229], v[76:79]
	v_mfma_f32_16x16x32_bf16 v[124:127], v[166:169], v[202:205], v[124:127]
	v_mfma_f32_16x16x32_bf16 v[120:123], v[178:181], v[202:205], v[120:123]
	v_mfma_f32_16x16x32_bf16 v[112:115], v[166:169], v[210:213], v[112:115]
	v_mfma_f32_16x16x32_bf16 v[104:107], v[178:181], v[210:213], v[104:107]
	v_mfma_f32_16x16x32_bf16 v[100:103], v[166:169], v[218:221], v[100:103]
	v_mfma_f32_16x16x32_bf16 v[92:95], v[178:181], v[218:221], v[92:95]
	v_mfma_f32_16x16x32_bf16 v[84:87], v[166:169], v[230:233], v[84:87]
	v_mfma_f32_16x16x32_bf16 v[76:79], v[178:181], v[230:233], v[76:79]
	v_mfma_f32_16x16x32_bf16 v[116:119], v[182:185], v[198:201], v[116:119]
	v_mfma_f32_16x16x32_bf16 v[108:111], v[190:193], v[198:201], v[108:111]
	v_mfma_f32_16x16x32_bf16 v[96:99], v[182:185], v[206:209], v[96:99]
	v_mfma_f32_16x16x32_bf16 v[88:91], v[190:193], v[206:209], v[88:91]
	v_mfma_f32_16x16x32_bf16 v[80:83], v[182:185], v[214:217], v[80:83]
	v_mfma_f32_16x16x32_bf16 v[72:75], v[190:193], v[214:217], v[72:75]
	v_mfma_f32_16x16x32_bf16 v[68:71], v[182:185], v[226:229], v[68:71]
	v_mfma_f32_16x16x32_bf16 v[64:67], v[190:193], v[226:229], v[64:67]
	v_mfma_f32_16x16x32_bf16 v[116:119], v[186:189], v[202:205], v[116:119]
	v_mfma_f32_16x16x32_bf16 v[108:111], v[194:197], v[202:205], v[108:111]
	v_mfma_f32_16x16x32_bf16 v[96:99], v[186:189], v[210:213], v[96:99]
	v_mfma_f32_16x16x32_bf16 v[88:91], v[194:197], v[210:213], v[88:91]
	v_mfma_f32_16x16x32_bf16 v[80:83], v[186:189], v[218:221], v[80:83]
	v_mfma_f32_16x16x32_bf16 v[72:75], v[194:197], v[218:221], v[72:75]
	v_mfma_f32_16x16x32_bf16 v[68:71], v[186:189], v[230:233], v[68:71]
	v_mfma_f32_16x16x32_bf16 v[64:67], v[194:197], v[230:233], v[64:67]
	s_barrier
	s_add_i32 s12, s90, s39
	v_lshl_add_u64 v[174:175], v[174:175], 0, s[30:31]
	s_mov_b32 m0, s12
	ds_read_b128 v[198:201], v164 offset:49152
	ds_read_b128 v[202:205], v164 offset:50176
	ds_read_b128 v[206:209], v164 offset:51200
	ds_read_b128 v[210:213], v164 offset:52224
	ds_read_b128 v[214:217], v164 offset:53248
	ds_read_b128 v[218:221], v164 offset:54272
	ds_read_b128 v[226:229], v164 offset:55296
	ds_read_b128 v[230:233], v164 offset:56320
	global_load_lds_dwordx4 v[174:175], off
	s_add_i32 m0, s12, 0x2000
	s_add_u32 s10, s10, 0x40080
	v_lshl_add_u64 v[174:175], v[222:223], 0, s[30:31]
	s_addc_u32 s11, s11, 0
	s_add_i32 s12, s91, s39
	global_load_lds_dwordx4 v[174:175], off
	s_mov_b32 m0, s12
	s_nop 0
	global_load_lds_dwordx4 v130, s[10:11]
	s_add_i32 m0, s12, 0x2000
	s_nop 0
	global_load_lds_dwordx4 v134, s[10:11]
	v_lshl_add_u64 v[174:175], v[234:235], 0, s[30:31]
	s_mov_b32 m0, s79
	s_nop 0
	global_load_lds_dwordx4 v[174:175], off
	v_lshl_add_u64 v[174:175], v[236:237], 0, s[30:31]
	s_mov_b32 m0, s80
	s_nop 0
	global_load_lds_dwordx4 v[174:175], off
	s_waitcnt vmcnt(8)
	s_waitcnt lgkmcnt(0)
	s_barrier
	s_waitcnt lgkmcnt(0)
	v_mfma_f32_16x16x32_bf16 v[60:63], v[146:149], v[198:201], v[60:63]
	v_mfma_f32_16x16x32_bf16 v[56:59], v[170:173], v[198:201], v[56:59]
	v_mfma_f32_16x16x32_bf16 v[52:55], v[146:149], v[206:209], v[52:55]
	v_mfma_f32_16x16x32_bf16 v[44:47], v[170:173], v[206:209], v[44:47]
	v_mfma_f32_16x16x32_bf16 v[36:39], v[146:149], v[214:217], v[36:39]
	v_mfma_f32_16x16x32_bf16 v[28:31], v[170:173], v[214:217], v[28:31]
	v_mfma_f32_16x16x32_bf16 v[20:23], v[146:149], v[226:229], v[20:23]
	v_mfma_f32_16x16x32_bf16 v[12:15], v[170:173], v[226:229], v[12:15]
	v_mfma_f32_16x16x32_bf16 v[60:63], v[166:169], v[202:205], v[60:63]
	v_mfma_f32_16x16x32_bf16 v[56:59], v[178:181], v[202:205], v[56:59]
	v_mfma_f32_16x16x32_bf16 v[52:55], v[166:169], v[210:213], v[52:55]
	v_mfma_f32_16x16x32_bf16 v[44:47], v[178:181], v[210:213], v[44:47]
	v_mfma_f32_16x16x32_bf16 v[36:39], v[166:169], v[218:221], v[36:39]
	v_mfma_f32_16x16x32_bf16 v[28:31], v[178:181], v[218:221], v[28:31]
	v_mfma_f32_16x16x32_bf16 v[20:23], v[166:169], v[230:233], v[20:23]
	v_mfma_f32_16x16x32_bf16 v[12:15], v[178:181], v[230:233], v[12:15]
	v_mfma_f32_16x16x32_bf16 v[48:51], v[182:185], v[198:201], v[48:51]
	v_mfma_f32_16x16x32_bf16 v[40:43], v[190:193], v[198:201], v[40:43]
	v_mfma_f32_16x16x32_bf16 v[32:35], v[182:185], v[206:209], v[32:35]
	v_mfma_f32_16x16x32_bf16 v[24:27], v[190:193], v[206:209], v[24:27]
	v_mfma_f32_16x16x32_bf16 v[16:19], v[182:185], v[214:217], v[16:19]
	v_mfma_f32_16x16x32_bf16 v[8:11], v[190:193], v[214:217], v[8:11]
	v_mfma_f32_16x16x32_bf16 v[4:7], v[182:185], v[226:229], v[4:7]
	v_mfma_f32_16x16x32_bf16 v[0:3], v[190:193], v[226:229], v[0:3]
	v_mfma_f32_16x16x32_bf16 v[48:51], v[186:189], v[202:205], v[48:51]
	v_mfma_f32_16x16x32_bf16 v[40:43], v[194:197], v[202:205], v[40:43]
	v_mfma_f32_16x16x32_bf16 v[32:35], v[186:189], v[210:213], v[32:35]
	v_mfma_f32_16x16x32_bf16 v[24:27], v[194:197], v[210:213], v[24:27]
	v_mfma_f32_16x16x32_bf16 v[16:19], v[186:189], v[218:221], v[16:19]
	v_mfma_f32_16x16x32_bf16 v[8:11], v[194:197], v[218:221], v[8:11]
	v_mfma_f32_16x16x32_bf16 v[4:7], v[186:189], v[230:233], v[4:7]
	v_mfma_f32_16x16x32_bf16 v[0:3], v[194:197], v[230:233], v[0:3]
	s_barrier
	s_add_i32 s89, s89, 2
	s_add_u32 s8, s8, 0x100
	s_addc_u32 s9, s9, 0
	s_add_u32 s76, s76, 0x100
	s_addc_u32 s77, s77, 0
	s_cmp_gt_u32 s89, 13
	s_cbranch_scc0 .LBB0_546
	s_and_b64 vcc, exec, s[34:35]
	s_cbranch_vccz .LBB0_549
	s_barrier

; #define PG8_STAGE(bufoff, gbase, voff) do { _Pragma("unroll") for (int _i = 0; _i < 2; ++_i) \
;         __builtin_amdgcn_global_load_lds((const unsigned*)((const char*)(gbase) + (voff)[_i]), (LAS unsigned*)(lds + (bufoff) + ldsw + _i * 8192), 16, 0, 0); } while (0)
; #define PG8_LDA(dst, b, h) do { _Pragma("unroll") for (int m = 0; m < 4; ++m) _Pragma("unroll") for (int k = 0; k < 2; ++k) dst[m][k] = *(const LAS bf16x8*)(lds + PG8_SA(b, h) + aoff + m * 2048 + k * 1024); } while (0)
; #define PG8_LDB(dst, b, h) do { _Pragma("unroll") for (int n = 0; n < 2; ++n) _Pragma("unroll") for (int k = 0; k < 2; ++k) dst[n][k] = *(const LAS bf16x8*)(lds + PG8_SB(b, h) + boff + n * 2048 + k * 1024); } while (0)
; #define PG8_MMA(ai, bj, At, Bt) do { __builtin_amdgcn_s_setprio(1); _Pragma("unroll") for (int m = 0; m < 4; ++m) _Pragma("unroll") for (int n = 0; n < 2; ++n) _Pragma("unroll") for (int k = 0; k < 2; ++k) \
;         acc[ai][bj][m][n] = __builtin_amdgcn_mfma_f32_16x16x32_bf16(Bt[n][k], At[m][k], acc[ai][bj][m][n], 0, 0, 0); __builtin_amdgcn_s_setprio(0); } while (0)
; #define PG8_BAR __builtin_amdgcn_s_barrier()
; template <class Epi>
; __device__ __forceinline__ void gemm_phase(LAS unsigned char* lds, const Gemm g, const StaticOrder& S, const Epi& E) {
;     ...
;         const bool has_next = S.next(ui + 1, nxt);
;         const char* nA = has_next ? (const char*)g.A + (size_t)nxt.pm * tstepA : cA; const char* nB = has_next ? (const char*)g.Bt + (size_t)nxt.pn * tstepB : cB;
; #pragma nounroll
;         for (int t = 0; t < nt; t += 2) {
;             const bool last = (t == nt - 2);
;             const char* a1 = cA + (size_t)(t + 1) * kstep;
;             const char* a2 = last ? nA : cA + (size_t)(t + 2) * kstep; const char* b2 = last ? nB : cB + (size_t)(t + 2) * kstep;
;             const char* a3 = a2 + kstep; const char* b3 = b2 + kstep;
;             PG8_LDB(B0, 0, 0); PG8_LDB(B1, 0, 1); PG8_SCHED; PG8_LDA(At, 0, 0); PG8_STAGE(PG8_SA(1, 1), a1 + hstepA, voffA);
;             PG8_WAIT_V(8); PG8_WAIT_L(0); PG8_BAR; PG8_MMA(0, 0, At, B0); PG8_MMA(0, 1, At, B1); PG8_BAR; PG8_SCHED;
;             PG8_LDA(At, 0, 1); PG8_STAGE(PG8_SB(0, 0), b2, voffB); PG8_STAGE(PG8_SB(0, 1), b2 + hstepB, voffB); PG8_STAGE(PG8_SA(0, 0), a2, voffA);
;             PG8_WAIT_V(8); PG8_WAIT_L(0); PG8_BAR; PG8_MMA(1, 0, At, B0); PG8_MMA(1, 1, At, B1); PG8_BAR; PG8_SCHED;
.LBB0_612:
	s_add_u32 s68, s42, s56
	s_addc_u32 s69, s43, s57
	s_add_u32 s64, s68, 0x100
	s_addc_u32 s65, s69, 0
	s_and_b64 s[62:63], s[54:55], exec
	s_cselect_b32 s63, s1, s65
	s_cselect_b32 s62, s19, s64
	s_add_u32 s56, s38, s56
	s_addc_u32 s57, s39, s57
	s_add_u32 s56, s56, 0x100
	s_addc_u32 s57, s57, 0
	s_and_b64 s[54:55], s[54:55], exec
	s_cselect_b32 s65, s13, s57
	s_cselect_b32 s64, s88, s56
	s_add_u32 s70, s68, 0x10080
	ds_read_b128 v[140:143], v145
	ds_read_b128 v[154:157], v145 offset:1024
	ds_read_b128 v[158:161], v145 offset:2048
	ds_read_b128 v[162:165], v145 offset:3072
	ds_read_b128 v[166:169], v146
	ds_read_b128 v[170:173], v146 offset:1024
	ds_read_b128 v[178:181], v146 offset:2048
	ds_read_b128 v[182:185], v146 offset:3072
	s_addc_u32 s71, s69, 0
	s_add_i32 vcc_lo, s86, s72
	s_add_i32 m0, s35, 0xc000
	s_add_i32 vcc_hi, s35, 0xe000
	s_add_i32 s95, vcc_lo, 0x2000
	s_add_u32 s68, s64, 0x10000
	s_addc_u32 s69, s65, 0
	s_add_i32 s97, s87, s72
	s_add_i32 s96, s97, 0x2000
	s_add_i32 s94, 0, 0x18000
	s_add_i32 s93, 0, 0x1c000
	s_add_u32 s56, s62, 0x10000
	s_addc_u32 s57, s63, 0
	s_add_i32 s92, s94, s72
	s_add_i32 s90, s92, 0x2000
	s_add_u32 s54, s64, 0x10080
	s_addc_u32 s55, s65, 0
	s_add_i32 s91, s93, s72
	s_add_i32 s89, s91, 0x2000
	ds_read_b128 v[186:189], v147
	ds_read_b128 v[190:193], v147 offset:1024
	ds_read_b128 v[194:197], v147 offset:2048
	ds_read_b128 v[198:201], v147 offset:3072
	ds_read_b128 v[202:205], v147 offset:4096
	ds_read_b128 v[206:209], v147 offset:5120
	ds_read_b128 v[210:213], v147 offset:6144
	ds_read_b128 v[214:217], v147 offset:7168
	global_load_lds_dwordx4 v128, s[70:71]
	s_mov_b32 m0, vcc_hi
	s_nop 0
	global_load_lds_dwordx4 v132, s[70:71]
	s_waitcnt vmcnt(8)
	s_waitcnt lgkmcnt(0)
	s_barrier
	s_waitcnt lgkmcnt(0)
	v_mfma_f32_16x16x32_bf16 v[124:127], v[140:143], v[186:189], v[124:127]
	v_mfma_f32_16x16x32_bf16 v[120:123], v[158:161], v[186:189], v[120:123]
	v_mfma_f32_16x16x32_bf16 v[108:111], v[140:143], v[194:197], v[108:111]
	v_mfma_f32_16x16x32_bf16 v[104:107], v[158:161], v[194:197], v[104:107]
	v_mfma_f32_16x16x32_bf16 v[92:95], v[140:143], v[202:205], v[92:95]
	v_mfma_f32_16x16x32_bf16 v[88:91], v[158:161], v[202:205], v[88:91]
	v_mfma_f32_16x16x32_bf16 v[76:79], v[140:143], v[210:213], v[76:79]
	v_mfma_f32_16x16x32_bf16 v[72:75], v[158:161], v[210:213], v[72:75]
	v_mfma_f32_16x16x32_bf16 v[124:127], v[154:157], v[190:193], v[124:127]
	v_mfma_f32_16x16x32_bf16 v[120:123], v[162:165], v[190:193], v[120:123]
	v_mfma_f32_16x16x32_bf16 v[108:111], v[154:157], v[198:201], v[108:111]
	v_mfma_f32_16x16x32_bf16 v[104:107], v[162:165], v[198:201], v[104:107]
	v_mfma_f32_16x16x32_bf16 v[92:95], v[154:157], v[206:209], v[92:95]
	v_mfma_f32_16x16x32_bf16 v[88:91], v[162:165], v[206:209], v[88:91]
	v_mfma_f32_16x16x32_bf16 v[76:79], v[154:157], v[214:217], v[76:79]
	v_mfma_f32_16x16x32_bf16 v[72:75], v[162:165], v[214:217], v[72:75]
	v_mfma_f32_16x16x32_bf16 v[116:119], v[166:169], v[186:189], v[116:119]
	v_mfma_f32_16x16x32_bf16 v[112:115], v[178:181], v[186:189], v[112:115]
	v_mfma_f32_16x16x32_bf16 v[100:103], v[166:169], v[194:197], v[100:103]
	v_mfma_f32_16x16x32_bf16 v[96:99], v[178:181], v[194:197], v[96:99]
	v_mfma_f32_16x16x32_bf16 v[84:87], v[166:169], v[202:205], v[84:87]
	v_mfma_f32_16x16x32_bf16 v[80:83], v[178:181], v[202:205], v[80:83]
	v_mfma_f32_16x16x32_bf16 v[68:71], v[166:169], v[210:213], v[68:71]
	v_mfma_f32_16x16x32_bf16 v[64:67], v[178:181], v[210:213], v[64:67]
	v_mfma_f32_16x16x32_bf16 v[116:119], v[170:173], v[190:193], v[116:119]
	v_mfma_f32_16x16x32_bf16 v[112:115], v[182:185], v[190:193], v[112:115]
	v_mfma_f32_16x16x32_bf16 v[100:103], v[170:173], v[198:201], v[100:103]
	v_mfma_f32_16x16x32_bf16 v[96:99], v[182:185], v[198:201], v[96:99]
	v_mfma_f32_16x16x32_bf16 v[84:87], v[170:173], v[206:209], v[84:87]
	v_mfma_f32_16x16x32_bf16 v[80:83], v[182:185], v[206:209], v[80:83]
	v_mfma_f32_16x16x32_bf16 v[68:71], v[170:173], v[214:217], v[68:71]
	v_mfma_f32_16x16x32_bf16 v[64:67], v[182:185], v[214:217], v[64:67]
	s_barrier
	s_mov_b32 m0, vcc_lo
	v_lshl_add_u64 v[174:175], s[64:65], 0, v[130:131]
	ds_read_b128 v[186:189], v147 offset:16384
	ds_read_b128 v[190:193], v147 offset:17408
	ds_read_b128 v[194:197], v147 offset:18432
	ds_read_b128 v[198:201], v147 offset:19456
	ds_read_b128 v[202:205], v147 offset:20480
	ds_read_b128 v[206:209], v147 offset:21504
	ds_read_b128 v[210:213], v147 offset:22528
	ds_read_b128 v[214:217], v147 offset:23552
	global_load_lds_dwordx4 v[174:175], off
	v_lshl_add_u64 v[218:219], s[64:65], 0, v[134:135]
	s_mov_b32 m0, s95
	global_load_lds_dwordx4 v[218:219], off
	s_mov_b32 m0, s97
	v_lshl_add_u64 v[222:223], s[62:63], 0, v[132:133]
	global_load_lds_dwordx4 v130, s[68:69]
	s_mov_b32 m0, s96
	s_nop 0
	global_load_lds_dwordx4 v134, s[68:69]
	v_lshl_add_u64 v[220:221], s[62:63], 0, v[128:129]
	s_mov_b32 m0, s35
	s_nop 0
	global_load_lds_dwordx4 v[220:221], off
	s_mov_b32 m0, s75
	s_nop 0
	global_load_lds_dwordx4 v[222:223], off
	s_waitcnt vmcnt(8)
	s_waitcnt lgkmcnt(0)
	s_barrier
; #define PG8_STAGE(bufoff, gbase, voff) do { _Pragma("unroll") for (int _i = 0; _i < 2; ++_i) \
;         __builtin_amdgcn_global_load_lds((const unsigned*)((const char*)(gbase) + (voff)[_i]), (LAS unsigned*)(lds + (bufoff) + ldsw + _i * 8192), 16, 0, 0); } while (0)
; #define PG8_LDA(dst, b, h) do { _Pragma("unroll") for (int m = 0; m < 4; ++m) _Pragma("unroll") for (int k = 0; k < 2; ++k) dst[m][k] = *(const LAS bf16x8*)(lds + PG8_SA(b, h) + aoff + m * 2048 + k * 1024); } while (0)
; #define PG8_LDB(dst, b, h) do { _Pragma("unroll") for (int n = 0; n < 2; ++n) _Pragma("unroll") for (int k = 0; k < 2; ++k) dst[n][k] = *(const LAS bf16x8*)(lds + PG8_SB(b, h) + boff + n * 2048 + k * 1024); } while (0)
; #define PG8_MMA(ai, bj, At, Bt) do { __builtin_amdgcn_s_setprio(1); _Pragma("unroll") for (int m = 0; m < 4; ++m) _Pragma("unroll") for (int n = 0; n < 2; ++n) _Pragma("unroll") for (int k = 0; k < 2; ++k) \
;         acc[ai][bj][m][n] = __builtin_amdgcn_mfma_f32_16x16x32_bf16(Bt[n][k], At[m][k], acc[ai][bj][m][n], 0, 0, 0); __builtin_amdgcn_s_setprio(0); } while (0)
; #define PG8_WAIT_V(n) asm volatile("s_waitcnt vmcnt(" #n ")" ::: "memory")
; #define PG8_WAIT_L(n) asm volatile("s_waitcnt lgkmcnt(" #n ")" ::: "memory")
; #define PG8_BAR __builtin_amdgcn_s_barrier()
; #define PG8_SCHED __builtin_amdgcn_sched_barrier(0)
; template <class Epi>
; __device__ __forceinline__ void gemm_phase(LAS unsigned char* lds, const Gemm g, const StaticOrder& S, const Epi& E) {
;     ...
;             PG8_WAIT_V(8); PG8_WAIT_L(0); PG8_BAR; PG8_MMA(1, 0, At, B0); PG8_MMA(1, 1, At, B1); PG8_BAR; PG8_SCHED;
;             PG8_LDB(B0, 1, 0); PG8_LDB(B1, 1, 1); PG8_SCHED; PG8_LDA(At, 1, 0); PG8_STAGE(PG8_SA(0, 1), a2 + hstepA, voffA);
;             PG8_WAIT_V(8); PG8_WAIT_L(0); PG8_BAR; PG8_MMA(0, 0, At, B0); PG8_MMA(0, 1, At, B1); PG8_BAR; PG8_SCHED;
	s_waitcnt lgkmcnt(0)
	v_mfma_f32_16x16x32_bf16 v[60:63], v[140:143], v[186:189], v[60:63]
	v_mfma_f32_16x16x32_bf16 v[56:59], v[158:161], v[186:189], v[56:59]
	v_mfma_f32_16x16x32_bf16 v[44:47], v[140:143], v[194:197], v[44:47]
	v_mfma_f32_16x16x32_bf16 v[40:43], v[158:161], v[194:197], v[40:43]
	v_mfma_f32_16x16x32_bf16 v[28:31], v[140:143], v[202:205], v[28:31]
	v_mfma_f32_16x16x32_bf16 v[24:27], v[158:161], v[202:205], v[24:27]
	v_mfma_f32_16x16x32_bf16 v[12:15], v[140:143], v[210:213], v[12:15]
	v_mfma_f32_16x16x32_bf16 v[8:11], v[158:161], v[210:213], v[8:11]
	v_mfma_f32_16x16x32_bf16 v[60:63], v[154:157], v[190:193], v[60:63]
	v_mfma_f32_16x16x32_bf16 v[56:59], v[162:165], v[190:193], v[56:59]
	v_mfma_f32_16x16x32_bf16 v[44:47], v[154:157], v[198:201], v[44:47]
	v_mfma_f32_16x16x32_bf16 v[40:43], v[162:165], v[198:201], v[40:43]
	v_mfma_f32_16x16x32_bf16 v[28:31], v[154:157], v[206:209], v[28:31]
	v_mfma_f32_16x16x32_bf16 v[24:27], v[162:165], v[206:209], v[24:27]
	v_mfma_f32_16x16x32_bf16 v[12:15], v[154:157], v[214:217], v[12:15]
	v_mfma_f32_16x16x32_bf16 v[8:11], v[162:165], v[214:217], v[8:11]
	v_mfma_f32_16x16x32_bf16 v[52:55], v[166:169], v[186:189], v[52:55]
	v_mfma_f32_16x16x32_bf16 v[48:51], v[178:181], v[186:189], v[48:51]
	v_mfma_f32_16x16x32_bf16 v[36:39], v[166:169], v[194:197], v[36:39]
	v_mfma_f32_16x16x32_bf16 v[32:35], v[178:181], v[194:197], v[32:35]
	v_mfma_f32_16x16x32_bf16 v[20:23], v[166:169], v[202:205], v[20:23]
	v_mfma_f32_16x16x32_bf16 v[16:19], v[178:181], v[202:205], v[16:19]
	v_mfma_f32_16x16x32_bf16 v[4:7], v[166:169], v[210:213], v[4:7]
	v_mfma_f32_16x16x32_bf16 v[0:3], v[178:181], v[210:213], v[0:3]
	v_mfma_f32_16x16x32_bf16 v[52:55], v[170:173], v[190:193], v[52:55]
	v_mfma_f32_16x16x32_bf16 v[48:51], v[182:185], v[190:193], v[48:51]
	v_mfma_f32_16x16x32_bf16 v[36:39], v[170:173], v[198:201], v[36:39]
	v_mfma_f32_16x16x32_bf16 v[32:35], v[182:185], v[198:201], v[32:35]
	v_mfma_f32_16x16x32_bf16 v[20:23], v[170:173], v[206:209], v[20:23]
	v_mfma_f32_16x16x32_bf16 v[16:19], v[182:185], v[206:209], v[16:19]
	v_mfma_f32_16x16x32_bf16 v[4:7], v[170:173], v[214:217], v[4:7]
	v_mfma_f32_16x16x32_bf16 v[0:3], v[182:185], v[214:217], v[0:3]
	s_barrier
	v_add_u32_e32 v149, s94, v144
	ds_read_b128 v[140:143], v149
	ds_read_b128 v[154:157], v149 offset:1024
	ds_read_b128 v[158:161], v149 offset:2048
	ds_read_b128 v[162:165], v149 offset:3072
	v_add_u32_e32 v149, s93, v144
	ds_read_b128 v[166:169], v149
	ds_read_b128 v[170:173], v149 offset:1024
	ds_read_b128 v[178:181], v149 offset:2048
	ds_read_b128 v[182:185], v149 offset:3072
	s_mov_b32 m0, s76
	ds_read_b128 v[186:189], v147 offset:32768
	ds_read_b128 v[190:193], v147 offset:33792
	ds_read_b128 v[194:197], v147 offset:34816
	ds_read_b128 v[198:201], v147 offset:35840
	ds_read_b128 v[202:205], v147 offset:36864
	ds_read_b128 v[206:209], v147 offset:37888
	ds_read_b128 v[210:213], v147 offset:38912
	ds_read_b128 v[214:217], v147 offset:39936
	global_load_lds_dwordx4 v128, s[56:57]
	s_mov_b32 m0, s77
	s_nop 0
	global_load_lds_dwordx4 v132, s[56:57]
	s_waitcnt vmcnt(8)
	s_waitcnt lgkmcnt(0)
	s_barrier
	s_waitcnt lgkmcnt(0)
	v_mfma_f32_16x16x32_bf16 v[124:127], v[140:143], v[186:189], v[124:127]
	v_mfma_f32_16x16x32_bf16 v[120:123], v[158:161], v[186:189], v[120:123]
	v_mfma_f32_16x16x32_bf16 v[108:111], v[140:143], v[194:197], v[108:111]
	v_mfma_f32_16x16x32_bf16 v[104:107], v[158:161], v[194:197], v[104:107]
	v_mfma_f32_16x16x32_bf16 v[92:95], v[140:143], v[202:205], v[92:95]
	v_mfma_f32_16x16x32_bf16 v[88:91], v[158:161], v[202:205], v[88:91]
	v_mfma_f32_16x16x32_bf16 v[76:79], v[140:143], v[210:213], v[76:79]
	v_mfma_f32_16x16x32_bf16 v[72:75], v[158:161], v[210:213], v[72:75]
	v_mfma_f32_16x16x32_bf16 v[124:127], v[154:157], v[190:193], v[124:127]
	v_mfma_f32_16x16x32_bf16 v[120:123], v[162:165], v[190:193], v[120:123]
	v_mfma_f32_16x16x32_bf16 v[108:111], v[154:157], v[198:201], v[108:111]
	v_mfma_f32_16x16x32_bf16 v[104:107], v[162:165], v[198:201], v[104:107]
	v_mfma_f32_16x16x32_bf16 v[92:95], v[154:157], v[206:209], v[92:95]
	v_mfma_f32_16x16x32_bf16 v[88:91], v[162:165], v[206:209], v[88:91]
	v_mfma_f32_16x16x32_bf16 v[76:79], v[154:157], v[214:217], v[76:79]
	v_mfma_f32_16x16x32_bf16 v[72:75], v[162:165], v[214:217], v[72:75]
	v_mfma_f32_16x16x32_bf16 v[116:119], v[166:169], v[186:189], v[116:119]
	v_mfma_f32_16x16x32_bf16 v[112:115], v[178:181], v[186:189], v[112:115]
	v_mfma_f32_16x16x32_bf16 v[100:103], v[166:169], v[194:197], v[100:103]
	v_mfma_f32_16x16x32_bf16 v[96:99], v[178:181], v[194:197], v[96:99]
	v_mfma_f32_16x16x32_bf16 v[84:87], v[166:169], v[202:205], v[84:87]
	v_mfma_f32_16x16x32_bf16 v[80:83], v[178:181], v[202:205], v[80:83]
	v_mfma_f32_16x16x32_bf16 v[68:71], v[166:169], v[210:213], v[68:71]
	v_mfma_f32_16x16x32_bf16 v[64:67], v[178:181], v[210:213], v[64:67]
	v_mfma_f32_16x16x32_bf16 v[116:119], v[170:173], v[190:193], v[116:119]
	v_mfma_f32_16x16x32_bf16 v[112:115], v[182:185], v[190:193], v[112:115]
	v_mfma_f32_16x16x32_bf16 v[100:103], v[170:173], v[198:201], v[100:103]
	v_mfma_f32_16x16x32_bf16 v[96:99], v[182:185], v[198:201], v[96:99]
	v_mfma_f32_16x16x32_bf16 v[84:87], v[170:173], v[206:209], v[84:87]
	v_mfma_f32_16x16x32_bf16 v[80:83], v[182:185], v[206:209], v[80:83]
	v_mfma_f32_16x16x32_bf16 v[68:71], v[170:173], v[214:217], v[68:71]
	v_mfma_f32_16x16x32_bf16 v[64:67], v[182:185], v[214:217], v[64:67]
	s_barrier
; #define PG8_STAGE(bufoff, gbase, voff) do { _Pragma("unroll") for (int _i = 0; _i < 2; ++_i) \
;         __builtin_amdgcn_global_load_lds((const unsigned*)((const char*)(gbase) + (voff)[_i]), (LAS unsigned*)(lds + (bufoff) + ldsw + _i * 8192), 16, 0, 0); } while (0)
; #define PG8_LDA(dst, b, h) do { _Pragma("unroll") for (int m = 0; m < 4; ++m) _Pragma("unroll") for (int k = 0; k < 2; ++k) dst[m][k] = *(const LAS bf16x8*)(lds + PG8_SA(b, h) + aoff + m * 2048 + k * 1024); } while (0)
; #define PG8_MMA(ai, bj, At, Bt) do { __builtin_amdgcn_s_setprio(1); _Pragma("unroll") for (int m = 0; m < 4; ++m) _Pragma("unroll") for (int n = 0; n < 2; ++n) _Pragma("unroll") for (int k = 0; k < 2; ++k) \
;         acc[ai][bj][m][n] = __builtin_amdgcn_mfma_f32_16x16x32_bf16(Bt[n][k], At[m][k], acc[ai][bj][m][n], 0, 0, 0); __builtin_amdgcn_s_setprio(0); } while (0)
; #define PG8_WAIT_V(n) asm volatile("s_waitcnt vmcnt(" #n ")" ::: "memory")
; #define PG8_WAIT_L(n) asm volatile("s_waitcnt lgkmcnt(" #n ")" ::: "memory")
; #define PG8_BAR __builtin_amdgcn_s_barrier()
; #define PG8_SCHED __builtin_amdgcn_sched_barrier(0)
; template <class Epi>
; __device__ __forceinline__ void gemm_phase(LAS unsigned char* lds, const Gemm g, const StaticOrder& S, const Epi& E) {
;     ...
;             PG8_LDA(At, 1, 1); PG8_STAGE(PG8_SB(1, 0), b3, voffB); PG8_STAGE(PG8_SB(1, 1), b3 + hstepB, voffB); PG8_STAGE(PG8_SA(1, 0), a3, voffA);
;             PG8_WAIT_V(8); PG8_WAIT_L(0); PG8_BAR; PG8_MMA(1, 0, At, B0); PG8_MMA(1, 1, At, B1); PG8_BAR; PG8_SCHED;
;         }
	s_mov_b32 m0, s92
	v_lshl_add_u64 v[174:175], v[174:175], 0, s[8:9]
	ds_read_b128 v[186:189], v147 offset:49152
	ds_read_b128 v[190:193], v147 offset:50176
	ds_read_b128 v[194:197], v147 offset:51200
	ds_read_b128 v[198:201], v147 offset:52224
	ds_read_b128 v[202:205], v147 offset:53248
	ds_read_b128 v[206:209], v147 offset:54272
	ds_read_b128 v[210:213], v147 offset:55296
	ds_read_b128 v[214:217], v147 offset:56320
	global_load_lds_dwordx4 v[174:175], off
	v_lshl_add_u64 v[174:175], v[218:219], 0, s[8:9]
	s_mov_b32 m0, s90
	s_nop 0
	global_load_lds_dwordx4 v[174:175], off
	s_mov_b32 m0, s91
	s_nop 0
	global_load_lds_dwordx4 v130, s[54:55]
	s_mov_b32 m0, s89
	s_nop 0
	global_load_lds_dwordx4 v134, s[54:55]
	v_lshl_add_u64 v[174:175], v[220:221], 0, s[8:9]
	s_mov_b32 m0, s81
	s_nop 0
	global_load_lds_dwordx4 v[174:175], off
	v_lshl_add_u64 v[174:175], v[222:223], 0, s[8:9]
	s_mov_b32 m0, s82
	s_nop 0
	global_load_lds_dwordx4 v[174:175], off
	s_waitcnt vmcnt(8)
	s_waitcnt lgkmcnt(0)
	s_barrier
	s_waitcnt lgkmcnt(0)
	v_mfma_f32_16x16x32_bf16 v[60:63], v[140:143], v[186:189], v[60:63]
	v_mfma_f32_16x16x32_bf16 v[56:59], v[158:161], v[186:189], v[56:59]
	v_mfma_f32_16x16x32_bf16 v[44:47], v[140:143], v[194:197], v[44:47]
	v_mfma_f32_16x16x32_bf16 v[40:43], v[158:161], v[194:197], v[40:43]
	v_mfma_f32_16x16x32_bf16 v[28:31], v[140:143], v[202:205], v[28:31]
	v_mfma_f32_16x16x32_bf16 v[24:27], v[158:161], v[202:205], v[24:27]
	v_mfma_f32_16x16x32_bf16 v[12:15], v[140:143], v[210:213], v[12:15]
	v_mfma_f32_16x16x32_bf16 v[8:11], v[158:161], v[210:213], v[8:11]
	v_mfma_f32_16x16x32_bf16 v[60:63], v[154:157], v[190:193], v[60:63]
	v_mfma_f32_16x16x32_bf16 v[56:59], v[162:165], v[190:193], v[56:59]
	v_mfma_f32_16x16x32_bf16 v[44:47], v[154:157], v[198:201], v[44:47]
	v_mfma_f32_16x16x32_bf16 v[40:43], v[162:165], v[198:201], v[40:43]
	v_mfma_f32_16x16x32_bf16 v[28:31], v[154:157], v[206:209], v[28:31]
	v_mfma_f32_16x16x32_bf16 v[24:27], v[162:165], v[206:209], v[24:27]
	v_mfma_f32_16x16x32_bf16 v[12:15], v[154:157], v[214:217], v[12:15]
	v_mfma_f32_16x16x32_bf16 v[8:11], v[162:165], v[214:217], v[8:11]
	v_mfma_f32_16x16x32_bf16 v[52:55], v[166:169], v[186:189], v[52:55]
	v_mfma_f32_16x16x32_bf16 v[48:51], v[178:181], v[186:189], v[48:51]
	v_mfma_f32_16x16x32_bf16 v[36:39], v[166:169], v[194:197], v[36:39]
	v_mfma_f32_16x16x32_bf16 v[32:35], v[178:181], v[194:197], v[32:35]
	v_mfma_f32_16x16x32_bf16 v[20:23], v[166:169], v[202:205], v[20:23]
	v_mfma_f32_16x16x32_bf16 v[16:19], v[178:181], v[202:205], v[16:19]
	v_mfma_f32_16x16x32_bf16 v[4:7], v[166:169], v[210:213], v[4:7]
	v_mfma_f32_16x16x32_bf16 v[0:3], v[178:181], v[210:213], v[0:3]
	v_mfma_f32_16x16x32_bf16 v[52:55], v[170:173], v[190:193], v[52:55]
	v_mfma_f32_16x16x32_bf16 v[48:51], v[182:185], v[190:193], v[48:51]
	v_mfma_f32_16x16x32_bf16 v[36:39], v[170:173], v[198:201], v[36:39]
	v_mfma_f32_16x16x32_bf16 v[32:35], v[182:185], v[198:201], v[32:35]
	v_mfma_f32_16x16x32_bf16 v[20:23], v[170:173], v[206:209], v[20:23]
	v_mfma_f32_16x16x32_bf16 v[16:19], v[182:185], v[206:209], v[16:19]
	v_mfma_f32_16x16x32_bf16 v[4:7], v[170:173], v[214:217], v[4:7]
	v_mfma_f32_16x16x32_bf16 v[0:3], v[182:185], v[214:217], v[0:3]
	s_barrier
	s_andn2_b64 vcc, exec, s[52:53]
	s_mov_b64 s[54:55], -1
	s_mov_b64 s[52:53], 0
	s_mov_b64 s[56:57], 0x100
	s_cbranch_vccz .LBB0_612
	s_and_b64 vcc, exec, s[10:11]
	s_cbranch_vccz .LBB0_615
	s_barrier

; #define PG8_STAGE(bufoff, gbase, voff) do { _Pragma("unroll") for (int _i = 0; _i < 2; ++_i) \
;         __builtin_amdgcn_global_load_lds((const unsigned*)((const char*)(gbase) + (voff)[_i]), (LAS unsigned*)(lds + (bufoff) + ldsw + _i * 8192), 16, 0, 0); } while (0)
; #define PG8_LDA(dst, b, h) do { _Pragma("unroll") for (int m = 0; m < 4; ++m) _Pragma("unroll") for (int k = 0; k < 2; ++k) dst[m][k] = *(const LAS bf16x8*)(lds + PG8_SA(b, h) + aoff + m * 2048 + k * 1024); } while (0)
; #define PG8_LDB(dst, b, h) do { _Pragma("unroll") for (int n = 0; n < 2; ++n) _Pragma("unroll") for (int k = 0; k < 2; ++k) dst[n][k] = *(const LAS bf16x8*)(lds + PG8_SB(b, h) + boff + n * 2048 + k * 1024); } while (0)
; #define PG8_MMA(ai, bj, At, Bt) do { __builtin_amdgcn_s_setprio(1); _Pragma("unroll") for (int m = 0; m < 4; ++m) _Pragma("unroll") for (int n = 0; n < 2; ++n) _Pragma("unroll") for (int k = 0; k < 2; ++k) \
;         acc[ai][bj][m][n] = __builtin_amdgcn_mfma_f32_16x16x32_bf16(Bt[n][k], At[m][k], acc[ai][bj][m][n], 0, 0, 0); __builtin_amdgcn_s_setprio(0); } while (0)
; #define PG8_BAR __builtin_amdgcn_s_barrier()
; template <class Epi>
; __device__ __forceinline__ void gemm_phase(LAS unsigned char* lds, const Gemm g, const StaticOrder& S, const Epi& E) {
;     ...
;         const bool has_next = S.next(ui + 1, nxt);
;         const char* nA = has_next ? (const char*)g.A + (size_t)nxt.pm * tstepA : cA; const char* nB = has_next ? (const char*)g.Bt + (size_t)nxt.pn * tstepB : cB;
; #pragma nounroll
;         for (int t = 0; t < nt; t += 2) {
;             const bool last = (t == nt - 2);
;             const char* a1 = cA + (size_t)(t + 1) * kstep;
;             const char* a2 = last ? nA : cA + (size_t)(t + 2) * kstep; const char* b2 = last ? nB : cB + (size_t)(t + 2) * kstep;
;             const char* a3 = a2 + kstep; const char* b3 = b2 + kstep;
;             PG8_LDB(B0, 0, 0); PG8_LDB(B1, 0, 1); PG8_SCHED; PG8_LDA(At, 0, 0); PG8_STAGE(PG8_SA(1, 1), a1 + hstepA, voffA);
;             PG8_WAIT_V(8); PG8_WAIT_L(0); PG8_BAR; PG8_MMA(0, 0, At, B0); PG8_MMA(0, 1, At, B1); PG8_BAR; PG8_SCHED;
;             PG8_LDA(At, 0, 1); PG8_STAGE(PG8_SB(0, 0), b2, voffB); PG8_STAGE(PG8_SB(0, 1), b2 + hstepB, voffB); PG8_STAGE(PG8_SA(0, 0), a2, voffA);
;             PG8_WAIT_V(8); PG8_WAIT_L(0); PG8_BAR; PG8_MMA(1, 0, At, B0); PG8_MMA(1, 1, At, B1); PG8_BAR; PG8_SCHED;
.LBB0_791:
	s_add_u32 s0, s0, 0xb0080
	s_addc_u32 s1, s1, 0
	s_add_u32 s75, s34, 0x100
	s_addc_u32 s76, s35, 0
	s_mov_b32 s77, -2
	s_waitcnt lgkmcnt(0)
	s_nop 0
	ds_read_b128 v[128:131], v182
	ds_read_b128 v[132:135], v182 offset:1024
	ds_read_b128 v[136:139], v182 offset:2048
	ds_read_b128 v[140:143], v182 offset:3072
	ds_read_b128 v[160:163], v183
	ds_read_b128 v[164:167], v183 offset:1024
	ds_read_b128 v[168:171], v183 offset:2048
	ds_read_b128 v[172:175], v183 offset:3072
	s_add_u32 s34, s0, 0xfff50080
	s_addc_u32 s35, s1, -1
	s_cmp_eq_u32 s77, 40
	s_cselect_b32 s39, s7, s35
	s_cselect_b32 s38, s6, s34
	s_cselect_b32 s35, s23, s76
	s_cselect_b32 s34, s22, s75
	s_add_i32 m0, s43, 0xc000
	ds_read_b128 v[186:189], v184
	ds_read_b128 v[190:193], v184 offset:1024
	ds_read_b128 v[194:197], v184 offset:2048
	ds_read_b128 v[198:201], v184 offset:3072
	ds_read_b128 v[202:205], v184 offset:4096
	ds_read_b128 v[206:209], v184 offset:5120
	ds_read_b128 v[210:213], v184 offset:6144
	ds_read_b128 v[214:217], v184 offset:7168
	global_load_lds_dwordx4 v152, s[0:1]
	s_add_i32 m0, s43, 0xe000
	s_nop 0
	global_load_lds_dwordx4 v154, s[0:1]
	s_waitcnt vmcnt(8)
	s_waitcnt lgkmcnt(0)
	s_barrier
	s_waitcnt lgkmcnt(0)
	v_mfma_f32_16x16x32_bf16 v[124:127], v[128:131], v[186:189], 0
	v_mfma_f32_16x16x32_bf16 v[120:123], v[136:139], v[186:189], 0
	v_mfma_f32_16x16x32_bf16 v[108:111], v[128:131], v[194:197], 0
	v_mfma_f32_16x16x32_bf16 v[104:107], v[136:139], v[194:197], 0
	v_mfma_f32_16x16x32_bf16 v[92:95], v[128:131], v[202:205], 0
	v_mfma_f32_16x16x32_bf16 v[88:91], v[136:139], v[202:205], 0
	v_mfma_f32_16x16x32_bf16 v[76:79], v[128:131], v[210:213], 0
	v_mfma_f32_16x16x32_bf16 v[72:75], v[136:139], v[210:213], 0
	v_mfma_f32_16x16x32_bf16 v[124:127], v[132:135], v[190:193], v[124:127]
	v_mfma_f32_16x16x32_bf16 v[120:123], v[140:143], v[190:193], v[120:123]
	v_mfma_f32_16x16x32_bf16 v[108:111], v[132:135], v[198:201], v[108:111]
	v_mfma_f32_16x16x32_bf16 v[104:107], v[140:143], v[198:201], v[104:107]
	v_mfma_f32_16x16x32_bf16 v[92:95], v[132:135], v[206:209], v[92:95]
	v_mfma_f32_16x16x32_bf16 v[88:91], v[140:143], v[206:209], v[88:91]
	v_mfma_f32_16x16x32_bf16 v[76:79], v[132:135], v[214:217], v[76:79]
	v_mfma_f32_16x16x32_bf16 v[72:75], v[140:143], v[214:217], v[72:75]
	v_mfma_f32_16x16x32_bf16 v[116:119], v[160:163], v[186:189], 0
	v_mfma_f32_16x16x32_bf16 v[112:115], v[168:171], v[186:189], 0
	v_mfma_f32_16x16x32_bf16 v[100:103], v[160:163], v[194:197], 0
	v_mfma_f32_16x16x32_bf16 v[96:99], v[168:171], v[194:197], 0
	v_mfma_f32_16x16x32_bf16 v[84:87], v[160:163], v[202:205], 0
	v_mfma_f32_16x16x32_bf16 v[80:83], v[168:171], v[202:205], 0
	v_mfma_f32_16x16x32_bf16 v[68:71], v[160:163], v[210:213], 0
	v_mfma_f32_16x16x32_bf16 v[64:67], v[168:171], v[210:213], 0
	v_mfma_f32_16x16x32_bf16 v[116:119], v[164:167], v[190:193], v[116:119]
	v_mfma_f32_16x16x32_bf16 v[112:115], v[172:175], v[190:193], v[112:115]
	v_mfma_f32_16x16x32_bf16 v[100:103], v[164:167], v[198:201], v[100:103]
	v_mfma_f32_16x16x32_bf16 v[96:99], v[172:175], v[198:201], v[96:99]
	v_mfma_f32_16x16x32_bf16 v[84:87], v[164:167], v[206:209], v[84:87]
	v_mfma_f32_16x16x32_bf16 v[80:83], v[172:175], v[206:209], v[80:83]
	v_mfma_f32_16x16x32_bf16 v[68:71], v[164:167], v[214:217], v[68:71]
	v_mfma_f32_16x16x32_bf16 v[64:67], v[172:175], v[214:217], v[64:67]
	s_barrier
	s_add_i32 s78, s69, s42
	v_lshl_add_u64 v[178:179], s[34:35], 0, v[146:147]
	s_mov_b32 m0, s78
	ds_read_b128 v[186:189], v184 offset:16384
	ds_read_b128 v[190:193], v184 offset:17408
	ds_read_b128 v[194:197], v184 offset:18432
	ds_read_b128 v[198:201], v184 offset:19456
	ds_read_b128 v[202:205], v184 offset:20480
	ds_read_b128 v[206:209], v184 offset:21504
	ds_read_b128 v[210:213], v184 offset:22528
	ds_read_b128 v[214:217], v184 offset:23552
	global_load_lds_dwordx4 v[178:179], off
	s_add_i32 m0, s78, 0x2000
	s_add_u32 s78, s34, 0xb0000
	v_lshl_add_u64 v[218:219], s[34:35], 0, v[150:151]
	s_addc_u32 s79, s35, 0
	s_add_i32 s80, s70, s42
	global_load_lds_dwordx4 v[218:219], off
	s_mov_b32 m0, s80
	v_lshl_add_u64 v[222:223], s[38:39], 0, v[148:149]
	global_load_lds_dwordx4 v146, s[78:79]
	s_add_i32 m0, s80, 0x2000
	s_nop 0
	global_load_lds_dwordx4 v150, s[78:79]
	v_lshl_add_u64 v[220:221], s[38:39], 0, v[144:145]
	s_mov_b32 m0, s43
	s_nop 0
	global_load_lds_dwordx4 v[220:221], off
	s_mov_b32 m0, s52
	s_nop 0
	global_load_lds_dwordx4 v[222:223], off
	s_waitcnt vmcnt(8)
	s_waitcnt lgkmcnt(0)
	s_barrier
	s_waitcnt lgkmcnt(0)
	v_mfma_f32_16x16x32_bf16 v[60:63], v[128:131], v[186:189], 0
	v_mfma_f32_16x16x32_bf16 v[56:59], v[136:139], v[186:189], 0
	v_mfma_f32_16x16x32_bf16 v[44:47], v[128:131], v[194:197], 0
	v_mfma_f32_16x16x32_bf16 v[40:43], v[136:139], v[194:197], 0
	v_mfma_f32_16x16x32_bf16 v[28:31], v[128:131], v[202:205], 0
	v_mfma_f32_16x16x32_bf16 v[24:27], v[136:139], v[202:205], 0
	v_mfma_f32_16x16x32_bf16 v[12:15], v[128:131], v[210:213], 0
	v_mfma_f32_16x16x32_bf16 v[8:11], v[136:139], v[210:213], 0
	v_mfma_f32_16x16x32_bf16 v[60:63], v[132:135], v[190:193], v[60:63]
	v_mfma_f32_16x16x32_bf16 v[56:59], v[140:143], v[190:193], v[56:59]
	v_mfma_f32_16x16x32_bf16 v[44:47], v[132:135], v[198:201], v[44:47]
	v_mfma_f32_16x16x32_bf16 v[40:43], v[140:143], v[198:201], v[40:43]
	v_mfma_f32_16x16x32_bf16 v[28:31], v[132:135], v[206:209], v[28:31]
	v_mfma_f32_16x16x32_bf16 v[24:27], v[140:143], v[206:209], v[24:27]
	v_mfma_f32_16x16x32_bf16 v[12:15], v[132:135], v[214:217], v[12:15]
	v_mfma_f32_16x16x32_bf16 v[8:11], v[140:143], v[214:217], v[8:11]
	v_mfma_f32_16x16x32_bf16 v[52:55], v[160:163], v[186:189], 0
	v_mfma_f32_16x16x32_bf16 v[48:51], v[168:171], v[186:189], 0
	v_mfma_f32_16x16x32_bf16 v[36:39], v[160:163], v[194:197], 0
	v_mfma_f32_16x16x32_bf16 v[32:35], v[168:171], v[194:197], 0
	v_mfma_f32_16x16x32_bf16 v[20:23], v[160:163], v[202:205], 0
	v_mfma_f32_16x16x32_bf16 v[16:19], v[168:171], v[202:205], 0
	v_mfma_f32_16x16x32_bf16 v[4:7], v[160:163], v[210:213], 0
	v_mfma_f32_16x16x32_bf16 v[0:3], v[168:171], v[210:213], 0
	v_mfma_f32_16x16x32_bf16 v[52:55], v[164:167], v[190:193], v[52:55]
	v_mfma_f32_16x16x32_bf16 v[48:51], v[172:175], v[190:193], v[48:51]
	v_mfma_f32_16x16x32_bf16 v[36:39], v[164:167], v[198:201], v[36:39]
	v_mfma_f32_16x16x32_bf16 v[32:35], v[172:175], v[198:201], v[32:35]
	v_mfma_f32_16x16x32_bf16 v[20:23], v[164:167], v[206:209], v[20:23]
	v_mfma_f32_16x16x32_bf16 v[16:19], v[172:175], v[206:209], v[16:19]
	v_mfma_f32_16x16x32_bf16 v[4:7], v[164:167], v[214:217], v[4:7]
	v_mfma_f32_16x16x32_bf16 v[0:3], v[172:175], v[214:217], v[0:3]
	s_barrier
; #define PG8_STAGE(bufoff, gbase, voff) do { _Pragma("unroll") for (int _i = 0; _i < 2; ++_i) \
;         __builtin_amdgcn_global_load_lds((const unsigned*)((const char*)(gbase) + (voff)[_i]), (LAS unsigned*)(lds + (bufoff) + ldsw + _i * 8192), 16, 0, 0); } while (0)
; #define PG8_LDA(dst, b, h) do { _Pragma("unroll") for (int m = 0; m < 4; ++m) _Pragma("unroll") for (int k = 0; k < 2; ++k) dst[m][k] = *(const LAS bf16x8*)(lds + PG8_SA(b, h) + aoff + m * 2048 + k * 1024); } while (0)
; #define PG8_LDB(dst, b, h) do { _Pragma("unroll") for (int n = 0; n < 2; ++n) _Pragma("unroll") for (int k = 0; k < 2; ++k) dst[n][k] = *(const LAS bf16x8*)(lds + PG8_SB(b, h) + boff + n * 2048 + k * 1024); } while (0)
; #define PG8_MMA(ai, bj, At, Bt) do { __builtin_amdgcn_s_setprio(1); _Pragma("unroll") for (int m = 0; m < 4; ++m) _Pragma("unroll") for (int n = 0; n < 2; ++n) _Pragma("unroll") for (int k = 0; k < 2; ++k) \
;         acc[ai][bj][m][n] = __builtin_amdgcn_mfma_f32_16x16x32_bf16(Bt[n][k], At[m][k], acc[ai][bj][m][n], 0, 0, 0); __builtin_amdgcn_s_setprio(0); } while (0)
; #define PG8_WAIT_V(n) asm volatile("s_waitcnt vmcnt(" #n ")" ::: "memory")
; #define PG8_WAIT_L(n) asm volatile("s_waitcnt lgkmcnt(" #n ")" ::: "memory")
; #define PG8_BAR __builtin_amdgcn_s_barrier()
; #define PG8_SCHED __builtin_amdgcn_sched_barrier(0)
; template <class Epi>
; __device__ __forceinline__ void gemm_phase(LAS unsigned char* lds, const Gemm g, const StaticOrder& S, const Epi& E) {
;     ...
;             PG8_WAIT_V(8); PG8_WAIT_L(0); PG8_BAR; PG8_MMA(1, 0, At, B0); PG8_MMA(1, 1, At, B1); PG8_BAR; PG8_SCHED;
;             PG8_LDB(B0, 1, 0); PG8_LDB(B1, 1, 1); PG8_SCHED; PG8_LDA(At, 1, 0); PG8_STAGE(PG8_SA(0, 1), a2 + hstepA, voffA);
;             PG8_WAIT_V(8); PG8_WAIT_L(0); PG8_BAR; PG8_MMA(0, 0, At, B0); PG8_MMA(0, 1, At, B1); PG8_BAR; PG8_SCHED;
;             PG8_LDA(At, 1, 1); PG8_STAGE(PG8_SB(1, 0), b3, voffB); PG8_STAGE(PG8_SB(1, 1), b3 + hstepB, voffB); PG8_STAGE(PG8_SA(1, 0), a3, voffA);
;             PG8_WAIT_V(8); PG8_WAIT_L(0); PG8_BAR; PG8_MMA(1, 0, At, B0); PG8_MMA(1, 1, At, B1); PG8_BAR; PG8_SCHED;
	s_add_i32 s78, 0, 0x18000
	s_add_i32 s79, 0, 0x1c000
	v_add_u32_e32 v140, s78, v181
	v_add_u32_e32 v172, s79, v181
	ds_read_b128 v[128:131], v140
	ds_read_b128 v[132:135], v140 offset:1024
	ds_read_b128 v[136:139], v140 offset:2048
	ds_read_b128 v[140:143], v140 offset:3072
	ds_read_b128 v[160:163], v172
	ds_read_b128 v[164:167], v172 offset:1024
	ds_read_b128 v[168:171], v172 offset:2048
	ds_read_b128 v[172:175], v172 offset:3072
	s_add_u32 s38, s38, 0xb0000
	s_addc_u32 s39, s39, 0
	s_mov_b32 m0, s53
	ds_read_b128 v[186:189], v184 offset:32768
	ds_read_b128 v[190:193], v184 offset:33792
	ds_read_b128 v[194:197], v184 offset:34816
	ds_read_b128 v[198:201], v184 offset:35840
	ds_read_b128 v[202:205], v184 offset:36864
	ds_read_b128 v[206:209], v184 offset:37888
	ds_read_b128 v[210:213], v184 offset:38912
	ds_read_b128 v[214:217], v184 offset:39936
	global_load_lds_dwordx4 v144, s[38:39]
	s_mov_b32 m0, s54
	s_nop 0
	global_load_lds_dwordx4 v148, s[38:39]
	s_waitcnt vmcnt(8)
	s_waitcnt lgkmcnt(0)
	s_barrier
	s_waitcnt lgkmcnt(0)
	v_mfma_f32_16x16x32_bf16 v[124:127], v[128:131], v[186:189], v[124:127]
	v_mfma_f32_16x16x32_bf16 v[120:123], v[136:139], v[186:189], v[120:123]
	v_mfma_f32_16x16x32_bf16 v[108:111], v[128:131], v[194:197], v[108:111]
	v_mfma_f32_16x16x32_bf16 v[104:107], v[136:139], v[194:197], v[104:107]
	v_mfma_f32_16x16x32_bf16 v[92:95], v[128:131], v[202:205], v[92:95]
	v_mfma_f32_16x16x32_bf16 v[88:91], v[136:139], v[202:205], v[88:91]
	v_mfma_f32_16x16x32_bf16 v[76:79], v[128:131], v[210:213], v[76:79]
	v_mfma_f32_16x16x32_bf16 v[72:75], v[136:139], v[210:213], v[72:75]
	v_mfma_f32_16x16x32_bf16 v[124:127], v[132:135], v[190:193], v[124:127]
	v_mfma_f32_16x16x32_bf16 v[120:123], v[140:143], v[190:193], v[120:123]
	v_mfma_f32_16x16x32_bf16 v[108:111], v[132:135], v[198:201], v[108:111]
	v_mfma_f32_16x16x32_bf16 v[104:107], v[140:143], v[198:201], v[104:107]
	v_mfma_f32_16x16x32_bf16 v[92:95], v[132:135], v[206:209], v[92:95]
	v_mfma_f32_16x16x32_bf16 v[88:91], v[140:143], v[206:209], v[88:91]
	v_mfma_f32_16x16x32_bf16 v[76:79], v[132:135], v[214:217], v[76:79]
	v_mfma_f32_16x16x32_bf16 v[72:75], v[140:143], v[214:217], v[72:75]
	v_mfma_f32_16x16x32_bf16 v[116:119], v[160:163], v[186:189], v[116:119]
	v_mfma_f32_16x16x32_bf16 v[112:115], v[168:171], v[186:189], v[112:115]
	v_mfma_f32_16x16x32_bf16 v[100:103], v[160:163], v[194:197], v[100:103]
	v_mfma_f32_16x16x32_bf16 v[96:99], v[168:171], v[194:197], v[96:99]
	v_mfma_f32_16x16x32_bf16 v[84:87], v[160:163], v[202:205], v[84:87]
	v_mfma_f32_16x16x32_bf16 v[80:83], v[168:171], v[202:205], v[80:83]
	v_mfma_f32_16x16x32_bf16 v[68:71], v[160:163], v[210:213], v[68:71]
	v_mfma_f32_16x16x32_bf16 v[64:67], v[168:171], v[210:213], v[64:67]
	v_mfma_f32_16x16x32_bf16 v[116:119], v[164:167], v[190:193], v[116:119]
	v_mfma_f32_16x16x32_bf16 v[112:115], v[172:175], v[190:193], v[112:115]
	v_mfma_f32_16x16x32_bf16 v[100:103], v[164:167], v[198:201], v[100:103]
	v_mfma_f32_16x16x32_bf16 v[96:99], v[172:175], v[198:201], v[96:99]
	v_mfma_f32_16x16x32_bf16 v[84:87], v[164:167], v[206:209], v[84:87]
	v_mfma_f32_16x16x32_bf16 v[80:83], v[172:175], v[206:209], v[80:83]
	v_mfma_f32_16x16x32_bf16 v[68:71], v[164:167], v[214:217], v[68:71]
	v_mfma_f32_16x16x32_bf16 v[64:67], v[172:175], v[214:217], v[64:67]
	s_barrier
	s_add_i32 s38, s78, s42
	v_lshl_add_u64 v[178:179], v[178:179], 0, s[16:17]
	s_mov_b32 m0, s38
	ds_read_b128 v[186:189], v184 offset:49152
	ds_read_b128 v[190:193], v184 offset:50176
	ds_read_b128 v[194:197], v184 offset:51200
	ds_read_b128 v[198:201], v184 offset:52224
	ds_read_b128 v[202:205], v184 offset:53248
	ds_read_b128 v[206:209], v184 offset:54272
	ds_read_b128 v[210:213], v184 offset:55296
	ds_read_b128 v[214:217], v184 offset:56320
	global_load_lds_dwordx4 v[178:179], off
	s_add_i32 m0, s38, 0x2000
	s_add_u32 s34, s34, 0xb0080
	v_lshl_add_u64 v[178:179], v[218:219], 0, s[16:17]
	s_addc_u32 s35, s35, 0
	s_add_i32 s38, s79, s42
	global_load_lds_dwordx4 v[178:179], off
	s_mov_b32 m0, s38
	s_nop 0
	global_load_lds_dwordx4 v146, s[34:35]
	s_add_i32 m0, s38, 0x2000
	s_nop 0
	global_load_lds_dwordx4 v150, s[34:35]
	v_lshl_add_u64 v[178:179], v[220:221], 0, s[16:17]
	s_mov_b32 m0, s62
	s_nop 0
	global_load_lds_dwordx4 v[178:179], off
	v_lshl_add_u64 v[178:179], v[222:223], 0, s[16:17]
	s_mov_b32 m0, s63
	s_nop 0
	global_load_lds_dwordx4 v[178:179], off
	s_waitcnt vmcnt(8)
	s_waitcnt lgkmcnt(0)
	s_barrier
	s_waitcnt lgkmcnt(0)
	v_mfma_f32_16x16x32_bf16 v[60:63], v[128:131], v[186:189], v[60:63]
	v_mfma_f32_16x16x32_bf16 v[56:59], v[136:139], v[186:189], v[56:59]
	v_mfma_f32_16x16x32_bf16 v[44:47], v[128:131], v[194:197], v[44:47]
	v_mfma_f32_16x16x32_bf16 v[40:43], v[136:139], v[194:197], v[40:43]
	v_mfma_f32_16x16x32_bf16 v[28:31], v[128:131], v[202:205], v[28:31]
	v_mfma_f32_16x16x32_bf16 v[24:27], v[136:139], v[202:205], v[24:27]
	v_mfma_f32_16x16x32_bf16 v[12:15], v[128:131], v[210:213], v[12:15]
	v_mfma_f32_16x16x32_bf16 v[8:11], v[136:139], v[210:213], v[8:11]
	v_mfma_f32_16x16x32_bf16 v[60:63], v[132:135], v[190:193], v[60:63]
	v_mfma_f32_16x16x32_bf16 v[56:59], v[140:143], v[190:193], v[56:59]
	v_mfma_f32_16x16x32_bf16 v[44:47], v[132:135], v[198:201], v[44:47]
	v_mfma_f32_16x16x32_bf16 v[40:43], v[140:143], v[198:201], v[40:43]
	v_mfma_f32_16x16x32_bf16 v[28:31], v[132:135], v[206:209], v[28:31]
	v_mfma_f32_16x16x32_bf16 v[24:27], v[140:143], v[206:209], v[24:27]
	v_mfma_f32_16x16x32_bf16 v[12:15], v[132:135], v[214:217], v[12:15]
	v_mfma_f32_16x16x32_bf16 v[8:11], v[140:143], v[214:217], v[8:11]
	v_mfma_f32_16x16x32_bf16 v[52:55], v[160:163], v[186:189], v[52:55]
	v_mfma_f32_16x16x32_bf16 v[48:51], v[168:171], v[186:189], v[48:51]
	v_mfma_f32_16x16x32_bf16 v[36:39], v[160:163], v[194:197], v[36:39]
	v_mfma_f32_16x16x32_bf16 v[32:35], v[168:171], v[194:197], v[32:35]
	v_mfma_f32_16x16x32_bf16 v[20:23], v[160:163], v[202:205], v[20:23]
	v_mfma_f32_16x16x32_bf16 v[16:19], v[168:171], v[202:205], v[16:19]
	v_mfma_f32_16x16x32_bf16 v[4:7], v[160:163], v[210:213], v[4:7]
	v_mfma_f32_16x16x32_bf16 v[0:3], v[168:171], v[210:213], v[0:3]
	v_mfma_f32_16x16x32_bf16 v[52:55], v[164:167], v[190:193], v[52:55]
	v_mfma_f32_16x16x32_bf16 v[48:51], v[172:175], v[190:193], v[48:51]
	v_mfma_f32_16x16x32_bf16 v[36:39], v[164:167], v[198:201], v[36:39]
	v_mfma_f32_16x16x32_bf16 v[32:35], v[172:175], v[198:201], v[32:35]
	v_mfma_f32_16x16x32_bf16 v[20:23], v[164:167], v[206:209], v[20:23]
	v_mfma_f32_16x16x32_bf16 v[16:19], v[172:175], v[206:209], v[16:19]
	v_mfma_f32_16x16x32_bf16 v[4:7], v[164:167], v[214:217], v[4:7]
	v_mfma_f32_16x16x32_bf16 v[0:3], v[172:175], v[214:217], v[0:3]
	s_barrier
	s_add_i32 s77, s77, 2
	s_add_u32 s0, s0, 0x100
	s_addc_u32 s1, s1, 0
	s_add_u32 s75, s75, 0x100
	s_addc_u32 s76, s76, 0
	s_cmp_gt_u32 s77, 41
; #define PG8_STAGE(bufoff, gbase, voff) do { _Pragma("unroll") for (int _i = 0; _i < 2; ++_i) \
;         __builtin_amdgcn_global_load_lds((const unsigned*)((const char*)(gbase) + (voff)[_i]), (LAS unsigned*)(lds + (bufoff) + ldsw + _i * 8192), 16, 0, 0); } while (0)
; #define PG8_LDA(dst, b, h) do { _Pragma("unroll") for (int m = 0; m < 4; ++m) _Pragma("unroll") for (int k = 0; k < 2; ++k) dst[m][k] = *(const LAS bf16x8*)(lds + PG8_SA(b, h) + aoff + m * 2048 + k * 1024); } while (0)
; #define PG8_LDB(dst, b, h) do { _Pragma("unroll") for (int n = 0; n < 2; ++n) _Pragma("unroll") for (int k = 0; k < 2; ++k) dst[n][k] = *(const LAS bf16x8*)(lds + PG8_SB(b, h) + boff + n * 2048 + k * 1024); } while (0)
; #define PG8_MMA(ai, bj, At, Bt) do { __builtin_amdgcn_s_setprio(1); _Pragma("unroll") for (int m = 0; m < 4; ++m) _Pragma("unroll") for (int n = 0; n < 2; ++n) _Pragma("unroll") for (int k = 0; k < 2; ++k) \
;         acc[ai][bj][m][n] = __builtin_amdgcn_mfma_f32_16x16x32_bf16(Bt[n][k], At[m][k], acc[ai][bj][m][n], 0, 0, 0); __builtin_amdgcn_s_setprio(0); } while (0)
; #define PG8_WAIT_V(n) asm volatile("s_waitcnt vmcnt(" #n ")" ::: "memory")
; #define PG8_WAIT_L(n) asm volatile("s_waitcnt lgkmcnt(" #n ")" ::: "memory")
; #define PG8_BAR __builtin_amdgcn_s_barrier()
; #define PG8_SCHED __builtin_amdgcn_sched_barrier(0)
; template <class Epi>
; __device__ __forceinline__ void gemm_phase(LAS unsigned char* lds, const Gemm g, const StaticOrder& S, const Epi& E) {
;     ...
;             PG8_LDB(B0, 0, 0); PG8_LDB(B1, 0, 1); PG8_SCHED; PG8_LDA(At, 0, 0); PG8_STAGE(PG8_SA(1, 1), a1 + hstepA, voffA);
;             PG8_WAIT_V(8); PG8_WAIT_L(0); PG8_BAR; PG8_MMA(0, 0, At, B0); PG8_MMA(0, 1, At, B1); PG8_BAR; PG8_SCHED;
;             PG8_LDA(At, 0, 1); PG8_STAGE(PG8_SB(0, 0), b2, voffB); PG8_STAGE(PG8_SB(0, 1), b2 + hstepB, voffB); PG8_STAGE(PG8_SA(0, 0), a2, voffA);
;             PG8_WAIT_V(8); PG8_WAIT_L(0); PG8_BAR; PG8_MMA(1, 0, At, B0); PG8_MMA(1, 1, At, B1); PG8_BAR; PG8_SCHED;
.LBB0_792:
	ds_read_b128 v[128:131], v182
	ds_read_b128 v[132:135], v182 offset:1024
	ds_read_b128 v[136:139], v182 offset:2048
	ds_read_b128 v[140:143], v182 offset:3072
	ds_read_b128 v[160:163], v183
	ds_read_b128 v[164:167], v183 offset:1024
	ds_read_b128 v[168:171], v183 offset:2048
	ds_read_b128 v[172:175], v183 offset:3072
	s_add_u32 s34, s0, 0xfff50080
	s_addc_u32 s35, s1, -1
	s_cmp_eq_u32 s77, 40
	s_cselect_b32 s39, s7, s35
	s_cselect_b32 s38, s6, s34
	s_cselect_b32 s35, s23, s76
	s_cselect_b32 s34, s22, s75
	s_add_i32 m0, s43, 0xc000
	ds_read_b128 v[186:189], v184
	ds_read_b128 v[190:193], v184 offset:1024
	ds_read_b128 v[194:197], v184 offset:2048
	ds_read_b128 v[198:201], v184 offset:3072
	ds_read_b128 v[202:205], v184 offset:4096
	ds_read_b128 v[206:209], v184 offset:5120
	ds_read_b128 v[210:213], v184 offset:6144
	ds_read_b128 v[214:217], v184 offset:7168
	global_load_lds_dwordx4 v152, s[0:1]
	s_add_i32 m0, s43, 0xe000
	s_nop 0
	global_load_lds_dwordx4 v154, s[0:1]
	s_waitcnt vmcnt(8)
	s_waitcnt lgkmcnt(0)
	s_barrier
	s_waitcnt lgkmcnt(0)
	v_mfma_f32_16x16x32_bf16 v[124:127], v[128:131], v[186:189], v[124:127]
	v_mfma_f32_16x16x32_bf16 v[120:123], v[136:139], v[186:189], v[120:123]
	v_mfma_f32_16x16x32_bf16 v[108:111], v[128:131], v[194:197], v[108:111]
	v_mfma_f32_16x16x32_bf16 v[104:107], v[136:139], v[194:197], v[104:107]
	v_mfma_f32_16x16x32_bf16 v[92:95], v[128:131], v[202:205], v[92:95]
	v_mfma_f32_16x16x32_bf16 v[88:91], v[136:139], v[202:205], v[88:91]
	v_mfma_f32_16x16x32_bf16 v[76:79], v[128:131], v[210:213], v[76:79]
	v_mfma_f32_16x16x32_bf16 v[72:75], v[136:139], v[210:213], v[72:75]
	v_mfma_f32_16x16x32_bf16 v[124:127], v[132:135], v[190:193], v[124:127]
	v_mfma_f32_16x16x32_bf16 v[120:123], v[140:143], v[190:193], v[120:123]
	v_mfma_f32_16x16x32_bf16 v[108:111], v[132:135], v[198:201], v[108:111]
	v_mfma_f32_16x16x32_bf16 v[104:107], v[140:143], v[198:201], v[104:107]
	v_mfma_f32_16x16x32_bf16 v[92:95], v[132:135], v[206:209], v[92:95]
	v_mfma_f32_16x16x32_bf16 v[88:91], v[140:143], v[206:209], v[88:91]
	v_mfma_f32_16x16x32_bf16 v[76:79], v[132:135], v[214:217], v[76:79]
	v_mfma_f32_16x16x32_bf16 v[72:75], v[140:143], v[214:217], v[72:75]
	v_mfma_f32_16x16x32_bf16 v[116:119], v[160:163], v[186:189], v[116:119]
	v_mfma_f32_16x16x32_bf16 v[112:115], v[168:171], v[186:189], v[112:115]
	v_mfma_f32_16x16x32_bf16 v[100:103], v[160:163], v[194:197], v[100:103]
	v_mfma_f32_16x16x32_bf16 v[96:99], v[168:171], v[194:197], v[96:99]
	v_mfma_f32_16x16x32_bf16 v[84:87], v[160:163], v[202:205], v[84:87]
	v_mfma_f32_16x16x32_bf16 v[80:83], v[168:171], v[202:205], v[80:83]
	v_mfma_f32_16x16x32_bf16 v[68:71], v[160:163], v[210:213], v[68:71]
	v_mfma_f32_16x16x32_bf16 v[64:67], v[168:171], v[210:213], v[64:67]
	v_mfma_f32_16x16x32_bf16 v[116:119], v[164:167], v[190:193], v[116:119]
	v_mfma_f32_16x16x32_bf16 v[112:115], v[172:175], v[190:193], v[112:115]
	v_mfma_f32_16x16x32_bf16 v[100:103], v[164:167], v[198:201], v[100:103]
	v_mfma_f32_16x16x32_bf16 v[96:99], v[172:175], v[198:201], v[96:99]
	v_mfma_f32_16x16x32_bf16 v[84:87], v[164:167], v[206:209], v[84:87]
	v_mfma_f32_16x16x32_bf16 v[80:83], v[172:175], v[206:209], v[80:83]
	v_mfma_f32_16x16x32_bf16 v[68:71], v[164:167], v[214:217], v[68:71]
	v_mfma_f32_16x16x32_bf16 v[64:67], v[172:175], v[214:217], v[64:67]
	s_barrier
	s_add_i32 s78, s69, s42
	v_lshl_add_u64 v[178:179], s[34:35], 0, v[146:147]
	s_mov_b32 m0, s78
	ds_read_b128 v[186:189], v184 offset:16384
	ds_read_b128 v[190:193], v184 offset:17408
	ds_read_b128 v[194:197], v184 offset:18432
	ds_read_b128 v[198:201], v184 offset:19456
	ds_read_b128 v[202:205], v184 offset:20480
	ds_read_b128 v[206:209], v184 offset:21504
	ds_read_b128 v[210:213], v184 offset:22528
	ds_read_b128 v[214:217], v184 offset:23552
	global_load_lds_dwordx4 v[178:179], off
	s_add_i32 m0, s78, 0x2000
	s_add_u32 s78, s34, 0xb0000
	v_lshl_add_u64 v[218:219], s[34:35], 0, v[150:151]
	s_addc_u32 s79, s35, 0
	s_add_i32 s80, s70, s42
	global_load_lds_dwordx4 v[218:219], off
	s_mov_b32 m0, s80
	v_lshl_add_u64 v[222:223], s[38:39], 0, v[148:149]
	global_load_lds_dwordx4 v146, s[78:79]
	s_add_i32 m0, s80, 0x2000
	s_nop 0
	global_load_lds_dwordx4 v150, s[78:79]
	v_lshl_add_u64 v[220:221], s[38:39], 0, v[144:145]
	s_mov_b32 m0, s43
	s_nop 0
	global_load_lds_dwordx4 v[220:221], off
	s_mov_b32 m0, s52
	s_nop 0
	global_load_lds_dwordx4 v[222:223], off
	s_waitcnt vmcnt(8)
	s_waitcnt lgkmcnt(0)
	s_barrier
	s_waitcnt lgkmcnt(0)
	v_mfma_f32_16x16x32_bf16 v[60:63], v[128:131], v[186:189], v[60:63]
	v_mfma_f32_16x16x32_bf16 v[56:59], v[136:139], v[186:189], v[56:59]
	v_mfma_f32_16x16x32_bf16 v[44:47], v[128:131], v[194:197], v[44:47]
	v_mfma_f32_16x16x32_bf16 v[40:43], v[136:139], v[194:197], v[40:43]
	v_mfma_f32_16x16x32_bf16 v[28:31], v[128:131], v[202:205], v[28:31]
	v_mfma_f32_16x16x32_bf16 v[24:27], v[136:139], v[202:205], v[24:27]
	v_mfma_f32_16x16x32_bf16 v[12:15], v[128:131], v[210:213], v[12:15]
	v_mfma_f32_16x16x32_bf16 v[8:11], v[136:139], v[210:213], v[8:11]
	v_mfma_f32_16x16x32_bf16 v[60:63], v[132:135], v[190:193], v[60:63]
	v_mfma_f32_16x16x32_bf16 v[56:59], v[140:143], v[190:193], v[56:59]
	v_mfma_f32_16x16x32_bf16 v[44:47], v[132:135], v[198:201], v[44:47]
	v_mfma_f32_16x16x32_bf16 v[40:43], v[140:143], v[198:201], v[40:43]
	v_mfma_f32_16x16x32_bf16 v[28:31], v[132:135], v[206:209], v[28:31]
	v_mfma_f32_16x16x32_bf16 v[24:27], v[140:143], v[206:209], v[24:27]
	v_mfma_f32_16x16x32_bf16 v[12:15], v[132:135], v[214:217], v[12:15]
	v_mfma_f32_16x16x32_bf16 v[8:11], v[140:143], v[214:217], v[8:11]
	v_mfma_f32_16x16x32_bf16 v[52:55], v[160:163], v[186:189], v[52:55]
	v_mfma_f32_16x16x32_bf16 v[48:51], v[168:171], v[186:189], v[48:51]
	v_mfma_f32_16x16x32_bf16 v[36:39], v[160:163], v[194:197], v[36:39]
	v_mfma_f32_16x16x32_bf16 v[32:35], v[168:171], v[194:197], v[32:35]
	v_mfma_f32_16x16x32_bf16 v[20:23], v[160:163], v[202:205], v[20:23]
	v_mfma_f32_16x16x32_bf16 v[16:19], v[168:171], v[202:205], v[16:19]
	v_mfma_f32_16x16x32_bf16 v[4:7], v[160:163], v[210:213], v[4:7]
	v_mfma_f32_16x16x32_bf16 v[0:3], v[168:171], v[210:213], v[0:3]
	v_mfma_f32_16x16x32_bf16 v[52:55], v[164:167], v[190:193], v[52:55]
	v_mfma_f32_16x16x32_bf16 v[48:51], v[172:175], v[190:193], v[48:51]
	v_mfma_f32_16x16x32_bf16 v[36:39], v[164:167], v[198:201], v[36:39]
	v_mfma_f32_16x16x32_bf16 v[32:35], v[172:175], v[198:201], v[32:35]
	v_mfma_f32_16x16x32_bf16 v[20:23], v[164:167], v[206:209], v[20:23]
	v_mfma_f32_16x16x32_bf16 v[16:19], v[172:175], v[206:209], v[16:19]
	v_mfma_f32_16x16x32_bf16 v[4:7], v[164:167], v[214:217], v[4:7]
	v_mfma_f32_16x16x32_bf16 v[0:3], v[172:175], v[214:217], v[0:3]
	s_barrier
; #define PG8_STAGE(bufoff, gbase, voff) do { _Pragma("unroll") for (int _i = 0; _i < 2; ++_i) \
;         __builtin_amdgcn_global_load_lds((const unsigned*)((const char*)(gbase) + (voff)[_i]), (LAS unsigned*)(lds + (bufoff) + ldsw + _i * 8192), 16, 0, 0); } while (0)
; #define PG8_LDA(dst, b, h) do { _Pragma("unroll") for (int m = 0; m < 4; ++m) _Pragma("unroll") for (int k = 0; k < 2; ++k) dst[m][k] = *(const LAS bf16x8*)(lds + PG8_SA(b, h) + aoff + m * 2048 + k * 1024); } while (0)
; #define PG8_LDB(dst, b, h) do { _Pragma("unroll") for (int n = 0; n < 2; ++n) _Pragma("unroll") for (int k = 0; k < 2; ++k) dst[n][k] = *(const LAS bf16x8*)(lds + PG8_SB(b, h) + boff + n * 2048 + k * 1024); } while (0)
; #define PG8_MMA(ai, bj, At, Bt) do { __builtin_amdgcn_s_setprio(1); _Pragma("unroll") for (int m = 0; m < 4; ++m) _Pragma("unroll") for (int n = 0; n < 2; ++n) _Pragma("unroll") for (int k = 0; k < 2; ++k) \
;         acc[ai][bj][m][n] = __builtin_amdgcn_mfma_f32_16x16x32_bf16(Bt[n][k], At[m][k], acc[ai][bj][m][n], 0, 0, 0); __builtin_amdgcn_s_setprio(0); } while (0)
; #define PG8_WAIT_V(n) asm volatile("s_waitcnt vmcnt(" #n ")" ::: "memory")
; #define PG8_WAIT_L(n) asm volatile("s_waitcnt lgkmcnt(" #n ")" ::: "memory")
; #define PG8_BAR __builtin_amdgcn_s_barrier()
; #define PG8_SCHED __builtin_amdgcn_sched_barrier(0)
; template <class Epi>
; __device__ __forceinline__ void gemm_phase(LAS unsigned char* lds, const Gemm g, const StaticOrder& S, const Epi& E) {
;     ...
;             PG8_LDB(B0, 1, 0); PG8_LDB(B1, 1, 1); PG8_SCHED; PG8_LDA(At, 1, 0); PG8_STAGE(PG8_SA(0, 1), a2 + hstepA, voffA);
;             PG8_WAIT_V(8); PG8_WAIT_L(0); PG8_BAR; PG8_MMA(0, 0, At, B0); PG8_MMA(0, 1, At, B1); PG8_BAR; PG8_SCHED;
;             PG8_LDA(At, 1, 1); PG8_STAGE(PG8_SB(1, 0), b3, voffB); PG8_STAGE(PG8_SB(1, 1), b3 + hstepB, voffB); PG8_STAGE(PG8_SA(1, 0), a3, voffA);
;             PG8_WAIT_V(8); PG8_WAIT_L(0); PG8_BAR; PG8_MMA(1, 0, At, B0); PG8_MMA(1, 1, At, B1); PG8_BAR; PG8_SCHED;
;         }
	s_add_i32 s78, 0, 0x18000
	s_add_i32 s79, 0, 0x1c000
	v_add_u32_e32 v140, s78, v181
	v_add_u32_e32 v172, s79, v181
	ds_read_b128 v[128:131], v140
	ds_read_b128 v[132:135], v140 offset:1024
	ds_read_b128 v[136:139], v140 offset:2048
	ds_read_b128 v[140:143], v140 offset:3072
	ds_read_b128 v[160:163], v172
	ds_read_b128 v[164:167], v172 offset:1024
	ds_read_b128 v[168:171], v172 offset:2048
	ds_read_b128 v[172:175], v172 offset:3072
	s_add_u32 s38, s38, 0xb0000
	s_addc_u32 s39, s39, 0
	s_mov_b32 m0, s53
	ds_read_b128 v[186:189], v184 offset:32768
	ds_read_b128 v[190:193], v184 offset:33792
	ds_read_b128 v[194:197], v184 offset:34816
	ds_read_b128 v[198:201], v184 offset:35840
	ds_read_b128 v[202:205], v184 offset:36864
	ds_read_b128 v[206:209], v184 offset:37888
	ds_read_b128 v[210:213], v184 offset:38912
	ds_read_b128 v[214:217], v184 offset:39936
	global_load_lds_dwordx4 v144, s[38:39]
	s_mov_b32 m0, s54
	s_nop 0
	global_load_lds_dwordx4 v148, s[38:39]
	s_waitcnt vmcnt(8)
	s_waitcnt lgkmcnt(0)
	s_barrier
	s_waitcnt lgkmcnt(0)
	v_mfma_f32_16x16x32_bf16 v[124:127], v[128:131], v[186:189], v[124:127]
	v_mfma_f32_16x16x32_bf16 v[120:123], v[136:139], v[186:189], v[120:123]
	v_mfma_f32_16x16x32_bf16 v[108:111], v[128:131], v[194:197], v[108:111]
	v_mfma_f32_16x16x32_bf16 v[104:107], v[136:139], v[194:197], v[104:107]
	v_mfma_f32_16x16x32_bf16 v[92:95], v[128:131], v[202:205], v[92:95]
	v_mfma_f32_16x16x32_bf16 v[88:91], v[136:139], v[202:205], v[88:91]
	v_mfma_f32_16x16x32_bf16 v[76:79], v[128:131], v[210:213], v[76:79]
	v_mfma_f32_16x16x32_bf16 v[72:75], v[136:139], v[210:213], v[72:75]
	v_mfma_f32_16x16x32_bf16 v[124:127], v[132:135], v[190:193], v[124:127]
	v_mfma_f32_16x16x32_bf16 v[120:123], v[140:143], v[190:193], v[120:123]
	v_mfma_f32_16x16x32_bf16 v[108:111], v[132:135], v[198:201], v[108:111]
	v_mfma_f32_16x16x32_bf16 v[104:107], v[140:143], v[198:201], v[104:107]
	v_mfma_f32_16x16x32_bf16 v[92:95], v[132:135], v[206:209], v[92:95]
	v_mfma_f32_16x16x32_bf16 v[88:91], v[140:143], v[206:209], v[88:91]
	v_mfma_f32_16x16x32_bf16 v[76:79], v[132:135], v[214:217], v[76:79]
	v_mfma_f32_16x16x32_bf16 v[72:75], v[140:143], v[214:217], v[72:75]
	v_mfma_f32_16x16x32_bf16 v[116:119], v[160:163], v[186:189], v[116:119]
	v_mfma_f32_16x16x32_bf16 v[112:115], v[168:171], v[186:189], v[112:115]
	v_mfma_f32_16x16x32_bf16 v[100:103], v[160:163], v[194:197], v[100:103]
	v_mfma_f32_16x16x32_bf16 v[96:99], v[168:171], v[194:197], v[96:99]
	v_mfma_f32_16x16x32_bf16 v[84:87], v[160:163], v[202:205], v[84:87]
	v_mfma_f32_16x16x32_bf16 v[80:83], v[168:171], v[202:205], v[80:83]
	v_mfma_f32_16x16x32_bf16 v[68:71], v[160:163], v[210:213], v[68:71]
	v_mfma_f32_16x16x32_bf16 v[64:67], v[168:171], v[210:213], v[64:67]
	v_mfma_f32_16x16x32_bf16 v[116:119], v[164:167], v[190:193], v[116:119]
	v_mfma_f32_16x16x32_bf16 v[112:115], v[172:175], v[190:193], v[112:115]
	v_mfma_f32_16x16x32_bf16 v[100:103], v[164:167], v[198:201], v[100:103]
	v_mfma_f32_16x16x32_bf16 v[96:99], v[172:175], v[198:201], v[96:99]
	v_mfma_f32_16x16x32_bf16 v[84:87], v[164:167], v[206:209], v[84:87]
	v_mfma_f32_16x16x32_bf16 v[80:83], v[172:175], v[206:209], v[80:83]
	v_mfma_f32_16x16x32_bf16 v[68:71], v[164:167], v[214:217], v[68:71]
	v_mfma_f32_16x16x32_bf16 v[64:67], v[172:175], v[214:217], v[64:67]
	s_barrier
	s_add_i32 s38, s78, s42
	v_lshl_add_u64 v[178:179], v[178:179], 0, s[16:17]
	s_mov_b32 m0, s38
	ds_read_b128 v[186:189], v184 offset:49152
	ds_read_b128 v[190:193], v184 offset:50176
	ds_read_b128 v[194:197], v184 offset:51200
	ds_read_b128 v[198:201], v184 offset:52224
	ds_read_b128 v[202:205], v184 offset:53248
	ds_read_b128 v[206:209], v184 offset:54272
	ds_read_b128 v[210:213], v184 offset:55296
	ds_read_b128 v[214:217], v184 offset:56320
	global_load_lds_dwordx4 v[178:179], off
	s_add_i32 m0, s38, 0x2000
	s_add_u32 s34, s34, 0xb0080
	v_lshl_add_u64 v[178:179], v[218:219], 0, s[16:17]
	s_addc_u32 s35, s35, 0
	s_add_i32 s38, s79, s42
	global_load_lds_dwordx4 v[178:179], off
	s_mov_b32 m0, s38
	s_nop 0
	global_load_lds_dwordx4 v146, s[34:35]
	s_add_i32 m0, s38, 0x2000
	s_nop 0
	global_load_lds_dwordx4 v150, s[34:35]
	v_lshl_add_u64 v[178:179], v[220:221], 0, s[16:17]
	s_mov_b32 m0, s62
	s_nop 0
	global_load_lds_dwordx4 v[178:179], off
	v_lshl_add_u64 v[178:179], v[222:223], 0, s[16:17]
	s_mov_b32 m0, s63
	s_nop 0
	global_load_lds_dwordx4 v[178:179], off
	s_waitcnt vmcnt(8)
	s_waitcnt lgkmcnt(0)
	s_barrier
	s_waitcnt lgkmcnt(0)
	v_mfma_f32_16x16x32_bf16 v[60:63], v[128:131], v[186:189], v[60:63]
	v_mfma_f32_16x16x32_bf16 v[56:59], v[136:139], v[186:189], v[56:59]
	v_mfma_f32_16x16x32_bf16 v[44:47], v[128:131], v[194:197], v[44:47]
	v_mfma_f32_16x16x32_bf16 v[40:43], v[136:139], v[194:197], v[40:43]
	v_mfma_f32_16x16x32_bf16 v[28:31], v[128:131], v[202:205], v[28:31]
	v_mfma_f32_16x16x32_bf16 v[24:27], v[136:139], v[202:205], v[24:27]
	v_mfma_f32_16x16x32_bf16 v[12:15], v[128:131], v[210:213], v[12:15]
	v_mfma_f32_16x16x32_bf16 v[8:11], v[136:139], v[210:213], v[8:11]
	v_mfma_f32_16x16x32_bf16 v[60:63], v[132:135], v[190:193], v[60:63]
	v_mfma_f32_16x16x32_bf16 v[56:59], v[140:143], v[190:193], v[56:59]
	v_mfma_f32_16x16x32_bf16 v[44:47], v[132:135], v[198:201], v[44:47]
	v_mfma_f32_16x16x32_bf16 v[40:43], v[140:143], v[198:201], v[40:43]
	v_mfma_f32_16x16x32_bf16 v[28:31], v[132:135], v[206:209], v[28:31]
	v_mfma_f32_16x16x32_bf16 v[24:27], v[140:143], v[206:209], v[24:27]
	v_mfma_f32_16x16x32_bf16 v[12:15], v[132:135], v[214:217], v[12:15]
	v_mfma_f32_16x16x32_bf16 v[8:11], v[140:143], v[214:217], v[8:11]
	v_mfma_f32_16x16x32_bf16 v[52:55], v[160:163], v[186:189], v[52:55]
	v_mfma_f32_16x16x32_bf16 v[48:51], v[168:171], v[186:189], v[48:51]
	v_mfma_f32_16x16x32_bf16 v[36:39], v[160:163], v[194:197], v[36:39]
	v_mfma_f32_16x16x32_bf16 v[32:35], v[168:171], v[194:197], v[32:35]
	v_mfma_f32_16x16x32_bf16 v[20:23], v[160:163], v[202:205], v[20:23]
	v_mfma_f32_16x16x32_bf16 v[16:19], v[168:171], v[202:205], v[16:19]
	v_mfma_f32_16x16x32_bf16 v[4:7], v[160:163], v[210:213], v[4:7]
	v_mfma_f32_16x16x32_bf16 v[0:3], v[168:171], v[210:213], v[0:3]
	v_mfma_f32_16x16x32_bf16 v[52:55], v[164:167], v[190:193], v[52:55]
	v_mfma_f32_16x16x32_bf16 v[48:51], v[172:175], v[190:193], v[48:51]
	v_mfma_f32_16x16x32_bf16 v[36:39], v[164:167], v[198:201], v[36:39]
	v_mfma_f32_16x16x32_bf16 v[32:35], v[172:175], v[198:201], v[32:35]
	v_mfma_f32_16x16x32_bf16 v[20:23], v[164:167], v[206:209], v[20:23]
	v_mfma_f32_16x16x32_bf16 v[16:19], v[172:175], v[206:209], v[16:19]
	v_mfma_f32_16x16x32_bf16 v[4:7], v[164:167], v[214:217], v[4:7]
	v_mfma_f32_16x16x32_bf16 v[0:3], v[172:175], v[214:217], v[0:3]
	s_barrier
	s_add_i32 s77, s77, 2
	s_add_u32 s0, s0, 0x100
	s_addc_u32 s1, s1, 0
	s_add_u32 s75, s75, 0x100
	s_addc_u32 s76, s76, 0
	s_cmp_gt_u32 s77, 41
	s_cbranch_scc0 .LBB0_792
	s_and_b64 vcc, exec, s[18:19]
	s_cbranch_vccz .LBB0_795
	s_barrier

; #define PG8_STAGE(bufoff, gbase, voff) do { _Pragma("unroll") for (int _i = 0; _i < 2; ++_i) \
;         __builtin_amdgcn_global_load_lds((const unsigned*)((const char*)(gbase) + (voff)[_i]), (LAS unsigned*)(lds + (bufoff) + ldsw + _i * 8192), 16, 0, 0); } while (0)
; #define PG8_LDA(dst, b, h) do { _Pragma("unroll") for (int m = 0; m < 4; ++m) _Pragma("unroll") for (int k = 0; k < 2; ++k) dst[m][k] = *(const LAS bf16x8*)(lds + PG8_SA(b, h) + aoff + m * 2048 + k * 1024); } while (0)
; #define PG8_LDB(dst, b, h) do { _Pragma("unroll") for (int n = 0; n < 2; ++n) _Pragma("unroll") for (int k = 0; k < 2; ++k) dst[n][k] = *(const LAS bf16x8*)(lds + PG8_SB(b, h) + boff + n * 2048 + k * 1024); } while (0)
; #define PG8_MMA(ai, bj, At, Bt) do { __builtin_amdgcn_s_setprio(1); _Pragma("unroll") for (int m = 0; m < 4; ++m) _Pragma("unroll") for (int n = 0; n < 2; ++n) _Pragma("unroll") for (int k = 0; k < 2; ++k) \
;         acc[ai][bj][m][n] = __builtin_amdgcn_mfma_f32_16x16x32_bf16(Bt[n][k], At[m][k], acc[ai][bj][m][n], 0, 0, 0); __builtin_amdgcn_s_setprio(0); } while (0)
; #define PG8_BAR __builtin_amdgcn_s_barrier()
; template <class Epi>
; __device__ __forceinline__ void gemm_phase(LAS unsigned char* lds, const Gemm g, const StaticOrder& S, const Epi& E) {
;     ...
;         const bool has_next = S.next(ui + 1, nxt);
;         const char* nA = has_next ? (const char*)g.A + (size_t)nxt.pm * tstepA : cA; const char* nB = has_next ? (const char*)g.Bt + (size_t)nxt.pn * tstepB : cB;
; #pragma nounroll
;         for (int t = 0; t < nt; t += 2) {
;             const bool last = (t == nt - 2);
;             const char* a1 = cA + (size_t)(t + 1) * kstep;
;             const char* a2 = last ? nA : cA + (size_t)(t + 2) * kstep; const char* b2 = last ? nB : cB + (size_t)(t + 2) * kstep;
;             const char* a3 = a2 + kstep; const char* b3 = b2 + kstep;
;             PG8_LDB(B0, 0, 0); PG8_LDB(B1, 0, 1); PG8_SCHED; PG8_LDA(At, 0, 0); PG8_STAGE(PG8_SA(1, 1), a1 + hstepA, voffA);
;             PG8_WAIT_V(8); PG8_WAIT_L(0); PG8_BAR; PG8_MMA(0, 0, At, B0); PG8_MMA(0, 1, At, B1); PG8_BAR; PG8_SCHED;
;             PG8_LDA(At, 0, 1); PG8_STAGE(PG8_SB(0, 0), b2, voffB); PG8_STAGE(PG8_SB(0, 1), b2 + hstepB, voffB); PG8_STAGE(PG8_SA(0, 0), a2, voffA);
;             PG8_WAIT_V(8); PG8_WAIT_L(0); PG8_BAR; PG8_MMA(1, 0, At, B0); PG8_MMA(1, 1, At, B1); PG8_BAR; PG8_SCHED;
.LBB0_888:
	s_ashr_i32 s43, s42, 31
	s_lshl_b64 s[52:53], s[42:43], 19
	s_add_u32 s52, s30, s52
	s_addc_u32 s53, s31, s53
	s_and_b64 s[54:55], s[4:5], exec
	s_cselect_b32 s7, s53, s57
	s_cselect_b32 s9, s52, s56
	s_ashr_i32 s39, s38, 31
	s_lshl_b64 s[54:55], s[38:39], 19
	s_add_u32 s54, s3, s54
	s_addc_u32 s55, s33, s55
	s_and_b64 s[64:65], s[4:5], exec
	s_cselect_b32 s39, s55, s63
	s_cselect_b32 s43, s54, s62
	s_add_u32 s56, s56, 0x40080
	s_addc_u32 s57, s57, 0
	s_add_u32 s83, s62, 0x100
	s_addc_u32 s84, s63, 0
	s_mov_b32 s85, -2
	s_waitcnt lgkmcnt(0)
	s_nop 0
	ds_read_b128 v[40:43], v208
	ds_read_b128 v[44:47], v208 offset:1024
	ds_read_b128 v[56:59], v208 offset:2048
	ds_read_b128 v[60:63], v208 offset:3072
	ds_read_b128 v[144:147], v209
	ds_read_b128 v[148:151], v209 offset:1024
	ds_read_b128 v[152:155], v209 offset:2048
	ds_read_b128 v[156:159], v209 offset:3072
	s_add_u32 s62, s56, 0xfffc0080
	s_addc_u32 s63, s57, -1
	s_cmp_eq_u32 s85, 12
	s_cselect_b32 s65, s7, s63
	s_cselect_b32 s64, s9, s62
	s_cselect_b32 s63, s39, s84
	s_cselect_b32 s62, s43, s83
	s_add_i32 m0, s69, 0xc000
	ds_read_b128 v[160:163], v210
	ds_read_b128 v[164:167], v210 offset:1024
	ds_read_b128 v[186:189], v210 offset:2048
	ds_read_b128 v[190:193], v210 offset:3072
	ds_read_b128 v[194:197], v210 offset:4096
	ds_read_b128 v[198:201], v210 offset:5120
	ds_read_b128 v[202:205], v210 offset:6144
	ds_read_b128 v[214:217], v210 offset:7168
	global_load_lds_dwordx4 v178, s[56:57]
	s_add_i32 m0, s69, 0xe000
	s_nop 0
	global_load_lds_dwordx4 v180, s[56:57]
	s_waitcnt vmcnt(8)
	s_waitcnt lgkmcnt(0)
	s_barrier
	s_waitcnt lgkmcnt(0)
	v_mfma_f32_16x16x32_bf16 v[140:143], v[40:43], v[160:163], 0
	v_mfma_f32_16x16x32_bf16 v[136:139], v[56:59], v[160:163], 0
	v_mfma_f32_16x16x32_bf16 v[124:127], v[40:43], v[186:189], 0
	v_mfma_f32_16x16x32_bf16 v[120:123], v[56:59], v[186:189], 0
	v_mfma_f32_16x16x32_bf16 v[108:111], v[40:43], v[194:197], 0
	v_mfma_f32_16x16x32_bf16 v[104:107], v[56:59], v[194:197], 0
	v_mfma_f32_16x16x32_bf16 v[92:95], v[40:43], v[202:205], 0
	v_mfma_f32_16x16x32_bf16 v[88:91], v[56:59], v[202:205], 0
	v_mfma_f32_16x16x32_bf16 v[140:143], v[44:47], v[164:167], v[140:143]
	v_mfma_f32_16x16x32_bf16 v[136:139], v[60:63], v[164:167], v[136:139]
	v_mfma_f32_16x16x32_bf16 v[124:127], v[44:47], v[190:193], v[124:127]
	v_mfma_f32_16x16x32_bf16 v[120:123], v[60:63], v[190:193], v[120:123]
	v_mfma_f32_16x16x32_bf16 v[108:111], v[44:47], v[198:201], v[108:111]
	v_mfma_f32_16x16x32_bf16 v[104:107], v[60:63], v[198:201], v[104:107]
	v_mfma_f32_16x16x32_bf16 v[92:95], v[44:47], v[214:217], v[92:95]
	v_mfma_f32_16x16x32_bf16 v[88:91], v[60:63], v[214:217], v[88:91]
	v_mfma_f32_16x16x32_bf16 v[132:135], v[144:147], v[160:163], 0
	v_mfma_f32_16x16x32_bf16 v[128:131], v[152:155], v[160:163], 0
	v_mfma_f32_16x16x32_bf16 v[116:119], v[144:147], v[186:189], 0
	v_mfma_f32_16x16x32_bf16 v[112:115], v[152:155], v[186:189], 0
	v_mfma_f32_16x16x32_bf16 v[100:103], v[144:147], v[194:197], 0
	v_mfma_f32_16x16x32_bf16 v[96:99], v[152:155], v[194:197], 0
	v_mfma_f32_16x16x32_bf16 v[84:87], v[144:147], v[202:205], 0
	v_mfma_f32_16x16x32_bf16 v[80:83], v[152:155], v[202:205], 0
	v_mfma_f32_16x16x32_bf16 v[132:135], v[148:151], v[164:167], v[132:135]
	v_mfma_f32_16x16x32_bf16 v[128:131], v[156:159], v[164:167], v[128:131]
	v_mfma_f32_16x16x32_bf16 v[116:119], v[148:151], v[190:193], v[116:119]
	v_mfma_f32_16x16x32_bf16 v[112:115], v[156:159], v[190:193], v[112:115]
	v_mfma_f32_16x16x32_bf16 v[100:103], v[148:151], v[198:201], v[100:103]
	v_mfma_f32_16x16x32_bf16 v[96:99], v[156:159], v[198:201], v[96:99]
	v_mfma_f32_16x16x32_bf16 v[84:87], v[148:151], v[214:217], v[84:87]
	v_mfma_f32_16x16x32_bf16 v[80:83], v[156:159], v[214:217], v[80:83]
	s_barrier
	s_add_i32 s86, s81, s68
	v_lshl_add_u64 v[218:219], s[62:63], 0, v[170:171]
	s_mov_b32 m0, s86
	ds_read_b128 v[160:163], v210 offset:16384
	ds_read_b128 v[164:167], v210 offset:17408
	ds_read_b128 v[186:189], v210 offset:18432
	ds_read_b128 v[190:193], v210 offset:19456
	ds_read_b128 v[194:197], v210 offset:20480
	ds_read_b128 v[198:201], v210 offset:21504
	ds_read_b128 v[202:205], v210 offset:22528
	ds_read_b128 v[214:217], v210 offset:23552
	global_load_lds_dwordx4 v[218:219], off
	s_add_i32 m0, s86, 0x2000
	s_add_u32 s86, s62, 0x40000
	v_lshl_add_u64 v[220:221], s[62:63], 0, v[174:175]
	s_addc_u32 s87, s63, 0
	s_add_i32 s88, s82, s68
	global_load_lds_dwordx4 v[220:221], off
	s_mov_b32 m0, s88
	v_lshl_add_u64 v[226:227], s[64:65], 0, v[172:173]
	global_load_lds_dwordx4 v170, s[86:87]
	s_add_i32 m0, s88, 0x2000
	s_nop 0
	global_load_lds_dwordx4 v174, s[86:87]
	v_lshl_add_u64 v[222:223], s[64:65], 0, v[168:169]
	s_mov_b32 m0, s69
	s_nop 0
	global_load_lds_dwordx4 v[222:223], off
	s_mov_b32 m0, s70
	s_nop 0
	global_load_lds_dwordx4 v[226:227], off
	s_waitcnt vmcnt(8)
	s_waitcnt lgkmcnt(0)
	s_barrier
; #define PG8_STAGE(bufoff, gbase, voff) do { _Pragma("unroll") for (int _i = 0; _i < 2; ++_i) \
;         __builtin_amdgcn_global_load_lds((const unsigned*)((const char*)(gbase) + (voff)[_i]), (LAS unsigned*)(lds + (bufoff) + ldsw + _i * 8192), 16, 0, 0); } while (0)
; #define PG8_LDA(dst, b, h) do { _Pragma("unroll") for (int m = 0; m < 4; ++m) _Pragma("unroll") for (int k = 0; k < 2; ++k) dst[m][k] = *(const LAS bf16x8*)(lds + PG8_SA(b, h) + aoff + m * 2048 + k * 1024); } while (0)
; #define PG8_LDB(dst, b, h) do { _Pragma("unroll") for (int n = 0; n < 2; ++n) _Pragma("unroll") for (int k = 0; k < 2; ++k) dst[n][k] = *(const LAS bf16x8*)(lds + PG8_SB(b, h) + boff + n * 2048 + k * 1024); } while (0)
; #define PG8_MMA(ai, bj, At, Bt) do { __builtin_amdgcn_s_setprio(1); _Pragma("unroll") for (int m = 0; m < 4; ++m) _Pragma("unroll") for (int n = 0; n < 2; ++n) _Pragma("unroll") for (int k = 0; k < 2; ++k) \
;         acc[ai][bj][m][n] = __builtin_amdgcn_mfma_f32_16x16x32_bf16(Bt[n][k], At[m][k], acc[ai][bj][m][n], 0, 0, 0); __builtin_amdgcn_s_setprio(0); } while (0)
; #define PG8_WAIT_V(n) asm volatile("s_waitcnt vmcnt(" #n ")" ::: "memory")
; #define PG8_WAIT_L(n) asm volatile("s_waitcnt lgkmcnt(" #n ")" ::: "memory")
; #define PG8_BAR __builtin_amdgcn_s_barrier()
; #define PG8_SCHED __builtin_amdgcn_sched_barrier(0)
; template <class Epi>
; __device__ __forceinline__ void gemm_phase(LAS unsigned char* lds, const Gemm g, const StaticOrder& S, const Epi& E) {
;     ...
;             PG8_WAIT_V(8); PG8_WAIT_L(0); PG8_BAR; PG8_MMA(1, 0, At, B0); PG8_MMA(1, 1, At, B1); PG8_BAR; PG8_SCHED;
;             PG8_LDB(B0, 1, 0); PG8_LDB(B1, 1, 1); PG8_SCHED; PG8_LDA(At, 1, 0); PG8_STAGE(PG8_SA(0, 1), a2 + hstepA, voffA);
;             PG8_WAIT_V(8); PG8_WAIT_L(0); PG8_BAR; PG8_MMA(0, 0, At, B0); PG8_MMA(0, 1, At, B1); PG8_BAR; PG8_SCHED;
	s_waitcnt lgkmcnt(0)
	v_mfma_f32_16x16x32_bf16 v[76:79], v[40:43], v[160:163], 0
	v_mfma_f32_16x16x32_bf16 v[72:75], v[56:59], v[160:163], 0
	v_mfma_f32_16x16x32_bf16 v[52:55], v[40:43], v[186:189], 0
	v_mfma_f32_16x16x32_bf16 v[48:51], v[56:59], v[186:189], 0
	v_mfma_f32_16x16x32_bf16 v[28:31], v[40:43], v[194:197], 0
	v_mfma_f32_16x16x32_bf16 v[24:27], v[56:59], v[194:197], 0
	v_mfma_f32_16x16x32_bf16 v[12:15], v[40:43], v[202:205], 0
	v_mfma_f32_16x16x32_bf16 v[8:11], v[56:59], v[202:205], 0
	v_mfma_f32_16x16x32_bf16 v[76:79], v[44:47], v[164:167], v[76:79]
	v_mfma_f32_16x16x32_bf16 v[72:75], v[60:63], v[164:167], v[72:75]
	v_mfma_f32_16x16x32_bf16 v[52:55], v[44:47], v[190:193], v[52:55]
	v_mfma_f32_16x16x32_bf16 v[48:51], v[60:63], v[190:193], v[48:51]
	v_mfma_f32_16x16x32_bf16 v[28:31], v[44:47], v[198:201], v[28:31]
	v_mfma_f32_16x16x32_bf16 v[24:27], v[60:63], v[198:201], v[24:27]
	v_mfma_f32_16x16x32_bf16 v[12:15], v[44:47], v[214:217], v[12:15]
	v_mfma_f32_16x16x32_bf16 v[8:11], v[60:63], v[214:217], v[8:11]
	v_mfma_f32_16x16x32_bf16 v[36:39], v[144:147], v[186:189], 0
	v_mfma_f32_16x16x32_bf16 v[32:35], v[152:155], v[186:189], 0
	v_mfma_f32_16x16x32_bf16 v[20:23], v[144:147], v[194:197], 0
	v_mfma_f32_16x16x32_bf16 v[16:19], v[152:155], v[194:197], 0
	v_mfma_f32_16x16x32_bf16 v[4:7], v[144:147], v[202:205], 0
	v_mfma_f32_16x16x32_bf16 v[0:3], v[152:155], v[202:205], 0
	v_mfma_f32_16x16x32_bf16 v[40:43], v[144:147], v[160:163], 0
	v_mfma_f32_16x16x32_bf16 v[44:47], v[152:155], v[160:163], 0
	v_mfma_f32_16x16x32_bf16 v[36:39], v[148:151], v[190:193], v[36:39]
	v_mfma_f32_16x16x32_bf16 v[32:35], v[156:159], v[190:193], v[32:35]
	v_mfma_f32_16x16x32_bf16 v[20:23], v[148:151], v[198:201], v[20:23]
	v_mfma_f32_16x16x32_bf16 v[16:19], v[156:159], v[198:201], v[16:19]
	v_mfma_f32_16x16x32_bf16 v[4:7], v[148:151], v[214:217], v[4:7]
	v_mfma_f32_16x16x32_bf16 v[0:3], v[156:159], v[214:217], v[0:3]
	v_mfma_f32_16x16x32_bf16 v[40:43], v[148:151], v[164:167], v[40:43]
	v_mfma_f32_16x16x32_bf16 v[44:47], v[156:159], v[164:167], v[44:47]
	s_barrier
	s_add_i32 s86, 0, 0x18000
	s_add_i32 s87, 0, 0x1c000
	v_add_u32_e32 v68, s86, v207
	v_add_u32_e32 v156, s87, v207
	ds_read_b128 v[56:59], v68
	ds_read_b128 v[60:63], v68 offset:1024
	ds_read_b128 v[64:67], v68 offset:2048
	ds_read_b128 v[68:71], v68 offset:3072
	ds_read_b128 v[144:147], v156
	ds_read_b128 v[148:151], v156 offset:1024
	ds_read_b128 v[152:155], v156 offset:2048
	ds_read_b128 v[156:159], v156 offset:3072
	s_add_u32 s64, s64, 0x40000
	s_addc_u32 s65, s65, 0
	s_mov_b32 m0, s71
	ds_read_b128 v[160:163], v210 offset:32768
	ds_read_b128 v[164:167], v210 offset:33792
	ds_read_b128 v[186:189], v210 offset:34816
	ds_read_b128 v[190:193], v210 offset:35840
	ds_read_b128 v[194:197], v210 offset:36864
	ds_read_b128 v[198:201], v210 offset:37888
	ds_read_b128 v[202:205], v210 offset:38912
	ds_read_b128 v[214:217], v210 offset:39936
	global_load_lds_dwordx4 v168, s[64:65]
	s_mov_b32 m0, s72
	s_nop 0
	global_load_lds_dwordx4 v172, s[64:65]
	s_waitcnt vmcnt(8)
	s_waitcnt lgkmcnt(0)
	s_barrier
	s_waitcnt lgkmcnt(0)
	v_mfma_f32_16x16x32_bf16 v[140:143], v[56:59], v[160:163], v[140:143]
	v_mfma_f32_16x16x32_bf16 v[136:139], v[64:67], v[160:163], v[136:139]
	v_mfma_f32_16x16x32_bf16 v[124:127], v[56:59], v[186:189], v[124:127]
	v_mfma_f32_16x16x32_bf16 v[120:123], v[64:67], v[186:189], v[120:123]
	v_mfma_f32_16x16x32_bf16 v[108:111], v[56:59], v[194:197], v[108:111]
	v_mfma_f32_16x16x32_bf16 v[104:107], v[64:67], v[194:197], v[104:107]
	v_mfma_f32_16x16x32_bf16 v[92:95], v[56:59], v[202:205], v[92:95]
	v_mfma_f32_16x16x32_bf16 v[88:91], v[64:67], v[202:205], v[88:91]
	v_mfma_f32_16x16x32_bf16 v[140:143], v[60:63], v[164:167], v[140:143]
	v_mfma_f32_16x16x32_bf16 v[136:139], v[68:71], v[164:167], v[136:139]
	v_mfma_f32_16x16x32_bf16 v[124:127], v[60:63], v[190:193], v[124:127]
	v_mfma_f32_16x16x32_bf16 v[120:123], v[68:71], v[190:193], v[120:123]
	v_mfma_f32_16x16x32_bf16 v[108:111], v[60:63], v[198:201], v[108:111]
	v_mfma_f32_16x16x32_bf16 v[104:107], v[68:71], v[198:201], v[104:107]
	v_mfma_f32_16x16x32_bf16 v[92:95], v[60:63], v[214:217], v[92:95]
	v_mfma_f32_16x16x32_bf16 v[88:91], v[68:71], v[214:217], v[88:91]
	v_mfma_f32_16x16x32_bf16 v[132:135], v[144:147], v[160:163], v[132:135]
	v_mfma_f32_16x16x32_bf16 v[128:131], v[152:155], v[160:163], v[128:131]
	v_mfma_f32_16x16x32_bf16 v[116:119], v[144:147], v[186:189], v[116:119]
	v_mfma_f32_16x16x32_bf16 v[112:115], v[152:155], v[186:189], v[112:115]
	v_mfma_f32_16x16x32_bf16 v[100:103], v[144:147], v[194:197], v[100:103]
	v_mfma_f32_16x16x32_bf16 v[96:99], v[152:155], v[194:197], v[96:99]
	v_mfma_f32_16x16x32_bf16 v[84:87], v[144:147], v[202:205], v[84:87]
	v_mfma_f32_16x16x32_bf16 v[80:83], v[152:155], v[202:205], v[80:83]
	v_mfma_f32_16x16x32_bf16 v[132:135], v[148:151], v[164:167], v[132:135]
	v_mfma_f32_16x16x32_bf16 v[128:131], v[156:159], v[164:167], v[128:131]
	v_mfma_f32_16x16x32_bf16 v[116:119], v[148:151], v[190:193], v[116:119]
	v_mfma_f32_16x16x32_bf16 v[112:115], v[156:159], v[190:193], v[112:115]
	v_mfma_f32_16x16x32_bf16 v[100:103], v[148:151], v[198:201], v[100:103]
	v_mfma_f32_16x16x32_bf16 v[96:99], v[156:159], v[198:201], v[96:99]
	v_mfma_f32_16x16x32_bf16 v[84:87], v[148:151], v[214:217], v[84:87]
	v_mfma_f32_16x16x32_bf16 v[80:83], v[156:159], v[214:217], v[80:83]
	s_barrier
; #define PG8_STAGE(bufoff, gbase, voff) do { _Pragma("unroll") for (int _i = 0; _i < 2; ++_i) \
;         __builtin_amdgcn_global_load_lds((const unsigned*)((const char*)(gbase) + (voff)[_i]), (LAS unsigned*)(lds + (bufoff) + ldsw + _i * 8192), 16, 0, 0); } while (0)
; #define PG8_LDA(dst, b, h) do { _Pragma("unroll") for (int m = 0; m < 4; ++m) _Pragma("unroll") for (int k = 0; k < 2; ++k) dst[m][k] = *(const LAS bf16x8*)(lds + PG8_SA(b, h) + aoff + m * 2048 + k * 1024); } while (0)
; #define PG8_LDB(dst, b, h) do { _Pragma("unroll") for (int n = 0; n < 2; ++n) _Pragma("unroll") for (int k = 0; k < 2; ++k) dst[n][k] = *(const LAS bf16x8*)(lds + PG8_SB(b, h) + boff + n * 2048 + k * 1024); } while (0)
; #define PG8_WAIT_V(n) asm volatile("s_waitcnt vmcnt(" #n ")" ::: "memory")
; #define PG8_WAIT_L(n) asm volatile("s_waitcnt lgkmcnt(" #n ")" ::: "memory")
; template <class Epi>
; __device__ __forceinline__ void gemm_phase(LAS unsigned char* lds, const Gemm g, const StaticOrder& S, const Epi& E) {
;     ...
;         for (int t = 0; t < nt; t += 2) {
;             const bool last = (t == nt - 2);
;             const char* a1 = cA + (size_t)(t + 1) * kstep;
;             const char* a2 = last ? nA : cA + (size_t)(t + 2) * kstep; const char* b2 = last ? nB : cB + (size_t)(t + 2) * kstep;
;             const char* a3 = a2 + kstep; const char* b3 = b2 + kstep;
;             PG8_LDB(B0, 0, 0); PG8_LDB(B1, 0, 1); PG8_SCHED; PG8_LDA(At, 0, 0); PG8_STAGE(PG8_SA(1, 1), a1 + hstepA, voffA);
;             PG8_WAIT_V(8); PG8_WAIT_L(0); PG8_BAR; PG8_MMA(0, 0, At, B0); PG8_MMA(0, 1, At, B1); PG8_BAR; PG8_SCHED;
;             PG8_LDA(At, 0, 1); PG8_STAGE(PG8_SB(0, 0), b2, voffB); PG8_STAGE(PG8_SB(0, 1), b2 + hstepB, voffB); PG8_STAGE(PG8_SA(0, 0), a2, voffA);
;             PG8_WAIT_V(8); PG8_WAIT_L(0); PG8_BAR; PG8_MMA(1, 0, At, B0); PG8_MMA(1, 1, At, B1); PG8_BAR; PG8_SCHED;
;             PG8_LDB(B0, 1, 0); PG8_LDB(B1, 1, 1); PG8_SCHED; PG8_LDA(At, 1, 0); PG8_STAGE(PG8_SA(0, 1), a2 + hstepA, voffA);
;             PG8_WAIT_V(8); PG8_WAIT_L(0); PG8_BAR; PG8_MMA(0, 0, At, B0); PG8_MMA(0, 1, At, B1); PG8_BAR; PG8_SCHED;
;             PG8_LDA(At, 1, 1); PG8_STAGE(PG8_SB(1, 0), b3, voffB); PG8_STAGE(PG8_SB(1, 1), b3 + hstepB, voffB); PG8_STAGE(PG8_SA(1, 0), a3, voffA);
;             PG8_WAIT_V(8); PG8_WAIT_L(0); PG8_BAR; PG8_MMA(1, 0, At, B0); PG8_MMA(1, 1, At, B1); PG8_BAR; PG8_SCHED;
	s_add_i32 s64, s86, s68
	v_lshl_add_u64 v[218:219], v[218:219], 0, s[18:19]
	s_mov_b32 m0, s64
	ds_read_b128 v[160:163], v210 offset:49152
	ds_read_b128 v[164:167], v210 offset:50176
	ds_read_b128 v[186:189], v210 offset:51200
	ds_read_b128 v[190:193], v210 offset:52224
	ds_read_b128 v[194:197], v210 offset:53248
	ds_read_b128 v[198:201], v210 offset:54272
	ds_read_b128 v[202:205], v210 offset:55296
	ds_read_b128 v[214:217], v210 offset:56320
	global_load_lds_dwordx4 v[218:219], off
	s_add_i32 m0, s64, 0x2000
	s_add_u32 s62, s62, 0x40080
	v_lshl_add_u64 v[218:219], v[220:221], 0, s[18:19]
	s_addc_u32 s63, s63, 0
	s_add_i32 s64, s87, s68
	global_load_lds_dwordx4 v[218:219], off
	s_mov_b32 m0, s64
	s_nop 0
	global_load_lds_dwordx4 v170, s[62:63]
	s_add_i32 m0, s64, 0x2000
	s_nop 0
	global_load_lds_dwordx4 v174, s[62:63]
	v_lshl_add_u64 v[218:219], v[222:223], 0, s[18:19]
	s_mov_b32 m0, s76
	s_nop 0
	global_load_lds_dwordx4 v[218:219], off
	v_lshl_add_u64 v[218:219], v[226:227], 0, s[18:19]
	s_mov_b32 m0, s77
	s_nop 0
	global_load_lds_dwordx4 v[218:219], off
	s_waitcnt vmcnt(8)
	s_waitcnt lgkmcnt(0)
	s_barrier
	s_waitcnt lgkmcnt(0)
	v_mfma_f32_16x16x32_bf16 v[76:79], v[56:59], v[160:163], v[76:79]
	v_mfma_f32_16x16x32_bf16 v[72:75], v[64:67], v[160:163], v[72:75]
	v_mfma_f32_16x16x32_bf16 v[52:55], v[56:59], v[186:189], v[52:55]
	v_mfma_f32_16x16x32_bf16 v[48:51], v[64:67], v[186:189], v[48:51]
	v_mfma_f32_16x16x32_bf16 v[28:31], v[56:59], v[194:197], v[28:31]
	v_mfma_f32_16x16x32_bf16 v[24:27], v[64:67], v[194:197], v[24:27]
	v_mfma_f32_16x16x32_bf16 v[12:15], v[56:59], v[202:205], v[12:15]
	v_mfma_f32_16x16x32_bf16 v[8:11], v[64:67], v[202:205], v[8:11]
	v_mfma_f32_16x16x32_bf16 v[76:79], v[60:63], v[164:167], v[76:79]
	v_mfma_f32_16x16x32_bf16 v[72:75], v[68:71], v[164:167], v[72:75]
	v_mfma_f32_16x16x32_bf16 v[52:55], v[60:63], v[190:193], v[52:55]
	v_mfma_f32_16x16x32_bf16 v[48:51], v[68:71], v[190:193], v[48:51]
	v_mfma_f32_16x16x32_bf16 v[28:31], v[60:63], v[198:201], v[28:31]
	v_mfma_f32_16x16x32_bf16 v[24:27], v[68:71], v[198:201], v[24:27]
	v_mfma_f32_16x16x32_bf16 v[12:15], v[60:63], v[214:217], v[12:15]
	v_mfma_f32_16x16x32_bf16 v[8:11], v[68:71], v[214:217], v[8:11]
	v_mfma_f32_16x16x32_bf16 v[40:43], v[144:147], v[160:163], v[40:43]
	v_mfma_f32_16x16x32_bf16 v[68:71], v[148:151], v[164:167], v[40:43]
	v_mfma_f32_16x16x32_bf16 v[40:43], v[152:155], v[160:163], v[44:47]
	v_mfma_f32_16x16x32_bf16 v[36:39], v[144:147], v[186:189], v[36:39]
	v_mfma_f32_16x16x32_bf16 v[32:35], v[152:155], v[186:189], v[32:35]
	v_mfma_f32_16x16x32_bf16 v[20:23], v[144:147], v[194:197], v[20:23]
	v_mfma_f32_16x16x32_bf16 v[16:19], v[152:155], v[194:197], v[16:19]
	v_mfma_f32_16x16x32_bf16 v[4:7], v[144:147], v[202:205], v[4:7]
	v_mfma_f32_16x16x32_bf16 v[0:3], v[152:155], v[202:205], v[0:3]
	v_mfma_f32_16x16x32_bf16 v[64:67], v[156:159], v[164:167], v[40:43]
	v_mfma_f32_16x16x32_bf16 v[36:39], v[148:151], v[190:193], v[36:39]
	v_mfma_f32_16x16x32_bf16 v[32:35], v[156:159], v[190:193], v[32:35]
	v_mfma_f32_16x16x32_bf16 v[20:23], v[148:151], v[198:201], v[20:23]
	v_mfma_f32_16x16x32_bf16 v[16:19], v[156:159], v[198:201], v[16:19]
	v_mfma_f32_16x16x32_bf16 v[4:7], v[148:151], v[214:217], v[4:7]
	v_mfma_f32_16x16x32_bf16 v[0:3], v[156:159], v[214:217], v[0:3]
	s_barrier
	s_add_i32 s85, s85, 2
	s_add_u32 s56, s56, 0x100
	s_addc_u32 s57, s57, 0
	s_add_u32 s83, s83, 0x100
	s_addc_u32 s84, s84, 0
	s_cmp_gt_u32 s85, 13
.LBB0_889:
	ds_read_b128 v[40:43], v208
	ds_read_b128 v[44:47], v208 offset:1024
	ds_read_b128 v[56:59], v208 offset:2048
	ds_read_b128 v[60:63], v208 offset:3072
	ds_read_b128 v[144:147], v209
	ds_read_b128 v[148:151], v209 offset:1024
	ds_read_b128 v[152:155], v209 offset:2048
	ds_read_b128 v[156:159], v209 offset:3072
	s_add_u32 s62, s56, 0xfffc0080
	s_addc_u32 s63, s57, -1
	s_cmp_eq_u32 s85, 12
	s_cselect_b32 s65, s7, s63
	s_cselect_b32 s64, s9, s62
	s_cselect_b32 s63, s39, s84
	s_cselect_b32 s62, s43, s83
	s_add_i32 m0, s69, 0xc000
	ds_read_b128 v[160:163], v210
	ds_read_b128 v[164:167], v210 offset:1024
	ds_read_b128 v[186:189], v210 offset:2048
	ds_read_b128 v[190:193], v210 offset:3072
	ds_read_b128 v[194:197], v210 offset:4096
	ds_read_b128 v[198:201], v210 offset:5120
	ds_read_b128 v[202:205], v210 offset:6144
	ds_read_b128 v[214:217], v210 offset:7168
	global_load_lds_dwordx4 v178, s[56:57]
	s_add_i32 m0, s69, 0xe000
	s_nop 0
	global_load_lds_dwordx4 v180, s[56:57]
	s_waitcnt vmcnt(8)
	s_waitcnt lgkmcnt(0)
	s_barrier
; #define PG8_STAGE(bufoff, gbase, voff) do { _Pragma("unroll") for (int _i = 0; _i < 2; ++_i) \
;         __builtin_amdgcn_global_load_lds((const unsigned*)((const char*)(gbase) + (voff)[_i]), (LAS unsigned*)(lds + (bufoff) + ldsw + _i * 8192), 16, 0, 0); } while (0)
; #define PG8_LDA(dst, b, h) do { _Pragma("unroll") for (int m = 0; m < 4; ++m) _Pragma("unroll") for (int k = 0; k < 2; ++k) dst[m][k] = *(const LAS bf16x8*)(lds + PG8_SA(b, h) + aoff + m * 2048 + k * 1024); } while (0)
; #define PG8_MMA(ai, bj, At, Bt) do { __builtin_amdgcn_s_setprio(1); _Pragma("unroll") for (int m = 0; m < 4; ++m) _Pragma("unroll") for (int n = 0; n < 2; ++n) _Pragma("unroll") for (int k = 0; k < 2; ++k) \
;         acc[ai][bj][m][n] = __builtin_amdgcn_mfma_f32_16x16x32_bf16(Bt[n][k], At[m][k], acc[ai][bj][m][n], 0, 0, 0); __builtin_amdgcn_s_setprio(0); } while (0)
; #define PG8_WAIT_V(n) asm volatile("s_waitcnt vmcnt(" #n ")" ::: "memory")
; #define PG8_WAIT_L(n) asm volatile("s_waitcnt lgkmcnt(" #n ")" ::: "memory")
; #define PG8_BAR __builtin_amdgcn_s_barrier()
; #define PG8_SCHED __builtin_amdgcn_sched_barrier(0)
; template <class Epi>
; __device__ __forceinline__ void gemm_phase(LAS unsigned char* lds, const Gemm g, const StaticOrder& S, const Epi& E) {
;     ...
;             PG8_WAIT_V(8); PG8_WAIT_L(0); PG8_BAR; PG8_MMA(0, 0, At, B0); PG8_MMA(0, 1, At, B1); PG8_BAR; PG8_SCHED;
;             PG8_LDA(At, 0, 1); PG8_STAGE(PG8_SB(0, 0), b2, voffB); PG8_STAGE(PG8_SB(0, 1), b2 + hstepB, voffB); PG8_STAGE(PG8_SA(0, 0), a2, voffA);
;             PG8_WAIT_V(8); PG8_WAIT_L(0); PG8_BAR; PG8_MMA(1, 0, At, B0); PG8_MMA(1, 1, At, B1); PG8_BAR; PG8_SCHED;
	s_waitcnt lgkmcnt(0)
	v_mfma_f32_16x16x32_bf16 v[140:143], v[40:43], v[160:163], v[140:143]
	v_mfma_f32_16x16x32_bf16 v[136:139], v[56:59], v[160:163], v[136:139]
	v_mfma_f32_16x16x32_bf16 v[124:127], v[40:43], v[186:189], v[124:127]
	v_mfma_f32_16x16x32_bf16 v[120:123], v[56:59], v[186:189], v[120:123]
	v_mfma_f32_16x16x32_bf16 v[108:111], v[40:43], v[194:197], v[108:111]
	v_mfma_f32_16x16x32_bf16 v[104:107], v[56:59], v[194:197], v[104:107]
	v_mfma_f32_16x16x32_bf16 v[92:95], v[40:43], v[202:205], v[92:95]
	v_mfma_f32_16x16x32_bf16 v[88:91], v[56:59], v[202:205], v[88:91]
	v_mfma_f32_16x16x32_bf16 v[140:143], v[44:47], v[164:167], v[140:143]
	v_mfma_f32_16x16x32_bf16 v[136:139], v[60:63], v[164:167], v[136:139]
	v_mfma_f32_16x16x32_bf16 v[124:127], v[44:47], v[190:193], v[124:127]
	v_mfma_f32_16x16x32_bf16 v[120:123], v[60:63], v[190:193], v[120:123]
	v_mfma_f32_16x16x32_bf16 v[108:111], v[44:47], v[198:201], v[108:111]
	v_mfma_f32_16x16x32_bf16 v[104:107], v[60:63], v[198:201], v[104:107]
	v_mfma_f32_16x16x32_bf16 v[92:95], v[44:47], v[214:217], v[92:95]
	v_mfma_f32_16x16x32_bf16 v[88:91], v[60:63], v[214:217], v[88:91]
	v_mfma_f32_16x16x32_bf16 v[132:135], v[144:147], v[160:163], v[132:135]
	v_mfma_f32_16x16x32_bf16 v[128:131], v[152:155], v[160:163], v[128:131]
	v_mfma_f32_16x16x32_bf16 v[116:119], v[144:147], v[186:189], v[116:119]
	v_mfma_f32_16x16x32_bf16 v[112:115], v[152:155], v[186:189], v[112:115]
	v_mfma_f32_16x16x32_bf16 v[100:103], v[144:147], v[194:197], v[100:103]
	v_mfma_f32_16x16x32_bf16 v[96:99], v[152:155], v[194:197], v[96:99]
	v_mfma_f32_16x16x32_bf16 v[84:87], v[144:147], v[202:205], v[84:87]
	v_mfma_f32_16x16x32_bf16 v[80:83], v[152:155], v[202:205], v[80:83]
	v_mfma_f32_16x16x32_bf16 v[132:135], v[148:151], v[164:167], v[132:135]
	v_mfma_f32_16x16x32_bf16 v[128:131], v[156:159], v[164:167], v[128:131]
	v_mfma_f32_16x16x32_bf16 v[116:119], v[148:151], v[190:193], v[116:119]
	v_mfma_f32_16x16x32_bf16 v[112:115], v[156:159], v[190:193], v[112:115]
	v_mfma_f32_16x16x32_bf16 v[100:103], v[148:151], v[198:201], v[100:103]
	v_mfma_f32_16x16x32_bf16 v[96:99], v[156:159], v[198:201], v[96:99]
	v_mfma_f32_16x16x32_bf16 v[84:87], v[148:151], v[214:217], v[84:87]
	v_mfma_f32_16x16x32_bf16 v[80:83], v[156:159], v[214:217], v[80:83]
	s_barrier
	s_add_i32 s86, s81, s68
	v_lshl_add_u64 v[218:219], s[62:63], 0, v[170:171]
	s_mov_b32 m0, s86
	ds_read_b128 v[160:163], v210 offset:16384
	ds_read_b128 v[164:167], v210 offset:17408
	ds_read_b128 v[186:189], v210 offset:18432
	ds_read_b128 v[190:193], v210 offset:19456
	ds_read_b128 v[194:197], v210 offset:20480
	ds_read_b128 v[198:201], v210 offset:21504
	ds_read_b128 v[202:205], v210 offset:22528
	ds_read_b128 v[214:217], v210 offset:23552
	global_load_lds_dwordx4 v[218:219], off
	s_add_i32 m0, s86, 0x2000
	s_add_u32 s86, s62, 0x40000
	v_lshl_add_u64 v[220:221], s[62:63], 0, v[174:175]
	s_addc_u32 s87, s63, 0
	s_add_i32 s88, s82, s68
	global_load_lds_dwordx4 v[220:221], off
	s_mov_b32 m0, s88
	v_lshl_add_u64 v[226:227], s[64:65], 0, v[172:173]
	global_load_lds_dwordx4 v170, s[86:87]
	s_add_i32 m0, s88, 0x2000
	s_nop 0
	global_load_lds_dwordx4 v174, s[86:87]
	v_lshl_add_u64 v[222:223], s[64:65], 0, v[168:169]
	s_mov_b32 m0, s69
	s_nop 0
	global_load_lds_dwordx4 v[222:223], off
	s_mov_b32 m0, s70
	s_nop 0
	global_load_lds_dwordx4 v[226:227], off
	s_waitcnt vmcnt(8)
	s_waitcnt lgkmcnt(0)
	s_barrier
	s_waitcnt lgkmcnt(0)
	v_mfma_f32_16x16x32_bf16 v[76:79], v[40:43], v[160:163], v[76:79]
	v_mfma_f32_16x16x32_bf16 v[72:75], v[56:59], v[160:163], v[72:75]
	v_mfma_f32_16x16x32_bf16 v[52:55], v[40:43], v[186:189], v[52:55]
	v_mfma_f32_16x16x32_bf16 v[48:51], v[56:59], v[186:189], v[48:51]
	v_mfma_f32_16x16x32_bf16 v[28:31], v[40:43], v[194:197], v[28:31]
	v_mfma_f32_16x16x32_bf16 v[24:27], v[56:59], v[194:197], v[24:27]
	v_mfma_f32_16x16x32_bf16 v[12:15], v[40:43], v[202:205], v[12:15]
	v_mfma_f32_16x16x32_bf16 v[8:11], v[56:59], v[202:205], v[8:11]
	v_mfma_f32_16x16x32_bf16 v[76:79], v[44:47], v[164:167], v[76:79]
	v_mfma_f32_16x16x32_bf16 v[72:75], v[60:63], v[164:167], v[72:75]
	v_mfma_f32_16x16x32_bf16 v[52:55], v[44:47], v[190:193], v[52:55]
	v_mfma_f32_16x16x32_bf16 v[48:51], v[60:63], v[190:193], v[48:51]
	v_mfma_f32_16x16x32_bf16 v[28:31], v[44:47], v[198:201], v[28:31]
	v_mfma_f32_16x16x32_bf16 v[24:27], v[60:63], v[198:201], v[24:27]
	v_mfma_f32_16x16x32_bf16 v[12:15], v[44:47], v[214:217], v[12:15]
	v_mfma_f32_16x16x32_bf16 v[8:11], v[60:63], v[214:217], v[8:11]
	v_mfma_f32_16x16x32_bf16 v[36:39], v[144:147], v[186:189], v[36:39]
	v_mfma_f32_16x16x32_bf16 v[32:35], v[152:155], v[186:189], v[32:35]
	v_mfma_f32_16x16x32_bf16 v[20:23], v[144:147], v[194:197], v[20:23]
	v_mfma_f32_16x16x32_bf16 v[16:19], v[152:155], v[194:197], v[16:19]
	v_mfma_f32_16x16x32_bf16 v[4:7], v[144:147], v[202:205], v[4:7]
	v_mfma_f32_16x16x32_bf16 v[0:3], v[152:155], v[202:205], v[0:3]
	v_mfma_f32_16x16x32_bf16 v[40:43], v[144:147], v[160:163], v[68:71]
	v_mfma_f32_16x16x32_bf16 v[44:47], v[152:155], v[160:163], v[64:67]
	v_mfma_f32_16x16x32_bf16 v[36:39], v[148:151], v[190:193], v[36:39]
	v_mfma_f32_16x16x32_bf16 v[32:35], v[156:159], v[190:193], v[32:35]
	v_mfma_f32_16x16x32_bf16 v[20:23], v[148:151], v[198:201], v[20:23]
	v_mfma_f32_16x16x32_bf16 v[16:19], v[156:159], v[198:201], v[16:19]
	v_mfma_f32_16x16x32_bf16 v[4:7], v[148:151], v[214:217], v[4:7]
	v_mfma_f32_16x16x32_bf16 v[0:3], v[156:159], v[214:217], v[0:3]
	v_mfma_f32_16x16x32_bf16 v[40:43], v[148:151], v[164:167], v[40:43]
	v_mfma_f32_16x16x32_bf16 v[44:47], v[156:159], v[164:167], v[44:47]
	s_barrier
; #define PG8_STAGE(bufoff, gbase, voff) do { _Pragma("unroll") for (int _i = 0; _i < 2; ++_i) \
;         __builtin_amdgcn_global_load_lds((const unsigned*)((const char*)(gbase) + (voff)[_i]), (LAS unsigned*)(lds + (bufoff) + ldsw + _i * 8192), 16, 0, 0); } while (0)
; #define PG8_LDA(dst, b, h) do { _Pragma("unroll") for (int m = 0; m < 4; ++m) _Pragma("unroll") for (int k = 0; k < 2; ++k) dst[m][k] = *(const LAS bf16x8*)(lds + PG8_SA(b, h) + aoff + m * 2048 + k * 1024); } while (0)
; #define PG8_LDB(dst, b, h) do { _Pragma("unroll") for (int n = 0; n < 2; ++n) _Pragma("unroll") for (int k = 0; k < 2; ++k) dst[n][k] = *(const LAS bf16x8*)(lds + PG8_SB(b, h) + boff + n * 2048 + k * 1024); } while (0)
; #define PG8_MMA(ai, bj, At, Bt) do { __builtin_amdgcn_s_setprio(1); _Pragma("unroll") for (int m = 0; m < 4; ++m) _Pragma("unroll") for (int n = 0; n < 2; ++n) _Pragma("unroll") for (int k = 0; k < 2; ++k) \
;         acc[ai][bj][m][n] = __builtin_amdgcn_mfma_f32_16x16x32_bf16(Bt[n][k], At[m][k], acc[ai][bj][m][n], 0, 0, 0); __builtin_amdgcn_s_setprio(0); } while (0)
; #define PG8_WAIT_V(n) asm volatile("s_waitcnt vmcnt(" #n ")" ::: "memory")
; #define PG8_WAIT_L(n) asm volatile("s_waitcnt lgkmcnt(" #n ")" ::: "memory")
; #define PG8_BAR __builtin_amdgcn_s_barrier()
; #define PG8_SCHED __builtin_amdgcn_sched_barrier(0)
; template <class Epi>
; __device__ __forceinline__ void gemm_phase(LAS unsigned char* lds, const Gemm g, const StaticOrder& S, const Epi& E) {
;     ...
;             PG8_LDB(B0, 1, 0); PG8_LDB(B1, 1, 1); PG8_SCHED; PG8_LDA(At, 1, 0); PG8_STAGE(PG8_SA(0, 1), a2 + hstepA, voffA);
;             PG8_WAIT_V(8); PG8_WAIT_L(0); PG8_BAR; PG8_MMA(0, 0, At, B0); PG8_MMA(0, 1, At, B1); PG8_BAR; PG8_SCHED;
;             PG8_LDA(At, 1, 1); PG8_STAGE(PG8_SB(1, 0), b3, voffB); PG8_STAGE(PG8_SB(1, 1), b3 + hstepB, voffB); PG8_STAGE(PG8_SA(1, 0), a3, voffA);
;             PG8_WAIT_V(8); PG8_WAIT_L(0); PG8_BAR; PG8_MMA(1, 0, At, B0); PG8_MMA(1, 1, At, B1); PG8_BAR; PG8_SCHED;
;         }
	s_add_i32 s86, 0, 0x18000
	s_add_i32 s87, 0, 0x1c000
	v_add_u32_e32 v68, s86, v207
	v_add_u32_e32 v156, s87, v207
	ds_read_b128 v[56:59], v68
	ds_read_b128 v[60:63], v68 offset:1024
	ds_read_b128 v[64:67], v68 offset:2048
	ds_read_b128 v[68:71], v68 offset:3072
	ds_read_b128 v[144:147], v156
	ds_read_b128 v[148:151], v156 offset:1024
	ds_read_b128 v[152:155], v156 offset:2048
	ds_read_b128 v[156:159], v156 offset:3072
	s_add_u32 s64, s64, 0x40000
	s_addc_u32 s65, s65, 0
	s_mov_b32 m0, s71
	ds_read_b128 v[160:163], v210 offset:32768
	ds_read_b128 v[164:167], v210 offset:33792
	ds_read_b128 v[186:189], v210 offset:34816
	ds_read_b128 v[190:193], v210 offset:35840
	ds_read_b128 v[194:197], v210 offset:36864
	ds_read_b128 v[198:201], v210 offset:37888
	ds_read_b128 v[202:205], v210 offset:38912
	ds_read_b128 v[214:217], v210 offset:39936
	global_load_lds_dwordx4 v168, s[64:65]
	s_mov_b32 m0, s72
	s_nop 0
	global_load_lds_dwordx4 v172, s[64:65]
	s_waitcnt vmcnt(8)
	s_waitcnt lgkmcnt(0)
	s_barrier
	s_waitcnt lgkmcnt(0)
	v_mfma_f32_16x16x32_bf16 v[140:143], v[56:59], v[160:163], v[140:143]
	v_mfma_f32_16x16x32_bf16 v[136:139], v[64:67], v[160:163], v[136:139]
	v_mfma_f32_16x16x32_bf16 v[124:127], v[56:59], v[186:189], v[124:127]
	v_mfma_f32_16x16x32_bf16 v[120:123], v[64:67], v[186:189], v[120:123]
	v_mfma_f32_16x16x32_bf16 v[108:111], v[56:59], v[194:197], v[108:111]
	v_mfma_f32_16x16x32_bf16 v[104:107], v[64:67], v[194:197], v[104:107]
	v_mfma_f32_16x16x32_bf16 v[92:95], v[56:59], v[202:205], v[92:95]
	v_mfma_f32_16x16x32_bf16 v[88:91], v[64:67], v[202:205], v[88:91]
	v_mfma_f32_16x16x32_bf16 v[140:143], v[60:63], v[164:167], v[140:143]
	v_mfma_f32_16x16x32_bf16 v[136:139], v[68:71], v[164:167], v[136:139]
	v_mfma_f32_16x16x32_bf16 v[124:127], v[60:63], v[190:193], v[124:127]
	v_mfma_f32_16x16x32_bf16 v[120:123], v[68:71], v[190:193], v[120:123]
	v_mfma_f32_16x16x32_bf16 v[108:111], v[60:63], v[198:201], v[108:111]
	v_mfma_f32_16x16x32_bf16 v[104:107], v[68:71], v[198:201], v[104:107]
	v_mfma_f32_16x16x32_bf16 v[92:95], v[60:63], v[214:217], v[92:95]
	v_mfma_f32_16x16x32_bf16 v[88:91], v[68:71], v[214:217], v[88:91]
	v_mfma_f32_16x16x32_bf16 v[132:135], v[144:147], v[160:163], v[132:135]
	v_mfma_f32_16x16x32_bf16 v[128:131], v[152:155], v[160:163], v[128:131]
	v_mfma_f32_16x16x32_bf16 v[116:119], v[144:147], v[186:189], v[116:119]
	v_mfma_f32_16x16x32_bf16 v[112:115], v[152:155], v[186:189], v[112:115]
	v_mfma_f32_16x16x32_bf16 v[100:103], v[144:147], v[194:197], v[100:103]
	v_mfma_f32_16x16x32_bf16 v[96:99], v[152:155], v[194:197], v[96:99]
	v_mfma_f32_16x16x32_bf16 v[84:87], v[144:147], v[202:205], v[84:87]
	v_mfma_f32_16x16x32_bf16 v[80:83], v[152:155], v[202:205], v[80:83]
	v_mfma_f32_16x16x32_bf16 v[132:135], v[148:151], v[164:167], v[132:135]
	v_mfma_f32_16x16x32_bf16 v[128:131], v[156:159], v[164:167], v[128:131]
	v_mfma_f32_16x16x32_bf16 v[116:119], v[148:151], v[190:193], v[116:119]
	v_mfma_f32_16x16x32_bf16 v[112:115], v[156:159], v[190:193], v[112:115]
	v_mfma_f32_16x16x32_bf16 v[100:103], v[148:151], v[198:201], v[100:103]
	v_mfma_f32_16x16x32_bf16 v[96:99], v[156:159], v[198:201], v[96:99]
	v_mfma_f32_16x16x32_bf16 v[84:87], v[148:151], v[214:217], v[84:87]
	v_mfma_f32_16x16x32_bf16 v[80:83], v[156:159], v[214:217], v[80:83]
	s_barrier
	s_add_i32 s64, s86, s68
	v_lshl_add_u64 v[218:219], v[218:219], 0, s[18:19]
	s_mov_b32 m0, s64
	ds_read_b128 v[160:163], v210 offset:49152
	ds_read_b128 v[164:167], v210 offset:50176
	ds_read_b128 v[186:189], v210 offset:51200
	ds_read_b128 v[190:193], v210 offset:52224
	ds_read_b128 v[194:197], v210 offset:53248
	ds_read_b128 v[198:201], v210 offset:54272
	ds_read_b128 v[202:205], v210 offset:55296
	ds_read_b128 v[214:217], v210 offset:56320
	global_load_lds_dwordx4 v[218:219], off
	s_add_i32 m0, s64, 0x2000
	s_add_u32 s62, s62, 0x40080
	v_lshl_add_u64 v[218:219], v[220:221], 0, s[18:19]
	s_addc_u32 s63, s63, 0
	s_add_i32 s64, s87, s68
	global_load_lds_dwordx4 v[218:219], off
	s_mov_b32 m0, s64
	s_nop 0
	global_load_lds_dwordx4 v170, s[62:63]
	s_add_i32 m0, s64, 0x2000
	s_nop 0
	global_load_lds_dwordx4 v174, s[62:63]
	v_lshl_add_u64 v[218:219], v[222:223], 0, s[18:19]
	s_mov_b32 m0, s76
	s_nop 0
	global_load_lds_dwordx4 v[218:219], off
	v_lshl_add_u64 v[218:219], v[226:227], 0, s[18:19]
	s_mov_b32 m0, s77
	s_nop 0
	global_load_lds_dwordx4 v[218:219], off
	s_waitcnt vmcnt(8)
	s_waitcnt lgkmcnt(0)
	s_barrier
	s_waitcnt lgkmcnt(0)
	v_mfma_f32_16x16x32_bf16 v[76:79], v[56:59], v[160:163], v[76:79]
	v_mfma_f32_16x16x32_bf16 v[72:75], v[64:67], v[160:163], v[72:75]
	v_mfma_f32_16x16x32_bf16 v[52:55], v[56:59], v[186:189], v[52:55]
	v_mfma_f32_16x16x32_bf16 v[48:51], v[64:67], v[186:189], v[48:51]
	v_mfma_f32_16x16x32_bf16 v[28:31], v[56:59], v[194:197], v[28:31]
	v_mfma_f32_16x16x32_bf16 v[24:27], v[64:67], v[194:197], v[24:27]
	v_mfma_f32_16x16x32_bf16 v[12:15], v[56:59], v[202:205], v[12:15]
	v_mfma_f32_16x16x32_bf16 v[8:11], v[64:67], v[202:205], v[8:11]
	v_mfma_f32_16x16x32_bf16 v[76:79], v[60:63], v[164:167], v[76:79]
	v_mfma_f32_16x16x32_bf16 v[72:75], v[68:71], v[164:167], v[72:75]
	v_mfma_f32_16x16x32_bf16 v[52:55], v[60:63], v[190:193], v[52:55]
	v_mfma_f32_16x16x32_bf16 v[48:51], v[68:71], v[190:193], v[48:51]
	v_mfma_f32_16x16x32_bf16 v[28:31], v[60:63], v[198:201], v[28:31]
	v_mfma_f32_16x16x32_bf16 v[24:27], v[68:71], v[198:201], v[24:27]
	v_mfma_f32_16x16x32_bf16 v[12:15], v[60:63], v[214:217], v[12:15]
	v_mfma_f32_16x16x32_bf16 v[8:11], v[68:71], v[214:217], v[8:11]
	v_mfma_f32_16x16x32_bf16 v[40:43], v[144:147], v[160:163], v[40:43]
	v_mfma_f32_16x16x32_bf16 v[68:71], v[148:151], v[164:167], v[40:43]
	v_mfma_f32_16x16x32_bf16 v[40:43], v[152:155], v[160:163], v[44:47]
	v_mfma_f32_16x16x32_bf16 v[36:39], v[144:147], v[186:189], v[36:39]
	v_mfma_f32_16x16x32_bf16 v[32:35], v[152:155], v[186:189], v[32:35]
	v_mfma_f32_16x16x32_bf16 v[20:23], v[144:147], v[194:197], v[20:23]
	v_mfma_f32_16x16x32_bf16 v[16:19], v[152:155], v[194:197], v[16:19]
	v_mfma_f32_16x16x32_bf16 v[4:7], v[144:147], v[202:205], v[4:7]
	v_mfma_f32_16x16x32_bf16 v[0:3], v[152:155], v[202:205], v[0:3]
	v_mfma_f32_16x16x32_bf16 v[64:67], v[156:159], v[164:167], v[40:43]
	v_mfma_f32_16x16x32_bf16 v[36:39], v[148:151], v[190:193], v[36:39]
	v_mfma_f32_16x16x32_bf16 v[32:35], v[156:159], v[190:193], v[32:35]
	v_mfma_f32_16x16x32_bf16 v[20:23], v[148:151], v[198:201], v[20:23]
	v_mfma_f32_16x16x32_bf16 v[16:19], v[156:159], v[198:201], v[16:19]
	v_mfma_f32_16x16x32_bf16 v[4:7], v[148:151], v[214:217], v[4:7]
	v_mfma_f32_16x16x32_bf16 v[0:3], v[156:159], v[214:217], v[0:3]
	s_barrier
	s_add_i32 s85, s85, 2
	s_add_u32 s56, s56, 0x100
	s_addc_u32 s57, s57, 0
	s_add_u32 s83, s83, 0x100
	s_addc_u32 s84, s84, 0
	s_cmp_gt_u32 s85, 13
	s_cbranch_scc0 .LBB0_889
	s_and_b64 vcc, exec, s[22:23]
	s_cbranch_vccz .LBB0_892
	s_barrier

; #define PG8_STAGE(bufoff, gbase, voff) do { _Pragma("unroll") for (int _i = 0; _i < 2; ++_i) \
;         __builtin_amdgcn_global_load_lds((const unsigned*)((const char*)(gbase) + (voff)[_i]), (LAS unsigned*)(lds + (bufoff) + ldsw + _i * 8192), 16, 0, 0); } while (0)
; #define PG8_LDA(dst, b, h) do { _Pragma("unroll") for (int m = 0; m < 4; ++m) _Pragma("unroll") for (int k = 0; k < 2; ++k) dst[m][k] = *(const LAS bf16x8*)(lds + PG8_SA(b, h) + aoff + m * 2048 + k * 1024); } while (0)
; #define PG8_LDB(dst, b, h) do { _Pragma("unroll") for (int n = 0; n < 2; ++n) _Pragma("unroll") for (int k = 0; k < 2; ++k) dst[n][k] = *(const LAS bf16x8*)(lds + PG8_SB(b, h) + boff + n * 2048 + k * 1024); } while (0)
; #define PG8_MMA(ai, bj, At, Bt) do { __builtin_amdgcn_s_setprio(1); _Pragma("unroll") for (int m = 0; m < 4; ++m) _Pragma("unroll") for (int n = 0; n < 2; ++n) _Pragma("unroll") for (int k = 0; k < 2; ++k) \
;         acc[ai][bj][m][n] = __builtin_amdgcn_mfma_f32_16x16x32_bf16(Bt[n][k], At[m][k], acc[ai][bj][m][n], 0, 0, 0); __builtin_amdgcn_s_setprio(0); } while (0)
; #define PG8_WAIT_V(n) asm volatile("s_waitcnt vmcnt(" #n ")" ::: "memory")
; #define PG8_WAIT_L(n) asm volatile("s_waitcnt lgkmcnt(" #n ")" ::: "memory")
; template <class Epi>
; __device__ __forceinline__ void gemm_phase(LAS unsigned char* lds, const Gemm g, const StaticOrder& S, const Epi& E) {
;     ...
;     for (;;) {
;         const bool has_next = S.next(ui + 1, nxt);
;         const char* nA = has_next ? (const char*)g.A + (size_t)nxt.pm * tstepA : cA; const char* nB = has_next ? (const char*)g.Bt + (size_t)nxt.pn * tstepB : cB;
; #pragma nounroll
;         for (int t = 0; t < nt; t += 2) {
;             const bool last = (t == nt - 2);
;             const char* a1 = cA + (size_t)(t + 1) * kstep;
;             const char* a2 = last ? nA : cA + (size_t)(t + 2) * kstep; const char* b2 = last ? nB : cB + (size_t)(t + 2) * kstep;
;             const char* a3 = a2 + kstep; const char* b3 = b2 + kstep;
;             PG8_LDB(B0, 0, 0); PG8_LDB(B1, 0, 1); PG8_SCHED; PG8_LDA(At, 0, 0); PG8_STAGE(PG8_SA(1, 1), a1 + hstepA, voffA);
;             PG8_WAIT_V(8); PG8_WAIT_L(0); PG8_BAR; PG8_MMA(0, 0, At, B0); PG8_MMA(0, 1, At, B1); PG8_BAR; PG8_SCHED;
;             PG8_LDA(At, 0, 1); PG8_STAGE(PG8_SB(0, 0), b2, voffB); PG8_STAGE(PG8_SB(0, 1), b2 + hstepB, voffB); PG8_STAGE(PG8_SA(0, 0), a2, voffA);
.LBB0_1017:
	s_ashr_i32 s35, s34, 31
	s_lshl_b64 s[38:39], s[34:35], 19
	s_add_u32 s38, s24, s38
	s_addc_u32 s39, s25, s39
	s_and_b64 s[42:43], s[4:5], exec
	s_cselect_b32 s7, s39, s55
	s_cselect_b32 s35, s38, s54
	s_ashr_i32 s23, s22, 31
	s_lshl_b64 s[42:43], s[22:23], 19
	s_add_u32 s42, s33, s42
	s_addc_u32 s43, s64, s43
	s_and_b64 s[62:63], s[4:5], exec
	s_cselect_b32 s23, s43, s57
	s_cselect_b32 s53, s42, s56
	s_add_u32 s54, s54, 0x40080
	s_addc_u32 s55, s55, 0
	s_add_u32 s83, s56, 0x100
	s_nop 0
	s_addc_u32 s84, s57, 0
	s_mov_b32 s85, -2
	v_lshl_add_u32 v248, s6, 8, v227
	v_add_u32_e32 v248, s74, v248
	v_ashrrev_i32_e32 v249, 31, v248
	v_lshl_add_u64 v[248:249], v[248:249], 2, s[10:11]
	global_load_dword v240, v[248:249], off
	global_load_dword v241, v[248:249], off offset:64
	global_load_dword v242, v[248:249], off offset:128
	global_load_dword v243, v[248:249], off offset:192
	global_load_dword v244, v[248:249], off offset:512
	global_load_dword v245, v[248:249], off offset:576
	global_load_dword v246, v[248:249], off offset:640
	global_load_dword v247, v[248:249], off offset:704
	ds_read_b128 v[0:3], v230
	ds_read_b128 v[4:7], v230 offset:1024
	ds_read_b128 v[8:11], v230 offset:2048
	ds_read_b128 v[12:15], v230 offset:3072
	ds_read_b128 v[144:147], v231
	ds_read_b128 v[148:151], v231 offset:1024
	ds_read_b128 v[152:155], v231 offset:2048
	ds_read_b128 v[156:159], v231 offset:3072
	s_add_u32 s56, s54, 0xfffc0080
	s_addc_u32 s57, s55, -1
	s_cmp_eq_u32 s85, 12
	s_cselect_b32 s63, s7, s57
	s_cselect_b32 s62, s35, s56
	s_cselect_b32 s57, s23, s84
	s_cselect_b32 s56, s53, s83
	s_add_i32 m0, s68, 0xc000
	ds_read_b128 v[160:163], v232
	ds_read_b128 v[164:167], v232 offset:1024
	ds_read_b128 v[168:171], v232 offset:2048
	ds_read_b128 v[172:175], v232 offset:3072
	ds_read_b128 v[196:199], v232 offset:4096
	ds_read_b128 v[200:203], v232 offset:5120
	ds_read_b128 v[204:207], v232 offset:6144
	ds_read_b128 v[208:211], v232 offset:7168
	global_load_lds_dwordx4 v188, s[54:55]
	s_add_i32 m0, s68, 0xe000
	s_nop 0
	global_load_lds_dwordx4 v190, s[54:55]
	s_waitcnt vmcnt(8)
	s_waitcnt lgkmcnt(0)
	s_barrier
	s_waitcnt lgkmcnt(0)
	v_mfma_f32_16x16x32_bf16 v[140:143], v[0:3], v[160:163], 0
	v_mfma_f32_16x16x32_bf16 v[132:135], v[8:11], v[160:163], 0
	v_mfma_f32_16x16x32_bf16 v[124:127], v[0:3], v[168:171], 0
	v_mfma_f32_16x16x32_bf16 v[120:123], v[8:11], v[168:171], 0
	v_mfma_f32_16x16x32_bf16 v[108:111], v[0:3], v[196:199], 0
	v_mfma_f32_16x16x32_bf16 v[104:107], v[8:11], v[196:199], 0
	v_mfma_f32_16x16x32_bf16 v[92:95], v[0:3], v[204:207], 0
	v_mfma_f32_16x16x32_bf16 v[88:91], v[8:11], v[204:207], 0
	v_mfma_f32_16x16x32_bf16 v[140:143], v[4:7], v[164:167], v[140:143]
	v_mfma_f32_16x16x32_bf16 v[132:135], v[12:15], v[164:167], v[132:135]
	v_mfma_f32_16x16x32_bf16 v[124:127], v[4:7], v[172:175], v[124:127]
	v_mfma_f32_16x16x32_bf16 v[120:123], v[12:15], v[172:175], v[120:123]
	v_mfma_f32_16x16x32_bf16 v[108:111], v[4:7], v[200:203], v[108:111]
	v_mfma_f32_16x16x32_bf16 v[104:107], v[12:15], v[200:203], v[104:107]
	v_mfma_f32_16x16x32_bf16 v[92:95], v[4:7], v[208:211], v[92:95]
	v_mfma_f32_16x16x32_bf16 v[88:91], v[12:15], v[208:211], v[88:91]
	v_mfma_f32_16x16x32_bf16 v[136:139], v[144:147], v[160:163], 0
	v_mfma_f32_16x16x32_bf16 v[128:131], v[152:155], v[160:163], 0
	v_mfma_f32_16x16x32_bf16 v[116:119], v[144:147], v[168:171], 0
	v_mfma_f32_16x16x32_bf16 v[112:115], v[152:155], v[168:171], 0
	v_mfma_f32_16x16x32_bf16 v[100:103], v[144:147], v[196:199], 0
	v_mfma_f32_16x16x32_bf16 v[96:99], v[152:155], v[196:199], 0
	v_mfma_f32_16x16x32_bf16 v[84:87], v[144:147], v[204:207], 0
	v_mfma_f32_16x16x32_bf16 v[80:83], v[152:155], v[204:207], 0
	v_mfma_f32_16x16x32_bf16 v[136:139], v[148:151], v[164:167], v[136:139]
	v_mfma_f32_16x16x32_bf16 v[128:131], v[156:159], v[164:167], v[128:131]
	v_mfma_f32_16x16x32_bf16 v[116:119], v[148:151], v[172:175], v[116:119]
	v_mfma_f32_16x16x32_bf16 v[112:115], v[156:159], v[172:175], v[112:115]
	v_mfma_f32_16x16x32_bf16 v[100:103], v[148:151], v[200:203], v[100:103]
	v_mfma_f32_16x16x32_bf16 v[96:99], v[156:159], v[200:203], v[96:99]
	v_mfma_f32_16x16x32_bf16 v[84:87], v[148:151], v[208:211], v[84:87]
	v_mfma_f32_16x16x32_bf16 v[80:83], v[156:159], v[208:211], v[80:83]
	s_barrier
	s_add_i32 s86, s81, s65
	v_lshl_add_u64 v[212:213], s[56:57], 0, v[180:181]
	s_mov_b32 m0, s86
	ds_read_b128 v[160:163], v232 offset:16384
	ds_read_b128 v[164:167], v232 offset:17408
	ds_read_b128 v[168:171], v232 offset:18432
	ds_read_b128 v[172:175], v232 offset:19456
	ds_read_b128 v[196:199], v232 offset:20480
	ds_read_b128 v[200:203], v232 offset:21504
	ds_read_b128 v[204:207], v232 offset:22528
	ds_read_b128 v[208:211], v232 offset:23552
	global_load_lds_dwordx4 v[212:213], off
	s_add_i32 m0, s86, 0x2000
	s_add_u32 s86, s56, 0x40000
	v_lshl_add_u64 v[214:215], s[56:57], 0, v[184:185]
	s_addc_u32 s87, s57, 0
	s_add_i32 s88, s82, s65
	global_load_lds_dwordx4 v[214:215], off
	s_mov_b32 m0, s88
	v_lshl_add_u64 v[218:219], s[62:63], 0, v[182:183]
	global_load_lds_dwordx4 v180, s[86:87]
	s_add_i32 m0, s88, 0x2000
	s_nop 0
	global_load_lds_dwordx4 v184, s[86:87]
	v_lshl_add_u64 v[216:217], s[62:63], 0, v[178:179]
	s_mov_b32 m0, s68
	s_nop 0
	global_load_lds_dwordx4 v[216:217], off
	s_mov_b32 m0, s69
	s_nop 0
	global_load_lds_dwordx4 v[218:219], off
	s_waitcnt vmcnt(8)
	s_waitcnt lgkmcnt(0)
	s_barrier
; #define PG8_STAGE(bufoff, gbase, voff) do { _Pragma("unroll") for (int _i = 0; _i < 2; ++_i) \
;         __builtin_amdgcn_global_load_lds((const unsigned*)((const char*)(gbase) + (voff)[_i]), (LAS unsigned*)(lds + (bufoff) + ldsw + _i * 8192), 16, 0, 0); } while (0)
; #define PG8_LDA(dst, b, h) do { _Pragma("unroll") for (int m = 0; m < 4; ++m) _Pragma("unroll") for (int k = 0; k < 2; ++k) dst[m][k] = *(const LAS bf16x8*)(lds + PG8_SA(b, h) + aoff + m * 2048 + k * 1024); } while (0)
; #define PG8_LDB(dst, b, h) do { _Pragma("unroll") for (int n = 0; n < 2; ++n) _Pragma("unroll") for (int k = 0; k < 2; ++k) dst[n][k] = *(const LAS bf16x8*)(lds + PG8_SB(b, h) + boff + n * 2048 + k * 1024); } while (0)
; #define PG8_MMA(ai, bj, At, Bt) do { __builtin_amdgcn_s_setprio(1); _Pragma("unroll") for (int m = 0; m < 4; ++m) _Pragma("unroll") for (int n = 0; n < 2; ++n) _Pragma("unroll") for (int k = 0; k < 2; ++k) \
;         acc[ai][bj][m][n] = __builtin_amdgcn_mfma_f32_16x16x32_bf16(Bt[n][k], At[m][k], acc[ai][bj][m][n], 0, 0, 0); __builtin_amdgcn_s_setprio(0); } while (0)
; #define PG8_WAIT_V(n) asm volatile("s_waitcnt vmcnt(" #n ")" ::: "memory")
; #define PG8_WAIT_L(n) asm volatile("s_waitcnt lgkmcnt(" #n ")" ::: "memory")
; #define PG8_BAR __builtin_amdgcn_s_barrier()
; #define PG8_SCHED __builtin_amdgcn_sched_barrier(0)
; template <class Epi>
; __device__ __forceinline__ void gemm_phase(LAS unsigned char* lds, const Gemm g, const StaticOrder& S, const Epi& E) {
;     ...
;             PG8_WAIT_V(8); PG8_WAIT_L(0); PG8_BAR; PG8_MMA(1, 0, At, B0); PG8_MMA(1, 1, At, B1); PG8_BAR; PG8_SCHED;
;             PG8_LDB(B0, 1, 0); PG8_LDB(B1, 1, 1); PG8_SCHED; PG8_LDA(At, 1, 0); PG8_STAGE(PG8_SA(0, 1), a2 + hstepA, voffA);
;             PG8_WAIT_V(8); PG8_WAIT_L(0); PG8_BAR; PG8_MMA(0, 0, At, B0); PG8_MMA(0, 1, At, B1); PG8_BAR; PG8_SCHED;
	s_waitcnt lgkmcnt(0)
	v_mfma_f32_16x16x32_bf16 v[76:79], v[0:3], v[160:163], 0
	v_mfma_f32_16x16x32_bf16 v[72:75], v[8:11], v[160:163], 0
	v_mfma_f32_16x16x32_bf16 v[60:63], v[0:3], v[168:171], 0
	v_mfma_f32_16x16x32_bf16 v[56:59], v[8:11], v[168:171], 0
	v_mfma_f32_16x16x32_bf16 v[44:47], v[0:3], v[196:199], 0
	v_mfma_f32_16x16x32_bf16 v[40:43], v[8:11], v[196:199], 0
	v_mfma_f32_16x16x32_bf16 v[0:3], v[0:3], v[204:207], 0
	v_mfma_f32_16x16x32_bf16 v[76:79], v[4:7], v[164:167], v[76:79]
	v_mfma_f32_16x16x32_bf16 v[72:75], v[12:15], v[164:167], v[72:75]
	v_mfma_f32_16x16x32_bf16 v[60:63], v[4:7], v[172:175], v[60:63]
	v_mfma_f32_16x16x32_bf16 v[56:59], v[12:15], v[172:175], v[56:59]
	v_mfma_f32_16x16x32_bf16 v[44:47], v[4:7], v[200:203], v[44:47]
	v_mfma_f32_16x16x32_bf16 v[40:43], v[12:15], v[200:203], v[40:43]
	v_mfma_f32_16x16x32_bf16 v[0:3], v[4:7], v[208:211], v[0:3]
	v_mfma_f32_16x16x32_bf16 v[4:7], v[8:11], v[204:207], 0
	v_mfma_f32_16x16x32_bf16 v[4:7], v[12:15], v[208:211], v[4:7]
	v_mfma_f32_16x16x32_bf16 v[20:23], v[144:147], v[168:171], 0
	v_mfma_f32_16x16x32_bf16 v[52:55], v[148:151], v[172:175], v[20:23]
	v_mfma_f32_16x16x32_bf16 v[20:23], v[152:155], v[168:171], 0
	v_mfma_f32_16x16x32_bf16 v[48:51], v[156:159], v[172:175], v[20:23]
	v_mfma_f32_16x16x32_bf16 v[20:23], v[144:147], v[196:199], 0
	v_mfma_f32_16x16x32_bf16 v[36:39], v[148:151], v[200:203], v[20:23]
	v_mfma_f32_16x16x32_bf16 v[20:23], v[152:155], v[196:199], 0
	v_mfma_f32_16x16x32_bf16 v[32:35], v[156:159], v[200:203], v[20:23]
	v_mfma_f32_16x16x32_bf16 v[20:23], v[144:147], v[204:207], 0
	v_mfma_f32_16x16x32_bf16 v[16:19], v[152:155], v[204:207], 0
	v_mfma_f32_16x16x32_bf16 v[8:11], v[144:147], v[160:163], 0
	v_mfma_f32_16x16x32_bf16 v[12:15], v[152:155], v[160:163], 0
	v_mfma_f32_16x16x32_bf16 v[24:27], v[148:151], v[208:211], v[20:23]
	v_mfma_f32_16x16x32_bf16 v[16:19], v[156:159], v[208:211], v[16:19]
	v_mfma_f32_16x16x32_bf16 v[8:11], v[148:151], v[164:167], v[8:11]
	v_mfma_f32_16x16x32_bf16 v[12:15], v[156:159], v[164:167], v[12:15]
	s_barrier
	s_add_i32 s86, 0, 0x18000
	s_add_i32 s87, 0, 0x1c000
	v_add_u32_e32 v68, s86, v229
	v_add_u32_e32 v156, s87, v229
	ds_read_b128 v[20:23], v68
	ds_read_b128 v[28:31], v68 offset:1024
	ds_read_b128 v[64:67], v68 offset:2048
	ds_read_b128 v[68:71], v68 offset:3072
	ds_read_b128 v[144:147], v156
	ds_read_b128 v[148:151], v156 offset:1024
	ds_read_b128 v[152:155], v156 offset:2048
	ds_read_b128 v[156:159], v156 offset:3072
	s_add_u32 s62, s62, 0x40000
	s_addc_u32 s63, s63, 0
	s_mov_b32 m0, s70
	ds_read_b128 v[160:163], v232 offset:32768
	ds_read_b128 v[164:167], v232 offset:33792
	ds_read_b128 v[168:171], v232 offset:34816
	ds_read_b128 v[172:175], v232 offset:35840
	ds_read_b128 v[196:199], v232 offset:36864
	ds_read_b128 v[200:203], v232 offset:37888
	ds_read_b128 v[204:207], v232 offset:38912
	ds_read_b128 v[208:211], v232 offset:39936
	global_load_lds_dwordx4 v178, s[62:63]
	s_mov_b32 m0, s71
	s_nop 0
	global_load_lds_dwordx4 v182, s[62:63]
	s_waitcnt vmcnt(8)
	s_waitcnt lgkmcnt(0)
	s_barrier
	s_waitcnt lgkmcnt(0)
	v_mfma_f32_16x16x32_bf16 v[140:143], v[20:23], v[160:163], v[140:143]
	v_mfma_f32_16x16x32_bf16 v[132:135], v[64:67], v[160:163], v[132:135]
	v_mfma_f32_16x16x32_bf16 v[124:127], v[20:23], v[168:171], v[124:127]
	v_mfma_f32_16x16x32_bf16 v[120:123], v[64:67], v[168:171], v[120:123]
	v_mfma_f32_16x16x32_bf16 v[108:111], v[20:23], v[196:199], v[108:111]
	v_mfma_f32_16x16x32_bf16 v[104:107], v[64:67], v[196:199], v[104:107]
	v_mfma_f32_16x16x32_bf16 v[92:95], v[20:23], v[204:207], v[92:95]
	v_mfma_f32_16x16x32_bf16 v[88:91], v[64:67], v[204:207], v[88:91]
	v_mfma_f32_16x16x32_bf16 v[140:143], v[28:31], v[164:167], v[140:143]
	v_mfma_f32_16x16x32_bf16 v[132:135], v[68:71], v[164:167], v[132:135]
	v_mfma_f32_16x16x32_bf16 v[124:127], v[28:31], v[172:175], v[124:127]
	v_mfma_f32_16x16x32_bf16 v[120:123], v[68:71], v[172:175], v[120:123]
	v_mfma_f32_16x16x32_bf16 v[108:111], v[28:31], v[200:203], v[108:111]
	v_mfma_f32_16x16x32_bf16 v[104:107], v[68:71], v[200:203], v[104:107]
	v_mfma_f32_16x16x32_bf16 v[92:95], v[28:31], v[208:211], v[92:95]
	v_mfma_f32_16x16x32_bf16 v[88:91], v[68:71], v[208:211], v[88:91]
	v_mfma_f32_16x16x32_bf16 v[136:139], v[144:147], v[160:163], v[136:139]
	v_mfma_f32_16x16x32_bf16 v[128:131], v[152:155], v[160:163], v[128:131]
	v_mfma_f32_16x16x32_bf16 v[116:119], v[144:147], v[168:171], v[116:119]
	v_mfma_f32_16x16x32_bf16 v[112:115], v[152:155], v[168:171], v[112:115]
	v_mfma_f32_16x16x32_bf16 v[100:103], v[144:147], v[196:199], v[100:103]
	v_mfma_f32_16x16x32_bf16 v[96:99], v[152:155], v[196:199], v[96:99]
	v_mfma_f32_16x16x32_bf16 v[84:87], v[144:147], v[204:207], v[84:87]
	v_mfma_f32_16x16x32_bf16 v[80:83], v[152:155], v[204:207], v[80:83]
	v_mfma_f32_16x16x32_bf16 v[136:139], v[148:151], v[164:167], v[136:139]
	v_mfma_f32_16x16x32_bf16 v[128:131], v[156:159], v[164:167], v[128:131]
	v_mfma_f32_16x16x32_bf16 v[116:119], v[148:151], v[172:175], v[116:119]
	v_mfma_f32_16x16x32_bf16 v[112:115], v[156:159], v[172:175], v[112:115]
	v_mfma_f32_16x16x32_bf16 v[100:103], v[148:151], v[200:203], v[100:103]
	v_mfma_f32_16x16x32_bf16 v[96:99], v[156:159], v[200:203], v[96:99]
	v_mfma_f32_16x16x32_bf16 v[84:87], v[148:151], v[208:211], v[84:87]
	v_mfma_f32_16x16x32_bf16 v[80:83], v[156:159], v[208:211], v[80:83]
	s_barrier
; #define PG8_STAGE(bufoff, gbase, voff) do { _Pragma("unroll") for (int _i = 0; _i < 2; ++_i) \
;         __builtin_amdgcn_global_load_lds((const unsigned*)((const char*)(gbase) + (voff)[_i]), (LAS unsigned*)(lds + (bufoff) + ldsw + _i * 8192), 16, 0, 0); } while (0)
; #define PG8_LDA(dst, b, h) do { _Pragma("unroll") for (int m = 0; m < 4; ++m) _Pragma("unroll") for (int k = 0; k < 2; ++k) dst[m][k] = *(const LAS bf16x8*)(lds + PG8_SA(b, h) + aoff + m * 2048 + k * 1024); } while (0)
; #define PG8_LDB(dst, b, h) do { _Pragma("unroll") for (int n = 0; n < 2; ++n) _Pragma("unroll") for (int k = 0; k < 2; ++k) dst[n][k] = *(const LAS bf16x8*)(lds + PG8_SB(b, h) + boff + n * 2048 + k * 1024); } while (0)
; #define PG8_WAIT_V(n) asm volatile("s_waitcnt vmcnt(" #n ")" ::: "memory")
; #define PG8_WAIT_L(n) asm volatile("s_waitcnt lgkmcnt(" #n ")" ::: "memory")
; template <class Epi>
; __device__ __forceinline__ void gemm_phase(LAS unsigned char* lds, const Gemm g, const StaticOrder& S, const Epi& E) {
;     ...
;         for (int t = 0; t < nt; t += 2) {
;             const bool last = (t == nt - 2);
;             const char* a1 = cA + (size_t)(t + 1) * kstep;
;             const char* a2 = last ? nA : cA + (size_t)(t + 2) * kstep; const char* b2 = last ? nB : cB + (size_t)(t + 2) * kstep;
;             const char* a3 = a2 + kstep; const char* b3 = b2 + kstep;
;             PG8_LDB(B0, 0, 0); PG8_LDB(B1, 0, 1); PG8_SCHED; PG8_LDA(At, 0, 0); PG8_STAGE(PG8_SA(1, 1), a1 + hstepA, voffA);
;             PG8_WAIT_V(8); PG8_WAIT_L(0); PG8_BAR; PG8_MMA(0, 0, At, B0); PG8_MMA(0, 1, At, B1); PG8_BAR; PG8_SCHED;
;             PG8_LDA(At, 0, 1); PG8_STAGE(PG8_SB(0, 0), b2, voffB); PG8_STAGE(PG8_SB(0, 1), b2 + hstepB, voffB); PG8_STAGE(PG8_SA(0, 0), a2, voffA);
;             PG8_WAIT_V(8); PG8_WAIT_L(0); PG8_BAR; PG8_MMA(1, 0, At, B0); PG8_MMA(1, 1, At, B1); PG8_BAR; PG8_SCHED;
;             PG8_LDB(B0, 1, 0); PG8_LDB(B1, 1, 1); PG8_SCHED; PG8_LDA(At, 1, 0); PG8_STAGE(PG8_SA(0, 1), a2 + hstepA, voffA);
;             PG8_WAIT_V(8); PG8_WAIT_L(0); PG8_BAR; PG8_MMA(0, 0, At, B0); PG8_MMA(0, 1, At, B1); PG8_BAR; PG8_SCHED;
;             PG8_LDA(At, 1, 1); PG8_STAGE(PG8_SB(1, 0), b3, voffB); PG8_STAGE(PG8_SB(1, 1), b3 + hstepB, voffB); PG8_STAGE(PG8_SA(1, 0), a3, voffA);
;             PG8_WAIT_V(8); PG8_WAIT_L(0); PG8_BAR; PG8_MMA(1, 0, At, B0); PG8_MMA(1, 1, At, B1); PG8_BAR; PG8_SCHED;
	s_add_i32 s62, s86, s65
	v_lshl_add_u64 v[212:213], v[212:213], 0, s[16:17]
	s_mov_b32 m0, s62
	ds_read_b128 v[160:163], v232 offset:49152
	ds_read_b128 v[164:167], v232 offset:50176
	ds_read_b128 v[168:171], v232 offset:51200
	ds_read_b128 v[172:175], v232 offset:52224
	ds_read_b128 v[196:199], v232 offset:53248
	ds_read_b128 v[200:203], v232 offset:54272
	ds_read_b128 v[204:207], v232 offset:55296
	ds_read_b128 v[208:211], v232 offset:56320
	global_load_lds_dwordx4 v[212:213], off
	s_add_i32 m0, s62, 0x2000
	s_add_u32 s56, s56, 0x40080
	v_lshl_add_u64 v[212:213], v[214:215], 0, s[16:17]
	s_addc_u32 s57, s57, 0
	s_add_i32 s62, s87, s65
	global_load_lds_dwordx4 v[212:213], off
	s_mov_b32 m0, s62
	s_nop 0
	global_load_lds_dwordx4 v180, s[56:57]
	s_add_i32 m0, s62, 0x2000
	s_nop 0
	global_load_lds_dwordx4 v184, s[56:57]
	v_lshl_add_u64 v[212:213], v[216:217], 0, s[16:17]
	s_mov_b32 m0, s76
	s_nop 0
	global_load_lds_dwordx4 v[212:213], off
	v_lshl_add_u64 v[212:213], v[218:219], 0, s[16:17]
	s_mov_b32 m0, s77
	s_nop 0
	global_load_lds_dwordx4 v[212:213], off
	s_waitcnt vmcnt(8)
	s_waitcnt lgkmcnt(0)
	s_barrier
	s_waitcnt lgkmcnt(0)
	v_mfma_f32_16x16x32_bf16 v[76:79], v[20:23], v[160:163], v[76:79]
	v_mfma_f32_16x16x32_bf16 v[60:63], v[20:23], v[168:171], v[60:63]
	v_mfma_f32_16x16x32_bf16 v[44:47], v[20:23], v[196:199], v[44:47]
	v_mfma_f32_16x16x32_bf16 v[0:3], v[20:23], v[204:207], v[0:3]
	v_mfma_f32_16x16x32_bf16 v[76:79], v[28:31], v[164:167], v[76:79]
	v_mfma_f32_16x16x32_bf16 v[72:75], v[64:67], v[160:163], v[72:75]
	v_mfma_f32_16x16x32_bf16 v[60:63], v[28:31], v[172:175], v[60:63]
	v_mfma_f32_16x16x32_bf16 v[56:59], v[64:67], v[168:171], v[56:59]
	v_mfma_f32_16x16x32_bf16 v[44:47], v[28:31], v[200:203], v[44:47]
	v_mfma_f32_16x16x32_bf16 v[40:43], v[64:67], v[196:199], v[40:43]
	v_mfma_f32_16x16x32_bf16 v[28:31], v[28:31], v[208:211], v[0:3]
	v_mfma_f32_16x16x32_bf16 v[0:3], v[64:67], v[204:207], v[4:7]
	v_mfma_f32_16x16x32_bf16 v[72:75], v[68:71], v[164:167], v[72:75]
	v_mfma_f32_16x16x32_bf16 v[56:59], v[68:71], v[172:175], v[56:59]
	v_mfma_f32_16x16x32_bf16 v[40:43], v[68:71], v[200:203], v[40:43]
	v_mfma_f32_16x16x32_bf16 v[20:23], v[68:71], v[208:211], v[0:3]
	v_mfma_f32_16x16x32_bf16 v[0:3], v[144:147], v[160:163], v[8:11]
	v_mfma_f32_16x16x32_bf16 v[68:71], v[148:151], v[164:167], v[0:3]
	v_mfma_f32_16x16x32_bf16 v[0:3], v[152:155], v[160:163], v[12:15]
	v_mfma_f32_16x16x32_bf16 v[64:67], v[156:159], v[164:167], v[0:3]
	v_mfma_f32_16x16x32_bf16 v[0:3], v[144:147], v[168:171], v[52:55]
	v_mfma_f32_16x16x32_bf16 v[52:55], v[148:151], v[172:175], v[0:3]
	v_mfma_f32_16x16x32_bf16 v[0:3], v[152:155], v[168:171], v[48:51]
	v_mfma_f32_16x16x32_bf16 v[48:51], v[156:159], v[172:175], v[0:3]
	v_mfma_f32_16x16x32_bf16 v[0:3], v[144:147], v[196:199], v[36:39]
	v_mfma_f32_16x16x32_bf16 v[36:39], v[148:151], v[200:203], v[0:3]
	v_mfma_f32_16x16x32_bf16 v[0:3], v[152:155], v[196:199], v[32:35]
	v_mfma_f32_16x16x32_bf16 v[32:35], v[156:159], v[200:203], v[0:3]
	v_mfma_f32_16x16x32_bf16 v[0:3], v[144:147], v[204:207], v[24:27]
	v_mfma_f32_16x16x32_bf16 v[24:27], v[148:151], v[208:211], v[0:3]
	v_mfma_f32_16x16x32_bf16 v[0:3], v[152:155], v[204:207], v[16:19]
	v_mfma_f32_16x16x32_bf16 v[16:19], v[156:159], v[208:211], v[0:3]
	s_barrier
	s_add_i32 s85, s85, 2
	s_add_u32 s54, s54, 0x100
	s_addc_u32 s55, s55, 0
	s_add_u32 s83, s83, 0x100
	s_addc_u32 s84, s84, 0
	s_cmp_gt_u32 s85, 13
.LBB0_1018:
	ds_read_b128 v[0:3], v230
	ds_read_b128 v[4:7], v230 offset:1024
	ds_read_b128 v[8:11], v230 offset:2048
	ds_read_b128 v[12:15], v230 offset:3072
	ds_read_b128 v[144:147], v231
	ds_read_b128 v[148:151], v231 offset:1024
	ds_read_b128 v[152:155], v231 offset:2048
	ds_read_b128 v[156:159], v231 offset:3072
	s_add_u32 s56, s54, 0xfffc0080
	s_addc_u32 s57, s55, -1
	s_cmp_eq_u32 s85, 12
	s_cselect_b32 s63, s7, s57
	s_cselect_b32 s62, s35, s56
	s_cselect_b32 s57, s23, s84
	s_cselect_b32 s56, s53, s83
	s_add_i32 m0, s68, 0xc000
	ds_read_b128 v[160:163], v232
	ds_read_b128 v[164:167], v232 offset:1024
	ds_read_b128 v[168:171], v232 offset:2048
	ds_read_b128 v[172:175], v232 offset:3072
	ds_read_b128 v[196:199], v232 offset:4096
	ds_read_b128 v[200:203], v232 offset:5120
	ds_read_b128 v[204:207], v232 offset:6144
	ds_read_b128 v[208:211], v232 offset:7168
	global_load_lds_dwordx4 v188, s[54:55]
	s_add_i32 m0, s68, 0xe000
	s_nop 0
	global_load_lds_dwordx4 v190, s[54:55]
	s_waitcnt vmcnt(8)
	s_waitcnt lgkmcnt(0)
	s_barrier
	s_waitcnt lgkmcnt(0)
	v_mfma_f32_16x16x32_bf16 v[140:143], v[0:3], v[160:163], v[140:143]
	v_mfma_f32_16x16x32_bf16 v[132:135], v[8:11], v[160:163], v[132:135]
	v_mfma_f32_16x16x32_bf16 v[124:127], v[0:3], v[168:171], v[124:127]
	v_mfma_f32_16x16x32_bf16 v[120:123], v[8:11], v[168:171], v[120:123]
	v_mfma_f32_16x16x32_bf16 v[108:111], v[0:3], v[196:199], v[108:111]
	v_mfma_f32_16x16x32_bf16 v[104:107], v[8:11], v[196:199], v[104:107]
	v_mfma_f32_16x16x32_bf16 v[92:95], v[0:3], v[204:207], v[92:95]
	v_mfma_f32_16x16x32_bf16 v[88:91], v[8:11], v[204:207], v[88:91]
	v_mfma_f32_16x16x32_bf16 v[140:143], v[4:7], v[164:167], v[140:143]
	v_mfma_f32_16x16x32_bf16 v[132:135], v[12:15], v[164:167], v[132:135]
	v_mfma_f32_16x16x32_bf16 v[124:127], v[4:7], v[172:175], v[124:127]
	v_mfma_f32_16x16x32_bf16 v[120:123], v[12:15], v[172:175], v[120:123]
	v_mfma_f32_16x16x32_bf16 v[108:111], v[4:7], v[200:203], v[108:111]
	v_mfma_f32_16x16x32_bf16 v[104:107], v[12:15], v[200:203], v[104:107]
	v_mfma_f32_16x16x32_bf16 v[92:95], v[4:7], v[208:211], v[92:95]
	v_mfma_f32_16x16x32_bf16 v[88:91], v[12:15], v[208:211], v[88:91]
	v_mfma_f32_16x16x32_bf16 v[136:139], v[144:147], v[160:163], v[136:139]
	v_mfma_f32_16x16x32_bf16 v[128:131], v[152:155], v[160:163], v[128:131]
	v_mfma_f32_16x16x32_bf16 v[116:119], v[144:147], v[168:171], v[116:119]
	v_mfma_f32_16x16x32_bf16 v[112:115], v[152:155], v[168:171], v[112:115]
	v_mfma_f32_16x16x32_bf16 v[100:103], v[144:147], v[196:199], v[100:103]
	v_mfma_f32_16x16x32_bf16 v[96:99], v[152:155], v[196:199], v[96:99]
	v_mfma_f32_16x16x32_bf16 v[84:87], v[144:147], v[204:207], v[84:87]
	v_mfma_f32_16x16x32_bf16 v[80:83], v[152:155], v[204:207], v[80:83]
	v_mfma_f32_16x16x32_bf16 v[136:139], v[148:151], v[164:167], v[136:139]
	v_mfma_f32_16x16x32_bf16 v[128:131], v[156:159], v[164:167], v[128:131]
	v_mfma_f32_16x16x32_bf16 v[116:119], v[148:151], v[172:175], v[116:119]
	v_mfma_f32_16x16x32_bf16 v[112:115], v[156:159], v[172:175], v[112:115]
	v_mfma_f32_16x16x32_bf16 v[100:103], v[148:151], v[200:203], v[100:103]
	v_mfma_f32_16x16x32_bf16 v[96:99], v[156:159], v[200:203], v[96:99]
	v_mfma_f32_16x16x32_bf16 v[84:87], v[148:151], v[208:211], v[84:87]
	v_mfma_f32_16x16x32_bf16 v[80:83], v[156:159], v[208:211], v[80:83]
	s_barrier
; #define PG8_STAGE(bufoff, gbase, voff) do { _Pragma("unroll") for (int _i = 0; _i < 2; ++_i) \
;         __builtin_amdgcn_global_load_lds((const unsigned*)((const char*)(gbase) + (voff)[_i]), (LAS unsigned*)(lds + (bufoff) + ldsw + _i * 8192), 16, 0, 0); } while (0)
; #define PG8_LDA(dst, b, h) do { _Pragma("unroll") for (int m = 0; m < 4; ++m) _Pragma("unroll") for (int k = 0; k < 2; ++k) dst[m][k] = *(const LAS bf16x8*)(lds + PG8_SA(b, h) + aoff + m * 2048 + k * 1024); } while (0)
; #define PG8_LDB(dst, b, h) do { _Pragma("unroll") for (int n = 0; n < 2; ++n) _Pragma("unroll") for (int k = 0; k < 2; ++k) dst[n][k] = *(const LAS bf16x8*)(lds + PG8_SB(b, h) + boff + n * 2048 + k * 1024); } while (0)
; #define PG8_MMA(ai, bj, At, Bt) do { __builtin_amdgcn_s_setprio(1); _Pragma("unroll") for (int m = 0; m < 4; ++m) _Pragma("unroll") for (int n = 0; n < 2; ++n) _Pragma("unroll") for (int k = 0; k < 2; ++k) \
;         acc[ai][bj][m][n] = __builtin_amdgcn_mfma_f32_16x16x32_bf16(Bt[n][k], At[m][k], acc[ai][bj][m][n], 0, 0, 0); __builtin_amdgcn_s_setprio(0); } while (0)
; #define PG8_WAIT_V(n) asm volatile("s_waitcnt vmcnt(" #n ")" ::: "memory")
; #define PG8_WAIT_L(n) asm volatile("s_waitcnt lgkmcnt(" #n ")" ::: "memory")
; #define PG8_BAR __builtin_amdgcn_s_barrier()
; #define PG8_SCHED __builtin_amdgcn_sched_barrier(0)
; template <class Epi>
; __device__ __forceinline__ void gemm_phase(LAS unsigned char* lds, const Gemm g, const StaticOrder& S, const Epi& E) {
;     ...
;             PG8_LDA(At, 0, 1); PG8_STAGE(PG8_SB(0, 0), b2, voffB); PG8_STAGE(PG8_SB(0, 1), b2 + hstepB, voffB); PG8_STAGE(PG8_SA(0, 0), a2, voffA);
;             PG8_WAIT_V(8); PG8_WAIT_L(0); PG8_BAR; PG8_MMA(1, 0, At, B0); PG8_MMA(1, 1, At, B1); PG8_BAR; PG8_SCHED;
;             PG8_LDB(B0, 1, 0); PG8_LDB(B1, 1, 1); PG8_SCHED; PG8_LDA(At, 1, 0); PG8_STAGE(PG8_SA(0, 1), a2 + hstepA, voffA);
;             PG8_WAIT_V(8); PG8_WAIT_L(0); PG8_BAR; PG8_MMA(0, 0, At, B0); PG8_MMA(0, 1, At, B1); PG8_BAR; PG8_SCHED;
	s_add_i32 s86, s81, s65
	v_lshl_add_u64 v[212:213], s[56:57], 0, v[180:181]
	s_mov_b32 m0, s86
	ds_read_b128 v[160:163], v232 offset:16384
	ds_read_b128 v[164:167], v232 offset:17408
	ds_read_b128 v[168:171], v232 offset:18432
	ds_read_b128 v[172:175], v232 offset:19456
	ds_read_b128 v[196:199], v232 offset:20480
	ds_read_b128 v[200:203], v232 offset:21504
	ds_read_b128 v[204:207], v232 offset:22528
	ds_read_b128 v[208:211], v232 offset:23552
	global_load_lds_dwordx4 v[212:213], off
	s_add_i32 m0, s86, 0x2000
	s_add_u32 s86, s56, 0x40000
	v_lshl_add_u64 v[214:215], s[56:57], 0, v[184:185]
	s_addc_u32 s87, s57, 0
	s_add_i32 s88, s82, s65
	global_load_lds_dwordx4 v[214:215], off
	s_mov_b32 m0, s88
	v_lshl_add_u64 v[218:219], s[62:63], 0, v[182:183]
	global_load_lds_dwordx4 v180, s[86:87]
	s_add_i32 m0, s88, 0x2000
	s_nop 0
	global_load_lds_dwordx4 v184, s[86:87]
	v_lshl_add_u64 v[216:217], s[62:63], 0, v[178:179]
	s_mov_b32 m0, s68
	s_nop 0
	global_load_lds_dwordx4 v[216:217], off
	s_mov_b32 m0, s69
	s_nop 0
	global_load_lds_dwordx4 v[218:219], off
	s_waitcnt vmcnt(8)
	s_waitcnt lgkmcnt(0)
	s_barrier
	s_waitcnt lgkmcnt(0)
	v_mfma_f32_16x16x32_bf16 v[76:79], v[0:3], v[160:163], v[76:79]
	v_mfma_f32_16x16x32_bf16 v[72:75], v[8:11], v[160:163], v[72:75]
	v_mfma_f32_16x16x32_bf16 v[60:63], v[0:3], v[168:171], v[60:63]
	v_mfma_f32_16x16x32_bf16 v[56:59], v[8:11], v[168:171], v[56:59]
	v_mfma_f32_16x16x32_bf16 v[44:47], v[0:3], v[196:199], v[44:47]
	v_mfma_f32_16x16x32_bf16 v[40:43], v[8:11], v[196:199], v[40:43]
	v_mfma_f32_16x16x32_bf16 v[0:3], v[0:3], v[204:207], v[28:31]
	v_mfma_f32_16x16x32_bf16 v[76:79], v[4:7], v[164:167], v[76:79]
	v_mfma_f32_16x16x32_bf16 v[72:75], v[12:15], v[164:167], v[72:75]
	v_mfma_f32_16x16x32_bf16 v[60:63], v[4:7], v[172:175], v[60:63]
	v_mfma_f32_16x16x32_bf16 v[56:59], v[12:15], v[172:175], v[56:59]
	v_mfma_f32_16x16x32_bf16 v[44:47], v[4:7], v[200:203], v[44:47]
	v_mfma_f32_16x16x32_bf16 v[40:43], v[12:15], v[200:203], v[40:43]
	v_mfma_f32_16x16x32_bf16 v[0:3], v[4:7], v[208:211], v[0:3]
	v_mfma_f32_16x16x32_bf16 v[4:7], v[8:11], v[204:207], v[20:23]
	v_mfma_f32_16x16x32_bf16 v[4:7], v[12:15], v[208:211], v[4:7]
	v_mfma_f32_16x16x32_bf16 v[20:23], v[144:147], v[168:171], v[52:55]
	v_mfma_f32_16x16x32_bf16 v[52:55], v[148:151], v[172:175], v[20:23]
	v_mfma_f32_16x16x32_bf16 v[20:23], v[152:155], v[168:171], v[48:51]
	v_mfma_f32_16x16x32_bf16 v[48:51], v[156:159], v[172:175], v[20:23]
	v_mfma_f32_16x16x32_bf16 v[20:23], v[144:147], v[196:199], v[36:39]
	v_mfma_f32_16x16x32_bf16 v[36:39], v[148:151], v[200:203], v[20:23]
	v_mfma_f32_16x16x32_bf16 v[20:23], v[152:155], v[196:199], v[32:35]
	v_mfma_f32_16x16x32_bf16 v[32:35], v[156:159], v[200:203], v[20:23]
	v_mfma_f32_16x16x32_bf16 v[20:23], v[144:147], v[204:207], v[24:27]
	v_mfma_f32_16x16x32_bf16 v[16:19], v[152:155], v[204:207], v[16:19]
	v_mfma_f32_16x16x32_bf16 v[8:11], v[144:147], v[160:163], v[68:71]
	v_mfma_f32_16x16x32_bf16 v[12:15], v[152:155], v[160:163], v[64:67]
	v_mfma_f32_16x16x32_bf16 v[24:27], v[148:151], v[208:211], v[20:23]
	v_mfma_f32_16x16x32_bf16 v[16:19], v[156:159], v[208:211], v[16:19]
	v_mfma_f32_16x16x32_bf16 v[8:11], v[148:151], v[164:167], v[8:11]
	v_mfma_f32_16x16x32_bf16 v[12:15], v[156:159], v[164:167], v[12:15]
	s_barrier
	s_add_i32 s86, 0, 0x18000
	s_add_i32 s87, 0, 0x1c000
	v_add_u32_e32 v68, s86, v229
	v_add_u32_e32 v156, s87, v229
	ds_read_b128 v[20:23], v68
	ds_read_b128 v[28:31], v68 offset:1024
	ds_read_b128 v[64:67], v68 offset:2048
	ds_read_b128 v[68:71], v68 offset:3072
	ds_read_b128 v[144:147], v156
	ds_read_b128 v[148:151], v156 offset:1024
	ds_read_b128 v[152:155], v156 offset:2048
	ds_read_b128 v[156:159], v156 offset:3072
	s_add_u32 s62, s62, 0x40000
	s_addc_u32 s63, s63, 0
	s_mov_b32 m0, s70
	ds_read_b128 v[160:163], v232 offset:32768
	ds_read_b128 v[164:167], v232 offset:33792
	ds_read_b128 v[168:171], v232 offset:34816
	ds_read_b128 v[172:175], v232 offset:35840
	ds_read_b128 v[196:199], v232 offset:36864
	ds_read_b128 v[200:203], v232 offset:37888
	ds_read_b128 v[204:207], v232 offset:38912
	ds_read_b128 v[208:211], v232 offset:39936
	global_load_lds_dwordx4 v178, s[62:63]
	s_mov_b32 m0, s71
	s_nop 0
	global_load_lds_dwordx4 v182, s[62:63]
	s_waitcnt vmcnt(8)
	s_waitcnt lgkmcnt(0)
	s_barrier
; #define PG8_STAGE(bufoff, gbase, voff) do { _Pragma("unroll") for (int _i = 0; _i < 2; ++_i) \
;         __builtin_amdgcn_global_load_lds((const unsigned*)((const char*)(gbase) + (voff)[_i]), (LAS unsigned*)(lds + (bufoff) + ldsw + _i * 8192), 16, 0, 0); } while (0)
; #define PG8_LDA(dst, b, h) do { _Pragma("unroll") for (int m = 0; m < 4; ++m) _Pragma("unroll") for (int k = 0; k < 2; ++k) dst[m][k] = *(const LAS bf16x8*)(lds + PG8_SA(b, h) + aoff + m * 2048 + k * 1024); } while (0)
; #define PG8_LDB(dst, b, h) do { _Pragma("unroll") for (int n = 0; n < 2; ++n) _Pragma("unroll") for (int k = 0; k < 2; ++k) dst[n][k] = *(const LAS bf16x8*)(lds + PG8_SB(b, h) + boff + n * 2048 + k * 1024); } while (0)
; #define PG8_MMA(ai, bj, At, Bt) do { __builtin_amdgcn_s_setprio(1); _Pragma("unroll") for (int m = 0; m < 4; ++m) _Pragma("unroll") for (int n = 0; n < 2; ++n) _Pragma("unroll") for (int k = 0; k < 2; ++k) \
;         acc[ai][bj][m][n] = __builtin_amdgcn_mfma_f32_16x16x32_bf16(Bt[n][k], At[m][k], acc[ai][bj][m][n], 0, 0, 0); __builtin_amdgcn_s_setprio(0); } while (0)
; #define PG8_WAIT_V(n) asm volatile("s_waitcnt vmcnt(" #n ")" ::: "memory")
; #define PG8_WAIT_L(n) asm volatile("s_waitcnt lgkmcnt(" #n ")" ::: "memory")
; #define PG8_BAR __builtin_amdgcn_s_barrier()
; #define PG8_SCHED __builtin_amdgcn_sched_barrier(0)
; template <class Epi>
; __device__ __forceinline__ void gemm_phase(LAS unsigned char* lds, const Gemm g, const StaticOrder& S, const Epi& E) {
;     ...
;             PG8_WAIT_V(8); PG8_WAIT_L(0); PG8_BAR; PG8_MMA(0, 0, At, B0); PG8_MMA(0, 1, At, B1); PG8_BAR; PG8_SCHED;
;             PG8_LDA(At, 0, 1); PG8_STAGE(PG8_SB(0, 0), b2, voffB); PG8_STAGE(PG8_SB(0, 1), b2 + hstepB, voffB); PG8_STAGE(PG8_SA(0, 0), a2, voffA);
;             PG8_WAIT_V(8); PG8_WAIT_L(0); PG8_BAR; PG8_MMA(1, 0, At, B0); PG8_MMA(1, 1, At, B1); PG8_BAR; PG8_SCHED;
;             PG8_LDB(B0, 1, 0); PG8_LDB(B1, 1, 1); PG8_SCHED; PG8_LDA(At, 1, 0); PG8_STAGE(PG8_SA(0, 1), a2 + hstepA, voffA);
;             PG8_WAIT_V(8); PG8_WAIT_L(0); PG8_BAR; PG8_MMA(0, 0, At, B0); PG8_MMA(0, 1, At, B1); PG8_BAR; PG8_SCHED;
;             PG8_LDA(At, 1, 1); PG8_STAGE(PG8_SB(1, 0), b3, voffB); PG8_STAGE(PG8_SB(1, 1), b3 + hstepB, voffB); PG8_STAGE(PG8_SA(1, 0), a3, voffA);
;             PG8_WAIT_V(8); PG8_WAIT_L(0); PG8_BAR; PG8_MMA(1, 0, At, B0); PG8_MMA(1, 1, At, B1); PG8_BAR; PG8_SCHED;
;         }
	s_waitcnt lgkmcnt(0)
	v_mfma_f32_16x16x32_bf16 v[140:143], v[20:23], v[160:163], v[140:143]
	v_mfma_f32_16x16x32_bf16 v[132:135], v[64:67], v[160:163], v[132:135]
	v_mfma_f32_16x16x32_bf16 v[124:127], v[20:23], v[168:171], v[124:127]
	v_mfma_f32_16x16x32_bf16 v[120:123], v[64:67], v[168:171], v[120:123]
	v_mfma_f32_16x16x32_bf16 v[108:111], v[20:23], v[196:199], v[108:111]
	v_mfma_f32_16x16x32_bf16 v[104:107], v[64:67], v[196:199], v[104:107]
	v_mfma_f32_16x16x32_bf16 v[92:95], v[20:23], v[204:207], v[92:95]
	v_mfma_f32_16x16x32_bf16 v[88:91], v[64:67], v[204:207], v[88:91]
	v_mfma_f32_16x16x32_bf16 v[140:143], v[28:31], v[164:167], v[140:143]
	v_mfma_f32_16x16x32_bf16 v[132:135], v[68:71], v[164:167], v[132:135]
	v_mfma_f32_16x16x32_bf16 v[124:127], v[28:31], v[172:175], v[124:127]
	v_mfma_f32_16x16x32_bf16 v[120:123], v[68:71], v[172:175], v[120:123]
	v_mfma_f32_16x16x32_bf16 v[108:111], v[28:31], v[200:203], v[108:111]
	v_mfma_f32_16x16x32_bf16 v[104:107], v[68:71], v[200:203], v[104:107]
	v_mfma_f32_16x16x32_bf16 v[92:95], v[28:31], v[208:211], v[92:95]
	v_mfma_f32_16x16x32_bf16 v[88:91], v[68:71], v[208:211], v[88:91]
	v_mfma_f32_16x16x32_bf16 v[136:139], v[144:147], v[160:163], v[136:139]
	v_mfma_f32_16x16x32_bf16 v[128:131], v[152:155], v[160:163], v[128:131]
	v_mfma_f32_16x16x32_bf16 v[116:119], v[144:147], v[168:171], v[116:119]
	v_mfma_f32_16x16x32_bf16 v[112:115], v[152:155], v[168:171], v[112:115]
	v_mfma_f32_16x16x32_bf16 v[100:103], v[144:147], v[196:199], v[100:103]
	v_mfma_f32_16x16x32_bf16 v[96:99], v[152:155], v[196:199], v[96:99]
	v_mfma_f32_16x16x32_bf16 v[84:87], v[144:147], v[204:207], v[84:87]
	v_mfma_f32_16x16x32_bf16 v[80:83], v[152:155], v[204:207], v[80:83]
	v_mfma_f32_16x16x32_bf16 v[136:139], v[148:151], v[164:167], v[136:139]
	v_mfma_f32_16x16x32_bf16 v[128:131], v[156:159], v[164:167], v[128:131]
	v_mfma_f32_16x16x32_bf16 v[116:119], v[148:151], v[172:175], v[116:119]
	v_mfma_f32_16x16x32_bf16 v[112:115], v[156:159], v[172:175], v[112:115]
	v_mfma_f32_16x16x32_bf16 v[100:103], v[148:151], v[200:203], v[100:103]
	v_mfma_f32_16x16x32_bf16 v[96:99], v[156:159], v[200:203], v[96:99]
	v_mfma_f32_16x16x32_bf16 v[84:87], v[148:151], v[208:211], v[84:87]
	v_mfma_f32_16x16x32_bf16 v[80:83], v[156:159], v[208:211], v[80:83]
	s_barrier
	s_add_i32 s62, s86, s65
	v_lshl_add_u64 v[212:213], v[212:213], 0, s[16:17]
	s_mov_b32 m0, s62
	ds_read_b128 v[160:163], v232 offset:49152
	ds_read_b128 v[164:167], v232 offset:50176
	ds_read_b128 v[168:171], v232 offset:51200
	ds_read_b128 v[172:175], v232 offset:52224
	ds_read_b128 v[196:199], v232 offset:53248
	ds_read_b128 v[200:203], v232 offset:54272
	ds_read_b128 v[204:207], v232 offset:55296
	ds_read_b128 v[208:211], v232 offset:56320
	global_load_lds_dwordx4 v[212:213], off
	s_add_i32 m0, s62, 0x2000
	s_add_u32 s56, s56, 0x40080
	v_lshl_add_u64 v[212:213], v[214:215], 0, s[16:17]
	s_addc_u32 s57, s57, 0
	s_add_i32 s62, s87, s65
	global_load_lds_dwordx4 v[212:213], off
	s_mov_b32 m0, s62
	s_nop 0
	global_load_lds_dwordx4 v180, s[56:57]
	s_add_i32 m0, s62, 0x2000
	s_nop 0
	global_load_lds_dwordx4 v184, s[56:57]
	v_lshl_add_u64 v[212:213], v[216:217], 0, s[16:17]
	s_mov_b32 m0, s76
	s_nop 0
	global_load_lds_dwordx4 v[212:213], off
	v_lshl_add_u64 v[212:213], v[218:219], 0, s[16:17]
	s_mov_b32 m0, s77
	s_nop 0
	global_load_lds_dwordx4 v[212:213], off
	s_waitcnt vmcnt(8)
	s_waitcnt lgkmcnt(0)
	s_barrier
	s_waitcnt lgkmcnt(0)
	v_mfma_f32_16x16x32_bf16 v[76:79], v[20:23], v[160:163], v[76:79]
	v_mfma_f32_16x16x32_bf16 v[60:63], v[20:23], v[168:171], v[60:63]
	v_mfma_f32_16x16x32_bf16 v[44:47], v[20:23], v[196:199], v[44:47]
	v_mfma_f32_16x16x32_bf16 v[0:3], v[20:23], v[204:207], v[0:3]
	v_mfma_f32_16x16x32_bf16 v[76:79], v[28:31], v[164:167], v[76:79]
	v_mfma_f32_16x16x32_bf16 v[72:75], v[64:67], v[160:163], v[72:75]
	v_mfma_f32_16x16x32_bf16 v[60:63], v[28:31], v[172:175], v[60:63]
	v_mfma_f32_16x16x32_bf16 v[56:59], v[64:67], v[168:171], v[56:59]
	v_mfma_f32_16x16x32_bf16 v[44:47], v[28:31], v[200:203], v[44:47]
	v_mfma_f32_16x16x32_bf16 v[40:43], v[64:67], v[196:199], v[40:43]
	v_mfma_f32_16x16x32_bf16 v[28:31], v[28:31], v[208:211], v[0:3]
	v_mfma_f32_16x16x32_bf16 v[0:3], v[64:67], v[204:207], v[4:7]
	v_mfma_f32_16x16x32_bf16 v[72:75], v[68:71], v[164:167], v[72:75]
	v_mfma_f32_16x16x32_bf16 v[56:59], v[68:71], v[172:175], v[56:59]
	v_mfma_f32_16x16x32_bf16 v[40:43], v[68:71], v[200:203], v[40:43]
	v_mfma_f32_16x16x32_bf16 v[20:23], v[68:71], v[208:211], v[0:3]
	v_mfma_f32_16x16x32_bf16 v[0:3], v[144:147], v[160:163], v[8:11]
	v_mfma_f32_16x16x32_bf16 v[68:71], v[148:151], v[164:167], v[0:3]
	v_mfma_f32_16x16x32_bf16 v[0:3], v[152:155], v[160:163], v[12:15]
	v_mfma_f32_16x16x32_bf16 v[64:67], v[156:159], v[164:167], v[0:3]
	v_mfma_f32_16x16x32_bf16 v[0:3], v[144:147], v[168:171], v[52:55]
	v_mfma_f32_16x16x32_bf16 v[52:55], v[148:151], v[172:175], v[0:3]
	v_mfma_f32_16x16x32_bf16 v[0:3], v[152:155], v[168:171], v[48:51]
	v_mfma_f32_16x16x32_bf16 v[48:51], v[156:159], v[172:175], v[0:3]
	v_mfma_f32_16x16x32_bf16 v[0:3], v[144:147], v[196:199], v[36:39]
	v_mfma_f32_16x16x32_bf16 v[36:39], v[148:151], v[200:203], v[0:3]
	v_mfma_f32_16x16x32_bf16 v[0:3], v[152:155], v[196:199], v[32:35]
	v_mfma_f32_16x16x32_bf16 v[32:35], v[156:159], v[200:203], v[0:3]
	v_mfma_f32_16x16x32_bf16 v[0:3], v[144:147], v[204:207], v[24:27]
	v_mfma_f32_16x16x32_bf16 v[24:27], v[148:151], v[208:211], v[0:3]
	v_mfma_f32_16x16x32_bf16 v[0:3], v[152:155], v[204:207], v[16:19]
	v_mfma_f32_16x16x32_bf16 v[16:19], v[156:159], v[208:211], v[0:3]
	s_barrier
	s_add_i32 s85, s85, 2
	s_add_u32 s54, s54, 0x100
	s_addc_u32 s55, s55, 0
	s_add_u32 s83, s83, 0x100
	s_addc_u32 s84, s84, 0
	s_cmp_gt_u32 s85, 13
	s_cbranch_scc0 .LBB0_1018
	s_and_b64 vcc, exec, s[18:19]
	s_cbranch_vccz .LBB0_1021
	s_barrier

; #define PG8_STAGE(bufoff, gbase, voff) do { _Pragma("unroll") for (int _i = 0; _i < 2; ++_i) \
;         __builtin_amdgcn_global_load_lds((const unsigned*)((const char*)(gbase) + (voff)[_i]), (LAS unsigned*)(lds + (bufoff) + ldsw + _i * 8192), 16, 0, 0); } while (0)
; #define PG8_LDA(dst, b, h) do { _Pragma("unroll") for (int m = 0; m < 4; ++m) _Pragma("unroll") for (int k = 0; k < 2; ++k) dst[m][k] = *(const LAS bf16x8*)(lds + PG8_SA(b, h) + aoff + m * 2048 + k * 1024); } while (0)
; #define PG8_LDB(dst, b, h) do { _Pragma("unroll") for (int n = 0; n < 2; ++n) _Pragma("unroll") for (int k = 0; k < 2; ++k) dst[n][k] = *(const LAS bf16x8*)(lds + PG8_SB(b, h) + boff + n * 2048 + k * 1024); } while (0)
; #define PG8_MMA(ai, bj, At, Bt) do { __builtin_amdgcn_s_setprio(1); _Pragma("unroll") for (int m = 0; m < 4; ++m) _Pragma("unroll") for (int n = 0; n < 2; ++n) _Pragma("unroll") for (int k = 0; k < 2; ++k) \
;         acc[ai][bj][m][n] = __builtin_amdgcn_mfma_f32_16x16x32_bf16(Bt[n][k], At[m][k], acc[ai][bj][m][n], 0, 0, 0); __builtin_amdgcn_s_setprio(0); } while (0)
; #define PG8_WAIT_V(n) asm volatile("s_waitcnt vmcnt(" #n ")" ::: "memory")
; #define PG8_WAIT_L(n) asm volatile("s_waitcnt lgkmcnt(" #n ")" ::: "memory")
; template <class Epi>
; __device__ __forceinline__ void gemm_phase(LAS unsigned char* lds, const Gemm g, const StaticOrder& S, const Epi& E) {
;     ...
;     for (;;) {
;         const bool has_next = S.next(ui + 1, nxt);
;         const char* nA = has_next ? (const char*)g.A + (size_t)nxt.pm * tstepA : cA; const char* nB = has_next ? (const char*)g.Bt + (size_t)nxt.pn * tstepB : cB;
; #pragma nounroll
;         for (int t = 0; t < nt; t += 2) {
;             const bool last = (t == nt - 2);
;             const char* a1 = cA + (size_t)(t + 1) * kstep;
;             const char* a2 = last ? nA : cA + (size_t)(t + 2) * kstep; const char* b2 = last ? nB : cB + (size_t)(t + 2) * kstep;
;             const char* a3 = a2 + kstep; const char* b3 = b2 + kstep;
;             PG8_LDB(B0, 0, 0); PG8_LDB(B1, 0, 1); PG8_SCHED; PG8_LDA(At, 0, 0); PG8_STAGE(PG8_SA(1, 1), a1 + hstepA, voffA);
;             PG8_WAIT_V(8); PG8_WAIT_L(0); PG8_BAR; PG8_MMA(0, 0, At, B0); PG8_MMA(0, 1, At, B1); PG8_BAR; PG8_SCHED;
;             PG8_LDA(At, 0, 1); PG8_STAGE(PG8_SB(0, 0), b2, voffB); PG8_STAGE(PG8_SB(0, 1), b2 + hstepB, voffB); PG8_STAGE(PG8_SA(0, 0), a2, voffA);
.LBB0_1232:
	s_ashr_i32 s23, s22, 31
	s_lshl_b64 s[34:35], s[22:23], 19
	s_add_u32 s34, s24, s34
	s_addc_u32 s35, s25, s35
	s_and_b64 s[38:39], s[4:5], exec
	s_cselect_b32 s23, s35, s53
	s_cselect_b32 s76, s34, s52
	s_ashr_i32 s21, s20, 31
	s_lshl_b64 s[38:39], s[20:21], 19
	s_add_u32 s38, s19, s38
	s_addc_u32 s39, s33, s39
	s_and_b64 s[56:57], s[4:5], exec
	s_cselect_b32 s21, s39, s55
	s_cselect_b32 s77, s38, s54
	s_add_u32 s52, s52, 0x40080
	s_addc_u32 s53, s53, 0
	s_add_u32 s78, s54, 0x100
	s_addc_u32 s79, s55, 0
	s_mov_b32 s80, -2
	ds_read_b128 v[56:59], v189
	ds_read_b128 v[60:63], v189 offset:1024
	ds_read_b128 v[72:75], v189 offset:2048
	ds_read_b128 v[76:79], v189 offset:3072
	ds_read_b128 v[144:147], v195
	ds_read_b128 v[148:151], v195 offset:1024
	ds_read_b128 v[168:171], v195 offset:2048
	ds_read_b128 v[178:181], v195 offset:3072
	s_add_u32 s54, s52, 0xfffc0080
	s_addc_u32 s55, s53, -1
	s_cmp_eq_u32 s80, 12
	s_cselect_b32 s57, s23, s55
	s_cselect_b32 s56, s76, s54
	s_cselect_b32 s55, s21, s79
	s_cselect_b32 s54, s77, s78
	s_add_i32 m0, s43, 0xc000
	ds_read_b128 v[184:187], v201
	ds_read_b128 v[190:193], v201 offset:1024
	ds_read_b128 v[196:199], v201 offset:2048
	ds_read_b128 v[202:205], v201 offset:3072
	ds_read_b128 v[208:211], v201 offset:4096
	ds_read_b128 v[212:215], v201 offset:5120
	ds_read_b128 v[216:219], v201 offset:6144
	ds_read_b128 v[220:223], v201 offset:7168
	global_load_lds_dwordx4 v160, s[52:53]
	s_add_i32 m0, s43, 0xe000
	s_nop 0
	global_load_lds_dwordx4 v162, s[52:53]
	s_waitcnt vmcnt(8)
	s_waitcnt lgkmcnt(0)
	s_barrier
	s_waitcnt lgkmcnt(0)
	v_mfma_f32_16x16x32_bf16 v[140:143], v[56:59], v[184:187], 0
	v_mfma_f32_16x16x32_bf16 v[136:139], v[72:75], v[184:187], 0
	v_mfma_f32_16x16x32_bf16 v[124:127], v[56:59], v[196:199], 0
	v_mfma_f32_16x16x32_bf16 v[120:123], v[72:75], v[196:199], 0
	v_mfma_f32_16x16x32_bf16 v[108:111], v[56:59], v[208:211], 0
	v_mfma_f32_16x16x32_bf16 v[104:107], v[72:75], v[208:211], 0
	v_mfma_f32_16x16x32_bf16 v[92:95], v[56:59], v[216:219], 0
	v_mfma_f32_16x16x32_bf16 v[88:91], v[72:75], v[216:219], 0
	v_mfma_f32_16x16x32_bf16 v[140:143], v[60:63], v[190:193], v[140:143]
	v_mfma_f32_16x16x32_bf16 v[136:139], v[76:79], v[190:193], v[136:139]
	v_mfma_f32_16x16x32_bf16 v[124:127], v[60:63], v[202:205], v[124:127]
	v_mfma_f32_16x16x32_bf16 v[120:123], v[76:79], v[202:205], v[120:123]
	v_mfma_f32_16x16x32_bf16 v[108:111], v[60:63], v[212:215], v[108:111]
	v_mfma_f32_16x16x32_bf16 v[104:107], v[76:79], v[212:215], v[104:107]
	v_mfma_f32_16x16x32_bf16 v[92:95], v[60:63], v[220:223], v[92:95]
	v_mfma_f32_16x16x32_bf16 v[88:91], v[76:79], v[220:223], v[88:91]
	v_mfma_f32_16x16x32_bf16 v[132:135], v[144:147], v[184:187], 0
	v_mfma_f32_16x16x32_bf16 v[128:131], v[168:171], v[184:187], 0
	v_mfma_f32_16x16x32_bf16 v[116:119], v[144:147], v[196:199], 0
	v_mfma_f32_16x16x32_bf16 v[112:115], v[168:171], v[196:199], 0
	v_mfma_f32_16x16x32_bf16 v[100:103], v[144:147], v[208:211], 0
	v_mfma_f32_16x16x32_bf16 v[96:99], v[168:171], v[208:211], 0
	v_mfma_f32_16x16x32_bf16 v[84:87], v[144:147], v[216:219], 0
	v_mfma_f32_16x16x32_bf16 v[80:83], v[168:171], v[216:219], 0
	v_mfma_f32_16x16x32_bf16 v[132:135], v[148:151], v[190:193], v[132:135]
	v_mfma_f32_16x16x32_bf16 v[128:131], v[178:181], v[190:193], v[128:131]
	v_mfma_f32_16x16x32_bf16 v[116:119], v[148:151], v[202:205], v[116:119]
	v_mfma_f32_16x16x32_bf16 v[112:115], v[178:181], v[202:205], v[112:115]
	v_mfma_f32_16x16x32_bf16 v[100:103], v[148:151], v[212:215], v[100:103]
	v_mfma_f32_16x16x32_bf16 v[96:99], v[178:181], v[212:215], v[96:99]
	v_mfma_f32_16x16x32_bf16 v[84:87], v[148:151], v[220:223], v[84:87]
	v_mfma_f32_16x16x32_bf16 v[80:83], v[178:181], v[220:223], v[80:83]
	s_barrier
	s_add_i32 s81, s73, s58
	v_lshl_add_u64 v[174:175], s[54:55], 0, v[154:155]
	s_mov_b32 m0, s81
	ds_read_b128 v[184:187], v201 offset:16384
	ds_read_b128 v[190:193], v201 offset:17408
	ds_read_b128 v[196:199], v201 offset:18432
	ds_read_b128 v[202:205], v201 offset:19456
	ds_read_b128 v[208:211], v201 offset:20480
	ds_read_b128 v[212:215], v201 offset:21504
	ds_read_b128 v[216:219], v201 offset:22528
	ds_read_b128 v[220:223], v201 offset:23552
	global_load_lds_dwordx4 v[174:175], off
	s_add_i32 m0, s81, 0x2000
	s_add_u32 s82, s54, 0x40000
	v_lshl_add_u64 v[224:225], s[54:55], 0, v[158:159]
	s_addc_u32 s83, s55, 0
	s_add_i32 s81, s74, s58
	global_load_lds_dwordx4 v[224:225], off
	s_mov_b32 m0, s81
	v_lshl_add_u64 v[228:229], s[56:57], 0, v[156:157]
	global_load_lds_dwordx4 v154, s[82:83]
	s_add_i32 m0, s81, 0x2000
	s_nop 0
	global_load_lds_dwordx4 v158, s[82:83]
	v_lshl_add_u64 v[226:227], s[56:57], 0, v[152:153]
	s_mov_b32 m0, s43
	s_nop 0
	global_load_lds_dwordx4 v[226:227], off
	s_mov_b32 m0, s59
	s_nop 0
	global_load_lds_dwordx4 v[228:229], off
	s_waitcnt vmcnt(8)
	s_waitcnt lgkmcnt(0)
	s_barrier
; #define PG8_STAGE(bufoff, gbase, voff) do { _Pragma("unroll") for (int _i = 0; _i < 2; ++_i) \
;         __builtin_amdgcn_global_load_lds((const unsigned*)((const char*)(gbase) + (voff)[_i]), (LAS unsigned*)(lds + (bufoff) + ldsw + _i * 8192), 16, 0, 0); } while (0)
; #define PG8_LDA(dst, b, h) do { _Pragma("unroll") for (int m = 0; m < 4; ++m) _Pragma("unroll") for (int k = 0; k < 2; ++k) dst[m][k] = *(const LAS bf16x8*)(lds + PG8_SA(b, h) + aoff + m * 2048 + k * 1024); } while (0)
; #define PG8_LDB(dst, b, h) do { _Pragma("unroll") for (int n = 0; n < 2; ++n) _Pragma("unroll") for (int k = 0; k < 2; ++k) dst[n][k] = *(const LAS bf16x8*)(lds + PG8_SB(b, h) + boff + n * 2048 + k * 1024); } while (0)
; #define PG8_MMA(ai, bj, At, Bt) do { __builtin_amdgcn_s_setprio(1); _Pragma("unroll") for (int m = 0; m < 4; ++m) _Pragma("unroll") for (int n = 0; n < 2; ++n) _Pragma("unroll") for (int k = 0; k < 2; ++k) \
;         acc[ai][bj][m][n] = __builtin_amdgcn_mfma_f32_16x16x32_bf16(Bt[n][k], At[m][k], acc[ai][bj][m][n], 0, 0, 0); __builtin_amdgcn_s_setprio(0); } while (0)
; #define PG8_WAIT_V(n) asm volatile("s_waitcnt vmcnt(" #n ")" ::: "memory")
; #define PG8_WAIT_L(n) asm volatile("s_waitcnt lgkmcnt(" #n ")" ::: "memory")
; #define PG8_BAR __builtin_amdgcn_s_barrier()
; #define PG8_SCHED __builtin_amdgcn_sched_barrier(0)
; template <class Epi>
; __device__ __forceinline__ void gemm_phase(LAS unsigned char* lds, const Gemm g, const StaticOrder& S, const Epi& E) {
;     ...
;             PG8_WAIT_V(8); PG8_WAIT_L(0); PG8_BAR; PG8_MMA(1, 0, At, B0); PG8_MMA(1, 1, At, B1); PG8_BAR; PG8_SCHED;
;             PG8_LDB(B0, 1, 0); PG8_LDB(B1, 1, 1); PG8_SCHED; PG8_LDA(At, 1, 0); PG8_STAGE(PG8_SA(0, 1), a2 + hstepA, voffA);
;             PG8_WAIT_V(8); PG8_WAIT_L(0); PG8_BAR; PG8_MMA(0, 0, At, B0); PG8_MMA(0, 1, At, B1); PG8_BAR; PG8_SCHED;
	s_waitcnt lgkmcnt(0)
	v_mfma_f32_16x16x32_bf16 v[68:71], v[56:59], v[184:187], 0
	v_mfma_f32_16x16x32_bf16 v[64:67], v[72:75], v[184:187], 0
	v_mfma_f32_16x16x32_bf16 v[44:47], v[56:59], v[196:199], 0
	v_mfma_f32_16x16x32_bf16 v[40:43], v[72:75], v[196:199], 0
	v_mfma_f32_16x16x32_bf16 v[28:31], v[56:59], v[208:211], 0
	v_mfma_f32_16x16x32_bf16 v[24:27], v[72:75], v[208:211], 0
	v_mfma_f32_16x16x32_bf16 v[12:15], v[56:59], v[216:219], 0
	v_mfma_f32_16x16x32_bf16 v[8:11], v[72:75], v[216:219], 0
	v_mfma_f32_16x16x32_bf16 v[68:71], v[60:63], v[190:193], v[68:71]
	v_mfma_f32_16x16x32_bf16 v[64:67], v[76:79], v[190:193], v[64:67]
	v_mfma_f32_16x16x32_bf16 v[44:47], v[60:63], v[202:205], v[44:47]
	v_mfma_f32_16x16x32_bf16 v[40:43], v[76:79], v[202:205], v[40:43]
	v_mfma_f32_16x16x32_bf16 v[28:31], v[60:63], v[212:215], v[28:31]
	v_mfma_f32_16x16x32_bf16 v[24:27], v[76:79], v[212:215], v[24:27]
	v_mfma_f32_16x16x32_bf16 v[12:15], v[60:63], v[220:223], v[12:15]
	v_mfma_f32_16x16x32_bf16 v[8:11], v[76:79], v[220:223], v[8:11]
	v_mfma_f32_16x16x32_bf16 v[52:55], v[144:147], v[184:187], 0
	v_mfma_f32_16x16x32_bf16 v[48:51], v[168:171], v[184:187], 0
	v_mfma_f32_16x16x32_bf16 v[36:39], v[144:147], v[196:199], 0
	v_mfma_f32_16x16x32_bf16 v[32:35], v[168:171], v[196:199], 0
	v_mfma_f32_16x16x32_bf16 v[20:23], v[144:147], v[208:211], 0
	v_mfma_f32_16x16x32_bf16 v[16:19], v[168:171], v[208:211], 0
	v_mfma_f32_16x16x32_bf16 v[4:7], v[144:147], v[216:219], 0
	v_mfma_f32_16x16x32_bf16 v[0:3], v[168:171], v[216:219], 0
	v_mfma_f32_16x16x32_bf16 v[52:55], v[148:151], v[190:193], v[52:55]
	v_mfma_f32_16x16x32_bf16 v[48:51], v[178:181], v[190:193], v[48:51]
	v_mfma_f32_16x16x32_bf16 v[36:39], v[148:151], v[202:205], v[36:39]
	v_mfma_f32_16x16x32_bf16 v[32:35], v[178:181], v[202:205], v[32:35]
	v_mfma_f32_16x16x32_bf16 v[20:23], v[148:151], v[212:215], v[20:23]
	v_mfma_f32_16x16x32_bf16 v[16:19], v[178:181], v[212:215], v[16:19]
	v_mfma_f32_16x16x32_bf16 v[4:7], v[148:151], v[220:223], v[4:7]
	v_mfma_f32_16x16x32_bf16 v[0:3], v[178:181], v[220:223], v[0:3]
	s_barrier
	s_add_i32 s81, 0, 0x18000
	s_add_i32 s82, 0, 0x1c000
	v_add_u32_e32 v76, s81, v183
	v_add_u32_e32 v172, s82, v183
	ds_read_b128 v[56:59], v76
	ds_read_b128 v[60:63], v76 offset:1024
	ds_read_b128 v[72:75], v76 offset:2048
	ds_read_b128 v[76:79], v76 offset:3072
	ds_read_b128 v[144:147], v172
	ds_read_b128 v[148:151], v172 offset:1024
	ds_read_b128 v[168:171], v172 offset:2048
	ds_read_b128 v[178:181], v172 offset:3072
	s_add_u32 s56, s56, 0x40000
	s_addc_u32 s57, s57, 0
	s_mov_b32 m0, s62
	ds_read_b128 v[184:187], v201 offset:32768
	ds_read_b128 v[190:193], v201 offset:33792
	ds_read_b128 v[196:199], v201 offset:34816
	ds_read_b128 v[202:205], v201 offset:35840
	ds_read_b128 v[208:211], v201 offset:36864
	ds_read_b128 v[212:215], v201 offset:37888
	ds_read_b128 v[216:219], v201 offset:38912
	ds_read_b128 v[220:223], v201 offset:39936
	global_load_lds_dwordx4 v152, s[56:57]
	s_mov_b32 m0, s63
	s_nop 0
	global_load_lds_dwordx4 v156, s[56:57]
	s_waitcnt vmcnt(8)
	s_waitcnt lgkmcnt(0)
	s_barrier
	s_waitcnt lgkmcnt(0)
	v_mfma_f32_16x16x32_bf16 v[140:143], v[56:59], v[184:187], v[140:143]
	v_mfma_f32_16x16x32_bf16 v[136:139], v[72:75], v[184:187], v[136:139]
	v_mfma_f32_16x16x32_bf16 v[124:127], v[56:59], v[196:199], v[124:127]
	v_mfma_f32_16x16x32_bf16 v[120:123], v[72:75], v[196:199], v[120:123]
	v_mfma_f32_16x16x32_bf16 v[108:111], v[56:59], v[208:211], v[108:111]
	v_mfma_f32_16x16x32_bf16 v[104:107], v[72:75], v[208:211], v[104:107]
	v_mfma_f32_16x16x32_bf16 v[92:95], v[56:59], v[216:219], v[92:95]
	v_mfma_f32_16x16x32_bf16 v[88:91], v[72:75], v[216:219], v[88:91]
	v_mfma_f32_16x16x32_bf16 v[140:143], v[60:63], v[190:193], v[140:143]
	v_mfma_f32_16x16x32_bf16 v[136:139], v[76:79], v[190:193], v[136:139]
	v_mfma_f32_16x16x32_bf16 v[124:127], v[60:63], v[202:205], v[124:127]
	v_mfma_f32_16x16x32_bf16 v[120:123], v[76:79], v[202:205], v[120:123]
	v_mfma_f32_16x16x32_bf16 v[108:111], v[60:63], v[212:215], v[108:111]
	v_mfma_f32_16x16x32_bf16 v[104:107], v[76:79], v[212:215], v[104:107]
	v_mfma_f32_16x16x32_bf16 v[92:95], v[60:63], v[220:223], v[92:95]
	v_mfma_f32_16x16x32_bf16 v[88:91], v[76:79], v[220:223], v[88:91]
	v_mfma_f32_16x16x32_bf16 v[132:135], v[144:147], v[184:187], v[132:135]
	v_mfma_f32_16x16x32_bf16 v[128:131], v[168:171], v[184:187], v[128:131]
	v_mfma_f32_16x16x32_bf16 v[116:119], v[144:147], v[196:199], v[116:119]
	v_mfma_f32_16x16x32_bf16 v[112:115], v[168:171], v[196:199], v[112:115]
	v_mfma_f32_16x16x32_bf16 v[100:103], v[144:147], v[208:211], v[100:103]
	v_mfma_f32_16x16x32_bf16 v[96:99], v[168:171], v[208:211], v[96:99]
	v_mfma_f32_16x16x32_bf16 v[84:87], v[144:147], v[216:219], v[84:87]
	v_mfma_f32_16x16x32_bf16 v[80:83], v[168:171], v[216:219], v[80:83]
	v_mfma_f32_16x16x32_bf16 v[132:135], v[148:151], v[190:193], v[132:135]
	v_mfma_f32_16x16x32_bf16 v[128:131], v[178:181], v[190:193], v[128:131]
	v_mfma_f32_16x16x32_bf16 v[116:119], v[148:151], v[202:205], v[116:119]
	v_mfma_f32_16x16x32_bf16 v[112:115], v[178:181], v[202:205], v[112:115]
	v_mfma_f32_16x16x32_bf16 v[100:103], v[148:151], v[212:215], v[100:103]
	v_mfma_f32_16x16x32_bf16 v[96:99], v[178:181], v[212:215], v[96:99]
	v_mfma_f32_16x16x32_bf16 v[84:87], v[148:151], v[220:223], v[84:87]
	v_mfma_f32_16x16x32_bf16 v[80:83], v[178:181], v[220:223], v[80:83]
	s_barrier
; #define PG8_STAGE(bufoff, gbase, voff) do { _Pragma("unroll") for (int _i = 0; _i < 2; ++_i) \
;         __builtin_amdgcn_global_load_lds((const unsigned*)((const char*)(gbase) + (voff)[_i]), (LAS unsigned*)(lds + (bufoff) + ldsw + _i * 8192), 16, 0, 0); } while (0)
; #define PG8_LDA(dst, b, h) do { _Pragma("unroll") for (int m = 0; m < 4; ++m) _Pragma("unroll") for (int k = 0; k < 2; ++k) dst[m][k] = *(const LAS bf16x8*)(lds + PG8_SA(b, h) + aoff + m * 2048 + k * 1024); } while (0)
; #define PG8_LDB(dst, b, h) do { _Pragma("unroll") for (int n = 0; n < 2; ++n) _Pragma("unroll") for (int k = 0; k < 2; ++k) dst[n][k] = *(const LAS bf16x8*)(lds + PG8_SB(b, h) + boff + n * 2048 + k * 1024); } while (0)
; #define PG8_WAIT_V(n) asm volatile("s_waitcnt vmcnt(" #n ")" ::: "memory")
; #define PG8_WAIT_L(n) asm volatile("s_waitcnt lgkmcnt(" #n ")" ::: "memory")
; template <class Epi>
; __device__ __forceinline__ void gemm_phase(LAS unsigned char* lds, const Gemm g, const StaticOrder& S, const Epi& E) {
;     ...
;         for (int t = 0; t < nt; t += 2) {
;             const bool last = (t == nt - 2);
;             const char* a1 = cA + (size_t)(t + 1) * kstep;
;             const char* a2 = last ? nA : cA + (size_t)(t + 2) * kstep; const char* b2 = last ? nB : cB + (size_t)(t + 2) * kstep;
;             const char* a3 = a2 + kstep; const char* b3 = b2 + kstep;
;             PG8_LDB(B0, 0, 0); PG8_LDB(B1, 0, 1); PG8_SCHED; PG8_LDA(At, 0, 0); PG8_STAGE(PG8_SA(1, 1), a1 + hstepA, voffA);
;             PG8_WAIT_V(8); PG8_WAIT_L(0); PG8_BAR; PG8_MMA(0, 0, At, B0); PG8_MMA(0, 1, At, B1); PG8_BAR; PG8_SCHED;
;             PG8_LDA(At, 0, 1); PG8_STAGE(PG8_SB(0, 0), b2, voffB); PG8_STAGE(PG8_SB(0, 1), b2 + hstepB, voffB); PG8_STAGE(PG8_SA(0, 0), a2, voffA);
;             PG8_WAIT_V(8); PG8_WAIT_L(0); PG8_BAR; PG8_MMA(1, 0, At, B0); PG8_MMA(1, 1, At, B1); PG8_BAR; PG8_SCHED;
;             PG8_LDB(B0, 1, 0); PG8_LDB(B1, 1, 1); PG8_SCHED; PG8_LDA(At, 1, 0); PG8_STAGE(PG8_SA(0, 1), a2 + hstepA, voffA);
;             PG8_WAIT_V(8); PG8_WAIT_L(0); PG8_BAR; PG8_MMA(0, 0, At, B0); PG8_MMA(0, 1, At, B1); PG8_BAR; PG8_SCHED;
;             PG8_LDA(At, 1, 1); PG8_STAGE(PG8_SB(1, 0), b3, voffB); PG8_STAGE(PG8_SB(1, 1), b3 + hstepB, voffB); PG8_STAGE(PG8_SA(1, 0), a3, voffA);
;             PG8_WAIT_V(8); PG8_WAIT_L(0); PG8_BAR; PG8_MMA(1, 0, At, B0); PG8_MMA(1, 1, At, B1); PG8_BAR; PG8_SCHED;
	s_add_i32 s56, s81, s58
	v_lshl_add_u64 v[174:175], v[174:175], 0, s[12:13]
	s_mov_b32 m0, s56
	ds_read_b128 v[184:187], v201 offset:49152
	ds_read_b128 v[190:193], v201 offset:50176
	ds_read_b128 v[196:199], v201 offset:51200
	ds_read_b128 v[202:205], v201 offset:52224
	ds_read_b128 v[208:211], v201 offset:53248
	ds_read_b128 v[212:215], v201 offset:54272
	ds_read_b128 v[216:219], v201 offset:55296
	ds_read_b128 v[220:223], v201 offset:56320
	global_load_lds_dwordx4 v[174:175], off
	s_add_i32 m0, s56, 0x2000
	s_add_u32 s54, s54, 0x40080
	v_lshl_add_u64 v[174:175], v[224:225], 0, s[12:13]
	s_addc_u32 s55, s55, 0
	s_add_i32 s56, s82, s58
	global_load_lds_dwordx4 v[174:175], off
	s_mov_b32 m0, s56
	s_nop 0
	global_load_lds_dwordx4 v154, s[54:55]
	s_add_i32 m0, s56, 0x2000
	s_nop 0
	global_load_lds_dwordx4 v158, s[54:55]
	v_lshl_add_u64 v[174:175], v[226:227], 0, s[12:13]
	s_mov_b32 m0, s69
	s_nop 0
	global_load_lds_dwordx4 v[174:175], off
	v_lshl_add_u64 v[174:175], v[228:229], 0, s[12:13]
	s_mov_b32 m0, s70
	s_nop 0
	global_load_lds_dwordx4 v[174:175], off
	s_waitcnt vmcnt(8)
	s_waitcnt lgkmcnt(0)
	s_barrier
	s_waitcnt lgkmcnt(0)
	v_mfma_f32_16x16x32_bf16 v[68:71], v[56:59], v[184:187], v[68:71]
	v_mfma_f32_16x16x32_bf16 v[64:67], v[72:75], v[184:187], v[64:67]
	v_mfma_f32_16x16x32_bf16 v[44:47], v[56:59], v[196:199], v[44:47]
	v_mfma_f32_16x16x32_bf16 v[40:43], v[72:75], v[196:199], v[40:43]
	v_mfma_f32_16x16x32_bf16 v[28:31], v[56:59], v[208:211], v[28:31]
	v_mfma_f32_16x16x32_bf16 v[24:27], v[72:75], v[208:211], v[24:27]
	v_mfma_f32_16x16x32_bf16 v[12:15], v[56:59], v[216:219], v[12:15]
	v_mfma_f32_16x16x32_bf16 v[8:11], v[72:75], v[216:219], v[8:11]
	v_mfma_f32_16x16x32_bf16 v[68:71], v[60:63], v[190:193], v[68:71]
	v_mfma_f32_16x16x32_bf16 v[64:67], v[76:79], v[190:193], v[64:67]
	v_mfma_f32_16x16x32_bf16 v[44:47], v[60:63], v[202:205], v[44:47]
	v_mfma_f32_16x16x32_bf16 v[40:43], v[76:79], v[202:205], v[40:43]
	v_mfma_f32_16x16x32_bf16 v[28:31], v[60:63], v[212:215], v[28:31]
	v_mfma_f32_16x16x32_bf16 v[24:27], v[76:79], v[212:215], v[24:27]
	v_mfma_f32_16x16x32_bf16 v[12:15], v[60:63], v[220:223], v[12:15]
	v_mfma_f32_16x16x32_bf16 v[8:11], v[76:79], v[220:223], v[8:11]
	v_mfma_f32_16x16x32_bf16 v[52:55], v[144:147], v[184:187], v[52:55]
	v_mfma_f32_16x16x32_bf16 v[48:51], v[168:171], v[184:187], v[48:51]
	v_mfma_f32_16x16x32_bf16 v[36:39], v[144:147], v[196:199], v[36:39]
	v_mfma_f32_16x16x32_bf16 v[32:35], v[168:171], v[196:199], v[32:35]
	v_mfma_f32_16x16x32_bf16 v[20:23], v[144:147], v[208:211], v[20:23]
	v_mfma_f32_16x16x32_bf16 v[16:19], v[168:171], v[208:211], v[16:19]
	v_mfma_f32_16x16x32_bf16 v[4:7], v[144:147], v[216:219], v[4:7]
	v_mfma_f32_16x16x32_bf16 v[0:3], v[168:171], v[216:219], v[0:3]
	v_mfma_f32_16x16x32_bf16 v[52:55], v[148:151], v[190:193], v[52:55]
	v_mfma_f32_16x16x32_bf16 v[48:51], v[178:181], v[190:193], v[48:51]
	v_mfma_f32_16x16x32_bf16 v[36:39], v[148:151], v[202:205], v[36:39]
	v_mfma_f32_16x16x32_bf16 v[32:35], v[178:181], v[202:205], v[32:35]
	v_mfma_f32_16x16x32_bf16 v[20:23], v[148:151], v[212:215], v[20:23]
	v_mfma_f32_16x16x32_bf16 v[16:19], v[178:181], v[212:215], v[16:19]
	v_mfma_f32_16x16x32_bf16 v[4:7], v[148:151], v[220:223], v[4:7]
	v_mfma_f32_16x16x32_bf16 v[0:3], v[178:181], v[220:223], v[0:3]
	s_barrier
	s_add_i32 s80, s80, 2
	s_add_u32 s52, s52, 0x100
	s_addc_u32 s53, s53, 0
	s_add_u32 s78, s78, 0x100
	s_addc_u32 s79, s79, 0
	s_cmp_gt_u32 s80, 13
.LBB0_1233:
	ds_read_b128 v[56:59], v189
	ds_read_b128 v[60:63], v189 offset:1024
	ds_read_b128 v[72:75], v189 offset:2048
	ds_read_b128 v[76:79], v189 offset:3072
	ds_read_b128 v[144:147], v195
	ds_read_b128 v[148:151], v195 offset:1024
	ds_read_b128 v[168:171], v195 offset:2048
	ds_read_b128 v[178:181], v195 offset:3072
	s_add_u32 s54, s52, 0xfffc0080
	s_addc_u32 s55, s53, -1
	s_cmp_eq_u32 s80, 12
	s_cselect_b32 s57, s23, s55
	s_cselect_b32 s56, s76, s54
	s_cselect_b32 s55, s21, s79
	s_cselect_b32 s54, s77, s78
	s_add_i32 m0, s43, 0xc000
	ds_read_b128 v[184:187], v201
	ds_read_b128 v[190:193], v201 offset:1024
	ds_read_b128 v[196:199], v201 offset:2048
	ds_read_b128 v[202:205], v201 offset:3072
	ds_read_b128 v[208:211], v201 offset:4096
	ds_read_b128 v[212:215], v201 offset:5120
	ds_read_b128 v[216:219], v201 offset:6144
	ds_read_b128 v[220:223], v201 offset:7168
	global_load_lds_dwordx4 v160, s[52:53]
	s_add_i32 m0, s43, 0xe000
	s_nop 0
	global_load_lds_dwordx4 v162, s[52:53]
	s_waitcnt vmcnt(8)
	s_waitcnt lgkmcnt(0)
	s_barrier
; #define PG8_STAGE(bufoff, gbase, voff) do { _Pragma("unroll") for (int _i = 0; _i < 2; ++_i) \
;         __builtin_amdgcn_global_load_lds((const unsigned*)((const char*)(gbase) + (voff)[_i]), (LAS unsigned*)(lds + (bufoff) + ldsw + _i * 8192), 16, 0, 0); } while (0)
; #define PG8_LDA(dst, b, h) do { _Pragma("unroll") for (int m = 0; m < 4; ++m) _Pragma("unroll") for (int k = 0; k < 2; ++k) dst[m][k] = *(const LAS bf16x8*)(lds + PG8_SA(b, h) + aoff + m * 2048 + k * 1024); } while (0)
; #define PG8_MMA(ai, bj, At, Bt) do { __builtin_amdgcn_s_setprio(1); _Pragma("unroll") for (int m = 0; m < 4; ++m) _Pragma("unroll") for (int n = 0; n < 2; ++n) _Pragma("unroll") for (int k = 0; k < 2; ++k) \
;         acc[ai][bj][m][n] = __builtin_amdgcn_mfma_f32_16x16x32_bf16(Bt[n][k], At[m][k], acc[ai][bj][m][n], 0, 0, 0); __builtin_amdgcn_s_setprio(0); } while (0)
; #define PG8_WAIT_V(n) asm volatile("s_waitcnt vmcnt(" #n ")" ::: "memory")
; #define PG8_WAIT_L(n) asm volatile("s_waitcnt lgkmcnt(" #n ")" ::: "memory")
; #define PG8_BAR __builtin_amdgcn_s_barrier()
; #define PG8_SCHED __builtin_amdgcn_sched_barrier(0)
; template <class Epi>
; __device__ __forceinline__ void gemm_phase(LAS unsigned char* lds, const Gemm g, const StaticOrder& S, const Epi& E) {
;     ...
;             PG8_WAIT_V(8); PG8_WAIT_L(0); PG8_BAR; PG8_MMA(0, 0, At, B0); PG8_MMA(0, 1, At, B1); PG8_BAR; PG8_SCHED;
;             PG8_LDA(At, 0, 1); PG8_STAGE(PG8_SB(0, 0), b2, voffB); PG8_STAGE(PG8_SB(0, 1), b2 + hstepB, voffB); PG8_STAGE(PG8_SA(0, 0), a2, voffA);
;             PG8_WAIT_V(8); PG8_WAIT_L(0); PG8_BAR; PG8_MMA(1, 0, At, B0); PG8_MMA(1, 1, At, B1); PG8_BAR; PG8_SCHED;
	s_waitcnt lgkmcnt(0)
	v_mfma_f32_16x16x32_bf16 v[140:143], v[56:59], v[184:187], v[140:143]
	v_mfma_f32_16x16x32_bf16 v[136:139], v[72:75], v[184:187], v[136:139]
	v_mfma_f32_16x16x32_bf16 v[124:127], v[56:59], v[196:199], v[124:127]
	v_mfma_f32_16x16x32_bf16 v[120:123], v[72:75], v[196:199], v[120:123]
	v_mfma_f32_16x16x32_bf16 v[108:111], v[56:59], v[208:211], v[108:111]
	v_mfma_f32_16x16x32_bf16 v[104:107], v[72:75], v[208:211], v[104:107]
	v_mfma_f32_16x16x32_bf16 v[92:95], v[56:59], v[216:219], v[92:95]
	v_mfma_f32_16x16x32_bf16 v[88:91], v[72:75], v[216:219], v[88:91]
	v_mfma_f32_16x16x32_bf16 v[140:143], v[60:63], v[190:193], v[140:143]
	v_mfma_f32_16x16x32_bf16 v[136:139], v[76:79], v[190:193], v[136:139]
	v_mfma_f32_16x16x32_bf16 v[124:127], v[60:63], v[202:205], v[124:127]
	v_mfma_f32_16x16x32_bf16 v[120:123], v[76:79], v[202:205], v[120:123]
	v_mfma_f32_16x16x32_bf16 v[108:111], v[60:63], v[212:215], v[108:111]
	v_mfma_f32_16x16x32_bf16 v[104:107], v[76:79], v[212:215], v[104:107]
	v_mfma_f32_16x16x32_bf16 v[92:95], v[60:63], v[220:223], v[92:95]
	v_mfma_f32_16x16x32_bf16 v[88:91], v[76:79], v[220:223], v[88:91]
	v_mfma_f32_16x16x32_bf16 v[132:135], v[144:147], v[184:187], v[132:135]
	v_mfma_f32_16x16x32_bf16 v[128:131], v[168:171], v[184:187], v[128:131]
	v_mfma_f32_16x16x32_bf16 v[116:119], v[144:147], v[196:199], v[116:119]
	v_mfma_f32_16x16x32_bf16 v[112:115], v[168:171], v[196:199], v[112:115]
	v_mfma_f32_16x16x32_bf16 v[100:103], v[144:147], v[208:211], v[100:103]
	v_mfma_f32_16x16x32_bf16 v[96:99], v[168:171], v[208:211], v[96:99]
	v_mfma_f32_16x16x32_bf16 v[84:87], v[144:147], v[216:219], v[84:87]
	v_mfma_f32_16x16x32_bf16 v[80:83], v[168:171], v[216:219], v[80:83]
	v_mfma_f32_16x16x32_bf16 v[132:135], v[148:151], v[190:193], v[132:135]
	v_mfma_f32_16x16x32_bf16 v[128:131], v[178:181], v[190:193], v[128:131]
	v_mfma_f32_16x16x32_bf16 v[116:119], v[148:151], v[202:205], v[116:119]
	v_mfma_f32_16x16x32_bf16 v[112:115], v[178:181], v[202:205], v[112:115]
	v_mfma_f32_16x16x32_bf16 v[100:103], v[148:151], v[212:215], v[100:103]
	v_mfma_f32_16x16x32_bf16 v[96:99], v[178:181], v[212:215], v[96:99]
	v_mfma_f32_16x16x32_bf16 v[84:87], v[148:151], v[220:223], v[84:87]
	v_mfma_f32_16x16x32_bf16 v[80:83], v[178:181], v[220:223], v[80:83]
	s_barrier
	s_add_i32 s81, s73, s58
	v_lshl_add_u64 v[174:175], s[54:55], 0, v[154:155]
	s_mov_b32 m0, s81
	ds_read_b128 v[184:187], v201 offset:16384
	ds_read_b128 v[190:193], v201 offset:17408
	ds_read_b128 v[196:199], v201 offset:18432
	ds_read_b128 v[202:205], v201 offset:19456
	ds_read_b128 v[208:211], v201 offset:20480
	ds_read_b128 v[212:215], v201 offset:21504
	ds_read_b128 v[216:219], v201 offset:22528
	ds_read_b128 v[220:223], v201 offset:23552
	global_load_lds_dwordx4 v[174:175], off
	s_add_i32 m0, s81, 0x2000
	s_add_u32 s82, s54, 0x40000
	v_lshl_add_u64 v[224:225], s[54:55], 0, v[158:159]
	s_addc_u32 s83, s55, 0
	s_add_i32 s81, s74, s58
	global_load_lds_dwordx4 v[224:225], off
	s_mov_b32 m0, s81
	v_lshl_add_u64 v[228:229], s[56:57], 0, v[156:157]
	global_load_lds_dwordx4 v154, s[82:83]
	s_add_i32 m0, s81, 0x2000
	s_nop 0
	global_load_lds_dwordx4 v158, s[82:83]
	v_lshl_add_u64 v[226:227], s[56:57], 0, v[152:153]
	s_mov_b32 m0, s43
	s_nop 0
	global_load_lds_dwordx4 v[226:227], off
	s_mov_b32 m0, s59
	s_nop 0
	global_load_lds_dwordx4 v[228:229], off
	s_waitcnt vmcnt(8)
	s_waitcnt lgkmcnt(0)
	s_barrier
	s_waitcnt lgkmcnt(0)
	v_mfma_f32_16x16x32_bf16 v[68:71], v[56:59], v[184:187], v[68:71]
	v_mfma_f32_16x16x32_bf16 v[64:67], v[72:75], v[184:187], v[64:67]
	v_mfma_f32_16x16x32_bf16 v[44:47], v[56:59], v[196:199], v[44:47]
	v_mfma_f32_16x16x32_bf16 v[40:43], v[72:75], v[196:199], v[40:43]
	v_mfma_f32_16x16x32_bf16 v[28:31], v[56:59], v[208:211], v[28:31]
	v_mfma_f32_16x16x32_bf16 v[24:27], v[72:75], v[208:211], v[24:27]
	v_mfma_f32_16x16x32_bf16 v[12:15], v[56:59], v[216:219], v[12:15]
	v_mfma_f32_16x16x32_bf16 v[8:11], v[72:75], v[216:219], v[8:11]
	v_mfma_f32_16x16x32_bf16 v[68:71], v[60:63], v[190:193], v[68:71]
	v_mfma_f32_16x16x32_bf16 v[64:67], v[76:79], v[190:193], v[64:67]
	v_mfma_f32_16x16x32_bf16 v[44:47], v[60:63], v[202:205], v[44:47]
	v_mfma_f32_16x16x32_bf16 v[40:43], v[76:79], v[202:205], v[40:43]
	v_mfma_f32_16x16x32_bf16 v[28:31], v[60:63], v[212:215], v[28:31]
	v_mfma_f32_16x16x32_bf16 v[24:27], v[76:79], v[212:215], v[24:27]
	v_mfma_f32_16x16x32_bf16 v[12:15], v[60:63], v[220:223], v[12:15]
	v_mfma_f32_16x16x32_bf16 v[8:11], v[76:79], v[220:223], v[8:11]
	v_mfma_f32_16x16x32_bf16 v[52:55], v[144:147], v[184:187], v[52:55]
	v_mfma_f32_16x16x32_bf16 v[48:51], v[168:171], v[184:187], v[48:51]
	v_mfma_f32_16x16x32_bf16 v[36:39], v[144:147], v[196:199], v[36:39]
	v_mfma_f32_16x16x32_bf16 v[32:35], v[168:171], v[196:199], v[32:35]
	v_mfma_f32_16x16x32_bf16 v[20:23], v[144:147], v[208:211], v[20:23]
	v_mfma_f32_16x16x32_bf16 v[16:19], v[168:171], v[208:211], v[16:19]
	v_mfma_f32_16x16x32_bf16 v[4:7], v[144:147], v[216:219], v[4:7]
	v_mfma_f32_16x16x32_bf16 v[0:3], v[168:171], v[216:219], v[0:3]
	v_mfma_f32_16x16x32_bf16 v[52:55], v[148:151], v[190:193], v[52:55]
	v_mfma_f32_16x16x32_bf16 v[48:51], v[178:181], v[190:193], v[48:51]
	v_mfma_f32_16x16x32_bf16 v[36:39], v[148:151], v[202:205], v[36:39]
	v_mfma_f32_16x16x32_bf16 v[32:35], v[178:181], v[202:205], v[32:35]
	v_mfma_f32_16x16x32_bf16 v[20:23], v[148:151], v[212:215], v[20:23]
	v_mfma_f32_16x16x32_bf16 v[16:19], v[178:181], v[212:215], v[16:19]
	v_mfma_f32_16x16x32_bf16 v[4:7], v[148:151], v[220:223], v[4:7]
	v_mfma_f32_16x16x32_bf16 v[0:3], v[178:181], v[220:223], v[0:3]
	s_barrier
; #define PG8_STAGE(bufoff, gbase, voff) do { _Pragma("unroll") for (int _i = 0; _i < 2; ++_i) \
;         __builtin_amdgcn_global_load_lds((const unsigned*)((const char*)(gbase) + (voff)[_i]), (LAS unsigned*)(lds + (bufoff) + ldsw + _i * 8192), 16, 0, 0); } while (0)
; #define PG8_LDA(dst, b, h) do { _Pragma("unroll") for (int m = 0; m < 4; ++m) _Pragma("unroll") for (int k = 0; k < 2; ++k) dst[m][k] = *(const LAS bf16x8*)(lds + PG8_SA(b, h) + aoff + m * 2048 + k * 1024); } while (0)
; #define PG8_LDB(dst, b, h) do { _Pragma("unroll") for (int n = 0; n < 2; ++n) _Pragma("unroll") for (int k = 0; k < 2; ++k) dst[n][k] = *(const LAS bf16x8*)(lds + PG8_SB(b, h) + boff + n * 2048 + k * 1024); } while (0)
; #define PG8_MMA(ai, bj, At, Bt) do { __builtin_amdgcn_s_setprio(1); _Pragma("unroll") for (int m = 0; m < 4; ++m) _Pragma("unroll") for (int n = 0; n < 2; ++n) _Pragma("unroll") for (int k = 0; k < 2; ++k) \
;         acc[ai][bj][m][n] = __builtin_amdgcn_mfma_f32_16x16x32_bf16(Bt[n][k], At[m][k], acc[ai][bj][m][n], 0, 0, 0); __builtin_amdgcn_s_setprio(0); } while (0)
; #define PG8_WAIT_V(n) asm volatile("s_waitcnt vmcnt(" #n ")" ::: "memory")
; #define PG8_WAIT_L(n) asm volatile("s_waitcnt lgkmcnt(" #n ")" ::: "memory")
; #define PG8_BAR __builtin_amdgcn_s_barrier()
; #define PG8_SCHED __builtin_amdgcn_sched_barrier(0)
; template <class Epi>
; __device__ __forceinline__ void gemm_phase(LAS unsigned char* lds, const Gemm g, const StaticOrder& S, const Epi& E) {
;     ...
;             PG8_LDB(B0, 1, 0); PG8_LDB(B1, 1, 1); PG8_SCHED; PG8_LDA(At, 1, 0); PG8_STAGE(PG8_SA(0, 1), a2 + hstepA, voffA);
;             PG8_WAIT_V(8); PG8_WAIT_L(0); PG8_BAR; PG8_MMA(0, 0, At, B0); PG8_MMA(0, 1, At, B1); PG8_BAR; PG8_SCHED;
;             PG8_LDA(At, 1, 1); PG8_STAGE(PG8_SB(1, 0), b3, voffB); PG8_STAGE(PG8_SB(1, 1), b3 + hstepB, voffB); PG8_STAGE(PG8_SA(1, 0), a3, voffA);
;             PG8_WAIT_V(8); PG8_WAIT_L(0); PG8_BAR; PG8_MMA(1, 0, At, B0); PG8_MMA(1, 1, At, B1); PG8_BAR; PG8_SCHED;
;         }
	s_add_i32 s81, 0, 0x18000
	s_add_i32 s82, 0, 0x1c000
	v_add_u32_e32 v76, s81, v183
	v_add_u32_e32 v172, s82, v183
	ds_read_b128 v[56:59], v76
	ds_read_b128 v[60:63], v76 offset:1024
	ds_read_b128 v[72:75], v76 offset:2048
	ds_read_b128 v[76:79], v76 offset:3072
	ds_read_b128 v[144:147], v172
	ds_read_b128 v[148:151], v172 offset:1024
	ds_read_b128 v[168:171], v172 offset:2048
	ds_read_b128 v[178:181], v172 offset:3072
	s_add_u32 s56, s56, 0x40000
	s_addc_u32 s57, s57, 0
	s_mov_b32 m0, s62
	ds_read_b128 v[184:187], v201 offset:32768
	ds_read_b128 v[190:193], v201 offset:33792
	ds_read_b128 v[196:199], v201 offset:34816
	ds_read_b128 v[202:205], v201 offset:35840
	ds_read_b128 v[208:211], v201 offset:36864
	ds_read_b128 v[212:215], v201 offset:37888
	ds_read_b128 v[216:219], v201 offset:38912
	ds_read_b128 v[220:223], v201 offset:39936
	global_load_lds_dwordx4 v152, s[56:57]
	s_mov_b32 m0, s63
	s_nop 0
	global_load_lds_dwordx4 v156, s[56:57]
	s_waitcnt vmcnt(8)
	s_waitcnt lgkmcnt(0)
	s_barrier
	s_waitcnt lgkmcnt(0)
	v_mfma_f32_16x16x32_bf16 v[140:143], v[56:59], v[184:187], v[140:143]
	v_mfma_f32_16x16x32_bf16 v[136:139], v[72:75], v[184:187], v[136:139]
	v_mfma_f32_16x16x32_bf16 v[124:127], v[56:59], v[196:199], v[124:127]
	v_mfma_f32_16x16x32_bf16 v[120:123], v[72:75], v[196:199], v[120:123]
	v_mfma_f32_16x16x32_bf16 v[108:111], v[56:59], v[208:211], v[108:111]
	v_mfma_f32_16x16x32_bf16 v[104:107], v[72:75], v[208:211], v[104:107]
	v_mfma_f32_16x16x32_bf16 v[92:95], v[56:59], v[216:219], v[92:95]
	v_mfma_f32_16x16x32_bf16 v[88:91], v[72:75], v[216:219], v[88:91]
	v_mfma_f32_16x16x32_bf16 v[140:143], v[60:63], v[190:193], v[140:143]
	v_mfma_f32_16x16x32_bf16 v[136:139], v[76:79], v[190:193], v[136:139]
	v_mfma_f32_16x16x32_bf16 v[124:127], v[60:63], v[202:205], v[124:127]
	v_mfma_f32_16x16x32_bf16 v[120:123], v[76:79], v[202:205], v[120:123]
	v_mfma_f32_16x16x32_bf16 v[108:111], v[60:63], v[212:215], v[108:111]
	v_mfma_f32_16x16x32_bf16 v[104:107], v[76:79], v[212:215], v[104:107]
	v_mfma_f32_16x16x32_bf16 v[92:95], v[60:63], v[220:223], v[92:95]
	v_mfma_f32_16x16x32_bf16 v[88:91], v[76:79], v[220:223], v[88:91]
	v_mfma_f32_16x16x32_bf16 v[132:135], v[144:147], v[184:187], v[132:135]
	v_mfma_f32_16x16x32_bf16 v[128:131], v[168:171], v[184:187], v[128:131]
	v_mfma_f32_16x16x32_bf16 v[116:119], v[144:147], v[196:199], v[116:119]
	v_mfma_f32_16x16x32_bf16 v[112:115], v[168:171], v[196:199], v[112:115]
	v_mfma_f32_16x16x32_bf16 v[100:103], v[144:147], v[208:211], v[100:103]
	v_mfma_f32_16x16x32_bf16 v[96:99], v[168:171], v[208:211], v[96:99]
	v_mfma_f32_16x16x32_bf16 v[84:87], v[144:147], v[216:219], v[84:87]
	v_mfma_f32_16x16x32_bf16 v[80:83], v[168:171], v[216:219], v[80:83]
	v_mfma_f32_16x16x32_bf16 v[132:135], v[148:151], v[190:193], v[132:135]
	v_mfma_f32_16x16x32_bf16 v[128:131], v[178:181], v[190:193], v[128:131]
	v_mfma_f32_16x16x32_bf16 v[116:119], v[148:151], v[202:205], v[116:119]
	v_mfma_f32_16x16x32_bf16 v[112:115], v[178:181], v[202:205], v[112:115]
	v_mfma_f32_16x16x32_bf16 v[100:103], v[148:151], v[212:215], v[100:103]
	v_mfma_f32_16x16x32_bf16 v[96:99], v[178:181], v[212:215], v[96:99]
	v_mfma_f32_16x16x32_bf16 v[84:87], v[148:151], v[220:223], v[84:87]
	v_mfma_f32_16x16x32_bf16 v[80:83], v[178:181], v[220:223], v[80:83]
	s_barrier
	s_add_i32 s56, s81, s58
	v_lshl_add_u64 v[174:175], v[174:175], 0, s[12:13]
	s_mov_b32 m0, s56
	ds_read_b128 v[184:187], v201 offset:49152
	ds_read_b128 v[190:193], v201 offset:50176
	ds_read_b128 v[196:199], v201 offset:51200
	ds_read_b128 v[202:205], v201 offset:52224
	ds_read_b128 v[208:211], v201 offset:53248
	ds_read_b128 v[212:215], v201 offset:54272
	ds_read_b128 v[216:219], v201 offset:55296
	ds_read_b128 v[220:223], v201 offset:56320
	global_load_lds_dwordx4 v[174:175], off
	s_add_i32 m0, s56, 0x2000
	s_add_u32 s54, s54, 0x40080
	v_lshl_add_u64 v[174:175], v[224:225], 0, s[12:13]
	s_addc_u32 s55, s55, 0
	s_add_i32 s56, s82, s58
	global_load_lds_dwordx4 v[174:175], off
	s_mov_b32 m0, s56
	s_nop 0
	global_load_lds_dwordx4 v154, s[54:55]
	s_add_i32 m0, s56, 0x2000
	s_nop 0
	global_load_lds_dwordx4 v158, s[54:55]
	v_lshl_add_u64 v[174:175], v[226:227], 0, s[12:13]
	s_mov_b32 m0, s69
	s_nop 0
	global_load_lds_dwordx4 v[174:175], off
	v_lshl_add_u64 v[174:175], v[228:229], 0, s[12:13]
	s_mov_b32 m0, s70
	s_nop 0
	global_load_lds_dwordx4 v[174:175], off
	s_waitcnt vmcnt(8)
	s_waitcnt lgkmcnt(0)
	s_barrier
	s_waitcnt lgkmcnt(0)
	v_mfma_f32_16x16x32_bf16 v[68:71], v[56:59], v[184:187], v[68:71]
	v_mfma_f32_16x16x32_bf16 v[64:67], v[72:75], v[184:187], v[64:67]
	v_mfma_f32_16x16x32_bf16 v[44:47], v[56:59], v[196:199], v[44:47]
	v_mfma_f32_16x16x32_bf16 v[40:43], v[72:75], v[196:199], v[40:43]
	v_mfma_f32_16x16x32_bf16 v[28:31], v[56:59], v[208:211], v[28:31]
	v_mfma_f32_16x16x32_bf16 v[24:27], v[72:75], v[208:211], v[24:27]
	v_mfma_f32_16x16x32_bf16 v[12:15], v[56:59], v[216:219], v[12:15]
	v_mfma_f32_16x16x32_bf16 v[8:11], v[72:75], v[216:219], v[8:11]
	v_mfma_f32_16x16x32_bf16 v[68:71], v[60:63], v[190:193], v[68:71]
	v_mfma_f32_16x16x32_bf16 v[64:67], v[76:79], v[190:193], v[64:67]
	v_mfma_f32_16x16x32_bf16 v[44:47], v[60:63], v[202:205], v[44:47]
	v_mfma_f32_16x16x32_bf16 v[40:43], v[76:79], v[202:205], v[40:43]
	v_mfma_f32_16x16x32_bf16 v[28:31], v[60:63], v[212:215], v[28:31]
	v_mfma_f32_16x16x32_bf16 v[24:27], v[76:79], v[212:215], v[24:27]
	v_mfma_f32_16x16x32_bf16 v[12:15], v[60:63], v[220:223], v[12:15]
	v_mfma_f32_16x16x32_bf16 v[8:11], v[76:79], v[220:223], v[8:11]
	v_mfma_f32_16x16x32_bf16 v[52:55], v[144:147], v[184:187], v[52:55]
	v_mfma_f32_16x16x32_bf16 v[48:51], v[168:171], v[184:187], v[48:51]
	v_mfma_f32_16x16x32_bf16 v[36:39], v[144:147], v[196:199], v[36:39]
	v_mfma_f32_16x16x32_bf16 v[32:35], v[168:171], v[196:199], v[32:35]
	v_mfma_f32_16x16x32_bf16 v[20:23], v[144:147], v[208:211], v[20:23]
	v_mfma_f32_16x16x32_bf16 v[16:19], v[168:171], v[208:211], v[16:19]
	v_mfma_f32_16x16x32_bf16 v[4:7], v[144:147], v[216:219], v[4:7]
	v_mfma_f32_16x16x32_bf16 v[0:3], v[168:171], v[216:219], v[0:3]
	v_mfma_f32_16x16x32_bf16 v[52:55], v[148:151], v[190:193], v[52:55]
	v_mfma_f32_16x16x32_bf16 v[48:51], v[178:181], v[190:193], v[48:51]
	v_mfma_f32_16x16x32_bf16 v[36:39], v[148:151], v[202:205], v[36:39]
	v_mfma_f32_16x16x32_bf16 v[32:35], v[178:181], v[202:205], v[32:35]
	v_mfma_f32_16x16x32_bf16 v[20:23], v[148:151], v[212:215], v[20:23]
	v_mfma_f32_16x16x32_bf16 v[16:19], v[178:181], v[212:215], v[16:19]
	v_mfma_f32_16x16x32_bf16 v[4:7], v[148:151], v[220:223], v[4:7]
	v_mfma_f32_16x16x32_bf16 v[0:3], v[178:181], v[220:223], v[0:3]
	s_barrier
	s_add_i32 s80, s80, 2
	s_add_u32 s52, s52, 0x100
	s_addc_u32 s53, s53, 0
	s_add_u32 s78, s78, 0x100
	s_addc_u32 s79, s79, 0
	s_cmp_gt_u32 s80, 13
	s_cbranch_scc0 .LBB0_1233
	s_and_b64 vcc, exec, s[14:15]
	s_cbranch_vccz .LBB0_1236
	s_barrier

; #define PG8_STAGE(bufoff, gbase, voff) do { _Pragma("unroll") for (int _i = 0; _i < 2; ++_i) \
;         __builtin_amdgcn_global_load_lds((const unsigned*)((const char*)(gbase) + (voff)[_i]), (LAS unsigned*)(lds + (bufoff) + ldsw + _i * 8192), 16, 0, 0); } while (0)
; #define PG8_LDA(dst, b, h) do { _Pragma("unroll") for (int m = 0; m < 4; ++m) _Pragma("unroll") for (int k = 0; k < 2; ++k) dst[m][k] = *(const LAS bf16x8*)(lds + PG8_SA(b, h) + aoff + m * 2048 + k * 1024); } while (0)
; #define PG8_LDB(dst, b, h) do { _Pragma("unroll") for (int n = 0; n < 2; ++n) _Pragma("unroll") for (int k = 0; k < 2; ++k) dst[n][k] = *(const LAS bf16x8*)(lds + PG8_SB(b, h) + boff + n * 2048 + k * 1024); } while (0)
; #define PG8_MMA(ai, bj, At, Bt) do { __builtin_amdgcn_s_setprio(1); _Pragma("unroll") for (int m = 0; m < 4; ++m) _Pragma("unroll") for (int n = 0; n < 2; ++n) _Pragma("unroll") for (int k = 0; k < 2; ++k) \
;         acc[ai][bj][m][n] = __builtin_amdgcn_mfma_f32_16x16x32_bf16(Bt[n][k], At[m][k], acc[ai][bj][m][n], 0, 0, 0); __builtin_amdgcn_s_setprio(0); } while (0)
; #define PG8_WAIT_V(n) asm volatile("s_waitcnt vmcnt(" #n ")" ::: "memory")
; #define PG8_WAIT_L(n) asm volatile("s_waitcnt lgkmcnt(" #n ")" ::: "memory")
; template <class Epi>
; __device__ __forceinline__ void gemm_phase(LAS unsigned char* lds, const Gemm g, const StaticOrder& S, const Epi& E) {
;     ...
;     for (;;) {
;         const bool has_next = S.next(ui + 1, nxt);
;         const char* nA = has_next ? (const char*)g.A + (size_t)nxt.pm * tstepA : cA; const char* nB = has_next ? (const char*)g.Bt + (size_t)nxt.pn * tstepB : cB;
; #pragma nounroll
;         for (int t = 0; t < nt; t += 2) {
;             const bool last = (t == nt - 2);
;             const char* a1 = cA + (size_t)(t + 1) * kstep;
;             const char* a2 = last ? nA : cA + (size_t)(t + 2) * kstep; const char* b2 = last ? nB : cB + (size_t)(t + 2) * kstep;
;             const char* a3 = a2 + kstep; const char* b3 = b2 + kstep;
;             PG8_LDB(B0, 0, 0); PG8_LDB(B1, 0, 1); PG8_SCHED; PG8_LDA(At, 0, 0); PG8_STAGE(PG8_SA(1, 1), a1 + hstepA, voffA);
;             PG8_WAIT_V(8); PG8_WAIT_L(0); PG8_BAR; PG8_MMA(0, 0, At, B0); PG8_MMA(0, 1, At, B1); PG8_BAR; PG8_SCHED;
;             PG8_LDA(At, 0, 1); PG8_STAGE(PG8_SB(0, 0), b2, voffB); PG8_STAGE(PG8_SB(0, 1), b2 + hstepB, voffB); PG8_STAGE(PG8_SA(0, 0), a2, voffA);
.LBB0_1313:
	s_ashr_i32 s19, s18, 31
	s_lshl_b64 s[20:21], s[18:19], 21
	s_add_u32 s20, s26, s20
	s_addc_u32 s21, s27, s21
	s_and_b64 s[22:23], s[4:5], exec
	s_cselect_b32 s1, s21, s39
	s_cselect_b32 s19, s20, s38
	s_ashr_i32 s17, s16, 31
	s_lshl_b64 s[22:23], s[16:17], 20
	s_add_u32 s22, s3, s22
	s_addc_u32 s23, s33, s23
	s_and_b64 s[52:53], s[4:5], exec
	s_cselect_b32 s17, s23, s43
	s_cselect_b32 s70, s22, s42
	s_add_u32 s38, s38, 0x100080
	s_addc_u32 s39, s39, 0
	s_add_u32 s71, s42, 0x100
	s_addc_u32 s72, s43, 0
	s_mov_b32 s73, -2
	s_waitcnt lgkmcnt(0)
	ds_read_b128 v[128:131], v182
	ds_read_b128 v[132:135], v182 offset:1024
	ds_read_b128 v[136:139], v182 offset:2048
	ds_read_b128 v[140:143], v182 offset:3072
	ds_read_b128 v[160:163], v183
	ds_read_b128 v[164:167], v183 offset:1024
	ds_read_b128 v[168:171], v183 offset:2048
	ds_read_b128 v[172:175], v183 offset:3072
	s_add_u32 s42, s38, 0xfff00080
	s_addc_u32 s43, s39, -1
	s_cmp_eq_u32 s73, 28
	s_cselect_b32 s53, s1, s43
	s_cselect_b32 s52, s19, s42
	s_cselect_b32 s43, s17, s72
	s_cselect_b32 s42, s70, s71
	s_add_i32 m0, s35, 0xc000
	ds_read_b128 v[186:189], v184
	ds_read_b128 v[190:193], v184 offset:1024
	ds_read_b128 v[194:197], v184 offset:2048
	ds_read_b128 v[198:201], v184 offset:3072
	ds_read_b128 v[202:205], v184 offset:4096
	ds_read_b128 v[206:209], v184 offset:5120
	ds_read_b128 v[210:213], v184 offset:6144
	ds_read_b128 v[214:217], v184 offset:7168
	global_load_lds_dwordx4 v152, s[38:39]
	s_add_i32 m0, s35, 0xe000
	s_nop 0
	global_load_lds_dwordx4 v154, s[38:39]
	s_waitcnt vmcnt(8)
	s_waitcnt lgkmcnt(0)
	s_barrier
	s_waitcnt lgkmcnt(0)
	v_mfma_f32_16x16x32_bf16 v[124:127], v[128:131], v[186:189], 0
	v_mfma_f32_16x16x32_bf16 v[120:123], v[136:139], v[186:189], 0
	v_mfma_f32_16x16x32_bf16 v[108:111], v[128:131], v[194:197], 0
	v_mfma_f32_16x16x32_bf16 v[104:107], v[136:139], v[194:197], 0
	v_mfma_f32_16x16x32_bf16 v[92:95], v[128:131], v[202:205], 0
	v_mfma_f32_16x16x32_bf16 v[88:91], v[136:139], v[202:205], 0
	v_mfma_f32_16x16x32_bf16 v[76:79], v[128:131], v[210:213], 0
	v_mfma_f32_16x16x32_bf16 v[72:75], v[136:139], v[210:213], 0
	v_mfma_f32_16x16x32_bf16 v[124:127], v[132:135], v[190:193], v[124:127]
	v_mfma_f32_16x16x32_bf16 v[120:123], v[140:143], v[190:193], v[120:123]
	v_mfma_f32_16x16x32_bf16 v[108:111], v[132:135], v[198:201], v[108:111]
	v_mfma_f32_16x16x32_bf16 v[104:107], v[140:143], v[198:201], v[104:107]
	v_mfma_f32_16x16x32_bf16 v[92:95], v[132:135], v[206:209], v[92:95]
	v_mfma_f32_16x16x32_bf16 v[88:91], v[140:143], v[206:209], v[88:91]
	v_mfma_f32_16x16x32_bf16 v[76:79], v[132:135], v[214:217], v[76:79]
	v_mfma_f32_16x16x32_bf16 v[72:75], v[140:143], v[214:217], v[72:75]
	v_mfma_f32_16x16x32_bf16 v[116:119], v[160:163], v[186:189], 0
	v_mfma_f32_16x16x32_bf16 v[112:115], v[168:171], v[186:189], 0
	v_mfma_f32_16x16x32_bf16 v[100:103], v[160:163], v[194:197], 0
	v_mfma_f32_16x16x32_bf16 v[96:99], v[168:171], v[194:197], 0
	v_mfma_f32_16x16x32_bf16 v[84:87], v[160:163], v[202:205], 0
	v_mfma_f32_16x16x32_bf16 v[80:83], v[168:171], v[202:205], 0
	v_mfma_f32_16x16x32_bf16 v[68:71], v[160:163], v[210:213], 0
	v_mfma_f32_16x16x32_bf16 v[64:67], v[168:171], v[210:213], 0
	v_mfma_f32_16x16x32_bf16 v[116:119], v[164:167], v[190:193], v[116:119]
	v_mfma_f32_16x16x32_bf16 v[112:115], v[172:175], v[190:193], v[112:115]
	v_mfma_f32_16x16x32_bf16 v[100:103], v[164:167], v[198:201], v[100:103]
	v_mfma_f32_16x16x32_bf16 v[96:99], v[172:175], v[198:201], v[96:99]
	v_mfma_f32_16x16x32_bf16 v[84:87], v[164:167], v[206:209], v[84:87]
	v_mfma_f32_16x16x32_bf16 v[80:83], v[172:175], v[206:209], v[80:83]
	v_mfma_f32_16x16x32_bf16 v[68:71], v[164:167], v[214:217], v[68:71]
	v_mfma_f32_16x16x32_bf16 v[64:67], v[172:175], v[214:217], v[64:67]
	s_barrier
	s_add_i32 s74, s68, s54
	v_lshl_add_u64 v[178:179], s[42:43], 0, v[146:147]
	s_mov_b32 m0, s74
	ds_read_b128 v[186:189], v184 offset:16384
	ds_read_b128 v[190:193], v184 offset:17408
	ds_read_b128 v[194:197], v184 offset:18432
	ds_read_b128 v[198:201], v184 offset:19456
	ds_read_b128 v[202:205], v184 offset:20480
	ds_read_b128 v[206:209], v184 offset:21504
	ds_read_b128 v[210:213], v184 offset:22528
	ds_read_b128 v[214:217], v184 offset:23552
	global_load_lds_dwordx4 v[178:179], off
	s_add_i32 m0, s74, 0x2000
	s_add_u32 s74, s42, 0x80000
	v_lshl_add_u64 v[218:219], s[42:43], 0, v[150:151]
	s_addc_u32 s75, s43, 0
	s_add_i32 s76, s69, s54
	global_load_lds_dwordx4 v[218:219], off
	s_mov_b32 m0, s76
	v_lshl_add_u64 v[222:223], s[52:53], 0, v[148:149]
	global_load_lds_dwordx4 v146, s[74:75]
	s_add_i32 m0, s76, 0x2000
	s_nop 0
	global_load_lds_dwordx4 v150, s[74:75]
	v_lshl_add_u64 v[220:221], s[52:53], 0, v[144:145]
	s_mov_b32 m0, s35
	s_nop 0
	global_load_lds_dwordx4 v[220:221], off
	s_mov_b32 m0, s55
	s_nop 0
	global_load_lds_dwordx4 v[222:223], off
	s_waitcnt vmcnt(8)
	s_waitcnt lgkmcnt(0)
	s_barrier
; #define PG8_STAGE(bufoff, gbase, voff) do { _Pragma("unroll") for (int _i = 0; _i < 2; ++_i) \
;         __builtin_amdgcn_global_load_lds((const unsigned*)((const char*)(gbase) + (voff)[_i]), (LAS unsigned*)(lds + (bufoff) + ldsw + _i * 8192), 16, 0, 0); } while (0)
; #define PG8_LDA(dst, b, h) do { _Pragma("unroll") for (int m = 0; m < 4; ++m) _Pragma("unroll") for (int k = 0; k < 2; ++k) dst[m][k] = *(const LAS bf16x8*)(lds + PG8_SA(b, h) + aoff + m * 2048 + k * 1024); } while (0)
; #define PG8_LDB(dst, b, h) do { _Pragma("unroll") for (int n = 0; n < 2; ++n) _Pragma("unroll") for (int k = 0; k < 2; ++k) dst[n][k] = *(const LAS bf16x8*)(lds + PG8_SB(b, h) + boff + n * 2048 + k * 1024); } while (0)
; #define PG8_MMA(ai, bj, At, Bt) do { __builtin_amdgcn_s_setprio(1); _Pragma("unroll") for (int m = 0; m < 4; ++m) _Pragma("unroll") for (int n = 0; n < 2; ++n) _Pragma("unroll") for (int k = 0; k < 2; ++k) \
;         acc[ai][bj][m][n] = __builtin_amdgcn_mfma_f32_16x16x32_bf16(Bt[n][k], At[m][k], acc[ai][bj][m][n], 0, 0, 0); __builtin_amdgcn_s_setprio(0); } while (0)
; #define PG8_WAIT_V(n) asm volatile("s_waitcnt vmcnt(" #n ")" ::: "memory")
; #define PG8_WAIT_L(n) asm volatile("s_waitcnt lgkmcnt(" #n ")" ::: "memory")
; #define PG8_BAR __builtin_amdgcn_s_barrier()
; #define PG8_SCHED __builtin_amdgcn_sched_barrier(0)
; template <class Epi>
; __device__ __forceinline__ void gemm_phase(LAS unsigned char* lds, const Gemm g, const StaticOrder& S, const Epi& E) {
;     ...
;             PG8_WAIT_V(8); PG8_WAIT_L(0); PG8_BAR; PG8_MMA(1, 0, At, B0); PG8_MMA(1, 1, At, B1); PG8_BAR; PG8_SCHED;
;             PG8_LDB(B0, 1, 0); PG8_LDB(B1, 1, 1); PG8_SCHED; PG8_LDA(At, 1, 0); PG8_STAGE(PG8_SA(0, 1), a2 + hstepA, voffA);
;             PG8_WAIT_V(8); PG8_WAIT_L(0); PG8_BAR; PG8_MMA(0, 0, At, B0); PG8_MMA(0, 1, At, B1); PG8_BAR; PG8_SCHED;
	s_waitcnt lgkmcnt(0)
	v_mfma_f32_16x16x32_bf16 v[60:63], v[128:131], v[186:189], 0
	v_mfma_f32_16x16x32_bf16 v[56:59], v[136:139], v[186:189], 0
	v_mfma_f32_16x16x32_bf16 v[44:47], v[128:131], v[194:197], 0
	v_mfma_f32_16x16x32_bf16 v[40:43], v[136:139], v[194:197], 0
	v_mfma_f32_16x16x32_bf16 v[28:31], v[128:131], v[202:205], 0
	v_mfma_f32_16x16x32_bf16 v[24:27], v[136:139], v[202:205], 0
	v_mfma_f32_16x16x32_bf16 v[12:15], v[128:131], v[210:213], 0
	v_mfma_f32_16x16x32_bf16 v[8:11], v[136:139], v[210:213], 0
	v_mfma_f32_16x16x32_bf16 v[60:63], v[132:135], v[190:193], v[60:63]
	v_mfma_f32_16x16x32_bf16 v[56:59], v[140:143], v[190:193], v[56:59]
	v_mfma_f32_16x16x32_bf16 v[44:47], v[132:135], v[198:201], v[44:47]
	v_mfma_f32_16x16x32_bf16 v[40:43], v[140:143], v[198:201], v[40:43]
	v_mfma_f32_16x16x32_bf16 v[28:31], v[132:135], v[206:209], v[28:31]
	v_mfma_f32_16x16x32_bf16 v[24:27], v[140:143], v[206:209], v[24:27]
	v_mfma_f32_16x16x32_bf16 v[12:15], v[132:135], v[214:217], v[12:15]
	v_mfma_f32_16x16x32_bf16 v[8:11], v[140:143], v[214:217], v[8:11]
	v_mfma_f32_16x16x32_bf16 v[52:55], v[160:163], v[186:189], 0
	v_mfma_f32_16x16x32_bf16 v[48:51], v[168:171], v[186:189], 0
	v_mfma_f32_16x16x32_bf16 v[36:39], v[160:163], v[194:197], 0
	v_mfma_f32_16x16x32_bf16 v[32:35], v[168:171], v[194:197], 0
	v_mfma_f32_16x16x32_bf16 v[20:23], v[160:163], v[202:205], 0
	v_mfma_f32_16x16x32_bf16 v[16:19], v[168:171], v[202:205], 0
	v_mfma_f32_16x16x32_bf16 v[4:7], v[160:163], v[210:213], 0
	v_mfma_f32_16x16x32_bf16 v[0:3], v[168:171], v[210:213], 0
	v_mfma_f32_16x16x32_bf16 v[52:55], v[164:167], v[190:193], v[52:55]
	v_mfma_f32_16x16x32_bf16 v[48:51], v[172:175], v[190:193], v[48:51]
	v_mfma_f32_16x16x32_bf16 v[36:39], v[164:167], v[198:201], v[36:39]
	v_mfma_f32_16x16x32_bf16 v[32:35], v[172:175], v[198:201], v[32:35]
	v_mfma_f32_16x16x32_bf16 v[20:23], v[164:167], v[206:209], v[20:23]
	v_mfma_f32_16x16x32_bf16 v[16:19], v[172:175], v[206:209], v[16:19]
	v_mfma_f32_16x16x32_bf16 v[4:7], v[164:167], v[214:217], v[4:7]
	v_mfma_f32_16x16x32_bf16 v[0:3], v[172:175], v[214:217], v[0:3]
	s_barrier
	s_add_i32 s74, 0, 0x18000
	s_add_i32 s75, 0, 0x1c000
	v_add_u32_e32 v140, s74, v181
	v_add_u32_e32 v172, s75, v181
	ds_read_b128 v[128:131], v140
	ds_read_b128 v[132:135], v140 offset:1024
	ds_read_b128 v[136:139], v140 offset:2048
	ds_read_b128 v[140:143], v140 offset:3072
	ds_read_b128 v[160:163], v172
	ds_read_b128 v[164:167], v172 offset:1024
	ds_read_b128 v[168:171], v172 offset:2048
	ds_read_b128 v[172:175], v172 offset:3072
	s_add_u32 s52, s52, 0x100000
	s_addc_u32 s53, s53, 0
	s_mov_b32 m0, s56
	ds_read_b128 v[186:189], v184 offset:32768
	ds_read_b128 v[190:193], v184 offset:33792
	ds_read_b128 v[194:197], v184 offset:34816
	ds_read_b128 v[198:201], v184 offset:35840
	ds_read_b128 v[202:205], v184 offset:36864
	ds_read_b128 v[206:209], v184 offset:37888
	ds_read_b128 v[210:213], v184 offset:38912
	ds_read_b128 v[214:217], v184 offset:39936
	global_load_lds_dwordx4 v144, s[52:53]
	s_mov_b32 m0, s57
	s_nop 0
	global_load_lds_dwordx4 v148, s[52:53]
	s_waitcnt vmcnt(8)
	s_waitcnt lgkmcnt(0)
	s_barrier
	s_waitcnt lgkmcnt(0)
	v_mfma_f32_16x16x32_bf16 v[124:127], v[128:131], v[186:189], v[124:127]
	v_mfma_f32_16x16x32_bf16 v[120:123], v[136:139], v[186:189], v[120:123]
	v_mfma_f32_16x16x32_bf16 v[108:111], v[128:131], v[194:197], v[108:111]
	v_mfma_f32_16x16x32_bf16 v[104:107], v[136:139], v[194:197], v[104:107]
	v_mfma_f32_16x16x32_bf16 v[92:95], v[128:131], v[202:205], v[92:95]
	v_mfma_f32_16x16x32_bf16 v[88:91], v[136:139], v[202:205], v[88:91]
	v_mfma_f32_16x16x32_bf16 v[76:79], v[128:131], v[210:213], v[76:79]
	v_mfma_f32_16x16x32_bf16 v[72:75], v[136:139], v[210:213], v[72:75]
	v_mfma_f32_16x16x32_bf16 v[124:127], v[132:135], v[190:193], v[124:127]
	v_mfma_f32_16x16x32_bf16 v[120:123], v[140:143], v[190:193], v[120:123]
	v_mfma_f32_16x16x32_bf16 v[108:111], v[132:135], v[198:201], v[108:111]
	v_mfma_f32_16x16x32_bf16 v[104:107], v[140:143], v[198:201], v[104:107]
	v_mfma_f32_16x16x32_bf16 v[92:95], v[132:135], v[206:209], v[92:95]
	v_mfma_f32_16x16x32_bf16 v[88:91], v[140:143], v[206:209], v[88:91]
	v_mfma_f32_16x16x32_bf16 v[76:79], v[132:135], v[214:217], v[76:79]
	v_mfma_f32_16x16x32_bf16 v[72:75], v[140:143], v[214:217], v[72:75]
	v_mfma_f32_16x16x32_bf16 v[116:119], v[160:163], v[186:189], v[116:119]
	v_mfma_f32_16x16x32_bf16 v[112:115], v[168:171], v[186:189], v[112:115]
	v_mfma_f32_16x16x32_bf16 v[100:103], v[160:163], v[194:197], v[100:103]
	v_mfma_f32_16x16x32_bf16 v[96:99], v[168:171], v[194:197], v[96:99]
	v_mfma_f32_16x16x32_bf16 v[84:87], v[160:163], v[202:205], v[84:87]
	v_mfma_f32_16x16x32_bf16 v[80:83], v[168:171], v[202:205], v[80:83]
	v_mfma_f32_16x16x32_bf16 v[68:71], v[160:163], v[210:213], v[68:71]
	v_mfma_f32_16x16x32_bf16 v[64:67], v[168:171], v[210:213], v[64:67]
	v_mfma_f32_16x16x32_bf16 v[116:119], v[164:167], v[190:193], v[116:119]
	v_mfma_f32_16x16x32_bf16 v[112:115], v[172:175], v[190:193], v[112:115]
	v_mfma_f32_16x16x32_bf16 v[100:103], v[164:167], v[198:201], v[100:103]
	v_mfma_f32_16x16x32_bf16 v[96:99], v[172:175], v[198:201], v[96:99]
	v_mfma_f32_16x16x32_bf16 v[84:87], v[164:167], v[206:209], v[84:87]
	v_mfma_f32_16x16x32_bf16 v[80:83], v[172:175], v[206:209], v[80:83]
	v_mfma_f32_16x16x32_bf16 v[68:71], v[164:167], v[214:217], v[68:71]
	v_mfma_f32_16x16x32_bf16 v[64:67], v[172:175], v[214:217], v[64:67]
	s_barrier
; #define PG8_STAGE(bufoff, gbase, voff) do { _Pragma("unroll") for (int _i = 0; _i < 2; ++_i) \
;         __builtin_amdgcn_global_load_lds((const unsigned*)((const char*)(gbase) + (voff)[_i]), (LAS unsigned*)(lds + (bufoff) + ldsw + _i * 8192), 16, 0, 0); } while (0)
; #define PG8_LDA(dst, b, h) do { _Pragma("unroll") for (int m = 0; m < 4; ++m) _Pragma("unroll") for (int k = 0; k < 2; ++k) dst[m][k] = *(const LAS bf16x8*)(lds + PG8_SA(b, h) + aoff + m * 2048 + k * 1024); } while (0)
; #define PG8_LDB(dst, b, h) do { _Pragma("unroll") for (int n = 0; n < 2; ++n) _Pragma("unroll") for (int k = 0; k < 2; ++k) dst[n][k] = *(const LAS bf16x8*)(lds + PG8_SB(b, h) + boff + n * 2048 + k * 1024); } while (0)
; #define PG8_WAIT_V(n) asm volatile("s_waitcnt vmcnt(" #n ")" ::: "memory")
; #define PG8_WAIT_L(n) asm volatile("s_waitcnt lgkmcnt(" #n ")" ::: "memory")
; template <class Epi>
; __device__ __forceinline__ void gemm_phase(LAS unsigned char* lds, const Gemm g, const StaticOrder& S, const Epi& E) {
;     ...
;         for (int t = 0; t < nt; t += 2) {
;             const bool last = (t == nt - 2);
;             const char* a1 = cA + (size_t)(t + 1) * kstep;
;             const char* a2 = last ? nA : cA + (size_t)(t + 2) * kstep; const char* b2 = last ? nB : cB + (size_t)(t + 2) * kstep;
;             const char* a3 = a2 + kstep; const char* b3 = b2 + kstep;
;             PG8_LDB(B0, 0, 0); PG8_LDB(B1, 0, 1); PG8_SCHED; PG8_LDA(At, 0, 0); PG8_STAGE(PG8_SA(1, 1), a1 + hstepA, voffA);
;             PG8_WAIT_V(8); PG8_WAIT_L(0); PG8_BAR; PG8_MMA(0, 0, At, B0); PG8_MMA(0, 1, At, B1); PG8_BAR; PG8_SCHED;
;             PG8_LDA(At, 0, 1); PG8_STAGE(PG8_SB(0, 0), b2, voffB); PG8_STAGE(PG8_SB(0, 1), b2 + hstepB, voffB); PG8_STAGE(PG8_SA(0, 0), a2, voffA);
;             PG8_WAIT_V(8); PG8_WAIT_L(0); PG8_BAR; PG8_MMA(1, 0, At, B0); PG8_MMA(1, 1, At, B1); PG8_BAR; PG8_SCHED;
;             PG8_LDB(B0, 1, 0); PG8_LDB(B1, 1, 1); PG8_SCHED; PG8_LDA(At, 1, 0); PG8_STAGE(PG8_SA(0, 1), a2 + hstepA, voffA);
;             PG8_WAIT_V(8); PG8_WAIT_L(0); PG8_BAR; PG8_MMA(0, 0, At, B0); PG8_MMA(0, 1, At, B1); PG8_BAR; PG8_SCHED;
;             PG8_LDA(At, 1, 1); PG8_STAGE(PG8_SB(1, 0), b3, voffB); PG8_STAGE(PG8_SB(1, 1), b3 + hstepB, voffB); PG8_STAGE(PG8_SA(1, 0), a3, voffA);
;             PG8_WAIT_V(8); PG8_WAIT_L(0); PG8_BAR; PG8_MMA(1, 0, At, B0); PG8_MMA(1, 1, At, B1); PG8_BAR; PG8_SCHED;
	s_add_i32 s52, s74, s54
	v_lshl_add_u64 v[178:179], v[178:179], 0, s[12:13]
	s_mov_b32 m0, s52
	ds_read_b128 v[186:189], v184 offset:49152
	ds_read_b128 v[190:193], v184 offset:50176
	ds_read_b128 v[194:197], v184 offset:51200
	ds_read_b128 v[198:201], v184 offset:52224
	ds_read_b128 v[202:205], v184 offset:53248
	ds_read_b128 v[206:209], v184 offset:54272
	ds_read_b128 v[210:213], v184 offset:55296
	ds_read_b128 v[214:217], v184 offset:56320
	global_load_lds_dwordx4 v[178:179], off
	s_add_i32 m0, s52, 0x2000
	s_add_u32 s42, s42, 0x80080
	v_lshl_add_u64 v[178:179], v[218:219], 0, s[12:13]
	s_addc_u32 s43, s43, 0
	s_add_i32 s52, s75, s54
	global_load_lds_dwordx4 v[178:179], off
	s_mov_b32 m0, s52
	s_nop 0
	global_load_lds_dwordx4 v146, s[42:43]
	s_add_i32 m0, s52, 0x2000
	s_nop 0
	global_load_lds_dwordx4 v150, s[42:43]
	v_lshl_add_u64 v[178:179], v[220:221], 0, s[12:13]
	s_mov_b32 m0, s61
	s_nop 0
	global_load_lds_dwordx4 v[178:179], off
	v_lshl_add_u64 v[178:179], v[222:223], 0, s[12:13]
	s_mov_b32 m0, s62
	s_nop 0
	global_load_lds_dwordx4 v[178:179], off
	s_waitcnt vmcnt(8)
	s_waitcnt lgkmcnt(0)
	s_barrier
	s_waitcnt lgkmcnt(0)
	v_mfma_f32_16x16x32_bf16 v[60:63], v[128:131], v[186:189], v[60:63]
	v_mfma_f32_16x16x32_bf16 v[56:59], v[136:139], v[186:189], v[56:59]
	v_mfma_f32_16x16x32_bf16 v[44:47], v[128:131], v[194:197], v[44:47]
	v_mfma_f32_16x16x32_bf16 v[40:43], v[136:139], v[194:197], v[40:43]
	v_mfma_f32_16x16x32_bf16 v[28:31], v[128:131], v[202:205], v[28:31]
	v_mfma_f32_16x16x32_bf16 v[24:27], v[136:139], v[202:205], v[24:27]
	v_mfma_f32_16x16x32_bf16 v[12:15], v[128:131], v[210:213], v[12:15]
	v_mfma_f32_16x16x32_bf16 v[8:11], v[136:139], v[210:213], v[8:11]
	v_mfma_f32_16x16x32_bf16 v[60:63], v[132:135], v[190:193], v[60:63]
	v_mfma_f32_16x16x32_bf16 v[56:59], v[140:143], v[190:193], v[56:59]
	v_mfma_f32_16x16x32_bf16 v[44:47], v[132:135], v[198:201], v[44:47]
	v_mfma_f32_16x16x32_bf16 v[40:43], v[140:143], v[198:201], v[40:43]
	v_mfma_f32_16x16x32_bf16 v[28:31], v[132:135], v[206:209], v[28:31]
	v_mfma_f32_16x16x32_bf16 v[24:27], v[140:143], v[206:209], v[24:27]
	v_mfma_f32_16x16x32_bf16 v[12:15], v[132:135], v[214:217], v[12:15]
	v_mfma_f32_16x16x32_bf16 v[8:11], v[140:143], v[214:217], v[8:11]
	v_mfma_f32_16x16x32_bf16 v[52:55], v[160:163], v[186:189], v[52:55]
	v_mfma_f32_16x16x32_bf16 v[48:51], v[168:171], v[186:189], v[48:51]
	v_mfma_f32_16x16x32_bf16 v[36:39], v[160:163], v[194:197], v[36:39]
	v_mfma_f32_16x16x32_bf16 v[32:35], v[168:171], v[194:197], v[32:35]
	v_mfma_f32_16x16x32_bf16 v[20:23], v[160:163], v[202:205], v[20:23]
	v_mfma_f32_16x16x32_bf16 v[16:19], v[168:171], v[202:205], v[16:19]
	v_mfma_f32_16x16x32_bf16 v[4:7], v[160:163], v[210:213], v[4:7]
	v_mfma_f32_16x16x32_bf16 v[0:3], v[168:171], v[210:213], v[0:3]
	v_mfma_f32_16x16x32_bf16 v[52:55], v[164:167], v[190:193], v[52:55]
	v_mfma_f32_16x16x32_bf16 v[48:51], v[172:175], v[190:193], v[48:51]
	v_mfma_f32_16x16x32_bf16 v[36:39], v[164:167], v[198:201], v[36:39]
	v_mfma_f32_16x16x32_bf16 v[32:35], v[172:175], v[198:201], v[32:35]
	v_mfma_f32_16x16x32_bf16 v[20:23], v[164:167], v[206:209], v[20:23]
	v_mfma_f32_16x16x32_bf16 v[16:19], v[172:175], v[206:209], v[16:19]
	v_mfma_f32_16x16x32_bf16 v[4:7], v[164:167], v[214:217], v[4:7]
	v_mfma_f32_16x16x32_bf16 v[0:3], v[172:175], v[214:217], v[0:3]
	s_barrier
	s_add_i32 s73, s73, 2
	s_add_u32 s38, s38, 0x100
	s_addc_u32 s39, s39, 0
	s_add_u32 s71, s71, 0x100
	s_addc_u32 s72, s72, 0
	s_cmp_gt_u32 s73, 29
.LBB0_1314:
	ds_read_b128 v[128:131], v182
	ds_read_b128 v[132:135], v182 offset:1024
	ds_read_b128 v[136:139], v182 offset:2048
	ds_read_b128 v[140:143], v182 offset:3072
	ds_read_b128 v[160:163], v183
	ds_read_b128 v[164:167], v183 offset:1024
	ds_read_b128 v[168:171], v183 offset:2048
	ds_read_b128 v[172:175], v183 offset:3072
	s_add_u32 s42, s38, 0xfff00080
	s_addc_u32 s43, s39, -1
	s_cmp_eq_u32 s73, 28
	s_cselect_b32 s53, s1, s43
	s_cselect_b32 s52, s19, s42
	s_cselect_b32 s43, s17, s72
	s_cselect_b32 s42, s70, s71
	s_add_i32 m0, s35, 0xc000
	ds_read_b128 v[186:189], v184
	ds_read_b128 v[190:193], v184 offset:1024
	ds_read_b128 v[194:197], v184 offset:2048
	ds_read_b128 v[198:201], v184 offset:3072
	ds_read_b128 v[202:205], v184 offset:4096
	ds_read_b128 v[206:209], v184 offset:5120
	ds_read_b128 v[210:213], v184 offset:6144
	ds_read_b128 v[214:217], v184 offset:7168
	global_load_lds_dwordx4 v152, s[38:39]
	s_add_i32 m0, s35, 0xe000
	s_nop 0
	global_load_lds_dwordx4 v154, s[38:39]
	s_waitcnt vmcnt(8)
	s_waitcnt lgkmcnt(0)
	s_barrier
; #define PG8_STAGE(bufoff, gbase, voff) do { _Pragma("unroll") for (int _i = 0; _i < 2; ++_i) \
;         __builtin_amdgcn_global_load_lds((const unsigned*)((const char*)(gbase) + (voff)[_i]), (LAS unsigned*)(lds + (bufoff) + ldsw + _i * 8192), 16, 0, 0); } while (0)
; #define PG8_LDA(dst, b, h) do { _Pragma("unroll") for (int m = 0; m < 4; ++m) _Pragma("unroll") for (int k = 0; k < 2; ++k) dst[m][k] = *(const LAS bf16x8*)(lds + PG8_SA(b, h) + aoff + m * 2048 + k * 1024); } while (0)
; #define PG8_MMA(ai, bj, At, Bt) do { __builtin_amdgcn_s_setprio(1); _Pragma("unroll") for (int m = 0; m < 4; ++m) _Pragma("unroll") for (int n = 0; n < 2; ++n) _Pragma("unroll") for (int k = 0; k < 2; ++k) \
;         acc[ai][bj][m][n] = __builtin_amdgcn_mfma_f32_16x16x32_bf16(Bt[n][k], At[m][k], acc[ai][bj][m][n], 0, 0, 0); __builtin_amdgcn_s_setprio(0); } while (0)
; #define PG8_WAIT_V(n) asm volatile("s_waitcnt vmcnt(" #n ")" ::: "memory")
; #define PG8_WAIT_L(n) asm volatile("s_waitcnt lgkmcnt(" #n ")" ::: "memory")
; #define PG8_BAR __builtin_amdgcn_s_barrier()
; #define PG8_SCHED __builtin_amdgcn_sched_barrier(0)
; template <class Epi>
; __device__ __forceinline__ void gemm_phase(LAS unsigned char* lds, const Gemm g, const StaticOrder& S, const Epi& E) {
;     ...
;             PG8_WAIT_V(8); PG8_WAIT_L(0); PG8_BAR; PG8_MMA(0, 0, At, B0); PG8_MMA(0, 1, At, B1); PG8_BAR; PG8_SCHED;
;             PG8_LDA(At, 0, 1); PG8_STAGE(PG8_SB(0, 0), b2, voffB); PG8_STAGE(PG8_SB(0, 1), b2 + hstepB, voffB); PG8_STAGE(PG8_SA(0, 0), a2, voffA);
;             PG8_WAIT_V(8); PG8_WAIT_L(0); PG8_BAR; PG8_MMA(1, 0, At, B0); PG8_MMA(1, 1, At, B1); PG8_BAR; PG8_SCHED;
	s_waitcnt lgkmcnt(0)
	v_mfma_f32_16x16x32_bf16 v[124:127], v[128:131], v[186:189], v[124:127]
	v_mfma_f32_16x16x32_bf16 v[120:123], v[136:139], v[186:189], v[120:123]
	v_mfma_f32_16x16x32_bf16 v[108:111], v[128:131], v[194:197], v[108:111]
	v_mfma_f32_16x16x32_bf16 v[104:107], v[136:139], v[194:197], v[104:107]
	v_mfma_f32_16x16x32_bf16 v[92:95], v[128:131], v[202:205], v[92:95]
	v_mfma_f32_16x16x32_bf16 v[88:91], v[136:139], v[202:205], v[88:91]
	v_mfma_f32_16x16x32_bf16 v[76:79], v[128:131], v[210:213], v[76:79]
	v_mfma_f32_16x16x32_bf16 v[72:75], v[136:139], v[210:213], v[72:75]
	v_mfma_f32_16x16x32_bf16 v[124:127], v[132:135], v[190:193], v[124:127]
	v_mfma_f32_16x16x32_bf16 v[120:123], v[140:143], v[190:193], v[120:123]
	v_mfma_f32_16x16x32_bf16 v[108:111], v[132:135], v[198:201], v[108:111]
	v_mfma_f32_16x16x32_bf16 v[104:107], v[140:143], v[198:201], v[104:107]
	v_mfma_f32_16x16x32_bf16 v[92:95], v[132:135], v[206:209], v[92:95]
	v_mfma_f32_16x16x32_bf16 v[88:91], v[140:143], v[206:209], v[88:91]
	v_mfma_f32_16x16x32_bf16 v[76:79], v[132:135], v[214:217], v[76:79]
	v_mfma_f32_16x16x32_bf16 v[72:75], v[140:143], v[214:217], v[72:75]
	v_mfma_f32_16x16x32_bf16 v[116:119], v[160:163], v[186:189], v[116:119]
	v_mfma_f32_16x16x32_bf16 v[112:115], v[168:171], v[186:189], v[112:115]
	v_mfma_f32_16x16x32_bf16 v[100:103], v[160:163], v[194:197], v[100:103]
	v_mfma_f32_16x16x32_bf16 v[96:99], v[168:171], v[194:197], v[96:99]
	v_mfma_f32_16x16x32_bf16 v[84:87], v[160:163], v[202:205], v[84:87]
	v_mfma_f32_16x16x32_bf16 v[80:83], v[168:171], v[202:205], v[80:83]
	v_mfma_f32_16x16x32_bf16 v[68:71], v[160:163], v[210:213], v[68:71]
	v_mfma_f32_16x16x32_bf16 v[64:67], v[168:171], v[210:213], v[64:67]
	v_mfma_f32_16x16x32_bf16 v[116:119], v[164:167], v[190:193], v[116:119]
	v_mfma_f32_16x16x32_bf16 v[112:115], v[172:175], v[190:193], v[112:115]
	v_mfma_f32_16x16x32_bf16 v[100:103], v[164:167], v[198:201], v[100:103]
	v_mfma_f32_16x16x32_bf16 v[96:99], v[172:175], v[198:201], v[96:99]
	v_mfma_f32_16x16x32_bf16 v[84:87], v[164:167], v[206:209], v[84:87]
	v_mfma_f32_16x16x32_bf16 v[80:83], v[172:175], v[206:209], v[80:83]
	v_mfma_f32_16x16x32_bf16 v[68:71], v[164:167], v[214:217], v[68:71]
	v_mfma_f32_16x16x32_bf16 v[64:67], v[172:175], v[214:217], v[64:67]
	s_barrier
	s_add_i32 s74, s68, s54
	v_lshl_add_u64 v[178:179], s[42:43], 0, v[146:147]
	s_mov_b32 m0, s74
	ds_read_b128 v[186:189], v184 offset:16384
	ds_read_b128 v[190:193], v184 offset:17408
	ds_read_b128 v[194:197], v184 offset:18432
	ds_read_b128 v[198:201], v184 offset:19456
	ds_read_b128 v[202:205], v184 offset:20480
	ds_read_b128 v[206:209], v184 offset:21504
	ds_read_b128 v[210:213], v184 offset:22528
	ds_read_b128 v[214:217], v184 offset:23552
	global_load_lds_dwordx4 v[178:179], off
	s_add_i32 m0, s74, 0x2000
	s_add_u32 s74, s42, 0x80000
	v_lshl_add_u64 v[218:219], s[42:43], 0, v[150:151]
	s_addc_u32 s75, s43, 0
	s_add_i32 s76, s69, s54
	global_load_lds_dwordx4 v[218:219], off
	s_mov_b32 m0, s76
	v_lshl_add_u64 v[222:223], s[52:53], 0, v[148:149]
	global_load_lds_dwordx4 v146, s[74:75]
	s_add_i32 m0, s76, 0x2000
	s_nop 0
	global_load_lds_dwordx4 v150, s[74:75]
	v_lshl_add_u64 v[220:221], s[52:53], 0, v[144:145]
	s_mov_b32 m0, s35
	s_nop 0
	global_load_lds_dwordx4 v[220:221], off
	s_mov_b32 m0, s55
	s_nop 0
	global_load_lds_dwordx4 v[222:223], off
	s_waitcnt vmcnt(8)
	s_waitcnt lgkmcnt(0)
	s_barrier
	s_waitcnt lgkmcnt(0)
	v_mfma_f32_16x16x32_bf16 v[60:63], v[128:131], v[186:189], v[60:63]
	v_mfma_f32_16x16x32_bf16 v[56:59], v[136:139], v[186:189], v[56:59]
	v_mfma_f32_16x16x32_bf16 v[44:47], v[128:131], v[194:197], v[44:47]
	v_mfma_f32_16x16x32_bf16 v[40:43], v[136:139], v[194:197], v[40:43]
	v_mfma_f32_16x16x32_bf16 v[28:31], v[128:131], v[202:205], v[28:31]
	v_mfma_f32_16x16x32_bf16 v[24:27], v[136:139], v[202:205], v[24:27]
	v_mfma_f32_16x16x32_bf16 v[12:15], v[128:131], v[210:213], v[12:15]
	v_mfma_f32_16x16x32_bf16 v[8:11], v[136:139], v[210:213], v[8:11]
	v_mfma_f32_16x16x32_bf16 v[60:63], v[132:135], v[190:193], v[60:63]
	v_mfma_f32_16x16x32_bf16 v[56:59], v[140:143], v[190:193], v[56:59]
	v_mfma_f32_16x16x32_bf16 v[44:47], v[132:135], v[198:201], v[44:47]
	v_mfma_f32_16x16x32_bf16 v[40:43], v[140:143], v[198:201], v[40:43]
	v_mfma_f32_16x16x32_bf16 v[28:31], v[132:135], v[206:209], v[28:31]
	v_mfma_f32_16x16x32_bf16 v[24:27], v[140:143], v[206:209], v[24:27]
	v_mfma_f32_16x16x32_bf16 v[12:15], v[132:135], v[214:217], v[12:15]
	v_mfma_f32_16x16x32_bf16 v[8:11], v[140:143], v[214:217], v[8:11]
	v_mfma_f32_16x16x32_bf16 v[52:55], v[160:163], v[186:189], v[52:55]
	v_mfma_f32_16x16x32_bf16 v[48:51], v[168:171], v[186:189], v[48:51]
	v_mfma_f32_16x16x32_bf16 v[36:39], v[160:163], v[194:197], v[36:39]
	v_mfma_f32_16x16x32_bf16 v[32:35], v[168:171], v[194:197], v[32:35]
	v_mfma_f32_16x16x32_bf16 v[20:23], v[160:163], v[202:205], v[20:23]
	v_mfma_f32_16x16x32_bf16 v[16:19], v[168:171], v[202:205], v[16:19]
	v_mfma_f32_16x16x32_bf16 v[4:7], v[160:163], v[210:213], v[4:7]
	v_mfma_f32_16x16x32_bf16 v[0:3], v[168:171], v[210:213], v[0:3]
	v_mfma_f32_16x16x32_bf16 v[52:55], v[164:167], v[190:193], v[52:55]
	v_mfma_f32_16x16x32_bf16 v[48:51], v[172:175], v[190:193], v[48:51]
	v_mfma_f32_16x16x32_bf16 v[36:39], v[164:167], v[198:201], v[36:39]
	v_mfma_f32_16x16x32_bf16 v[32:35], v[172:175], v[198:201], v[32:35]
	v_mfma_f32_16x16x32_bf16 v[20:23], v[164:167], v[206:209], v[20:23]
	v_mfma_f32_16x16x32_bf16 v[16:19], v[172:175], v[206:209], v[16:19]
	v_mfma_f32_16x16x32_bf16 v[4:7], v[164:167], v[214:217], v[4:7]
	v_mfma_f32_16x16x32_bf16 v[0:3], v[172:175], v[214:217], v[0:3]
	s_barrier
; #define PG8_STAGE(bufoff, gbase, voff) do { _Pragma("unroll") for (int _i = 0; _i < 2; ++_i) \
;         __builtin_amdgcn_global_load_lds((const unsigned*)((const char*)(gbase) + (voff)[_i]), (LAS unsigned*)(lds + (bufoff) + ldsw + _i * 8192), 16, 0, 0); } while (0)
; #define PG8_LDA(dst, b, h) do { _Pragma("unroll") for (int m = 0; m < 4; ++m) _Pragma("unroll") for (int k = 0; k < 2; ++k) dst[m][k] = *(const LAS bf16x8*)(lds + PG8_SA(b, h) + aoff + m * 2048 + k * 1024); } while (0)
; #define PG8_LDB(dst, b, h) do { _Pragma("unroll") for (int n = 0; n < 2; ++n) _Pragma("unroll") for (int k = 0; k < 2; ++k) dst[n][k] = *(const LAS bf16x8*)(lds + PG8_SB(b, h) + boff + n * 2048 + k * 1024); } while (0)
; #define PG8_MMA(ai, bj, At, Bt) do { __builtin_amdgcn_s_setprio(1); _Pragma("unroll") for (int m = 0; m < 4; ++m) _Pragma("unroll") for (int n = 0; n < 2; ++n) _Pragma("unroll") for (int k = 0; k < 2; ++k) \
;         acc[ai][bj][m][n] = __builtin_amdgcn_mfma_f32_16x16x32_bf16(Bt[n][k], At[m][k], acc[ai][bj][m][n], 0, 0, 0); __builtin_amdgcn_s_setprio(0); } while (0)
; #define PG8_WAIT_V(n) asm volatile("s_waitcnt vmcnt(" #n ")" ::: "memory")
; #define PG8_WAIT_L(n) asm volatile("s_waitcnt lgkmcnt(" #n ")" ::: "memory")
; #define PG8_BAR __builtin_amdgcn_s_barrier()
; #define PG8_SCHED __builtin_amdgcn_sched_barrier(0)
; template <class Epi>
; __device__ __forceinline__ void gemm_phase(LAS unsigned char* lds, const Gemm g, const StaticOrder& S, const Epi& E) {
;     ...
;             PG8_LDB(B0, 1, 0); PG8_LDB(B1, 1, 1); PG8_SCHED; PG8_LDA(At, 1, 0); PG8_STAGE(PG8_SA(0, 1), a2 + hstepA, voffA);
;             PG8_WAIT_V(8); PG8_WAIT_L(0); PG8_BAR; PG8_MMA(0, 0, At, B0); PG8_MMA(0, 1, At, B1); PG8_BAR; PG8_SCHED;
;             PG8_LDA(At, 1, 1); PG8_STAGE(PG8_SB(1, 0), b3, voffB); PG8_STAGE(PG8_SB(1, 1), b3 + hstepB, voffB); PG8_STAGE(PG8_SA(1, 0), a3, voffA);
;             PG8_WAIT_V(8); PG8_WAIT_L(0); PG8_BAR; PG8_MMA(1, 0, At, B0); PG8_MMA(1, 1, At, B1); PG8_BAR; PG8_SCHED;
;         }
	s_add_i32 s74, 0, 0x18000
	s_add_i32 s75, 0, 0x1c000
	v_add_u32_e32 v140, s74, v181
	v_add_u32_e32 v172, s75, v181
	ds_read_b128 v[128:131], v140
	ds_read_b128 v[132:135], v140 offset:1024
	ds_read_b128 v[136:139], v140 offset:2048
	ds_read_b128 v[140:143], v140 offset:3072
	ds_read_b128 v[160:163], v172
	ds_read_b128 v[164:167], v172 offset:1024
	ds_read_b128 v[168:171], v172 offset:2048
	ds_read_b128 v[172:175], v172 offset:3072
	s_add_u32 s52, s52, 0x100000
	s_addc_u32 s53, s53, 0
	s_mov_b32 m0, s56
	ds_read_b128 v[186:189], v184 offset:32768
	ds_read_b128 v[190:193], v184 offset:33792
	ds_read_b128 v[194:197], v184 offset:34816
	ds_read_b128 v[198:201], v184 offset:35840
	ds_read_b128 v[202:205], v184 offset:36864
	ds_read_b128 v[206:209], v184 offset:37888
	ds_read_b128 v[210:213], v184 offset:38912
	ds_read_b128 v[214:217], v184 offset:39936
	global_load_lds_dwordx4 v144, s[52:53]
	s_mov_b32 m0, s57
	s_nop 0
	global_load_lds_dwordx4 v148, s[52:53]
	s_waitcnt vmcnt(8)
	s_waitcnt lgkmcnt(0)
	s_barrier
	s_waitcnt lgkmcnt(0)
	v_mfma_f32_16x16x32_bf16 v[124:127], v[128:131], v[186:189], v[124:127]
	v_mfma_f32_16x16x32_bf16 v[120:123], v[136:139], v[186:189], v[120:123]
	v_mfma_f32_16x16x32_bf16 v[108:111], v[128:131], v[194:197], v[108:111]
	v_mfma_f32_16x16x32_bf16 v[104:107], v[136:139], v[194:197], v[104:107]
	v_mfma_f32_16x16x32_bf16 v[92:95], v[128:131], v[202:205], v[92:95]
	v_mfma_f32_16x16x32_bf16 v[88:91], v[136:139], v[202:205], v[88:91]
	v_mfma_f32_16x16x32_bf16 v[76:79], v[128:131], v[210:213], v[76:79]
	v_mfma_f32_16x16x32_bf16 v[72:75], v[136:139], v[210:213], v[72:75]
	v_mfma_f32_16x16x32_bf16 v[124:127], v[132:135], v[190:193], v[124:127]
	v_mfma_f32_16x16x32_bf16 v[120:123], v[140:143], v[190:193], v[120:123]
	v_mfma_f32_16x16x32_bf16 v[108:111], v[132:135], v[198:201], v[108:111]
	v_mfma_f32_16x16x32_bf16 v[104:107], v[140:143], v[198:201], v[104:107]
	v_mfma_f32_16x16x32_bf16 v[92:95], v[132:135], v[206:209], v[92:95]
	v_mfma_f32_16x16x32_bf16 v[88:91], v[140:143], v[206:209], v[88:91]
	v_mfma_f32_16x16x32_bf16 v[76:79], v[132:135], v[214:217], v[76:79]
	v_mfma_f32_16x16x32_bf16 v[72:75], v[140:143], v[214:217], v[72:75]
	v_mfma_f32_16x16x32_bf16 v[116:119], v[160:163], v[186:189], v[116:119]
	v_mfma_f32_16x16x32_bf16 v[112:115], v[168:171], v[186:189], v[112:115]
	v_mfma_f32_16x16x32_bf16 v[100:103], v[160:163], v[194:197], v[100:103]
	v_mfma_f32_16x16x32_bf16 v[96:99], v[168:171], v[194:197], v[96:99]
	v_mfma_f32_16x16x32_bf16 v[84:87], v[160:163], v[202:205], v[84:87]
	v_mfma_f32_16x16x32_bf16 v[80:83], v[168:171], v[202:205], v[80:83]
	v_mfma_f32_16x16x32_bf16 v[68:71], v[160:163], v[210:213], v[68:71]
	v_mfma_f32_16x16x32_bf16 v[64:67], v[168:171], v[210:213], v[64:67]
	v_mfma_f32_16x16x32_bf16 v[116:119], v[164:167], v[190:193], v[116:119]
	v_mfma_f32_16x16x32_bf16 v[112:115], v[172:175], v[190:193], v[112:115]
	v_mfma_f32_16x16x32_bf16 v[100:103], v[164:167], v[198:201], v[100:103]
	v_mfma_f32_16x16x32_bf16 v[96:99], v[172:175], v[198:201], v[96:99]
	v_mfma_f32_16x16x32_bf16 v[84:87], v[164:167], v[206:209], v[84:87]
	v_mfma_f32_16x16x32_bf16 v[80:83], v[172:175], v[206:209], v[80:83]
	v_mfma_f32_16x16x32_bf16 v[68:71], v[164:167], v[214:217], v[68:71]
	v_mfma_f32_16x16x32_bf16 v[64:67], v[172:175], v[214:217], v[64:67]
	s_barrier
	s_add_i32 s52, s74, s54
	v_lshl_add_u64 v[178:179], v[178:179], 0, s[12:13]
	s_mov_b32 m0, s52
	ds_read_b128 v[186:189], v184 offset:49152
	ds_read_b128 v[190:193], v184 offset:50176
	ds_read_b128 v[194:197], v184 offset:51200
	ds_read_b128 v[198:201], v184 offset:52224
	ds_read_b128 v[202:205], v184 offset:53248
	ds_read_b128 v[206:209], v184 offset:54272
	ds_read_b128 v[210:213], v184 offset:55296
	ds_read_b128 v[214:217], v184 offset:56320
	global_load_lds_dwordx4 v[178:179], off
	s_add_i32 m0, s52, 0x2000
	s_add_u32 s42, s42, 0x80080
	v_lshl_add_u64 v[178:179], v[218:219], 0, s[12:13]
	s_addc_u32 s43, s43, 0
	s_add_i32 s52, s75, s54
	global_load_lds_dwordx4 v[178:179], off
	s_mov_b32 m0, s52
	s_nop 0
	global_load_lds_dwordx4 v146, s[42:43]
	s_add_i32 m0, s52, 0x2000
	s_nop 0
	global_load_lds_dwordx4 v150, s[42:43]
	v_lshl_add_u64 v[178:179], v[220:221], 0, s[12:13]
	s_mov_b32 m0, s61
	s_nop 0
	global_load_lds_dwordx4 v[178:179], off
	v_lshl_add_u64 v[178:179], v[222:223], 0, s[12:13]
	s_mov_b32 m0, s62
	s_nop 0
	global_load_lds_dwordx4 v[178:179], off
	s_waitcnt vmcnt(8)
	s_waitcnt lgkmcnt(0)
	s_barrier
	s_waitcnt lgkmcnt(0)
	v_mfma_f32_16x16x32_bf16 v[60:63], v[128:131], v[186:189], v[60:63]
	v_mfma_f32_16x16x32_bf16 v[56:59], v[136:139], v[186:189], v[56:59]
	v_mfma_f32_16x16x32_bf16 v[44:47], v[128:131], v[194:197], v[44:47]
	v_mfma_f32_16x16x32_bf16 v[40:43], v[136:139], v[194:197], v[40:43]
	v_mfma_f32_16x16x32_bf16 v[28:31], v[128:131], v[202:205], v[28:31]
	v_mfma_f32_16x16x32_bf16 v[24:27], v[136:139], v[202:205], v[24:27]
	v_mfma_f32_16x16x32_bf16 v[12:15], v[128:131], v[210:213], v[12:15]
	v_mfma_f32_16x16x32_bf16 v[8:11], v[136:139], v[210:213], v[8:11]
	v_mfma_f32_16x16x32_bf16 v[60:63], v[132:135], v[190:193], v[60:63]
	v_mfma_f32_16x16x32_bf16 v[56:59], v[140:143], v[190:193], v[56:59]
	v_mfma_f32_16x16x32_bf16 v[44:47], v[132:135], v[198:201], v[44:47]
	v_mfma_f32_16x16x32_bf16 v[40:43], v[140:143], v[198:201], v[40:43]
	v_mfma_f32_16x16x32_bf16 v[28:31], v[132:135], v[206:209], v[28:31]
	v_mfma_f32_16x16x32_bf16 v[24:27], v[140:143], v[206:209], v[24:27]
	v_mfma_f32_16x16x32_bf16 v[12:15], v[132:135], v[214:217], v[12:15]
	v_mfma_f32_16x16x32_bf16 v[8:11], v[140:143], v[214:217], v[8:11]
	v_mfma_f32_16x16x32_bf16 v[52:55], v[160:163], v[186:189], v[52:55]
	v_mfma_f32_16x16x32_bf16 v[48:51], v[168:171], v[186:189], v[48:51]
	v_mfma_f32_16x16x32_bf16 v[36:39], v[160:163], v[194:197], v[36:39]
	v_mfma_f32_16x16x32_bf16 v[32:35], v[168:171], v[194:197], v[32:35]
	v_mfma_f32_16x16x32_bf16 v[20:23], v[160:163], v[202:205], v[20:23]
	v_mfma_f32_16x16x32_bf16 v[16:19], v[168:171], v[202:205], v[16:19]
	v_mfma_f32_16x16x32_bf16 v[4:7], v[160:163], v[210:213], v[4:7]
	v_mfma_f32_16x16x32_bf16 v[0:3], v[168:171], v[210:213], v[0:3]
	v_mfma_f32_16x16x32_bf16 v[52:55], v[164:167], v[190:193], v[52:55]
	v_mfma_f32_16x16x32_bf16 v[48:51], v[172:175], v[190:193], v[48:51]
	v_mfma_f32_16x16x32_bf16 v[36:39], v[164:167], v[198:201], v[36:39]
	v_mfma_f32_16x16x32_bf16 v[32:35], v[172:175], v[198:201], v[32:35]
	v_mfma_f32_16x16x32_bf16 v[20:23], v[164:167], v[206:209], v[20:23]
	v_mfma_f32_16x16x32_bf16 v[16:19], v[172:175], v[206:209], v[16:19]
	v_mfma_f32_16x16x32_bf16 v[4:7], v[164:167], v[214:217], v[4:7]
	v_mfma_f32_16x16x32_bf16 v[0:3], v[172:175], v[214:217], v[0:3]
	s_barrier
	s_add_i32 s73, s73, 2
	s_add_u32 s38, s38, 0x100
	s_addc_u32 s39, s39, 0
	s_add_u32 s71, s71, 0x100
	s_addc_u32 s72, s72, 0
	s_cmp_gt_u32 s73, 29
	s_cbranch_scc0 .LBB0_1314
	s_and_b64 vcc, exec, s[14:15]
	s_cbranch_vccz .LBB0_1317
	s_barrier

; #define PG8_STAGE(bufoff, gbase, voff) do { _Pragma("unroll") for (int _i = 0; _i < 2; ++_i) \
;         __builtin_amdgcn_global_load_lds((const unsigned*)((const char*)(gbase) + (voff)[_i]), (LAS unsigned*)(lds + (bufoff) + ldsw + _i * 8192), 16, 0, 0); } while (0)
; #define PG8_LDA(dst, b, h) do { _Pragma("unroll") for (int m = 0; m < 4; ++m) _Pragma("unroll") for (int k = 0; k < 2; ++k) dst[m][k] = *(const LAS bf16x8*)(lds + PG8_SA(b, h) + aoff + m * 2048 + k * 1024); } while (0)
; #define PG8_LDB(dst, b, h) do { _Pragma("unroll") for (int n = 0; n < 2; ++n) _Pragma("unroll") for (int k = 0; k < 2; ++k) dst[n][k] = *(const LAS bf16x8*)(lds + PG8_SB(b, h) + boff + n * 2048 + k * 1024); } while (0)
; #define PG8_MMA(ai, bj, At, Bt) do { __builtin_amdgcn_s_setprio(1); _Pragma("unroll") for (int m = 0; m < 4; ++m) _Pragma("unroll") for (int n = 0; n < 2; ++n) _Pragma("unroll") for (int k = 0; k < 2; ++k) \
;         acc[ai][bj][m][n] = __builtin_amdgcn_mfma_f32_16x16x32_bf16(Bt[n][k], At[m][k], acc[ai][bj][m][n], 0, 0, 0); __builtin_amdgcn_s_setprio(0); } while (0)
; #define PG8_WAIT_V(n) asm volatile("s_waitcnt vmcnt(" #n ")" ::: "memory")
; #define PG8_WAIT_L(n) asm volatile("s_waitcnt lgkmcnt(" #n ")" ::: "memory")
; template <class Epi>
; __device__ __forceinline__ void gemm_phase(LAS unsigned char* lds, const Gemm g, const StaticOrder& S, const Epi& E) {
;     ...
;     for (;;) {
;         const bool has_next = S.next(ui + 1, nxt);
;         const char* nA = has_next ? (const char*)g.A + (size_t)nxt.pm * tstepA : cA; const char* nB = has_next ? (const char*)g.Bt + (size_t)nxt.pn * tstepB : cB;
; #pragma nounroll
;         for (int t = 0; t < nt; t += 2) {
;             const bool last = (t == nt - 2);
;             const char* a1 = cA + (size_t)(t + 1) * kstep;
;             const char* a2 = last ? nA : cA + (size_t)(t + 2) * kstep; const char* b2 = last ? nB : cB + (size_t)(t + 2) * kstep;
;             const char* a3 = a2 + kstep; const char* b3 = b2 + kstep;
;             PG8_LDB(B0, 0, 0); PG8_LDB(B1, 0, 1); PG8_SCHED; PG8_LDA(At, 0, 0); PG8_STAGE(PG8_SA(1, 1), a1 + hstepA, voffA);
;             PG8_WAIT_V(8); PG8_WAIT_L(0); PG8_BAR; PG8_MMA(0, 0, At, B0); PG8_MMA(0, 1, At, B1); PG8_BAR; PG8_SCHED;
;             PG8_LDA(At, 0, 1); PG8_STAGE(PG8_SB(0, 0), b2, voffB); PG8_STAGE(PG8_SB(0, 1), b2 + hstepB, voffB); PG8_STAGE(PG8_SA(0, 0), a2, voffA);
.LBB0_1402:
	s_ashr_i32 s69, s68, 31
	s_lshl_b64 s[12:13], s[68:69], 19
	s_add_u32 s70, s24, s12
	s_addc_u32 s71, s25, s13
	s_and_b64 s[12:13], s[4:5], exec
	s_cselect_b32 s1, s71, s9
	s_cselect_b32 s7, s70, s8
	s_ashr_i32 s65, s64, 31
	s_lshl_b64 s[12:13], s[64:65], 19
	s_add_u32 s72, s3, s12
	s_addc_u32 s73, s33, s13
	s_and_b64 s[12:13], s[4:5], exec
	s_cselect_b32 s65, s73, s11
	s_cselect_b32 s69, s72, s10
	s_add_u32 s8, s8, 0x40080
	s_addc_u32 s9, s9, 0
	s_add_u32 s74, s10, 0x100
	s_addc_u32 s75, s11, 0
	s_mov_b32 s87, -2
	v_lshl_add_u32 v248, s6, 8, v151
	v_add_u32_e32 v248, s63, v248
	v_ashrrev_i32_e32 v249, 31, v248
	v_lshl_add_u64 v[248:249], v[248:249], 2, s[18:19]
	global_load_dword v240, v[248:249], off
	global_load_dword v241, v[248:249], off offset:64
	global_load_dword v242, v[248:249], off offset:128
	global_load_dword v243, v[248:249], off offset:192
	global_load_dword v244, v[248:249], off offset:512
	global_load_dword v245, v[248:249], off offset:576
	global_load_dword v246, v[248:249], off offset:640
	global_load_dword v247, v[248:249], off offset:704
	ds_read_b128 v[146:149], v162
	ds_read_b128 v[166:169], v162 offset:1024
	ds_read_b128 v[170:173], v162 offset:2048
	ds_read_b128 v[178:181], v162 offset:3072
	ds_read_b128 v[182:185], v163
	ds_read_b128 v[186:189], v163 offset:1024
	ds_read_b128 v[190:193], v163 offset:2048
	ds_read_b128 v[194:197], v163 offset:3072
	s_add_u32 s10, s8, 0xfffc0080
	s_addc_u32 s11, s9, -1
	s_cmp_eq_u32 s87, 12
	s_cselect_b32 s13, s1, s11
	s_cselect_b32 s12, s7, s10
	s_cselect_b32 s11, s65, s75
	s_cselect_b32 s10, s69, s74
	s_add_i32 m0, s53, 0xc000
	ds_read_b128 v[198:201], v164
	ds_read_b128 v[202:205], v164 offset:1024
	ds_read_b128 v[206:209], v164 offset:2048
	ds_read_b128 v[210:213], v164 offset:3072
	ds_read_b128 v[214:217], v164 offset:4096
	ds_read_b128 v[218:221], v164 offset:5120
	ds_read_b128 v[222:225], v164 offset:6144
	ds_read_b128 v[226:229], v164 offset:7168
	global_load_lds_dwordx4 v138, s[8:9]
	s_add_i32 m0, s53, 0xe000
	s_nop 0
	global_load_lds_dwordx4 v140, s[8:9]
	s_waitcnt vmcnt(8)
	s_waitcnt lgkmcnt(0)
	s_barrier
	s_waitcnt lgkmcnt(0)
	v_mfma_f32_16x16x32_bf16 v[124:127], v[146:149], v[198:201], 0
	v_mfma_f32_16x16x32_bf16 v[120:123], v[170:173], v[198:201], 0
	v_mfma_f32_16x16x32_bf16 v[112:115], v[146:149], v[206:209], 0
	v_mfma_f32_16x16x32_bf16 v[104:107], v[170:173], v[206:209], 0
	v_mfma_f32_16x16x32_bf16 v[100:103], v[146:149], v[214:217], 0
	v_mfma_f32_16x16x32_bf16 v[92:95], v[170:173], v[214:217], 0
	v_mfma_f32_16x16x32_bf16 v[84:87], v[146:149], v[222:225], 0
	v_mfma_f32_16x16x32_bf16 v[76:79], v[170:173], v[222:225], 0
	v_mfma_f32_16x16x32_bf16 v[124:127], v[166:169], v[202:205], v[124:127]
	v_mfma_f32_16x16x32_bf16 v[120:123], v[178:181], v[202:205], v[120:123]
	v_mfma_f32_16x16x32_bf16 v[112:115], v[166:169], v[210:213], v[112:115]
	v_mfma_f32_16x16x32_bf16 v[104:107], v[178:181], v[210:213], v[104:107]
	v_mfma_f32_16x16x32_bf16 v[100:103], v[166:169], v[218:221], v[100:103]
	v_mfma_f32_16x16x32_bf16 v[92:95], v[178:181], v[218:221], v[92:95]
	v_mfma_f32_16x16x32_bf16 v[84:87], v[166:169], v[226:229], v[84:87]
	v_mfma_f32_16x16x32_bf16 v[76:79], v[178:181], v[226:229], v[76:79]
	v_mfma_f32_16x16x32_bf16 v[116:119], v[182:185], v[198:201], 0
	v_mfma_f32_16x16x32_bf16 v[108:111], v[190:193], v[198:201], 0
	v_mfma_f32_16x16x32_bf16 v[96:99], v[182:185], v[206:209], 0
	v_mfma_f32_16x16x32_bf16 v[88:91], v[190:193], v[206:209], 0
	v_mfma_f32_16x16x32_bf16 v[80:83], v[182:185], v[214:217], 0
	v_mfma_f32_16x16x32_bf16 v[72:75], v[190:193], v[214:217], 0
	v_mfma_f32_16x16x32_bf16 v[68:71], v[182:185], v[222:225], 0
	v_mfma_f32_16x16x32_bf16 v[64:67], v[190:193], v[222:225], 0
	v_mfma_f32_16x16x32_bf16 v[116:119], v[186:189], v[202:205], v[116:119]
	v_mfma_f32_16x16x32_bf16 v[108:111], v[194:197], v[202:205], v[108:111]
	v_mfma_f32_16x16x32_bf16 v[96:99], v[186:189], v[210:213], v[96:99]
	v_mfma_f32_16x16x32_bf16 v[88:91], v[194:197], v[210:213], v[88:91]
	v_mfma_f32_16x16x32_bf16 v[80:83], v[186:189], v[218:221], v[80:83]
	v_mfma_f32_16x16x32_bf16 v[72:75], v[194:197], v[218:221], v[72:75]
	v_mfma_f32_16x16x32_bf16 v[68:71], v[186:189], v[226:229], v[68:71]
	v_mfma_f32_16x16x32_bf16 v[64:67], v[194:197], v[226:229], v[64:67]
	s_barrier
	s_add_i32 s88, s83, s43
	v_lshl_add_u64 v[174:175], s[10:11], 0, v[130:131]
	s_mov_b32 m0, s88
	ds_read_b128 v[198:201], v164 offset:16384
	ds_read_b128 v[202:205], v164 offset:17408
	ds_read_b128 v[206:209], v164 offset:18432
	ds_read_b128 v[210:213], v164 offset:19456
	ds_read_b128 v[214:217], v164 offset:20480
	ds_read_b128 v[218:221], v164 offset:21504
	ds_read_b128 v[222:225], v164 offset:22528
	ds_read_b128 v[226:229], v164 offset:23552
	global_load_lds_dwordx4 v[174:175], off
	s_add_i32 m0, s88, 0x2000
	s_add_u32 s88, s10, 0x40000
	v_lshl_add_u64 v[230:231], s[10:11], 0, v[134:135]
	s_addc_u32 s89, s11, 0
	s_add_i32 s90, s84, s43
	global_load_lds_dwordx4 v[230:231], off
	s_mov_b32 m0, s90
	v_lshl_add_u64 v[234:235], s[12:13], 0, v[132:133]
	global_load_lds_dwordx4 v130, s[88:89]
	s_add_i32 m0, s90, 0x2000
	s_nop 0
	global_load_lds_dwordx4 v134, s[88:89]
	v_lshl_add_u64 v[232:233], s[12:13], 0, v[128:129]
	s_mov_b32 m0, s53
	s_nop 0
	global_load_lds_dwordx4 v[232:233], off
	s_mov_b32 m0, s55
	s_nop 0
	global_load_lds_dwordx4 v[234:235], off
	s_waitcnt vmcnt(8)
	s_waitcnt lgkmcnt(0)
	s_barrier
; #define PG8_STAGE(bufoff, gbase, voff) do { _Pragma("unroll") for (int _i = 0; _i < 2; ++_i) \
;         __builtin_amdgcn_global_load_lds((const unsigned*)((const char*)(gbase) + (voff)[_i]), (LAS unsigned*)(lds + (bufoff) + ldsw + _i * 8192), 16, 0, 0); } while (0)
; #define PG8_LDA(dst, b, h) do { _Pragma("unroll") for (int m = 0; m < 4; ++m) _Pragma("unroll") for (int k = 0; k < 2; ++k) dst[m][k] = *(const LAS bf16x8*)(lds + PG8_SA(b, h) + aoff + m * 2048 + k * 1024); } while (0)
; #define PG8_LDB(dst, b, h) do { _Pragma("unroll") for (int n = 0; n < 2; ++n) _Pragma("unroll") for (int k = 0; k < 2; ++k) dst[n][k] = *(const LAS bf16x8*)(lds + PG8_SB(b, h) + boff + n * 2048 + k * 1024); } while (0)
; #define PG8_MMA(ai, bj, At, Bt) do { __builtin_amdgcn_s_setprio(1); _Pragma("unroll") for (int m = 0; m < 4; ++m) _Pragma("unroll") for (int n = 0; n < 2; ++n) _Pragma("unroll") for (int k = 0; k < 2; ++k) \
;         acc[ai][bj][m][n] = __builtin_amdgcn_mfma_f32_16x16x32_bf16(Bt[n][k], At[m][k], acc[ai][bj][m][n], 0, 0, 0); __builtin_amdgcn_s_setprio(0); } while (0)
; #define PG8_WAIT_V(n) asm volatile("s_waitcnt vmcnt(" #n ")" ::: "memory")
; #define PG8_WAIT_L(n) asm volatile("s_waitcnt lgkmcnt(" #n ")" ::: "memory")
; #define PG8_BAR __builtin_amdgcn_s_barrier()
; #define PG8_SCHED __builtin_amdgcn_sched_barrier(0)
; template <class Epi>
; __device__ __forceinline__ void gemm_phase(LAS unsigned char* lds, const Gemm g, const StaticOrder& S, const Epi& E) {
;     ...
;             PG8_WAIT_V(8); PG8_WAIT_L(0); PG8_BAR; PG8_MMA(1, 0, At, B0); PG8_MMA(1, 1, At, B1); PG8_BAR; PG8_SCHED;
;             PG8_LDB(B0, 1, 0); PG8_LDB(B1, 1, 1); PG8_SCHED; PG8_LDA(At, 1, 0); PG8_STAGE(PG8_SA(0, 1), a2 + hstepA, voffA);
;             PG8_WAIT_V(8); PG8_WAIT_L(0); PG8_BAR; PG8_MMA(0, 0, At, B0); PG8_MMA(0, 1, At, B1); PG8_BAR; PG8_SCHED;
	s_waitcnt lgkmcnt(0)
	v_mfma_f32_16x16x32_bf16 v[60:63], v[146:149], v[198:201], 0
	v_mfma_f32_16x16x32_bf16 v[56:59], v[170:173], v[198:201], 0
	v_mfma_f32_16x16x32_bf16 v[52:55], v[146:149], v[206:209], 0
	v_mfma_f32_16x16x32_bf16 v[44:47], v[170:173], v[206:209], 0
	v_mfma_f32_16x16x32_bf16 v[36:39], v[146:149], v[214:217], 0
	v_mfma_f32_16x16x32_bf16 v[28:31], v[170:173], v[214:217], 0
	v_mfma_f32_16x16x32_bf16 v[20:23], v[146:149], v[222:225], 0
	v_mfma_f32_16x16x32_bf16 v[12:15], v[170:173], v[222:225], 0
	v_mfma_f32_16x16x32_bf16 v[60:63], v[166:169], v[202:205], v[60:63]
	v_mfma_f32_16x16x32_bf16 v[56:59], v[178:181], v[202:205], v[56:59]
	v_mfma_f32_16x16x32_bf16 v[52:55], v[166:169], v[210:213], v[52:55]
	v_mfma_f32_16x16x32_bf16 v[44:47], v[178:181], v[210:213], v[44:47]
	v_mfma_f32_16x16x32_bf16 v[36:39], v[166:169], v[218:221], v[36:39]
	v_mfma_f32_16x16x32_bf16 v[28:31], v[178:181], v[218:221], v[28:31]
	v_mfma_f32_16x16x32_bf16 v[20:23], v[166:169], v[226:229], v[20:23]
	v_mfma_f32_16x16x32_bf16 v[12:15], v[178:181], v[226:229], v[12:15]
	v_mfma_f32_16x16x32_bf16 v[48:51], v[182:185], v[198:201], 0
	v_mfma_f32_16x16x32_bf16 v[40:43], v[190:193], v[198:201], 0
	v_mfma_f32_16x16x32_bf16 v[32:35], v[182:185], v[206:209], 0
	v_mfma_f32_16x16x32_bf16 v[24:27], v[190:193], v[206:209], 0
	v_mfma_f32_16x16x32_bf16 v[16:19], v[182:185], v[214:217], 0
	v_mfma_f32_16x16x32_bf16 v[8:11], v[190:193], v[214:217], 0
	v_mfma_f32_16x16x32_bf16 v[4:7], v[182:185], v[222:225], 0
	v_mfma_f32_16x16x32_bf16 v[0:3], v[190:193], v[222:225], 0
	v_mfma_f32_16x16x32_bf16 v[48:51], v[186:189], v[202:205], v[48:51]
	v_mfma_f32_16x16x32_bf16 v[40:43], v[194:197], v[202:205], v[40:43]
	v_mfma_f32_16x16x32_bf16 v[32:35], v[186:189], v[210:213], v[32:35]
	v_mfma_f32_16x16x32_bf16 v[24:27], v[194:197], v[210:213], v[24:27]
	v_mfma_f32_16x16x32_bf16 v[16:19], v[186:189], v[218:221], v[16:19]
	v_mfma_f32_16x16x32_bf16 v[8:11], v[194:197], v[218:221], v[8:11]
	v_mfma_f32_16x16x32_bf16 v[4:7], v[186:189], v[226:229], v[4:7]
	v_mfma_f32_16x16x32_bf16 v[0:3], v[194:197], v[226:229], v[0:3]
	s_barrier
	s_add_i32 s88, 0, 0x18000
	v_add_u32_e32 v136, s88, v161
	s_add_i32 s89, 0, 0x1c000
	ds_read_b128 v[146:149], v136
	ds_read_b128 v[166:169], v136 offset:1024
	ds_read_b128 v[170:173], v136 offset:2048
	ds_read_b128 v[178:181], v136 offset:3072
	v_add_u32_e32 v136, s89, v161
	ds_read_b128 v[182:185], v136
	ds_read_b128 v[186:189], v136 offset:1024
	ds_read_b128 v[190:193], v136 offset:2048
	ds_read_b128 v[194:197], v136 offset:3072
	s_add_u32 s12, s12, 0x40000
	s_addc_u32 s13, s13, 0
	s_mov_b32 m0, s57
	ds_read_b128 v[198:201], v164 offset:32768
	ds_read_b128 v[202:205], v164 offset:33792
	ds_read_b128 v[206:209], v164 offset:34816
	ds_read_b128 v[210:213], v164 offset:35840
	ds_read_b128 v[214:217], v164 offset:36864
	ds_read_b128 v[218:221], v164 offset:37888
	ds_read_b128 v[222:225], v164 offset:38912
	ds_read_b128 v[226:229], v164 offset:39936
	global_load_lds_dwordx4 v128, s[12:13]
	s_mov_b32 m0, s59
	s_nop 0
	global_load_lds_dwordx4 v132, s[12:13]
	s_waitcnt vmcnt(8)
	s_waitcnt lgkmcnt(0)
	s_barrier
	s_waitcnt lgkmcnt(0)
	v_mfma_f32_16x16x32_bf16 v[124:127], v[146:149], v[198:201], v[124:127]
	v_mfma_f32_16x16x32_bf16 v[120:123], v[170:173], v[198:201], v[120:123]
	v_mfma_f32_16x16x32_bf16 v[112:115], v[146:149], v[206:209], v[112:115]
	v_mfma_f32_16x16x32_bf16 v[104:107], v[170:173], v[206:209], v[104:107]
	v_mfma_f32_16x16x32_bf16 v[100:103], v[146:149], v[214:217], v[100:103]
	v_mfma_f32_16x16x32_bf16 v[92:95], v[170:173], v[214:217], v[92:95]
	v_mfma_f32_16x16x32_bf16 v[84:87], v[146:149], v[222:225], v[84:87]
	v_mfma_f32_16x16x32_bf16 v[76:79], v[170:173], v[222:225], v[76:79]
	v_mfma_f32_16x16x32_bf16 v[124:127], v[166:169], v[202:205], v[124:127]
	v_mfma_f32_16x16x32_bf16 v[120:123], v[178:181], v[202:205], v[120:123]
	v_mfma_f32_16x16x32_bf16 v[112:115], v[166:169], v[210:213], v[112:115]
	v_mfma_f32_16x16x32_bf16 v[104:107], v[178:181], v[210:213], v[104:107]
	v_mfma_f32_16x16x32_bf16 v[100:103], v[166:169], v[218:221], v[100:103]
	v_mfma_f32_16x16x32_bf16 v[92:95], v[178:181], v[218:221], v[92:95]
	v_mfma_f32_16x16x32_bf16 v[84:87], v[166:169], v[226:229], v[84:87]
	v_mfma_f32_16x16x32_bf16 v[76:79], v[178:181], v[226:229], v[76:79]
	v_mfma_f32_16x16x32_bf16 v[116:119], v[182:185], v[198:201], v[116:119]
	v_mfma_f32_16x16x32_bf16 v[108:111], v[190:193], v[198:201], v[108:111]
	v_mfma_f32_16x16x32_bf16 v[96:99], v[182:185], v[206:209], v[96:99]
	v_mfma_f32_16x16x32_bf16 v[88:91], v[190:193], v[206:209], v[88:91]
	v_mfma_f32_16x16x32_bf16 v[80:83], v[182:185], v[214:217], v[80:83]
	v_mfma_f32_16x16x32_bf16 v[72:75], v[190:193], v[214:217], v[72:75]
	v_mfma_f32_16x16x32_bf16 v[68:71], v[182:185], v[222:225], v[68:71]
	v_mfma_f32_16x16x32_bf16 v[64:67], v[190:193], v[222:225], v[64:67]
	v_mfma_f32_16x16x32_bf16 v[116:119], v[186:189], v[202:205], v[116:119]
	v_mfma_f32_16x16x32_bf16 v[108:111], v[194:197], v[202:205], v[108:111]
	v_mfma_f32_16x16x32_bf16 v[96:99], v[186:189], v[210:213], v[96:99]
	v_mfma_f32_16x16x32_bf16 v[88:91], v[194:197], v[210:213], v[88:91]
	v_mfma_f32_16x16x32_bf16 v[80:83], v[186:189], v[218:221], v[80:83]
	v_mfma_f32_16x16x32_bf16 v[72:75], v[194:197], v[218:221], v[72:75]
	v_mfma_f32_16x16x32_bf16 v[68:71], v[186:189], v[226:229], v[68:71]
	v_mfma_f32_16x16x32_bf16 v[64:67], v[194:197], v[226:229], v[64:67]
	s_barrier
; #define PG8_STAGE(bufoff, gbase, voff) do { _Pragma("unroll") for (int _i = 0; _i < 2; ++_i) \
;         __builtin_amdgcn_global_load_lds((const unsigned*)((const char*)(gbase) + (voff)[_i]), (LAS unsigned*)(lds + (bufoff) + ldsw + _i * 8192), 16, 0, 0); } while (0)
; #define PG8_LDA(dst, b, h) do { _Pragma("unroll") for (int m = 0; m < 4; ++m) _Pragma("unroll") for (int k = 0; k < 2; ++k) dst[m][k] = *(const LAS bf16x8*)(lds + PG8_SA(b, h) + aoff + m * 2048 + k * 1024); } while (0)
; #define PG8_LDB(dst, b, h) do { _Pragma("unroll") for (int n = 0; n < 2; ++n) _Pragma("unroll") for (int k = 0; k < 2; ++k) dst[n][k] = *(const LAS bf16x8*)(lds + PG8_SB(b, h) + boff + n * 2048 + k * 1024); } while (0)
; #define PG8_MMA(ai, bj, At, Bt) do { __builtin_amdgcn_s_setprio(1); _Pragma("unroll") for (int m = 0; m < 4; ++m) _Pragma("unroll") for (int n = 0; n < 2; ++n) _Pragma("unroll") for (int k = 0; k < 2; ++k) \
;         acc[ai][bj][m][n] = __builtin_amdgcn_mfma_f32_16x16x32_bf16(Bt[n][k], At[m][k], acc[ai][bj][m][n], 0, 0, 0); __builtin_amdgcn_s_setprio(0); } while (0)
; #define PG8_WAIT_V(n) asm volatile("s_waitcnt vmcnt(" #n ")" ::: "memory")
; #define PG8_BAR __builtin_amdgcn_s_barrier()
; template <class Epi>
; __device__ __forceinline__ void gemm_phase(LAS unsigned char* lds, const Gemm g, const StaticOrder& S, const Epi& E) {
;     ...
;             PG8_LDB(B0, 0, 0); PG8_LDB(B1, 0, 1); PG8_SCHED; PG8_LDA(At, 0, 0); PG8_STAGE(PG8_SA(1, 1), a1 + hstepA, voffA);
;             PG8_WAIT_V(8); PG8_WAIT_L(0); PG8_BAR; PG8_MMA(0, 0, At, B0); PG8_MMA(0, 1, At, B1); PG8_BAR; PG8_SCHED;
;             PG8_LDA(At, 0, 1); PG8_STAGE(PG8_SB(0, 0), b2, voffB); PG8_STAGE(PG8_SB(0, 1), b2 + hstepB, voffB); PG8_STAGE(PG8_SA(0, 0), a2, voffA);
;             PG8_WAIT_V(8); PG8_WAIT_L(0); PG8_BAR; PG8_MMA(1, 0, At, B0); PG8_MMA(1, 1, At, B1); PG8_BAR; PG8_SCHED;
;             PG8_LDB(B0, 1, 0); PG8_LDB(B1, 1, 1); PG8_SCHED; PG8_LDA(At, 1, 0); PG8_STAGE(PG8_SA(0, 1), a2 + hstepA, voffA);
;             PG8_WAIT_V(8); PG8_WAIT_L(0); PG8_BAR; PG8_MMA(0, 0, At, B0); PG8_MMA(0, 1, At, B1); PG8_BAR; PG8_SCHED;
;             PG8_LDA(At, 1, 1); PG8_STAGE(PG8_SB(1, 0), b3, voffB); PG8_STAGE(PG8_SB(1, 1), b3 + hstepB, voffB); PG8_STAGE(PG8_SA(1, 0), a3, voffA);
;             PG8_WAIT_V(8); PG8_WAIT_L(0); PG8_BAR; PG8_MMA(1, 0, At, B0); PG8_MMA(1, 1, At, B1); PG8_BAR; PG8_SCHED;
	s_add_i32 s12, s88, s43
	v_lshl_add_u64 v[174:175], v[174:175], 0, s[34:35]
	s_mov_b32 m0, s12
	ds_read_b128 v[198:201], v164 offset:49152
	ds_read_b128 v[202:205], v164 offset:50176
	ds_read_b128 v[206:209], v164 offset:51200
	ds_read_b128 v[210:213], v164 offset:52224
	ds_read_b128 v[214:217], v164 offset:53248
	ds_read_b128 v[218:221], v164 offset:54272
	ds_read_b128 v[222:225], v164 offset:55296
	ds_read_b128 v[226:229], v164 offset:56320
	global_load_lds_dwordx4 v[174:175], off
	s_add_i32 m0, s12, 0x2000
	s_add_u32 s10, s10, 0x40080
	v_lshl_add_u64 v[174:175], v[230:231], 0, s[34:35]
	s_addc_u32 s11, s11, 0
	s_add_i32 s12, s89, s43
	global_load_lds_dwordx4 v[174:175], off
	s_mov_b32 m0, s12
	s_nop 0
	global_load_lds_dwordx4 v130, s[10:11]
	s_add_i32 m0, s12, 0x2000
	s_nop 0
	global_load_lds_dwordx4 v134, s[10:11]
	v_lshl_add_u64 v[174:175], v[232:233], 0, s[34:35]
	s_mov_b32 m0, s77
	s_nop 0
	global_load_lds_dwordx4 v[174:175], off
	v_lshl_add_u64 v[174:175], v[234:235], 0, s[34:35]
	s_mov_b32 m0, s78
	s_nop 0
	global_load_lds_dwordx4 v[174:175], off
	s_waitcnt vmcnt(8)
	s_waitcnt lgkmcnt(0)
	s_barrier
	s_waitcnt lgkmcnt(0)
	v_mfma_f32_16x16x32_bf16 v[60:63], v[146:149], v[198:201], v[60:63]
	v_mfma_f32_16x16x32_bf16 v[56:59], v[170:173], v[198:201], v[56:59]
	v_mfma_f32_16x16x32_bf16 v[52:55], v[146:149], v[206:209], v[52:55]
	v_mfma_f32_16x16x32_bf16 v[44:47], v[170:173], v[206:209], v[44:47]
	v_mfma_f32_16x16x32_bf16 v[36:39], v[146:149], v[214:217], v[36:39]
	v_mfma_f32_16x16x32_bf16 v[28:31], v[170:173], v[214:217], v[28:31]
	v_mfma_f32_16x16x32_bf16 v[20:23], v[146:149], v[222:225], v[20:23]
	v_mfma_f32_16x16x32_bf16 v[12:15], v[170:173], v[222:225], v[12:15]
	v_mfma_f32_16x16x32_bf16 v[60:63], v[166:169], v[202:205], v[60:63]
	v_mfma_f32_16x16x32_bf16 v[56:59], v[178:181], v[202:205], v[56:59]
	v_mfma_f32_16x16x32_bf16 v[52:55], v[166:169], v[210:213], v[52:55]
	v_mfma_f32_16x16x32_bf16 v[44:47], v[178:181], v[210:213], v[44:47]
	v_mfma_f32_16x16x32_bf16 v[36:39], v[166:169], v[218:221], v[36:39]
	v_mfma_f32_16x16x32_bf16 v[28:31], v[178:181], v[218:221], v[28:31]
	v_mfma_f32_16x16x32_bf16 v[20:23], v[166:169], v[226:229], v[20:23]
	v_mfma_f32_16x16x32_bf16 v[12:15], v[178:181], v[226:229], v[12:15]
	v_mfma_f32_16x16x32_bf16 v[48:51], v[182:185], v[198:201], v[48:51]
	v_mfma_f32_16x16x32_bf16 v[40:43], v[190:193], v[198:201], v[40:43]
	v_mfma_f32_16x16x32_bf16 v[32:35], v[182:185], v[206:209], v[32:35]
	v_mfma_f32_16x16x32_bf16 v[24:27], v[190:193], v[206:209], v[24:27]
	v_mfma_f32_16x16x32_bf16 v[16:19], v[182:185], v[214:217], v[16:19]
	v_mfma_f32_16x16x32_bf16 v[8:11], v[190:193], v[214:217], v[8:11]
	v_mfma_f32_16x16x32_bf16 v[4:7], v[182:185], v[222:225], v[4:7]
	v_mfma_f32_16x16x32_bf16 v[0:3], v[190:193], v[222:225], v[0:3]
	v_mfma_f32_16x16x32_bf16 v[48:51], v[186:189], v[202:205], v[48:51]
	v_mfma_f32_16x16x32_bf16 v[40:43], v[194:197], v[202:205], v[40:43]
	v_mfma_f32_16x16x32_bf16 v[32:35], v[186:189], v[210:213], v[32:35]
	v_mfma_f32_16x16x32_bf16 v[24:27], v[194:197], v[210:213], v[24:27]
	v_mfma_f32_16x16x32_bf16 v[16:19], v[186:189], v[218:221], v[16:19]
	v_mfma_f32_16x16x32_bf16 v[8:11], v[194:197], v[218:221], v[8:11]
	v_mfma_f32_16x16x32_bf16 v[4:7], v[186:189], v[226:229], v[4:7]
	v_mfma_f32_16x16x32_bf16 v[0:3], v[194:197], v[226:229], v[0:3]
	s_barrier
	s_add_i32 s87, s87, 2
	s_add_u32 s8, s8, 0x100
	s_addc_u32 s9, s9, 0
	s_add_u32 s74, s74, 0x100
	s_addc_u32 s75, s75, 0
	s_cmp_gt_u32 s87, 13
.LBB0_1403:
	ds_read_b128 v[146:149], v162
	ds_read_b128 v[166:169], v162 offset:1024
	ds_read_b128 v[170:173], v162 offset:2048
	ds_read_b128 v[178:181], v162 offset:3072
	ds_read_b128 v[182:185], v163
	ds_read_b128 v[186:189], v163 offset:1024
	ds_read_b128 v[190:193], v163 offset:2048
	ds_read_b128 v[194:197], v163 offset:3072
	s_add_u32 s10, s8, 0xfffc0080
	s_addc_u32 s11, s9, -1
	s_cmp_eq_u32 s87, 12
	s_cselect_b32 s13, s1, s11
	s_cselect_b32 s12, s7, s10
	s_cselect_b32 s11, s65, s75
	s_cselect_b32 s10, s69, s74
	s_add_i32 m0, s53, 0xc000
	ds_read_b128 v[198:201], v164
	ds_read_b128 v[202:205], v164 offset:1024
	ds_read_b128 v[206:209], v164 offset:2048
	ds_read_b128 v[210:213], v164 offset:3072
	ds_read_b128 v[214:217], v164 offset:4096
	ds_read_b128 v[218:221], v164 offset:5120
	ds_read_b128 v[222:225], v164 offset:6144
	ds_read_b128 v[226:229], v164 offset:7168
	global_load_lds_dwordx4 v138, s[8:9]
	s_add_i32 m0, s53, 0xe000
	s_nop 0
	global_load_lds_dwordx4 v140, s[8:9]
	s_waitcnt vmcnt(8)
	s_waitcnt lgkmcnt(0)
	s_barrier
; #define PG8_STAGE(bufoff, gbase, voff) do { _Pragma("unroll") for (int _i = 0; _i < 2; ++_i) \
;         __builtin_amdgcn_global_load_lds((const unsigned*)((const char*)(gbase) + (voff)[_i]), (LAS unsigned*)(lds + (bufoff) + ldsw + _i * 8192), 16, 0, 0); } while (0)
; #define PG8_LDA(dst, b, h) do { _Pragma("unroll") for (int m = 0; m < 4; ++m) _Pragma("unroll") for (int k = 0; k < 2; ++k) dst[m][k] = *(const LAS bf16x8*)(lds + PG8_SA(b, h) + aoff + m * 2048 + k * 1024); } while (0)
; #define PG8_LDB(dst, b, h) do { _Pragma("unroll") for (int n = 0; n < 2; ++n) _Pragma("unroll") for (int k = 0; k < 2; ++k) dst[n][k] = *(const LAS bf16x8*)(lds + PG8_SB(b, h) + boff + n * 2048 + k * 1024); } while (0)
; #define PG8_MMA(ai, bj, At, Bt) do { __builtin_amdgcn_s_setprio(1); _Pragma("unroll") for (int m = 0; m < 4; ++m) _Pragma("unroll") for (int n = 0; n < 2; ++n) _Pragma("unroll") for (int k = 0; k < 2; ++k) \
;         acc[ai][bj][m][n] = __builtin_amdgcn_mfma_f32_16x16x32_bf16(Bt[n][k], At[m][k], acc[ai][bj][m][n], 0, 0, 0); __builtin_amdgcn_s_setprio(0); } while (0)
; #define PG8_WAIT_V(n) asm volatile("s_waitcnt vmcnt(" #n ")" ::: "memory")
; #define PG8_BAR __builtin_amdgcn_s_barrier()
; template <class Epi>
; __device__ __forceinline__ void gemm_phase(LAS unsigned char* lds, const Gemm g, const StaticOrder& S, const Epi& E) {
;     ...
;             PG8_LDB(B0, 0, 0); PG8_LDB(B1, 0, 1); PG8_SCHED; PG8_LDA(At, 0, 0); PG8_STAGE(PG8_SA(1, 1), a1 + hstepA, voffA);
;             PG8_WAIT_V(8); PG8_WAIT_L(0); PG8_BAR; PG8_MMA(0, 0, At, B0); PG8_MMA(0, 1, At, B1); PG8_BAR; PG8_SCHED;
;             PG8_LDA(At, 0, 1); PG8_STAGE(PG8_SB(0, 0), b2, voffB); PG8_STAGE(PG8_SB(0, 1), b2 + hstepB, voffB); PG8_STAGE(PG8_SA(0, 0), a2, voffA);
;             PG8_WAIT_V(8); PG8_WAIT_L(0); PG8_BAR; PG8_MMA(1, 0, At, B0); PG8_MMA(1, 1, At, B1); PG8_BAR; PG8_SCHED;
;             PG8_LDB(B0, 1, 0); PG8_LDB(B1, 1, 1); PG8_SCHED; PG8_LDA(At, 1, 0); PG8_STAGE(PG8_SA(0, 1), a2 + hstepA, voffA);
;             PG8_WAIT_V(8); PG8_WAIT_L(0); PG8_BAR; PG8_MMA(0, 0, At, B0); PG8_MMA(0, 1, At, B1); PG8_BAR; PG8_SCHED;
;             PG8_LDA(At, 1, 1); PG8_STAGE(PG8_SB(1, 0), b3, voffB); PG8_STAGE(PG8_SB(1, 1), b3 + hstepB, voffB); PG8_STAGE(PG8_SA(1, 0), a3, voffA);
;             PG8_WAIT_V(8); PG8_WAIT_L(0); PG8_BAR; PG8_MMA(1, 0, At, B0); PG8_MMA(1, 1, At, B1); PG8_BAR; PG8_SCHED;
	s_waitcnt lgkmcnt(0)
	v_mfma_f32_16x16x32_bf16 v[124:127], v[146:149], v[198:201], v[124:127]
	v_mfma_f32_16x16x32_bf16 v[120:123], v[170:173], v[198:201], v[120:123]
	v_mfma_f32_16x16x32_bf16 v[112:115], v[146:149], v[206:209], v[112:115]
	v_mfma_f32_16x16x32_bf16 v[104:107], v[170:173], v[206:209], v[104:107]
	v_mfma_f32_16x16x32_bf16 v[100:103], v[146:149], v[214:217], v[100:103]
	v_mfma_f32_16x16x32_bf16 v[92:95], v[170:173], v[214:217], v[92:95]
	v_mfma_f32_16x16x32_bf16 v[84:87], v[146:149], v[222:225], v[84:87]
	v_mfma_f32_16x16x32_bf16 v[76:79], v[170:173], v[222:225], v[76:79]
	v_mfma_f32_16x16x32_bf16 v[124:127], v[166:169], v[202:205], v[124:127]
	v_mfma_f32_16x16x32_bf16 v[120:123], v[178:181], v[202:205], v[120:123]
	v_mfma_f32_16x16x32_bf16 v[112:115], v[166:169], v[210:213], v[112:115]
	v_mfma_f32_16x16x32_bf16 v[104:107], v[178:181], v[210:213], v[104:107]
	v_mfma_f32_16x16x32_bf16 v[100:103], v[166:169], v[218:221], v[100:103]
	v_mfma_f32_16x16x32_bf16 v[92:95], v[178:181], v[218:221], v[92:95]
	v_mfma_f32_16x16x32_bf16 v[84:87], v[166:169], v[226:229], v[84:87]
	v_mfma_f32_16x16x32_bf16 v[76:79], v[178:181], v[226:229], v[76:79]
	v_mfma_f32_16x16x32_bf16 v[116:119], v[182:185], v[198:201], v[116:119]
	v_mfma_f32_16x16x32_bf16 v[108:111], v[190:193], v[198:201], v[108:111]
	v_mfma_f32_16x16x32_bf16 v[96:99], v[182:185], v[206:209], v[96:99]
	v_mfma_f32_16x16x32_bf16 v[88:91], v[190:193], v[206:209], v[88:91]
	v_mfma_f32_16x16x32_bf16 v[80:83], v[182:185], v[214:217], v[80:83]
	v_mfma_f32_16x16x32_bf16 v[72:75], v[190:193], v[214:217], v[72:75]
	v_mfma_f32_16x16x32_bf16 v[68:71], v[182:185], v[222:225], v[68:71]
	v_mfma_f32_16x16x32_bf16 v[64:67], v[190:193], v[222:225], v[64:67]
	v_mfma_f32_16x16x32_bf16 v[116:119], v[186:189], v[202:205], v[116:119]
	v_mfma_f32_16x16x32_bf16 v[108:111], v[194:197], v[202:205], v[108:111]
	v_mfma_f32_16x16x32_bf16 v[96:99], v[186:189], v[210:213], v[96:99]
	v_mfma_f32_16x16x32_bf16 v[88:91], v[194:197], v[210:213], v[88:91]
	v_mfma_f32_16x16x32_bf16 v[80:83], v[186:189], v[218:221], v[80:83]
	v_mfma_f32_16x16x32_bf16 v[72:75], v[194:197], v[218:221], v[72:75]
	v_mfma_f32_16x16x32_bf16 v[68:71], v[186:189], v[226:229], v[68:71]
	v_mfma_f32_16x16x32_bf16 v[64:67], v[194:197], v[226:229], v[64:67]
	s_barrier
	s_add_i32 s88, s83, s43
	v_lshl_add_u64 v[174:175], s[10:11], 0, v[130:131]
	s_mov_b32 m0, s88
	ds_read_b128 v[198:201], v164 offset:16384
	ds_read_b128 v[202:205], v164 offset:17408
	ds_read_b128 v[206:209], v164 offset:18432
	ds_read_b128 v[210:213], v164 offset:19456
	ds_read_b128 v[214:217], v164 offset:20480
	ds_read_b128 v[218:221], v164 offset:21504
	ds_read_b128 v[222:225], v164 offset:22528
	ds_read_b128 v[226:229], v164 offset:23552
	global_load_lds_dwordx4 v[174:175], off
	s_add_i32 m0, s88, 0x2000
	s_add_u32 s88, s10, 0x40000
	v_lshl_add_u64 v[230:231], s[10:11], 0, v[134:135]
	s_addc_u32 s89, s11, 0
	s_add_i32 s90, s84, s43
	global_load_lds_dwordx4 v[230:231], off
	s_mov_b32 m0, s90
	v_lshl_add_u64 v[234:235], s[12:13], 0, v[132:133]
	global_load_lds_dwordx4 v130, s[88:89]
	s_add_i32 m0, s90, 0x2000
	s_nop 0
	global_load_lds_dwordx4 v134, s[88:89]
	v_lshl_add_u64 v[232:233], s[12:13], 0, v[128:129]
	s_mov_b32 m0, s53
	s_nop 0
	global_load_lds_dwordx4 v[232:233], off
	s_mov_b32 m0, s55
	s_nop 0
	global_load_lds_dwordx4 v[234:235], off
	s_waitcnt vmcnt(8)
	s_waitcnt lgkmcnt(0)
	s_barrier
	s_waitcnt lgkmcnt(0)
	v_mfma_f32_16x16x32_bf16 v[60:63], v[146:149], v[198:201], v[60:63]
	v_mfma_f32_16x16x32_bf16 v[56:59], v[170:173], v[198:201], v[56:59]
	v_mfma_f32_16x16x32_bf16 v[52:55], v[146:149], v[206:209], v[52:55]
	v_mfma_f32_16x16x32_bf16 v[44:47], v[170:173], v[206:209], v[44:47]
	v_mfma_f32_16x16x32_bf16 v[36:39], v[146:149], v[214:217], v[36:39]
	v_mfma_f32_16x16x32_bf16 v[28:31], v[170:173], v[214:217], v[28:31]
	v_mfma_f32_16x16x32_bf16 v[20:23], v[146:149], v[222:225], v[20:23]
	v_mfma_f32_16x16x32_bf16 v[12:15], v[170:173], v[222:225], v[12:15]
	v_mfma_f32_16x16x32_bf16 v[60:63], v[166:169], v[202:205], v[60:63]
	v_mfma_f32_16x16x32_bf16 v[56:59], v[178:181], v[202:205], v[56:59]
	v_mfma_f32_16x16x32_bf16 v[52:55], v[166:169], v[210:213], v[52:55]
	v_mfma_f32_16x16x32_bf16 v[44:47], v[178:181], v[210:213], v[44:47]
	v_mfma_f32_16x16x32_bf16 v[36:39], v[166:169], v[218:221], v[36:39]
	v_mfma_f32_16x16x32_bf16 v[28:31], v[178:181], v[218:221], v[28:31]
	v_mfma_f32_16x16x32_bf16 v[20:23], v[166:169], v[226:229], v[20:23]
	v_mfma_f32_16x16x32_bf16 v[12:15], v[178:181], v[226:229], v[12:15]
	v_mfma_f32_16x16x32_bf16 v[48:51], v[182:185], v[198:201], v[48:51]
	v_mfma_f32_16x16x32_bf16 v[40:43], v[190:193], v[198:201], v[40:43]
	v_mfma_f32_16x16x32_bf16 v[32:35], v[182:185], v[206:209], v[32:35]
	v_mfma_f32_16x16x32_bf16 v[24:27], v[190:193], v[206:209], v[24:27]
	v_mfma_f32_16x16x32_bf16 v[16:19], v[182:185], v[214:217], v[16:19]
	v_mfma_f32_16x16x32_bf16 v[8:11], v[190:193], v[214:217], v[8:11]
	v_mfma_f32_16x16x32_bf16 v[4:7], v[182:185], v[222:225], v[4:7]
	v_mfma_f32_16x16x32_bf16 v[0:3], v[190:193], v[222:225], v[0:3]
	v_mfma_f32_16x16x32_bf16 v[48:51], v[186:189], v[202:205], v[48:51]
	v_mfma_f32_16x16x32_bf16 v[40:43], v[194:197], v[202:205], v[40:43]
	v_mfma_f32_16x16x32_bf16 v[32:35], v[186:189], v[210:213], v[32:35]
	v_mfma_f32_16x16x32_bf16 v[24:27], v[194:197], v[210:213], v[24:27]
	v_mfma_f32_16x16x32_bf16 v[16:19], v[186:189], v[218:221], v[16:19]
	v_mfma_f32_16x16x32_bf16 v[8:11], v[194:197], v[218:221], v[8:11]
	v_mfma_f32_16x16x32_bf16 v[4:7], v[186:189], v[226:229], v[4:7]
	v_mfma_f32_16x16x32_bf16 v[0:3], v[194:197], v[226:229], v[0:3]
	s_barrier
; #define PG8_STAGE(bufoff, gbase, voff) do { _Pragma("unroll") for (int _i = 0; _i < 2; ++_i) \
;         __builtin_amdgcn_global_load_lds((const unsigned*)((const char*)(gbase) + (voff)[_i]), (LAS unsigned*)(lds + (bufoff) + ldsw + _i * 8192), 16, 0, 0); } while (0)
; #define PG8_LDA(dst, b, h) do { _Pragma("unroll") for (int m = 0; m < 4; ++m) _Pragma("unroll") for (int k = 0; k < 2; ++k) dst[m][k] = *(const LAS bf16x8*)(lds + PG8_SA(b, h) + aoff + m * 2048 + k * 1024); } while (0)
; #define PG8_LDB(dst, b, h) do { _Pragma("unroll") for (int n = 0; n < 2; ++n) _Pragma("unroll") for (int k = 0; k < 2; ++k) dst[n][k] = *(const LAS bf16x8*)(lds + PG8_SB(b, h) + boff + n * 2048 + k * 1024); } while (0)
; #define PG8_MMA(ai, bj, At, Bt) do { __builtin_amdgcn_s_setprio(1); _Pragma("unroll") for (int m = 0; m < 4; ++m) _Pragma("unroll") for (int n = 0; n < 2; ++n) _Pragma("unroll") for (int k = 0; k < 2; ++k) \
;         acc[ai][bj][m][n] = __builtin_amdgcn_mfma_f32_16x16x32_bf16(Bt[n][k], At[m][k], acc[ai][bj][m][n], 0, 0, 0); __builtin_amdgcn_s_setprio(0); } while (0)
; #define PG8_WAIT_V(n) asm volatile("s_waitcnt vmcnt(" #n ")" ::: "memory")
; #define PG8_WAIT_L(n) asm volatile("s_waitcnt lgkmcnt(" #n ")" ::: "memory")
; #define PG8_BAR __builtin_amdgcn_s_barrier()
; #define PG8_SCHED __builtin_amdgcn_sched_barrier(0)
; template <class Epi>
; __device__ __forceinline__ void gemm_phase(LAS unsigned char* lds, const Gemm g, const StaticOrder& S, const Epi& E) {
;     ...
;             PG8_LDB(B0, 1, 0); PG8_LDB(B1, 1, 1); PG8_SCHED; PG8_LDA(At, 1, 0); PG8_STAGE(PG8_SA(0, 1), a2 + hstepA, voffA);
;             PG8_WAIT_V(8); PG8_WAIT_L(0); PG8_BAR; PG8_MMA(0, 0, At, B0); PG8_MMA(0, 1, At, B1); PG8_BAR; PG8_SCHED;
;             PG8_LDA(At, 1, 1); PG8_STAGE(PG8_SB(1, 0), b3, voffB); PG8_STAGE(PG8_SB(1, 1), b3 + hstepB, voffB); PG8_STAGE(PG8_SA(1, 0), a3, voffA);
;             PG8_WAIT_V(8); PG8_WAIT_L(0); PG8_BAR; PG8_MMA(1, 0, At, B0); PG8_MMA(1, 1, At, B1); PG8_BAR; PG8_SCHED;
;         }
;         if (wr == 0) PG8_BAR;
	s_add_i32 s88, 0, 0x18000
	v_add_u32_e32 v136, s88, v161
	s_add_i32 s89, 0, 0x1c000
	ds_read_b128 v[146:149], v136
	ds_read_b128 v[166:169], v136 offset:1024
	ds_read_b128 v[170:173], v136 offset:2048
	ds_read_b128 v[178:181], v136 offset:3072
	v_add_u32_e32 v136, s89, v161
	ds_read_b128 v[182:185], v136
	ds_read_b128 v[186:189], v136 offset:1024
	ds_read_b128 v[190:193], v136 offset:2048
	ds_read_b128 v[194:197], v136 offset:3072
	s_add_u32 s12, s12, 0x40000
	s_addc_u32 s13, s13, 0
	s_mov_b32 m0, s57
	ds_read_b128 v[198:201], v164 offset:32768
	ds_read_b128 v[202:205], v164 offset:33792
	ds_read_b128 v[206:209], v164 offset:34816
	ds_read_b128 v[210:213], v164 offset:35840
	ds_read_b128 v[214:217], v164 offset:36864
	ds_read_b128 v[218:221], v164 offset:37888
	ds_read_b128 v[222:225], v164 offset:38912
	ds_read_b128 v[226:229], v164 offset:39936
	global_load_lds_dwordx4 v128, s[12:13]
	v_lshl_add_u64 v[236:237], s[12:13], 0, v[132:133]
	s_mov_b32 m0, s59
	s_nop 0
	global_load_lds_dwordx4 v[236:237], off
	s_waitcnt vmcnt(8)
	s_waitcnt lgkmcnt(0)
	s_barrier
	s_waitcnt lgkmcnt(0)
	v_mfma_f32_16x16x32_bf16 v[124:127], v[146:149], v[198:201], v[124:127]
	v_mfma_f32_16x16x32_bf16 v[120:123], v[170:173], v[198:201], v[120:123]
	v_mfma_f32_16x16x32_bf16 v[112:115], v[146:149], v[206:209], v[112:115]
	v_mfma_f32_16x16x32_bf16 v[104:107], v[170:173], v[206:209], v[104:107]
	v_mfma_f32_16x16x32_bf16 v[100:103], v[146:149], v[214:217], v[100:103]
	v_mfma_f32_16x16x32_bf16 v[92:95], v[170:173], v[214:217], v[92:95]
	v_mfma_f32_16x16x32_bf16 v[84:87], v[146:149], v[222:225], v[84:87]
	v_mfma_f32_16x16x32_bf16 v[76:79], v[170:173], v[222:225], v[76:79]
	v_mfma_f32_16x16x32_bf16 v[124:127], v[166:169], v[202:205], v[124:127]
	v_mfma_f32_16x16x32_bf16 v[120:123], v[178:181], v[202:205], v[120:123]
	v_mfma_f32_16x16x32_bf16 v[112:115], v[166:169], v[210:213], v[112:115]
	v_mfma_f32_16x16x32_bf16 v[104:107], v[178:181], v[210:213], v[104:107]
	v_mfma_f32_16x16x32_bf16 v[100:103], v[166:169], v[218:221], v[100:103]
	v_mfma_f32_16x16x32_bf16 v[92:95], v[178:181], v[218:221], v[92:95]
	v_mfma_f32_16x16x32_bf16 v[84:87], v[166:169], v[226:229], v[84:87]
	v_mfma_f32_16x16x32_bf16 v[76:79], v[178:181], v[226:229], v[76:79]
	v_mfma_f32_16x16x32_bf16 v[116:119], v[182:185], v[198:201], v[116:119]
	v_mfma_f32_16x16x32_bf16 v[108:111], v[190:193], v[198:201], v[108:111]
	v_mfma_f32_16x16x32_bf16 v[96:99], v[182:185], v[206:209], v[96:99]
	v_mfma_f32_16x16x32_bf16 v[88:91], v[190:193], v[206:209], v[88:91]
	v_mfma_f32_16x16x32_bf16 v[80:83], v[182:185], v[214:217], v[80:83]
	v_mfma_f32_16x16x32_bf16 v[72:75], v[190:193], v[214:217], v[72:75]
	v_mfma_f32_16x16x32_bf16 v[68:71], v[182:185], v[222:225], v[68:71]
	v_mfma_f32_16x16x32_bf16 v[64:67], v[190:193], v[222:225], v[64:67]
	v_mfma_f32_16x16x32_bf16 v[116:119], v[186:189], v[202:205], v[116:119]
	v_mfma_f32_16x16x32_bf16 v[108:111], v[194:197], v[202:205], v[108:111]
	v_mfma_f32_16x16x32_bf16 v[96:99], v[186:189], v[210:213], v[96:99]
	v_mfma_f32_16x16x32_bf16 v[88:91], v[194:197], v[210:213], v[88:91]
	v_mfma_f32_16x16x32_bf16 v[80:83], v[186:189], v[218:221], v[80:83]
	v_mfma_f32_16x16x32_bf16 v[72:75], v[194:197], v[218:221], v[72:75]
	v_mfma_f32_16x16x32_bf16 v[68:71], v[186:189], v[226:229], v[68:71]
	v_mfma_f32_16x16x32_bf16 v[64:67], v[194:197], v[226:229], v[64:67]
	s_barrier
	s_add_i32 s12, s88, s43
	v_lshl_add_u64 v[174:175], v[174:175], 0, s[34:35]
	s_mov_b32 m0, s12
	ds_read_b128 v[198:201], v164 offset:49152
	ds_read_b128 v[202:205], v164 offset:50176
	ds_read_b128 v[206:209], v164 offset:51200
	ds_read_b128 v[210:213], v164 offset:52224
	ds_read_b128 v[214:217], v164 offset:53248
	ds_read_b128 v[218:221], v164 offset:54272
	ds_read_b128 v[222:225], v164 offset:55296
	ds_read_b128 v[226:229], v164 offset:56320
	global_load_lds_dwordx4 v[174:175], off
	s_add_i32 m0, s12, 0x2000
	s_add_u32 s10, s10, 0x40080
	v_lshl_add_u64 v[174:175], v[230:231], 0, s[34:35]
	s_addc_u32 s11, s11, 0
	s_add_i32 s12, s89, s43
	global_load_lds_dwordx4 v[174:175], off
	s_mov_b32 m0, s12
	s_nop 0
	global_load_lds_dwordx4 v130, s[10:11]
	s_add_i32 m0, s12, 0x2000
	s_nop 0
	global_load_lds_dwordx4 v134, s[10:11]
	v_lshl_add_u64 v[174:175], v[232:233], 0, s[34:35]
	s_mov_b32 m0, s77
	s_nop 0
	global_load_lds_dwordx4 v[174:175], off
	v_lshl_add_u64 v[174:175], v[234:235], 0, s[34:35]
	s_mov_b32 m0, s78
	s_nop 0
	global_load_lds_dwordx4 v[174:175], off
	s_waitcnt vmcnt(8)
	s_waitcnt lgkmcnt(0)
	s_barrier
	s_waitcnt lgkmcnt(0)
	v_mfma_f32_16x16x32_bf16 v[60:63], v[146:149], v[198:201], v[60:63]
	v_mfma_f32_16x16x32_bf16 v[56:59], v[170:173], v[198:201], v[56:59]
	v_mfma_f32_16x16x32_bf16 v[52:55], v[146:149], v[206:209], v[52:55]
	v_mfma_f32_16x16x32_bf16 v[44:47], v[170:173], v[206:209], v[44:47]
	v_mfma_f32_16x16x32_bf16 v[36:39], v[146:149], v[214:217], v[36:39]
	v_mfma_f32_16x16x32_bf16 v[28:31], v[170:173], v[214:217], v[28:31]
	v_mfma_f32_16x16x32_bf16 v[20:23], v[146:149], v[222:225], v[20:23]
	v_mfma_f32_16x16x32_bf16 v[12:15], v[170:173], v[222:225], v[12:15]
	v_mfma_f32_16x16x32_bf16 v[60:63], v[166:169], v[202:205], v[60:63]
	v_mfma_f32_16x16x32_bf16 v[56:59], v[178:181], v[202:205], v[56:59]
	v_mfma_f32_16x16x32_bf16 v[52:55], v[166:169], v[210:213], v[52:55]
	v_mfma_f32_16x16x32_bf16 v[44:47], v[178:181], v[210:213], v[44:47]
	v_mfma_f32_16x16x32_bf16 v[36:39], v[166:169], v[218:221], v[36:39]
	v_mfma_f32_16x16x32_bf16 v[28:31], v[178:181], v[218:221], v[28:31]
	v_mfma_f32_16x16x32_bf16 v[20:23], v[166:169], v[226:229], v[20:23]
	v_mfma_f32_16x16x32_bf16 v[12:15], v[178:181], v[226:229], v[12:15]
	v_mfma_f32_16x16x32_bf16 v[48:51], v[182:185], v[198:201], v[48:51]
	v_mfma_f32_16x16x32_bf16 v[40:43], v[190:193], v[198:201], v[40:43]
	v_mfma_f32_16x16x32_bf16 v[32:35], v[182:185], v[206:209], v[32:35]
	v_mfma_f32_16x16x32_bf16 v[24:27], v[190:193], v[206:209], v[24:27]
	v_mfma_f32_16x16x32_bf16 v[16:19], v[182:185], v[214:217], v[16:19]
	v_mfma_f32_16x16x32_bf16 v[8:11], v[190:193], v[214:217], v[8:11]
	v_mfma_f32_16x16x32_bf16 v[4:7], v[182:185], v[222:225], v[4:7]
	v_mfma_f32_16x16x32_bf16 v[0:3], v[190:193], v[222:225], v[0:3]
	v_mfma_f32_16x16x32_bf16 v[48:51], v[186:189], v[202:205], v[48:51]
	v_mfma_f32_16x16x32_bf16 v[40:43], v[194:197], v[202:205], v[40:43]
	v_mfma_f32_16x16x32_bf16 v[32:35], v[186:189], v[210:213], v[32:35]
	v_mfma_f32_16x16x32_bf16 v[24:27], v[194:197], v[210:213], v[24:27]
	v_mfma_f32_16x16x32_bf16 v[16:19], v[186:189], v[218:221], v[16:19]
	v_mfma_f32_16x16x32_bf16 v[8:11], v[194:197], v[218:221], v[8:11]
	v_mfma_f32_16x16x32_bf16 v[4:7], v[186:189], v[226:229], v[4:7]
	v_mfma_f32_16x16x32_bf16 v[0:3], v[194:197], v[226:229], v[0:3]
	s_barrier
	s_add_i32 s87, s87, 2
	s_add_u32 s8, s8, 0x100
	s_addc_u32 s9, s9, 0
	s_add_u32 s74, s74, 0x100
	s_addc_u32 s75, s75, 0
	s_cmp_gt_u32 s87, 13
	s_cbranch_scc0 .LBB0_1403
	s_and_b64 vcc, exec, s[38:39]
	s_cbranch_vccz .LBB0_1406
	s_barrier

; #define PG8_STAGE(bufoff, gbase, voff) do { _Pragma("unroll") for (int _i = 0; _i < 2; ++_i) \
;         __builtin_amdgcn_global_load_lds((const unsigned*)((const char*)(gbase) + (voff)[_i]), (LAS unsigned*)(lds + (bufoff) + ldsw + _i * 8192), 16, 0, 0); } while (0)
; #define PG8_LDA(dst, b, h) do { _Pragma("unroll") for (int m = 0; m < 4; ++m) _Pragma("unroll") for (int k = 0; k < 2; ++k) dst[m][k] = *(const LAS bf16x8*)(lds + PG8_SA(b, h) + aoff + m * 2048 + k * 1024); } while (0)
; #define PG8_LDB(dst, b, h) do { _Pragma("unroll") for (int n = 0; n < 2; ++n) _Pragma("unroll") for (int k = 0; k < 2; ++k) dst[n][k] = *(const LAS bf16x8*)(lds + PG8_SB(b, h) + boff + n * 2048 + k * 1024); } while (0)
; #define PG8_MMA(ai, bj, At, Bt) do { __builtin_amdgcn_s_setprio(1); _Pragma("unroll") for (int m = 0; m < 4; ++m) _Pragma("unroll") for (int n = 0; n < 2; ++n) _Pragma("unroll") for (int k = 0; k < 2; ++k) \
;         acc[ai][bj][m][n] = __builtin_amdgcn_mfma_f32_16x16x32_bf16(Bt[n][k], At[m][k], acc[ai][bj][m][n], 0, 0, 0); __builtin_amdgcn_s_setprio(0); } while (0)
; #define PG8_BAR __builtin_amdgcn_s_barrier()
; template <class Epi>
; __device__ __forceinline__ void gemm_phase(LAS unsigned char* lds, const Gemm g, const StaticOrder& S, const Epi& E) {
;     ...
;         const bool has_next = S.next(ui + 1, nxt);
;         const char* nA = has_next ? (const char*)g.A + (size_t)nxt.pm * tstepA : cA; const char* nB = has_next ? (const char*)g.Bt + (size_t)nxt.pn * tstepB : cB;
; #pragma nounroll
;         for (int t = 0; t < nt; t += 2) {
;             const bool last = (t == nt - 2);
;             const char* a1 = cA + (size_t)(t + 1) * kstep;
;             const char* a2 = last ? nA : cA + (size_t)(t + 2) * kstep; const char* b2 = last ? nB : cB + (size_t)(t + 2) * kstep;
;             const char* a3 = a2 + kstep; const char* b3 = b2 + kstep;
;             PG8_LDB(B0, 0, 0); PG8_LDB(B1, 0, 1); PG8_SCHED; PG8_LDA(At, 0, 0); PG8_STAGE(PG8_SA(1, 1), a1 + hstepA, voffA);
;             PG8_WAIT_V(8); PG8_WAIT_L(0); PG8_BAR; PG8_MMA(0, 0, At, B0); PG8_MMA(0, 1, At, B1); PG8_BAR; PG8_SCHED;
;             PG8_LDA(At, 0, 1); PG8_STAGE(PG8_SB(0, 0), b2, voffB); PG8_STAGE(PG8_SB(0, 1), b2 + hstepB, voffB); PG8_STAGE(PG8_SA(0, 0), a2, voffA);
;             PG8_WAIT_V(8); PG8_WAIT_L(0); PG8_BAR; PG8_MMA(1, 0, At, B0); PG8_MMA(1, 1, At, B1); PG8_BAR; PG8_SCHED;
.LBB0_1469:
	s_add_u32 s62, s42, s56
	s_addc_u32 s63, s43, s57
	s_add_u32 s60, s62, 0x100
	s_addc_u32 s61, s63, 0
	s_and_b64 s[58:59], s[54:55], exec
	s_cselect_b32 s59, s1, s61
	s_cselect_b32 s58, s19, s60
	s_add_u32 s56, s38, s56
	s_addc_u32 s57, s39, s57
	s_add_u32 s56, s56, 0x100
	s_addc_u32 s57, s57, 0
	s_and_b64 s[54:55], s[54:55], exec
	s_cselect_b32 s61, s17, s57
	s_cselect_b32 s60, s84, s56
	s_add_u32 s64, s62, 0x10080
	ds_read_b128 v[140:143], v145
	ds_read_b128 v[154:157], v145 offset:1024
	ds_read_b128 v[158:161], v145 offset:2048
	ds_read_b128 v[162:165], v145 offset:3072
	ds_read_b128 v[166:169], v146
	ds_read_b128 v[170:173], v146 offset:1024
	ds_read_b128 v[178:181], v146 offset:2048
	ds_read_b128 v[182:185], v146 offset:3072
	s_addc_u32 s65, s63, 0
	s_add_i32 s94, s82, s70
	s_add_i32 m0, s35, 0xc000
	s_add_i32 s95, s35, 0xe000
	s_add_i32 s91, s94, 0x2000
	s_add_u32 s62, s60, 0x10000
	s_addc_u32 s63, s61, 0
	s_add_i32 s93, s83, s70
	s_add_i32 s92, s93, 0x2000
	s_add_i32 s90, 0, 0x18000
	s_add_i32 s89, 0, 0x1c000
	s_add_u32 s56, s58, 0x10000
	s_addc_u32 s57, s59, 0
	s_add_i32 s88, s90, s70
	s_add_i32 s86, s88, 0x2000
	s_add_u32 s54, s60, 0x10080
	s_addc_u32 s55, s61, 0
	s_add_i32 s87, s89, s70
	s_add_i32 s85, s87, 0x2000
	ds_read_b128 v[186:189], v147
	ds_read_b128 v[190:193], v147 offset:1024
	ds_read_b128 v[194:197], v147 offset:2048
	ds_read_b128 v[198:201], v147 offset:3072
	ds_read_b128 v[202:205], v147 offset:4096
	ds_read_b128 v[206:209], v147 offset:5120
	ds_read_b128 v[210:213], v147 offset:6144
	ds_read_b128 v[214:217], v147 offset:7168
	global_load_lds_dwordx4 v128, s[64:65]
	s_mov_b32 m0, s95
	s_nop 0
	global_load_lds_dwordx4 v132, s[64:65]
	s_waitcnt vmcnt(8)
	s_waitcnt lgkmcnt(0)
	s_barrier
	s_waitcnt lgkmcnt(0)
	v_mfma_f32_16x16x32_bf16 v[124:127], v[140:143], v[186:189], v[124:127]
	v_mfma_f32_16x16x32_bf16 v[120:123], v[158:161], v[186:189], v[120:123]
	v_mfma_f32_16x16x32_bf16 v[108:111], v[140:143], v[194:197], v[108:111]
	v_mfma_f32_16x16x32_bf16 v[104:107], v[158:161], v[194:197], v[104:107]
	v_mfma_f32_16x16x32_bf16 v[92:95], v[140:143], v[202:205], v[92:95]
	v_mfma_f32_16x16x32_bf16 v[88:91], v[158:161], v[202:205], v[88:91]
	v_mfma_f32_16x16x32_bf16 v[76:79], v[140:143], v[210:213], v[76:79]
	v_mfma_f32_16x16x32_bf16 v[72:75], v[158:161], v[210:213], v[72:75]
	v_mfma_f32_16x16x32_bf16 v[124:127], v[154:157], v[190:193], v[124:127]
	v_mfma_f32_16x16x32_bf16 v[120:123], v[162:165], v[190:193], v[120:123]
	v_mfma_f32_16x16x32_bf16 v[108:111], v[154:157], v[198:201], v[108:111]
	v_mfma_f32_16x16x32_bf16 v[104:107], v[162:165], v[198:201], v[104:107]
	v_mfma_f32_16x16x32_bf16 v[92:95], v[154:157], v[206:209], v[92:95]
	v_mfma_f32_16x16x32_bf16 v[88:91], v[162:165], v[206:209], v[88:91]
	v_mfma_f32_16x16x32_bf16 v[76:79], v[154:157], v[214:217], v[76:79]
	v_mfma_f32_16x16x32_bf16 v[72:75], v[162:165], v[214:217], v[72:75]
	v_mfma_f32_16x16x32_bf16 v[116:119], v[166:169], v[186:189], v[116:119]
	v_mfma_f32_16x16x32_bf16 v[112:115], v[178:181], v[186:189], v[112:115]
	v_mfma_f32_16x16x32_bf16 v[100:103], v[166:169], v[194:197], v[100:103]
	v_mfma_f32_16x16x32_bf16 v[96:99], v[178:181], v[194:197], v[96:99]
	v_mfma_f32_16x16x32_bf16 v[84:87], v[166:169], v[202:205], v[84:87]
	v_mfma_f32_16x16x32_bf16 v[80:83], v[178:181], v[202:205], v[80:83]
	v_mfma_f32_16x16x32_bf16 v[68:71], v[166:169], v[210:213], v[68:71]
	v_mfma_f32_16x16x32_bf16 v[64:67], v[178:181], v[210:213], v[64:67]
	v_mfma_f32_16x16x32_bf16 v[116:119], v[170:173], v[190:193], v[116:119]
	v_mfma_f32_16x16x32_bf16 v[112:115], v[182:185], v[190:193], v[112:115]
	v_mfma_f32_16x16x32_bf16 v[100:103], v[170:173], v[198:201], v[100:103]
	v_mfma_f32_16x16x32_bf16 v[96:99], v[182:185], v[198:201], v[96:99]
	v_mfma_f32_16x16x32_bf16 v[84:87], v[170:173], v[206:209], v[84:87]
	v_mfma_f32_16x16x32_bf16 v[80:83], v[182:185], v[206:209], v[80:83]
	v_mfma_f32_16x16x32_bf16 v[68:71], v[170:173], v[214:217], v[68:71]
	v_mfma_f32_16x16x32_bf16 v[64:67], v[182:185], v[214:217], v[64:67]
	s_barrier
	s_mov_b32 m0, s94
	v_lshl_add_u64 v[174:175], s[60:61], 0, v[130:131]
	ds_read_b128 v[186:189], v147 offset:16384
	ds_read_b128 v[190:193], v147 offset:17408
	ds_read_b128 v[194:197], v147 offset:18432
	ds_read_b128 v[198:201], v147 offset:19456
	ds_read_b128 v[202:205], v147 offset:20480
	ds_read_b128 v[206:209], v147 offset:21504
	ds_read_b128 v[210:213], v147 offset:22528
	ds_read_b128 v[214:217], v147 offset:23552
	global_load_lds_dwordx4 v[174:175], off
	v_lshl_add_u64 v[218:219], s[60:61], 0, v[134:135]
	s_mov_b32 m0, s91
	global_load_lds_dwordx4 v[218:219], off
	s_mov_b32 m0, s93
	v_lshl_add_u64 v[222:223], s[58:59], 0, v[132:133]
	global_load_lds_dwordx4 v130, s[62:63]
	s_mov_b32 m0, s92
	s_nop 0
	global_load_lds_dwordx4 v134, s[62:63]
	v_lshl_add_u64 v[220:221], s[58:59], 0, v[128:129]
	s_mov_b32 m0, s35
	s_nop 0
	global_load_lds_dwordx4 v[220:221], off
	s_mov_b32 m0, s71
	s_nop 0
	global_load_lds_dwordx4 v[222:223], off
	s_waitcnt vmcnt(8)
	s_waitcnt lgkmcnt(0)
	s_barrier
; #define PG8_STAGE(bufoff, gbase, voff) do { _Pragma("unroll") for (int _i = 0; _i < 2; ++_i) \
;         __builtin_amdgcn_global_load_lds((const unsigned*)((const char*)(gbase) + (voff)[_i]), (LAS unsigned*)(lds + (bufoff) + ldsw + _i * 8192), 16, 0, 0); } while (0)
; #define PG8_LDA(dst, b, h) do { _Pragma("unroll") for (int m = 0; m < 4; ++m) _Pragma("unroll") for (int k = 0; k < 2; ++k) dst[m][k] = *(const LAS bf16x8*)(lds + PG8_SA(b, h) + aoff + m * 2048 + k * 1024); } while (0)
; #define PG8_LDB(dst, b, h) do { _Pragma("unroll") for (int n = 0; n < 2; ++n) _Pragma("unroll") for (int k = 0; k < 2; ++k) dst[n][k] = *(const LAS bf16x8*)(lds + PG8_SB(b, h) + boff + n * 2048 + k * 1024); } while (0)
; #define PG8_MMA(ai, bj, At, Bt) do { __builtin_amdgcn_s_setprio(1); _Pragma("unroll") for (int m = 0; m < 4; ++m) _Pragma("unroll") for (int n = 0; n < 2; ++n) _Pragma("unroll") for (int k = 0; k < 2; ++k) \
;         acc[ai][bj][m][n] = __builtin_amdgcn_mfma_f32_16x16x32_bf16(Bt[n][k], At[m][k], acc[ai][bj][m][n], 0, 0, 0); __builtin_amdgcn_s_setprio(0); } while (0)
; #define PG8_WAIT_V(n) asm volatile("s_waitcnt vmcnt(" #n ")" ::: "memory")
; #define PG8_WAIT_L(n) asm volatile("s_waitcnt lgkmcnt(" #n ")" ::: "memory")
; #define PG8_BAR __builtin_amdgcn_s_barrier()
; #define PG8_SCHED __builtin_amdgcn_sched_barrier(0)
; template <class Epi>
; __device__ __forceinline__ void gemm_phase(LAS unsigned char* lds, const Gemm g, const StaticOrder& S, const Epi& E) {
;     ...
;             PG8_WAIT_V(8); PG8_WAIT_L(0); PG8_BAR; PG8_MMA(1, 0, At, B0); PG8_MMA(1, 1, At, B1); PG8_BAR; PG8_SCHED;
;             PG8_LDB(B0, 1, 0); PG8_LDB(B1, 1, 1); PG8_SCHED; PG8_LDA(At, 1, 0); PG8_STAGE(PG8_SA(0, 1), a2 + hstepA, voffA);
;             PG8_WAIT_V(8); PG8_WAIT_L(0); PG8_BAR; PG8_MMA(0, 0, At, B0); PG8_MMA(0, 1, At, B1); PG8_BAR; PG8_SCHED;
	s_waitcnt lgkmcnt(0)
	v_mfma_f32_16x16x32_bf16 v[60:63], v[140:143], v[186:189], v[60:63]
	v_mfma_f32_16x16x32_bf16 v[56:59], v[158:161], v[186:189], v[56:59]
	v_mfma_f32_16x16x32_bf16 v[44:47], v[140:143], v[194:197], v[44:47]
	v_mfma_f32_16x16x32_bf16 v[40:43], v[158:161], v[194:197], v[40:43]
	v_mfma_f32_16x16x32_bf16 v[28:31], v[140:143], v[202:205], v[28:31]
	v_mfma_f32_16x16x32_bf16 v[24:27], v[158:161], v[202:205], v[24:27]
	v_mfma_f32_16x16x32_bf16 v[12:15], v[140:143], v[210:213], v[12:15]
	v_mfma_f32_16x16x32_bf16 v[8:11], v[158:161], v[210:213], v[8:11]
	v_mfma_f32_16x16x32_bf16 v[60:63], v[154:157], v[190:193], v[60:63]
	v_mfma_f32_16x16x32_bf16 v[56:59], v[162:165], v[190:193], v[56:59]
	v_mfma_f32_16x16x32_bf16 v[44:47], v[154:157], v[198:201], v[44:47]
	v_mfma_f32_16x16x32_bf16 v[40:43], v[162:165], v[198:201], v[40:43]
	v_mfma_f32_16x16x32_bf16 v[28:31], v[154:157], v[206:209], v[28:31]
	v_mfma_f32_16x16x32_bf16 v[24:27], v[162:165], v[206:209], v[24:27]
	v_mfma_f32_16x16x32_bf16 v[12:15], v[154:157], v[214:217], v[12:15]
	v_mfma_f32_16x16x32_bf16 v[8:11], v[162:165], v[214:217], v[8:11]
	v_mfma_f32_16x16x32_bf16 v[52:55], v[166:169], v[186:189], v[52:55]
	v_mfma_f32_16x16x32_bf16 v[48:51], v[178:181], v[186:189], v[48:51]
	v_mfma_f32_16x16x32_bf16 v[36:39], v[166:169], v[194:197], v[36:39]
	v_mfma_f32_16x16x32_bf16 v[32:35], v[178:181], v[194:197], v[32:35]
	v_mfma_f32_16x16x32_bf16 v[20:23], v[166:169], v[202:205], v[20:23]
	v_mfma_f32_16x16x32_bf16 v[16:19], v[178:181], v[202:205], v[16:19]
	v_mfma_f32_16x16x32_bf16 v[4:7], v[166:169], v[210:213], v[4:7]
	v_mfma_f32_16x16x32_bf16 v[0:3], v[178:181], v[210:213], v[0:3]
	v_mfma_f32_16x16x32_bf16 v[52:55], v[170:173], v[190:193], v[52:55]
	v_mfma_f32_16x16x32_bf16 v[48:51], v[182:185], v[190:193], v[48:51]
	v_mfma_f32_16x16x32_bf16 v[36:39], v[170:173], v[198:201], v[36:39]
	v_mfma_f32_16x16x32_bf16 v[32:35], v[182:185], v[198:201], v[32:35]
	v_mfma_f32_16x16x32_bf16 v[20:23], v[170:173], v[206:209], v[20:23]
	v_mfma_f32_16x16x32_bf16 v[16:19], v[182:185], v[206:209], v[16:19]
	v_mfma_f32_16x16x32_bf16 v[4:7], v[170:173], v[214:217], v[4:7]
	v_mfma_f32_16x16x32_bf16 v[0:3], v[182:185], v[214:217], v[0:3]
	s_barrier
	v_add_u32_e32 v149, s90, v144
	ds_read_b128 v[140:143], v149
	ds_read_b128 v[154:157], v149 offset:1024
	ds_read_b128 v[158:161], v149 offset:2048
	ds_read_b128 v[162:165], v149 offset:3072
	v_add_u32_e32 v149, s89, v144
	ds_read_b128 v[166:169], v149
	ds_read_b128 v[170:173], v149 offset:1024
	ds_read_b128 v[178:181], v149 offset:2048
	ds_read_b128 v[182:185], v149 offset:3072
	s_mov_b32 m0, s72
	ds_read_b128 v[186:189], v147 offset:32768
	ds_read_b128 v[190:193], v147 offset:33792
	ds_read_b128 v[194:197], v147 offset:34816
	ds_read_b128 v[198:201], v147 offset:35840
	ds_read_b128 v[202:205], v147 offset:36864
	ds_read_b128 v[206:209], v147 offset:37888
	ds_read_b128 v[210:213], v147 offset:38912
	ds_read_b128 v[214:217], v147 offset:39936
	global_load_lds_dwordx4 v128, s[56:57]
	s_mov_b32 m0, s73
	s_nop 0
	global_load_lds_dwordx4 v132, s[56:57]
	s_waitcnt vmcnt(8)
	s_waitcnt lgkmcnt(0)
	s_barrier
	s_waitcnt lgkmcnt(0)
	v_mfma_f32_16x16x32_bf16 v[124:127], v[140:143], v[186:189], v[124:127]
	v_mfma_f32_16x16x32_bf16 v[120:123], v[158:161], v[186:189], v[120:123]
	v_mfma_f32_16x16x32_bf16 v[108:111], v[140:143], v[194:197], v[108:111]
	v_mfma_f32_16x16x32_bf16 v[104:107], v[158:161], v[194:197], v[104:107]
	v_mfma_f32_16x16x32_bf16 v[92:95], v[140:143], v[202:205], v[92:95]
	v_mfma_f32_16x16x32_bf16 v[88:91], v[158:161], v[202:205], v[88:91]
	v_mfma_f32_16x16x32_bf16 v[76:79], v[140:143], v[210:213], v[76:79]
	v_mfma_f32_16x16x32_bf16 v[72:75], v[158:161], v[210:213], v[72:75]
	v_mfma_f32_16x16x32_bf16 v[124:127], v[154:157], v[190:193], v[124:127]
	v_mfma_f32_16x16x32_bf16 v[120:123], v[162:165], v[190:193], v[120:123]
	v_mfma_f32_16x16x32_bf16 v[108:111], v[154:157], v[198:201], v[108:111]
	v_mfma_f32_16x16x32_bf16 v[104:107], v[162:165], v[198:201], v[104:107]
	v_mfma_f32_16x16x32_bf16 v[92:95], v[154:157], v[206:209], v[92:95]
	v_mfma_f32_16x16x32_bf16 v[88:91], v[162:165], v[206:209], v[88:91]
	v_mfma_f32_16x16x32_bf16 v[76:79], v[154:157], v[214:217], v[76:79]
	v_mfma_f32_16x16x32_bf16 v[72:75], v[162:165], v[214:217], v[72:75]
	v_mfma_f32_16x16x32_bf16 v[116:119], v[166:169], v[186:189], v[116:119]
	v_mfma_f32_16x16x32_bf16 v[112:115], v[178:181], v[186:189], v[112:115]
	v_mfma_f32_16x16x32_bf16 v[100:103], v[166:169], v[194:197], v[100:103]
	v_mfma_f32_16x16x32_bf16 v[96:99], v[178:181], v[194:197], v[96:99]
	v_mfma_f32_16x16x32_bf16 v[84:87], v[166:169], v[202:205], v[84:87]
	v_mfma_f32_16x16x32_bf16 v[80:83], v[178:181], v[202:205], v[80:83]
	v_mfma_f32_16x16x32_bf16 v[68:71], v[166:169], v[210:213], v[68:71]
	v_mfma_f32_16x16x32_bf16 v[64:67], v[178:181], v[210:213], v[64:67]
	v_mfma_f32_16x16x32_bf16 v[116:119], v[170:173], v[190:193], v[116:119]
	v_mfma_f32_16x16x32_bf16 v[112:115], v[182:185], v[190:193], v[112:115]
	v_mfma_f32_16x16x32_bf16 v[100:103], v[170:173], v[198:201], v[100:103]
	v_mfma_f32_16x16x32_bf16 v[96:99], v[182:185], v[198:201], v[96:99]
	v_mfma_f32_16x16x32_bf16 v[84:87], v[170:173], v[206:209], v[84:87]
	v_mfma_f32_16x16x32_bf16 v[80:83], v[182:185], v[206:209], v[80:83]
	v_mfma_f32_16x16x32_bf16 v[68:71], v[170:173], v[214:217], v[68:71]
	v_mfma_f32_16x16x32_bf16 v[64:67], v[182:185], v[214:217], v[64:67]
	s_barrier
; #define PG8_STAGE(bufoff, gbase, voff) do { _Pragma("unroll") for (int _i = 0; _i < 2; ++_i) \
;         __builtin_amdgcn_global_load_lds((const unsigned*)((const char*)(gbase) + (voff)[_i]), (LAS unsigned*)(lds + (bufoff) + ldsw + _i * 8192), 16, 0, 0); } while (0)
; #define PG8_LDA(dst, b, h) do { _Pragma("unroll") for (int m = 0; m < 4; ++m) _Pragma("unroll") for (int k = 0; k < 2; ++k) dst[m][k] = *(const LAS bf16x8*)(lds + PG8_SA(b, h) + aoff + m * 2048 + k * 1024); } while (0)
; #define PG8_MMA(ai, bj, At, Bt) do { __builtin_amdgcn_s_setprio(1); _Pragma("unroll") for (int m = 0; m < 4; ++m) _Pragma("unroll") for (int n = 0; n < 2; ++n) _Pragma("unroll") for (int k = 0; k < 2; ++k) \
;         acc[ai][bj][m][n] = __builtin_amdgcn_mfma_f32_16x16x32_bf16(Bt[n][k], At[m][k], acc[ai][bj][m][n], 0, 0, 0); __builtin_amdgcn_s_setprio(0); } while (0)
; #define PG8_WAIT_V(n) asm volatile("s_waitcnt vmcnt(" #n ")" ::: "memory")
; #define PG8_WAIT_L(n) asm volatile("s_waitcnt lgkmcnt(" #n ")" ::: "memory")
; #define PG8_BAR __builtin_amdgcn_s_barrier()
; #define PG8_SCHED __builtin_amdgcn_sched_barrier(0)
; template <class Epi>
; __device__ __forceinline__ void gemm_phase(LAS unsigned char* lds, const Gemm g, const StaticOrder& S, const Epi& E) {
;     ...
;             PG8_LDA(At, 1, 1); PG8_STAGE(PG8_SB(1, 0), b3, voffB); PG8_STAGE(PG8_SB(1, 1), b3 + hstepB, voffB); PG8_STAGE(PG8_SA(1, 0), a3, voffA);
;             PG8_WAIT_V(8); PG8_WAIT_L(0); PG8_BAR; PG8_MMA(1, 0, At, B0); PG8_MMA(1, 1, At, B1); PG8_BAR; PG8_SCHED;
;         }
;         if (wr == 0) PG8_BAR;
	s_mov_b32 m0, s88
	v_lshl_add_u64 v[174:175], v[174:175], 0, s[10:11]
	ds_read_b128 v[186:189], v147 offset:49152
	ds_read_b128 v[190:193], v147 offset:50176
	ds_read_b128 v[194:197], v147 offset:51200
	ds_read_b128 v[198:201], v147 offset:52224
	ds_read_b128 v[202:205], v147 offset:53248
	ds_read_b128 v[206:209], v147 offset:54272
	ds_read_b128 v[210:213], v147 offset:55296
	ds_read_b128 v[214:217], v147 offset:56320
	global_load_lds_dwordx4 v[174:175], off
	v_lshl_add_u64 v[174:175], v[218:219], 0, s[10:11]
	s_mov_b32 m0, s86
	s_nop 0
	global_load_lds_dwordx4 v[174:175], off
	s_mov_b32 m0, s87
	s_nop 0
	global_load_lds_dwordx4 v130, s[54:55]
	s_mov_b32 m0, s85
	s_nop 0
	global_load_lds_dwordx4 v134, s[54:55]
	v_lshl_add_u64 v[174:175], v[220:221], 0, s[10:11]
	s_mov_b32 m0, s77
	s_nop 0
	global_load_lds_dwordx4 v[174:175], off
	v_lshl_add_u64 v[174:175], v[222:223], 0, s[10:11]
	s_mov_b32 m0, s78
	s_nop 0
	global_load_lds_dwordx4 v[174:175], off
	s_waitcnt vmcnt(8)
	s_waitcnt lgkmcnt(0)
	s_barrier
	s_waitcnt lgkmcnt(0)
	v_mfma_f32_16x16x32_bf16 v[60:63], v[140:143], v[186:189], v[60:63]
	v_mfma_f32_16x16x32_bf16 v[56:59], v[158:161], v[186:189], v[56:59]
	v_mfma_f32_16x16x32_bf16 v[44:47], v[140:143], v[194:197], v[44:47]
	v_mfma_f32_16x16x32_bf16 v[40:43], v[158:161], v[194:197], v[40:43]
	v_mfma_f32_16x16x32_bf16 v[28:31], v[140:143], v[202:205], v[28:31]
	v_mfma_f32_16x16x32_bf16 v[24:27], v[158:161], v[202:205], v[24:27]
	v_mfma_f32_16x16x32_bf16 v[12:15], v[140:143], v[210:213], v[12:15]
	v_mfma_f32_16x16x32_bf16 v[8:11], v[158:161], v[210:213], v[8:11]
	v_mfma_f32_16x16x32_bf16 v[60:63], v[154:157], v[190:193], v[60:63]
	v_mfma_f32_16x16x32_bf16 v[56:59], v[162:165], v[190:193], v[56:59]
	v_mfma_f32_16x16x32_bf16 v[44:47], v[154:157], v[198:201], v[44:47]
	v_mfma_f32_16x16x32_bf16 v[40:43], v[162:165], v[198:201], v[40:43]
	v_mfma_f32_16x16x32_bf16 v[28:31], v[154:157], v[206:209], v[28:31]
	v_mfma_f32_16x16x32_bf16 v[24:27], v[162:165], v[206:209], v[24:27]
	v_mfma_f32_16x16x32_bf16 v[12:15], v[154:157], v[214:217], v[12:15]
	v_mfma_f32_16x16x32_bf16 v[8:11], v[162:165], v[214:217], v[8:11]
	v_mfma_f32_16x16x32_bf16 v[52:55], v[166:169], v[186:189], v[52:55]
	v_mfma_f32_16x16x32_bf16 v[48:51], v[178:181], v[186:189], v[48:51]
	v_mfma_f32_16x16x32_bf16 v[36:39], v[166:169], v[194:197], v[36:39]
	v_mfma_f32_16x16x32_bf16 v[32:35], v[178:181], v[194:197], v[32:35]
	v_mfma_f32_16x16x32_bf16 v[20:23], v[166:169], v[202:205], v[20:23]
	v_mfma_f32_16x16x32_bf16 v[16:19], v[178:181], v[202:205], v[16:19]
	v_mfma_f32_16x16x32_bf16 v[4:7], v[166:169], v[210:213], v[4:7]
	v_mfma_f32_16x16x32_bf16 v[0:3], v[178:181], v[210:213], v[0:3]
	v_mfma_f32_16x16x32_bf16 v[52:55], v[170:173], v[190:193], v[52:55]
	v_mfma_f32_16x16x32_bf16 v[48:51], v[182:185], v[190:193], v[48:51]
	v_mfma_f32_16x16x32_bf16 v[36:39], v[170:173], v[198:201], v[36:39]
	v_mfma_f32_16x16x32_bf16 v[32:35], v[182:185], v[198:201], v[32:35]
	v_mfma_f32_16x16x32_bf16 v[20:23], v[170:173], v[206:209], v[20:23]
	v_mfma_f32_16x16x32_bf16 v[16:19], v[182:185], v[206:209], v[16:19]
	v_mfma_f32_16x16x32_bf16 v[4:7], v[170:173], v[214:217], v[4:7]
	v_mfma_f32_16x16x32_bf16 v[0:3], v[182:185], v[214:217], v[0:3]
	s_barrier
	s_andn2_b64 vcc, exec, s[52:53]
	s_mov_b64 s[54:55], -1
	s_mov_b64 s[52:53], 0
	s_mov_b64 s[56:57], 0x100
	s_cbranch_vccz .LBB0_1469
	s_and_b64 vcc, exec, s[12:13]
	s_cbranch_vccz .LBB0_1472
	s_barrier

; #define PG8_STAGE(bufoff, gbase, voff) do { _Pragma("unroll") for (int _i = 0; _i < 2; ++_i) \
;         __builtin_amdgcn_global_load_lds((const unsigned*)((const char*)(gbase) + (voff)[_i]), (LAS unsigned*)(lds + (bufoff) + ldsw + _i * 8192), 16, 0, 0); } while (0)
; #define PG8_LDA(dst, b, h) do { _Pragma("unroll") for (int m = 0; m < 4; ++m) _Pragma("unroll") for (int k = 0; k < 2; ++k) dst[m][k] = *(const LAS bf16x8*)(lds + PG8_SA(b, h) + aoff + m * 2048 + k * 1024); } while (0)
; #define PG8_LDB(dst, b, h) do { _Pragma("unroll") for (int n = 0; n < 2; ++n) _Pragma("unroll") for (int k = 0; k < 2; ++k) dst[n][k] = *(const LAS bf16x8*)(lds + PG8_SB(b, h) + boff + n * 2048 + k * 1024); } while (0)
; #define PG8_WAIT_V(n) asm volatile("s_waitcnt vmcnt(" #n ")" ::: "memory")
; #define PG8_BAR __builtin_amdgcn_s_barrier()
; template <class Epi>
; __device__ __forceinline__ void gemm_phase(LAS unsigned char* lds, const Gemm g, const StaticOrder& S, const Epi& E) {
;     ...
;     f32x4 acc[2][2][4][2];
; #pragma unroll
;     for (int a = 0; a < 2; ++a)
; #pragma unroll
;         for (int b = 0; b < 2; ++b)
; #pragma unroll
;             for (int m = 0; m < 4; ++m)
; #pragma unroll
;                 for (int n = 0; n < 2; ++n) acc[a][b][m][n] = (f32x4){0.f, 0.f, 0.f, 0.f};
;     ...
;         const bool has_next = S.next(ui + 1, nxt);
;         const char* nA = has_next ? (const char*)g.A + (size_t)nxt.pm * tstepA : cA; const char* nB = has_next ? (const char*)g.Bt + (size_t)nxt.pn * tstepB : cB;
; #pragma nounroll
;         for (int t = 0; t < nt; t += 2) {
;             const bool last = (t == nt - 2);
;             const char* a1 = cA + (size_t)(t + 1) * kstep;
;             const char* a2 = last ? nA : cA + (size_t)(t + 2) * kstep; const char* b2 = last ? nB : cB + (size_t)(t + 2) * kstep;
;             const char* a3 = a2 + kstep; const char* b3 = b2 + kstep;
;             PG8_LDB(B0, 0, 0); PG8_LDB(B1, 0, 1); PG8_SCHED; PG8_LDA(At, 0, 0); PG8_STAGE(PG8_SA(1, 1), a1 + hstepA, voffA);
;             PG8_WAIT_V(8); PG8_WAIT_L(0); PG8_BAR; PG8_MMA(0, 0, At, B0); PG8_MMA(0, 1, At, B1); PG8_BAR; PG8_SCHED;
;             PG8_LDA(At, 0, 1); PG8_STAGE(PG8_SB(0, 0), b2, voffB); PG8_STAGE(PG8_SB(0, 1), b2 + hstepB, voffB); PG8_STAGE(PG8_SA(0, 0), a2, voffA);
;             PG8_WAIT_V(8); PG8_WAIT_L(0); PG8_BAR; PG8_MMA(1, 0, At, B0); PG8_MMA(1, 1, At, B1); PG8_BAR; PG8_SCHED;
.LBB0_1648:
	s_add_u32 s0, s0, 0xb0080
	s_addc_u32 s1, s1, 0
	s_add_u32 s61, s20, 0x100
	s_addc_u32 s62, s21, 0
	s_mov_b32 s63, -2
	s_waitcnt lgkmcnt(0)
	ds_read_b128 v[128:131], v182
	ds_read_b128 v[132:135], v182 offset:1024
	ds_read_b128 v[136:139], v182 offset:2048
	ds_read_b128 v[140:143], v182 offset:3072
	ds_read_b128 v[160:163], v183
	ds_read_b128 v[164:167], v183 offset:1024
	ds_read_b128 v[168:171], v183 offset:2048
	ds_read_b128 v[172:175], v183 offset:3072
	s_add_u32 s20, s0, 0xfff50080
	s_addc_u32 s21, s1, -1
	s_cmp_eq_u32 s63, 40
	s_cselect_b32 s23, s7, s21
	s_cselect_b32 s22, s6, s20
	s_cselect_b32 s21, s19, s62
	s_cselect_b32 s20, s18, s61
	s_add_i32 m0, s33, 0xc000
	ds_read_b128 v[186:189], v184
	ds_read_b128 v[190:193], v184 offset:1024
	ds_read_b128 v[194:197], v184 offset:2048
	ds_read_b128 v[198:201], v184 offset:3072
	ds_read_b128 v[202:205], v184 offset:4096
	ds_read_b128 v[206:209], v184 offset:5120
	ds_read_b128 v[210:213], v184 offset:6144
	ds_read_b128 v[214:217], v184 offset:7168
	global_load_lds_dwordx4 v152, s[0:1]
	s_add_i32 m0, s33, 0xe000
	s_nop 0
	global_load_lds_dwordx4 v154, s[0:1]
	s_waitcnt vmcnt(8)
	s_waitcnt lgkmcnt(0)
	s_barrier
	s_waitcnt lgkmcnt(0)
	v_mfma_f32_16x16x32_bf16 v[124:127], v[128:131], v[186:189], 0
	v_mfma_f32_16x16x32_bf16 v[120:123], v[136:139], v[186:189], 0
	v_mfma_f32_16x16x32_bf16 v[108:111], v[128:131], v[194:197], 0
	v_mfma_f32_16x16x32_bf16 v[104:107], v[136:139], v[194:197], 0
	v_mfma_f32_16x16x32_bf16 v[92:95], v[128:131], v[202:205], 0
	v_mfma_f32_16x16x32_bf16 v[88:91], v[136:139], v[202:205], 0
	v_mfma_f32_16x16x32_bf16 v[76:79], v[128:131], v[210:213], 0
	v_mfma_f32_16x16x32_bf16 v[72:75], v[136:139], v[210:213], 0
	v_mfma_f32_16x16x32_bf16 v[124:127], v[132:135], v[190:193], v[124:127]
	v_mfma_f32_16x16x32_bf16 v[120:123], v[140:143], v[190:193], v[120:123]
	v_mfma_f32_16x16x32_bf16 v[108:111], v[132:135], v[198:201], v[108:111]
	v_mfma_f32_16x16x32_bf16 v[104:107], v[140:143], v[198:201], v[104:107]
	v_mfma_f32_16x16x32_bf16 v[92:95], v[132:135], v[206:209], v[92:95]
	v_mfma_f32_16x16x32_bf16 v[88:91], v[140:143], v[206:209], v[88:91]
	v_mfma_f32_16x16x32_bf16 v[76:79], v[132:135], v[214:217], v[76:79]
	v_mfma_f32_16x16x32_bf16 v[72:75], v[140:143], v[214:217], v[72:75]
	v_mfma_f32_16x16x32_bf16 v[116:119], v[160:163], v[186:189], 0
	v_mfma_f32_16x16x32_bf16 v[112:115], v[168:171], v[186:189], 0
	v_mfma_f32_16x16x32_bf16 v[100:103], v[160:163], v[194:197], 0
	v_mfma_f32_16x16x32_bf16 v[96:99], v[168:171], v[194:197], 0
	v_mfma_f32_16x16x32_bf16 v[84:87], v[160:163], v[202:205], 0
	v_mfma_f32_16x16x32_bf16 v[80:83], v[168:171], v[202:205], 0
	v_mfma_f32_16x16x32_bf16 v[68:71], v[160:163], v[210:213], 0
	v_mfma_f32_16x16x32_bf16 v[64:67], v[168:171], v[210:213], 0
	v_mfma_f32_16x16x32_bf16 v[116:119], v[164:167], v[190:193], v[116:119]
	v_mfma_f32_16x16x32_bf16 v[112:115], v[172:175], v[190:193], v[112:115]
	v_mfma_f32_16x16x32_bf16 v[100:103], v[164:167], v[198:201], v[100:103]
	v_mfma_f32_16x16x32_bf16 v[96:99], v[172:175], v[198:201], v[96:99]
	v_mfma_f32_16x16x32_bf16 v[84:87], v[164:167], v[206:209], v[84:87]
	v_mfma_f32_16x16x32_bf16 v[80:83], v[172:175], v[206:209], v[80:83]
	v_mfma_f32_16x16x32_bf16 v[68:71], v[164:167], v[214:217], v[68:71]
	v_mfma_f32_16x16x32_bf16 v[64:67], v[172:175], v[214:217], v[64:67]
	s_barrier
	s_add_i32 s64, s55, s29
	v_lshl_add_u64 v[178:179], s[20:21], 0, v[146:147]
	s_mov_b32 m0, s64
	ds_read_b128 v[186:189], v184 offset:16384
	ds_read_b128 v[190:193], v184 offset:17408
	ds_read_b128 v[194:197], v184 offset:18432
	ds_read_b128 v[198:201], v184 offset:19456
	ds_read_b128 v[202:205], v184 offset:20480
	ds_read_b128 v[206:209], v184 offset:21504
	ds_read_b128 v[210:213], v184 offset:22528
	ds_read_b128 v[214:217], v184 offset:23552
	global_load_lds_dwordx4 v[178:179], off
	s_add_i32 m0, s64, 0x2000
	s_add_u32 s64, s20, 0xb0000
	v_lshl_add_u64 v[218:219], s[20:21], 0, v[150:151]
	s_addc_u32 s65, s21, 0
	s_add_i32 s66, s56, s29
	global_load_lds_dwordx4 v[218:219], off
	s_mov_b32 m0, s66
	v_lshl_add_u64 v[222:223], s[22:23], 0, v[148:149]
	global_load_lds_dwordx4 v146, s[64:65]
	s_add_i32 m0, s66, 0x2000
	s_nop 0
	global_load_lds_dwordx4 v150, s[64:65]
	v_lshl_add_u64 v[220:221], s[22:23], 0, v[144:145]
	s_mov_b32 m0, s33
	s_nop 0
	global_load_lds_dwordx4 v[220:221], off
	s_mov_b32 m0, s34
	s_nop 0
	global_load_lds_dwordx4 v[222:223], off
	s_waitcnt vmcnt(8)
	s_waitcnt lgkmcnt(0)
	s_barrier
	s_waitcnt lgkmcnt(0)
	v_mfma_f32_16x16x32_bf16 v[60:63], v[128:131], v[186:189], 0
	v_mfma_f32_16x16x32_bf16 v[56:59], v[136:139], v[186:189], 0
	v_mfma_f32_16x16x32_bf16 v[44:47], v[128:131], v[194:197], 0
	v_mfma_f32_16x16x32_bf16 v[40:43], v[136:139], v[194:197], 0
	v_mfma_f32_16x16x32_bf16 v[28:31], v[128:131], v[202:205], 0
	v_mfma_f32_16x16x32_bf16 v[24:27], v[136:139], v[202:205], 0
	v_mfma_f32_16x16x32_bf16 v[12:15], v[128:131], v[210:213], 0
	v_mfma_f32_16x16x32_bf16 v[8:11], v[136:139], v[210:213], 0
	v_mfma_f32_16x16x32_bf16 v[60:63], v[132:135], v[190:193], v[60:63]
	v_mfma_f32_16x16x32_bf16 v[56:59], v[140:143], v[190:193], v[56:59]
	v_mfma_f32_16x16x32_bf16 v[44:47], v[132:135], v[198:201], v[44:47]
	v_mfma_f32_16x16x32_bf16 v[40:43], v[140:143], v[198:201], v[40:43]
	v_mfma_f32_16x16x32_bf16 v[28:31], v[132:135], v[206:209], v[28:31]
	v_mfma_f32_16x16x32_bf16 v[24:27], v[140:143], v[206:209], v[24:27]
	v_mfma_f32_16x16x32_bf16 v[12:15], v[132:135], v[214:217], v[12:15]
	v_mfma_f32_16x16x32_bf16 v[8:11], v[140:143], v[214:217], v[8:11]
	v_mfma_f32_16x16x32_bf16 v[52:55], v[160:163], v[186:189], 0
	v_mfma_f32_16x16x32_bf16 v[48:51], v[168:171], v[186:189], 0
	v_mfma_f32_16x16x32_bf16 v[36:39], v[160:163], v[194:197], 0
	v_mfma_f32_16x16x32_bf16 v[32:35], v[168:171], v[194:197], 0
	v_mfma_f32_16x16x32_bf16 v[20:23], v[160:163], v[202:205], 0
	v_mfma_f32_16x16x32_bf16 v[16:19], v[168:171], v[202:205], 0
	v_mfma_f32_16x16x32_bf16 v[4:7], v[160:163], v[210:213], 0
	v_mfma_f32_16x16x32_bf16 v[0:3], v[168:171], v[210:213], 0
	v_mfma_f32_16x16x32_bf16 v[52:55], v[164:167], v[190:193], v[52:55]
	v_mfma_f32_16x16x32_bf16 v[48:51], v[172:175], v[190:193], v[48:51]
	v_mfma_f32_16x16x32_bf16 v[36:39], v[164:167], v[198:201], v[36:39]
	v_mfma_f32_16x16x32_bf16 v[32:35], v[172:175], v[198:201], v[32:35]
	v_mfma_f32_16x16x32_bf16 v[20:23], v[164:167], v[206:209], v[20:23]
	v_mfma_f32_16x16x32_bf16 v[16:19], v[172:175], v[206:209], v[16:19]
	v_mfma_f32_16x16x32_bf16 v[4:7], v[164:167], v[214:217], v[4:7]
	v_mfma_f32_16x16x32_bf16 v[0:3], v[172:175], v[214:217], v[0:3]
	s_barrier
; #define PG8_STAGE(bufoff, gbase, voff) do { _Pragma("unroll") for (int _i = 0; _i < 2; ++_i) \
;         __builtin_amdgcn_global_load_lds((const unsigned*)((const char*)(gbase) + (voff)[_i]), (LAS unsigned*)(lds + (bufoff) + ldsw + _i * 8192), 16, 0, 0); } while (0)
; #define PG8_LDA(dst, b, h) do { _Pragma("unroll") for (int m = 0; m < 4; ++m) _Pragma("unroll") for (int k = 0; k < 2; ++k) dst[m][k] = *(const LAS bf16x8*)(lds + PG8_SA(b, h) + aoff + m * 2048 + k * 1024); } while (0)
; #define PG8_LDB(dst, b, h) do { _Pragma("unroll") for (int n = 0; n < 2; ++n) _Pragma("unroll") for (int k = 0; k < 2; ++k) dst[n][k] = *(const LAS bf16x8*)(lds + PG8_SB(b, h) + boff + n * 2048 + k * 1024); } while (0)
; #define PG8_MMA(ai, bj, At, Bt) do { __builtin_amdgcn_s_setprio(1); _Pragma("unroll") for (int m = 0; m < 4; ++m) _Pragma("unroll") for (int n = 0; n < 2; ++n) _Pragma("unroll") for (int k = 0; k < 2; ++k) \
;         acc[ai][bj][m][n] = __builtin_amdgcn_mfma_f32_16x16x32_bf16(Bt[n][k], At[m][k], acc[ai][bj][m][n], 0, 0, 0); __builtin_amdgcn_s_setprio(0); } while (0)
; #define PG8_WAIT_V(n) asm volatile("s_waitcnt vmcnt(" #n ")" ::: "memory")
; #define PG8_WAIT_L(n) asm volatile("s_waitcnt lgkmcnt(" #n ")" ::: "memory")
; #define PG8_BAR __builtin_amdgcn_s_barrier()
; #define PG8_SCHED __builtin_amdgcn_sched_barrier(0)
; template <class Epi>
; __device__ __forceinline__ void gemm_phase(LAS unsigned char* lds, const Gemm g, const StaticOrder& S, const Epi& E) {
;     ...
;         for (int t = 0; t < nt; t += 2) {
;             const bool last = (t == nt - 2);
;             const char* a1 = cA + (size_t)(t + 1) * kstep;
;     ...
;             PG8_LDB(B0, 1, 0); PG8_LDB(B1, 1, 1); PG8_SCHED; PG8_LDA(At, 1, 0); PG8_STAGE(PG8_SA(0, 1), a2 + hstepA, voffA);
;             PG8_WAIT_V(8); PG8_WAIT_L(0); PG8_BAR; PG8_MMA(0, 0, At, B0); PG8_MMA(0, 1, At, B1); PG8_BAR; PG8_SCHED;
;             PG8_LDA(At, 1, 1); PG8_STAGE(PG8_SB(1, 0), b3, voffB); PG8_STAGE(PG8_SB(1, 1), b3 + hstepB, voffB); PG8_STAGE(PG8_SA(1, 0), a3, voffA);
;             PG8_WAIT_V(8); PG8_WAIT_L(0); PG8_BAR; PG8_MMA(1, 0, At, B0); PG8_MMA(1, 1, At, B1); PG8_BAR; PG8_SCHED;
	s_add_i32 s64, 0, 0x18000
	s_add_i32 s65, 0, 0x1c000
	v_add_u32_e32 v140, s64, v181
	v_add_u32_e32 v172, s65, v181
	ds_read_b128 v[128:131], v140
	ds_read_b128 v[132:135], v140 offset:1024
	ds_read_b128 v[136:139], v140 offset:2048
	ds_read_b128 v[140:143], v140 offset:3072
	ds_read_b128 v[160:163], v172
	ds_read_b128 v[164:167], v172 offset:1024
	ds_read_b128 v[168:171], v172 offset:2048
	ds_read_b128 v[172:175], v172 offset:3072
	s_add_u32 s22, s22, 0xb0000
	s_addc_u32 s23, s23, 0
	s_mov_b32 m0, s35
	ds_read_b128 v[186:189], v184 offset:32768
	ds_read_b128 v[190:193], v184 offset:33792
	ds_read_b128 v[194:197], v184 offset:34816
	ds_read_b128 v[198:201], v184 offset:35840
	ds_read_b128 v[202:205], v184 offset:36864
	ds_read_b128 v[206:209], v184 offset:37888
	ds_read_b128 v[210:213], v184 offset:38912
	ds_read_b128 v[214:217], v184 offset:39936
	global_load_lds_dwordx4 v144, s[22:23]
	s_mov_b32 m0, s36
	s_nop 0
	global_load_lds_dwordx4 v148, s[22:23]
	s_waitcnt vmcnt(8)
	s_waitcnt lgkmcnt(0)
	s_barrier
	s_waitcnt lgkmcnt(0)
	v_mfma_f32_16x16x32_bf16 v[124:127], v[128:131], v[186:189], v[124:127]
	v_mfma_f32_16x16x32_bf16 v[120:123], v[136:139], v[186:189], v[120:123]
	v_mfma_f32_16x16x32_bf16 v[108:111], v[128:131], v[194:197], v[108:111]
	v_mfma_f32_16x16x32_bf16 v[104:107], v[136:139], v[194:197], v[104:107]
	v_mfma_f32_16x16x32_bf16 v[92:95], v[128:131], v[202:205], v[92:95]
	v_mfma_f32_16x16x32_bf16 v[88:91], v[136:139], v[202:205], v[88:91]
	v_mfma_f32_16x16x32_bf16 v[76:79], v[128:131], v[210:213], v[76:79]
	v_mfma_f32_16x16x32_bf16 v[72:75], v[136:139], v[210:213], v[72:75]
	v_mfma_f32_16x16x32_bf16 v[124:127], v[132:135], v[190:193], v[124:127]
	v_mfma_f32_16x16x32_bf16 v[120:123], v[140:143], v[190:193], v[120:123]
	v_mfma_f32_16x16x32_bf16 v[108:111], v[132:135], v[198:201], v[108:111]
	v_mfma_f32_16x16x32_bf16 v[104:107], v[140:143], v[198:201], v[104:107]
	v_mfma_f32_16x16x32_bf16 v[92:95], v[132:135], v[206:209], v[92:95]
	v_mfma_f32_16x16x32_bf16 v[88:91], v[140:143], v[206:209], v[88:91]
	v_mfma_f32_16x16x32_bf16 v[76:79], v[132:135], v[214:217], v[76:79]
	v_mfma_f32_16x16x32_bf16 v[72:75], v[140:143], v[214:217], v[72:75]
	v_mfma_f32_16x16x32_bf16 v[116:119], v[160:163], v[186:189], v[116:119]
	v_mfma_f32_16x16x32_bf16 v[112:115], v[168:171], v[186:189], v[112:115]
	v_mfma_f32_16x16x32_bf16 v[100:103], v[160:163], v[194:197], v[100:103]
	v_mfma_f32_16x16x32_bf16 v[96:99], v[168:171], v[194:197], v[96:99]
	v_mfma_f32_16x16x32_bf16 v[84:87], v[160:163], v[202:205], v[84:87]
	v_mfma_f32_16x16x32_bf16 v[80:83], v[168:171], v[202:205], v[80:83]
	v_mfma_f32_16x16x32_bf16 v[68:71], v[160:163], v[210:213], v[68:71]
	v_mfma_f32_16x16x32_bf16 v[64:67], v[168:171], v[210:213], v[64:67]
	v_mfma_f32_16x16x32_bf16 v[116:119], v[164:167], v[190:193], v[116:119]
	v_mfma_f32_16x16x32_bf16 v[112:115], v[172:175], v[190:193], v[112:115]
	v_mfma_f32_16x16x32_bf16 v[100:103], v[164:167], v[198:201], v[100:103]
	v_mfma_f32_16x16x32_bf16 v[96:99], v[172:175], v[198:201], v[96:99]
	v_mfma_f32_16x16x32_bf16 v[84:87], v[164:167], v[206:209], v[84:87]
	v_mfma_f32_16x16x32_bf16 v[80:83], v[172:175], v[206:209], v[80:83]
	v_mfma_f32_16x16x32_bf16 v[68:71], v[164:167], v[214:217], v[68:71]
	v_mfma_f32_16x16x32_bf16 v[64:67], v[172:175], v[214:217], v[64:67]
	s_barrier
	s_add_i32 s22, s64, s29
	v_lshl_add_u64 v[178:179], v[178:179], 0, s[14:15]
	s_mov_b32 m0, s22
	ds_read_b128 v[186:189], v184 offset:49152
	ds_read_b128 v[190:193], v184 offset:50176
	ds_read_b128 v[194:197], v184 offset:51200
	ds_read_b128 v[198:201], v184 offset:52224
	ds_read_b128 v[202:205], v184 offset:53248
	ds_read_b128 v[206:209], v184 offset:54272
	ds_read_b128 v[210:213], v184 offset:55296
	ds_read_b128 v[214:217], v184 offset:56320
	global_load_lds_dwordx4 v[178:179], off
	s_add_i32 m0, s22, 0x2000
	s_add_u32 s20, s20, 0xb0080
	v_lshl_add_u64 v[178:179], v[218:219], 0, s[14:15]
	s_addc_u32 s21, s21, 0
	s_add_i32 s22, s65, s29
	global_load_lds_dwordx4 v[178:179], off
	s_mov_b32 m0, s22
	s_nop 0
	global_load_lds_dwordx4 v146, s[20:21]
	s_add_i32 m0, s22, 0x2000
	s_nop 0
	global_load_lds_dwordx4 v150, s[20:21]
	v_lshl_add_u64 v[178:179], v[220:221], 0, s[14:15]
	s_mov_b32 m0, s42
	s_nop 0
	global_load_lds_dwordx4 v[178:179], off
	v_lshl_add_u64 v[178:179], v[222:223], 0, s[14:15]
	s_mov_b32 m0, s43
	s_nop 0
	global_load_lds_dwordx4 v[178:179], off
	s_waitcnt vmcnt(8)
	s_waitcnt lgkmcnt(0)
	s_barrier
	s_waitcnt lgkmcnt(0)
	v_mfma_f32_16x16x32_bf16 v[60:63], v[128:131], v[186:189], v[60:63]
	v_mfma_f32_16x16x32_bf16 v[56:59], v[136:139], v[186:189], v[56:59]
	v_mfma_f32_16x16x32_bf16 v[44:47], v[128:131], v[194:197], v[44:47]
	v_mfma_f32_16x16x32_bf16 v[40:43], v[136:139], v[194:197], v[40:43]
	v_mfma_f32_16x16x32_bf16 v[28:31], v[128:131], v[202:205], v[28:31]
	v_mfma_f32_16x16x32_bf16 v[24:27], v[136:139], v[202:205], v[24:27]
	v_mfma_f32_16x16x32_bf16 v[12:15], v[128:131], v[210:213], v[12:15]
	v_mfma_f32_16x16x32_bf16 v[8:11], v[136:139], v[210:213], v[8:11]
	v_mfma_f32_16x16x32_bf16 v[60:63], v[132:135], v[190:193], v[60:63]
	v_mfma_f32_16x16x32_bf16 v[56:59], v[140:143], v[190:193], v[56:59]
	v_mfma_f32_16x16x32_bf16 v[44:47], v[132:135], v[198:201], v[44:47]
	v_mfma_f32_16x16x32_bf16 v[40:43], v[140:143], v[198:201], v[40:43]
	v_mfma_f32_16x16x32_bf16 v[28:31], v[132:135], v[206:209], v[28:31]
	v_mfma_f32_16x16x32_bf16 v[24:27], v[140:143], v[206:209], v[24:27]
	v_mfma_f32_16x16x32_bf16 v[12:15], v[132:135], v[214:217], v[12:15]
	v_mfma_f32_16x16x32_bf16 v[8:11], v[140:143], v[214:217], v[8:11]
	v_mfma_f32_16x16x32_bf16 v[52:55], v[160:163], v[186:189], v[52:55]
	v_mfma_f32_16x16x32_bf16 v[48:51], v[168:171], v[186:189], v[48:51]
	v_mfma_f32_16x16x32_bf16 v[36:39], v[160:163], v[194:197], v[36:39]
	v_mfma_f32_16x16x32_bf16 v[32:35], v[168:171], v[194:197], v[32:35]
	v_mfma_f32_16x16x32_bf16 v[20:23], v[160:163], v[202:205], v[20:23]
	v_mfma_f32_16x16x32_bf16 v[16:19], v[168:171], v[202:205], v[16:19]
	v_mfma_f32_16x16x32_bf16 v[4:7], v[160:163], v[210:213], v[4:7]
	v_mfma_f32_16x16x32_bf16 v[0:3], v[168:171], v[210:213], v[0:3]
	v_mfma_f32_16x16x32_bf16 v[52:55], v[164:167], v[190:193], v[52:55]
	v_mfma_f32_16x16x32_bf16 v[48:51], v[172:175], v[190:193], v[48:51]
	v_mfma_f32_16x16x32_bf16 v[36:39], v[164:167], v[198:201], v[36:39]
	v_mfma_f32_16x16x32_bf16 v[32:35], v[172:175], v[198:201], v[32:35]
	v_mfma_f32_16x16x32_bf16 v[20:23], v[164:167], v[206:209], v[20:23]
	v_mfma_f32_16x16x32_bf16 v[16:19], v[172:175], v[206:209], v[16:19]
	v_mfma_f32_16x16x32_bf16 v[4:7], v[164:167], v[214:217], v[4:7]
	v_mfma_f32_16x16x32_bf16 v[0:3], v[172:175], v[214:217], v[0:3]
	s_barrier
	s_add_i32 s63, s63, 2
	s_add_u32 s0, s0, 0x100
	s_addc_u32 s1, s1, 0
	s_add_u32 s61, s61, 0x100
	s_addc_u32 s62, s62, 0
	s_cmp_gt_u32 s63, 41
; #define PG8_STAGE(bufoff, gbase, voff) do { _Pragma("unroll") for (int _i = 0; _i < 2; ++_i) \
;         __builtin_amdgcn_global_load_lds((const unsigned*)((const char*)(gbase) + (voff)[_i]), (LAS unsigned*)(lds + (bufoff) + ldsw + _i * 8192), 16, 0, 0); } while (0)
; #define PG8_LDA(dst, b, h) do { _Pragma("unroll") for (int m = 0; m < 4; ++m) _Pragma("unroll") for (int k = 0; k < 2; ++k) dst[m][k] = *(const LAS bf16x8*)(lds + PG8_SA(b, h) + aoff + m * 2048 + k * 1024); } while (0)
; #define PG8_LDB(dst, b, h) do { _Pragma("unroll") for (int n = 0; n < 2; ++n) _Pragma("unroll") for (int k = 0; k < 2; ++k) dst[n][k] = *(const LAS bf16x8*)(lds + PG8_SB(b, h) + boff + n * 2048 + k * 1024); } while (0)
; #define PG8_MMA(ai, bj, At, Bt) do { __builtin_amdgcn_s_setprio(1); _Pragma("unroll") for (int m = 0; m < 4; ++m) _Pragma("unroll") for (int n = 0; n < 2; ++n) _Pragma("unroll") for (int k = 0; k < 2; ++k) \
;         acc[ai][bj][m][n] = __builtin_amdgcn_mfma_f32_16x16x32_bf16(Bt[n][k], At[m][k], acc[ai][bj][m][n], 0, 0, 0); __builtin_amdgcn_s_setprio(0); } while (0)
; #define PG8_WAIT_V(n) asm volatile("s_waitcnt vmcnt(" #n ")" ::: "memory")
; #define PG8_WAIT_L(n) asm volatile("s_waitcnt lgkmcnt(" #n ")" ::: "memory")
; #define PG8_BAR __builtin_amdgcn_s_barrier()
; #define PG8_SCHED __builtin_amdgcn_sched_barrier(0)
; template <class Epi>
; __device__ __forceinline__ void gemm_phase(LAS unsigned char* lds, const Gemm g, const StaticOrder& S, const Epi& E) {
;     ...
;             PG8_LDB(B0, 0, 0); PG8_LDB(B1, 0, 1); PG8_SCHED; PG8_LDA(At, 0, 0); PG8_STAGE(PG8_SA(1, 1), a1 + hstepA, voffA);
;             PG8_WAIT_V(8); PG8_WAIT_L(0); PG8_BAR; PG8_MMA(0, 0, At, B0); PG8_MMA(0, 1, At, B1); PG8_BAR; PG8_SCHED;
;             PG8_LDA(At, 0, 1); PG8_STAGE(PG8_SB(0, 0), b2, voffB); PG8_STAGE(PG8_SB(0, 1), b2 + hstepB, voffB); PG8_STAGE(PG8_SA(0, 0), a2, voffA);
;             PG8_WAIT_V(8); PG8_WAIT_L(0); PG8_BAR; PG8_MMA(1, 0, At, B0); PG8_MMA(1, 1, At, B1); PG8_BAR; PG8_SCHED;
.LBB0_1649:
	ds_read_b128 v[128:131], v182
	ds_read_b128 v[132:135], v182 offset:1024
	ds_read_b128 v[136:139], v182 offset:2048
	ds_read_b128 v[140:143], v182 offset:3072
	ds_read_b128 v[160:163], v183
	ds_read_b128 v[164:167], v183 offset:1024
	ds_read_b128 v[168:171], v183 offset:2048
	ds_read_b128 v[172:175], v183 offset:3072
	s_add_u32 s20, s0, 0xfff50080
	s_addc_u32 s21, s1, -1
	s_cmp_eq_u32 s63, 40
	s_cselect_b32 s23, s7, s21
	s_cselect_b32 s22, s6, s20
	s_cselect_b32 s21, s19, s62
	s_cselect_b32 s20, s18, s61
	s_add_i32 m0, s33, 0xc000
	ds_read_b128 v[186:189], v184
	ds_read_b128 v[190:193], v184 offset:1024
	ds_read_b128 v[194:197], v184 offset:2048
	ds_read_b128 v[198:201], v184 offset:3072
	ds_read_b128 v[202:205], v184 offset:4096
	ds_read_b128 v[206:209], v184 offset:5120
	ds_read_b128 v[210:213], v184 offset:6144
	ds_read_b128 v[214:217], v184 offset:7168
	global_load_lds_dwordx4 v152, s[0:1]
	s_add_i32 m0, s33, 0xe000
	s_nop 0
	global_load_lds_dwordx4 v154, s[0:1]
	s_waitcnt vmcnt(8)
	s_waitcnt lgkmcnt(0)
	s_barrier
	s_waitcnt lgkmcnt(0)
	v_mfma_f32_16x16x32_bf16 v[124:127], v[128:131], v[186:189], v[124:127]
	v_mfma_f32_16x16x32_bf16 v[120:123], v[136:139], v[186:189], v[120:123]
	v_mfma_f32_16x16x32_bf16 v[108:111], v[128:131], v[194:197], v[108:111]
	v_mfma_f32_16x16x32_bf16 v[104:107], v[136:139], v[194:197], v[104:107]
	v_mfma_f32_16x16x32_bf16 v[92:95], v[128:131], v[202:205], v[92:95]
	v_mfma_f32_16x16x32_bf16 v[88:91], v[136:139], v[202:205], v[88:91]
	v_mfma_f32_16x16x32_bf16 v[76:79], v[128:131], v[210:213], v[76:79]
	v_mfma_f32_16x16x32_bf16 v[72:75], v[136:139], v[210:213], v[72:75]
	v_mfma_f32_16x16x32_bf16 v[124:127], v[132:135], v[190:193], v[124:127]
	v_mfma_f32_16x16x32_bf16 v[120:123], v[140:143], v[190:193], v[120:123]
	v_mfma_f32_16x16x32_bf16 v[108:111], v[132:135], v[198:201], v[108:111]
	v_mfma_f32_16x16x32_bf16 v[104:107], v[140:143], v[198:201], v[104:107]
	v_mfma_f32_16x16x32_bf16 v[92:95], v[132:135], v[206:209], v[92:95]
	v_mfma_f32_16x16x32_bf16 v[88:91], v[140:143], v[206:209], v[88:91]
	v_mfma_f32_16x16x32_bf16 v[76:79], v[132:135], v[214:217], v[76:79]
	v_mfma_f32_16x16x32_bf16 v[72:75], v[140:143], v[214:217], v[72:75]
	v_mfma_f32_16x16x32_bf16 v[116:119], v[160:163], v[186:189], v[116:119]
	v_mfma_f32_16x16x32_bf16 v[112:115], v[168:171], v[186:189], v[112:115]
	v_mfma_f32_16x16x32_bf16 v[100:103], v[160:163], v[194:197], v[100:103]
	v_mfma_f32_16x16x32_bf16 v[96:99], v[168:171], v[194:197], v[96:99]
	v_mfma_f32_16x16x32_bf16 v[84:87], v[160:163], v[202:205], v[84:87]
	v_mfma_f32_16x16x32_bf16 v[80:83], v[168:171], v[202:205], v[80:83]
	v_mfma_f32_16x16x32_bf16 v[68:71], v[160:163], v[210:213], v[68:71]
	v_mfma_f32_16x16x32_bf16 v[64:67], v[168:171], v[210:213], v[64:67]
	v_mfma_f32_16x16x32_bf16 v[116:119], v[164:167], v[190:193], v[116:119]
	v_mfma_f32_16x16x32_bf16 v[112:115], v[172:175], v[190:193], v[112:115]
	v_mfma_f32_16x16x32_bf16 v[100:103], v[164:167], v[198:201], v[100:103]
	v_mfma_f32_16x16x32_bf16 v[96:99], v[172:175], v[198:201], v[96:99]
	v_mfma_f32_16x16x32_bf16 v[84:87], v[164:167], v[206:209], v[84:87]
	v_mfma_f32_16x16x32_bf16 v[80:83], v[172:175], v[206:209], v[80:83]
	v_mfma_f32_16x16x32_bf16 v[68:71], v[164:167], v[214:217], v[68:71]
	v_mfma_f32_16x16x32_bf16 v[64:67], v[172:175], v[214:217], v[64:67]
	s_barrier
	s_add_i32 s64, s55, s29
	v_lshl_add_u64 v[178:179], s[20:21], 0, v[146:147]
	s_mov_b32 m0, s64
	ds_read_b128 v[186:189], v184 offset:16384
	ds_read_b128 v[190:193], v184 offset:17408
	ds_read_b128 v[194:197], v184 offset:18432
	ds_read_b128 v[198:201], v184 offset:19456
	ds_read_b128 v[202:205], v184 offset:20480
	ds_read_b128 v[206:209], v184 offset:21504
	ds_read_b128 v[210:213], v184 offset:22528
	ds_read_b128 v[214:217], v184 offset:23552
	global_load_lds_dwordx4 v[178:179], off
	s_add_i32 m0, s64, 0x2000
	s_add_u32 s64, s20, 0xb0000
	v_lshl_add_u64 v[218:219], s[20:21], 0, v[150:151]
	s_addc_u32 s65, s21, 0
	s_add_i32 s66, s56, s29
	global_load_lds_dwordx4 v[218:219], off
	s_mov_b32 m0, s66
	v_lshl_add_u64 v[222:223], s[22:23], 0, v[148:149]
	global_load_lds_dwordx4 v146, s[64:65]
	s_add_i32 m0, s66, 0x2000
	s_nop 0
	global_load_lds_dwordx4 v150, s[64:65]
	v_lshl_add_u64 v[220:221], s[22:23], 0, v[144:145]
	s_mov_b32 m0, s33
	s_nop 0
	global_load_lds_dwordx4 v[220:221], off
	s_mov_b32 m0, s34
	s_nop 0
	global_load_lds_dwordx4 v[222:223], off
	s_waitcnt vmcnt(8)
	s_waitcnt lgkmcnt(0)
	s_barrier
	s_waitcnt lgkmcnt(0)
	v_mfma_f32_16x16x32_bf16 v[60:63], v[128:131], v[186:189], v[60:63]
	v_mfma_f32_16x16x32_bf16 v[56:59], v[136:139], v[186:189], v[56:59]
	v_mfma_f32_16x16x32_bf16 v[44:47], v[128:131], v[194:197], v[44:47]
	v_mfma_f32_16x16x32_bf16 v[40:43], v[136:139], v[194:197], v[40:43]
	v_mfma_f32_16x16x32_bf16 v[28:31], v[128:131], v[202:205], v[28:31]
	v_mfma_f32_16x16x32_bf16 v[24:27], v[136:139], v[202:205], v[24:27]
	v_mfma_f32_16x16x32_bf16 v[12:15], v[128:131], v[210:213], v[12:15]
	v_mfma_f32_16x16x32_bf16 v[8:11], v[136:139], v[210:213], v[8:11]
	v_mfma_f32_16x16x32_bf16 v[60:63], v[132:135], v[190:193], v[60:63]
	v_mfma_f32_16x16x32_bf16 v[56:59], v[140:143], v[190:193], v[56:59]
	v_mfma_f32_16x16x32_bf16 v[44:47], v[132:135], v[198:201], v[44:47]
	v_mfma_f32_16x16x32_bf16 v[40:43], v[140:143], v[198:201], v[40:43]
	v_mfma_f32_16x16x32_bf16 v[28:31], v[132:135], v[206:209], v[28:31]
	v_mfma_f32_16x16x32_bf16 v[24:27], v[140:143], v[206:209], v[24:27]
	v_mfma_f32_16x16x32_bf16 v[12:15], v[132:135], v[214:217], v[12:15]
	v_mfma_f32_16x16x32_bf16 v[8:11], v[140:143], v[214:217], v[8:11]
	v_mfma_f32_16x16x32_bf16 v[52:55], v[160:163], v[186:189], v[52:55]
	v_mfma_f32_16x16x32_bf16 v[48:51], v[168:171], v[186:189], v[48:51]
	v_mfma_f32_16x16x32_bf16 v[36:39], v[160:163], v[194:197], v[36:39]
	v_mfma_f32_16x16x32_bf16 v[32:35], v[168:171], v[194:197], v[32:35]
	v_mfma_f32_16x16x32_bf16 v[20:23], v[160:163], v[202:205], v[20:23]
	v_mfma_f32_16x16x32_bf16 v[16:19], v[168:171], v[202:205], v[16:19]
	v_mfma_f32_16x16x32_bf16 v[4:7], v[160:163], v[210:213], v[4:7]
	v_mfma_f32_16x16x32_bf16 v[0:3], v[168:171], v[210:213], v[0:3]
	v_mfma_f32_16x16x32_bf16 v[52:55], v[164:167], v[190:193], v[52:55]
	v_mfma_f32_16x16x32_bf16 v[48:51], v[172:175], v[190:193], v[48:51]
	v_mfma_f32_16x16x32_bf16 v[36:39], v[164:167], v[198:201], v[36:39]
	v_mfma_f32_16x16x32_bf16 v[32:35], v[172:175], v[198:201], v[32:35]
	v_mfma_f32_16x16x32_bf16 v[20:23], v[164:167], v[206:209], v[20:23]
	v_mfma_f32_16x16x32_bf16 v[16:19], v[172:175], v[206:209], v[16:19]
	v_mfma_f32_16x16x32_bf16 v[4:7], v[164:167], v[214:217], v[4:7]
	v_mfma_f32_16x16x32_bf16 v[0:3], v[172:175], v[214:217], v[0:3]
	s_barrier
; #define PG8_STAGE(bufoff, gbase, voff) do { _Pragma("unroll") for (int _i = 0; _i < 2; ++_i) \
;         __builtin_amdgcn_global_load_lds((const unsigned*)((const char*)(gbase) + (voff)[_i]), (LAS unsigned*)(lds + (bufoff) + ldsw + _i * 8192), 16, 0, 0); } while (0)
; #define PG8_LDA(dst, b, h) do { _Pragma("unroll") for (int m = 0; m < 4; ++m) _Pragma("unroll") for (int k = 0; k < 2; ++k) dst[m][k] = *(const LAS bf16x8*)(lds + PG8_SA(b, h) + aoff + m * 2048 + k * 1024); } while (0)
; #define PG8_LDB(dst, b, h) do { _Pragma("unroll") for (int n = 0; n < 2; ++n) _Pragma("unroll") for (int k = 0; k < 2; ++k) dst[n][k] = *(const LAS bf16x8*)(lds + PG8_SB(b, h) + boff + n * 2048 + k * 1024); } while (0)
; #define PG8_MMA(ai, bj, At, Bt) do { __builtin_amdgcn_s_setprio(1); _Pragma("unroll") for (int m = 0; m < 4; ++m) _Pragma("unroll") for (int n = 0; n < 2; ++n) _Pragma("unroll") for (int k = 0; k < 2; ++k) \
;         acc[ai][bj][m][n] = __builtin_amdgcn_mfma_f32_16x16x32_bf16(Bt[n][k], At[m][k], acc[ai][bj][m][n], 0, 0, 0); __builtin_amdgcn_s_setprio(0); } while (0)
; #define PG8_WAIT_V(n) asm volatile("s_waitcnt vmcnt(" #n ")" ::: "memory")
; #define PG8_WAIT_L(n) asm volatile("s_waitcnt lgkmcnt(" #n ")" ::: "memory")
; #define PG8_BAR __builtin_amdgcn_s_barrier()
; #define PG8_SCHED __builtin_amdgcn_sched_barrier(0)
; template <class Epi>
; __device__ __forceinline__ void gemm_phase(LAS unsigned char* lds, const Gemm g, const StaticOrder& S, const Epi& E) {
;     ...
;             PG8_LDB(B0, 1, 0); PG8_LDB(B1, 1, 1); PG8_SCHED; PG8_LDA(At, 1, 0); PG8_STAGE(PG8_SA(0, 1), a2 + hstepA, voffA);
;             PG8_WAIT_V(8); PG8_WAIT_L(0); PG8_BAR; PG8_MMA(0, 0, At, B0); PG8_MMA(0, 1, At, B1); PG8_BAR; PG8_SCHED;
;             PG8_LDA(At, 1, 1); PG8_STAGE(PG8_SB(1, 0), b3, voffB); PG8_STAGE(PG8_SB(1, 1), b3 + hstepB, voffB); PG8_STAGE(PG8_SA(1, 0), a3, voffA);
;             PG8_WAIT_V(8); PG8_WAIT_L(0); PG8_BAR; PG8_MMA(1, 0, At, B0); PG8_MMA(1, 1, At, B1); PG8_BAR; PG8_SCHED;
;         }
	s_add_i32 s64, 0, 0x18000
	s_add_i32 s65, 0, 0x1c000
	v_add_u32_e32 v140, s64, v181
	v_add_u32_e32 v172, s65, v181
	ds_read_b128 v[128:131], v140
	ds_read_b128 v[132:135], v140 offset:1024
	ds_read_b128 v[136:139], v140 offset:2048
	ds_read_b128 v[140:143], v140 offset:3072
	ds_read_b128 v[160:163], v172
	ds_read_b128 v[164:167], v172 offset:1024
	ds_read_b128 v[168:171], v172 offset:2048
	ds_read_b128 v[172:175], v172 offset:3072
	s_add_u32 s22, s22, 0xb0000
	s_addc_u32 s23, s23, 0
	s_mov_b32 m0, s35
	ds_read_b128 v[186:189], v184 offset:32768
	ds_read_b128 v[190:193], v184 offset:33792
	ds_read_b128 v[194:197], v184 offset:34816
	ds_read_b128 v[198:201], v184 offset:35840
	ds_read_b128 v[202:205], v184 offset:36864
	ds_read_b128 v[206:209], v184 offset:37888
	ds_read_b128 v[210:213], v184 offset:38912
	ds_read_b128 v[214:217], v184 offset:39936
	global_load_lds_dwordx4 v144, s[22:23]
	s_mov_b32 m0, s36
	s_nop 0
	global_load_lds_dwordx4 v148, s[22:23]
	s_waitcnt vmcnt(8)
	s_waitcnt lgkmcnt(0)
	s_barrier
	s_waitcnt lgkmcnt(0)
	v_mfma_f32_16x16x32_bf16 v[124:127], v[128:131], v[186:189], v[124:127]
	v_mfma_f32_16x16x32_bf16 v[120:123], v[136:139], v[186:189], v[120:123]
	v_mfma_f32_16x16x32_bf16 v[108:111], v[128:131], v[194:197], v[108:111]
	v_mfma_f32_16x16x32_bf16 v[104:107], v[136:139], v[194:197], v[104:107]
	v_mfma_f32_16x16x32_bf16 v[92:95], v[128:131], v[202:205], v[92:95]
	v_mfma_f32_16x16x32_bf16 v[88:91], v[136:139], v[202:205], v[88:91]
	v_mfma_f32_16x16x32_bf16 v[76:79], v[128:131], v[210:213], v[76:79]
	v_mfma_f32_16x16x32_bf16 v[72:75], v[136:139], v[210:213], v[72:75]
	v_mfma_f32_16x16x32_bf16 v[124:127], v[132:135], v[190:193], v[124:127]
	v_mfma_f32_16x16x32_bf16 v[120:123], v[140:143], v[190:193], v[120:123]
	v_mfma_f32_16x16x32_bf16 v[108:111], v[132:135], v[198:201], v[108:111]
	v_mfma_f32_16x16x32_bf16 v[104:107], v[140:143], v[198:201], v[104:107]
	v_mfma_f32_16x16x32_bf16 v[92:95], v[132:135], v[206:209], v[92:95]
	v_mfma_f32_16x16x32_bf16 v[88:91], v[140:143], v[206:209], v[88:91]
	v_mfma_f32_16x16x32_bf16 v[76:79], v[132:135], v[214:217], v[76:79]
	v_mfma_f32_16x16x32_bf16 v[72:75], v[140:143], v[214:217], v[72:75]
	v_mfma_f32_16x16x32_bf16 v[116:119], v[160:163], v[186:189], v[116:119]
	v_mfma_f32_16x16x32_bf16 v[112:115], v[168:171], v[186:189], v[112:115]
	v_mfma_f32_16x16x32_bf16 v[100:103], v[160:163], v[194:197], v[100:103]
	v_mfma_f32_16x16x32_bf16 v[96:99], v[168:171], v[194:197], v[96:99]
	v_mfma_f32_16x16x32_bf16 v[84:87], v[160:163], v[202:205], v[84:87]
	v_mfma_f32_16x16x32_bf16 v[80:83], v[168:171], v[202:205], v[80:83]
	v_mfma_f32_16x16x32_bf16 v[68:71], v[160:163], v[210:213], v[68:71]
	v_mfma_f32_16x16x32_bf16 v[64:67], v[168:171], v[210:213], v[64:67]
	v_mfma_f32_16x16x32_bf16 v[116:119], v[164:167], v[190:193], v[116:119]
	v_mfma_f32_16x16x32_bf16 v[112:115], v[172:175], v[190:193], v[112:115]
	v_mfma_f32_16x16x32_bf16 v[100:103], v[164:167], v[198:201], v[100:103]
	v_mfma_f32_16x16x32_bf16 v[96:99], v[172:175], v[198:201], v[96:99]
	v_mfma_f32_16x16x32_bf16 v[84:87], v[164:167], v[206:209], v[84:87]
	v_mfma_f32_16x16x32_bf16 v[80:83], v[172:175], v[206:209], v[80:83]
	v_mfma_f32_16x16x32_bf16 v[68:71], v[164:167], v[214:217], v[68:71]
	v_mfma_f32_16x16x32_bf16 v[64:67], v[172:175], v[214:217], v[64:67]
	s_barrier
	s_add_i32 s22, s64, s29
	v_lshl_add_u64 v[178:179], v[178:179], 0, s[14:15]
	s_mov_b32 m0, s22
	ds_read_b128 v[186:189], v184 offset:49152
	ds_read_b128 v[190:193], v184 offset:50176
	ds_read_b128 v[194:197], v184 offset:51200
	ds_read_b128 v[198:201], v184 offset:52224
	ds_read_b128 v[202:205], v184 offset:53248
	ds_read_b128 v[206:209], v184 offset:54272
	ds_read_b128 v[210:213], v184 offset:55296
	ds_read_b128 v[214:217], v184 offset:56320
	global_load_lds_dwordx4 v[178:179], off
	s_add_i32 m0, s22, 0x2000
	s_add_u32 s20, s20, 0xb0080
	v_lshl_add_u64 v[178:179], v[218:219], 0, s[14:15]
	s_addc_u32 s21, s21, 0
	s_add_i32 s22, s65, s29
	global_load_lds_dwordx4 v[178:179], off
	s_mov_b32 m0, s22
	s_nop 0
	global_load_lds_dwordx4 v146, s[20:21]
	s_add_i32 m0, s22, 0x2000
	s_nop 0
	global_load_lds_dwordx4 v150, s[20:21]
	v_lshl_add_u64 v[178:179], v[220:221], 0, s[14:15]
	s_mov_b32 m0, s42
	s_nop 0
	global_load_lds_dwordx4 v[178:179], off
	v_lshl_add_u64 v[178:179], v[222:223], 0, s[14:15]
	s_mov_b32 m0, s43
	s_nop 0
	global_load_lds_dwordx4 v[178:179], off
	s_waitcnt vmcnt(8)
	s_waitcnt lgkmcnt(0)
	s_barrier
	s_waitcnt lgkmcnt(0)
	v_mfma_f32_16x16x32_bf16 v[60:63], v[128:131], v[186:189], v[60:63]
	v_mfma_f32_16x16x32_bf16 v[56:59], v[136:139], v[186:189], v[56:59]
	v_mfma_f32_16x16x32_bf16 v[44:47], v[128:131], v[194:197], v[44:47]
	v_mfma_f32_16x16x32_bf16 v[40:43], v[136:139], v[194:197], v[40:43]
	v_mfma_f32_16x16x32_bf16 v[28:31], v[128:131], v[202:205], v[28:31]
	v_mfma_f32_16x16x32_bf16 v[24:27], v[136:139], v[202:205], v[24:27]
	v_mfma_f32_16x16x32_bf16 v[12:15], v[128:131], v[210:213], v[12:15]
	v_mfma_f32_16x16x32_bf16 v[8:11], v[136:139], v[210:213], v[8:11]
	v_mfma_f32_16x16x32_bf16 v[60:63], v[132:135], v[190:193], v[60:63]
	v_mfma_f32_16x16x32_bf16 v[56:59], v[140:143], v[190:193], v[56:59]
	v_mfma_f32_16x16x32_bf16 v[44:47], v[132:135], v[198:201], v[44:47]
	v_mfma_f32_16x16x32_bf16 v[40:43], v[140:143], v[198:201], v[40:43]
	v_mfma_f32_16x16x32_bf16 v[28:31], v[132:135], v[206:209], v[28:31]
	v_mfma_f32_16x16x32_bf16 v[24:27], v[140:143], v[206:209], v[24:27]
	v_mfma_f32_16x16x32_bf16 v[12:15], v[132:135], v[214:217], v[12:15]
	v_mfma_f32_16x16x32_bf16 v[8:11], v[140:143], v[214:217], v[8:11]
	v_mfma_f32_16x16x32_bf16 v[52:55], v[160:163], v[186:189], v[52:55]
	v_mfma_f32_16x16x32_bf16 v[48:51], v[168:171], v[186:189], v[48:51]
	v_mfma_f32_16x16x32_bf16 v[36:39], v[160:163], v[194:197], v[36:39]
	v_mfma_f32_16x16x32_bf16 v[32:35], v[168:171], v[194:197], v[32:35]
	v_mfma_f32_16x16x32_bf16 v[20:23], v[160:163], v[202:205], v[20:23]
	v_mfma_f32_16x16x32_bf16 v[16:19], v[168:171], v[202:205], v[16:19]
	v_mfma_f32_16x16x32_bf16 v[4:7], v[160:163], v[210:213], v[4:7]
	v_mfma_f32_16x16x32_bf16 v[0:3], v[168:171], v[210:213], v[0:3]
	v_mfma_f32_16x16x32_bf16 v[52:55], v[164:167], v[190:193], v[52:55]
	v_mfma_f32_16x16x32_bf16 v[48:51], v[172:175], v[190:193], v[48:51]
	v_mfma_f32_16x16x32_bf16 v[36:39], v[164:167], v[198:201], v[36:39]
	v_mfma_f32_16x16x32_bf16 v[32:35], v[172:175], v[198:201], v[32:35]
	v_mfma_f32_16x16x32_bf16 v[20:23], v[164:167], v[206:209], v[20:23]
	v_mfma_f32_16x16x32_bf16 v[16:19], v[172:175], v[206:209], v[16:19]
	v_mfma_f32_16x16x32_bf16 v[4:7], v[164:167], v[214:217], v[4:7]
	v_mfma_f32_16x16x32_bf16 v[0:3], v[172:175], v[214:217], v[0:3]
	s_barrier
	s_add_i32 s63, s63, 2
	s_add_u32 s0, s0, 0x100
	s_addc_u32 s1, s1, 0
	s_add_u32 s61, s61, 0x100
	s_addc_u32 s62, s62, 0
	s_cmp_gt_u32 s63, 41
	s_cbranch_scc0 .LBB0_1649
	s_and_b64 vcc, exec, s[16:17]
	s_cbranch_vccz .LBB0_1652
	s_barrier

; #define PG8_STAGE(bufoff, gbase, voff) do { _Pragma("unroll") for (int _i = 0; _i < 2; ++_i) \
;         __builtin_amdgcn_global_load_lds((const unsigned*)((const char*)(gbase) + (voff)[_i]), (LAS unsigned*)(lds + (bufoff) + ldsw + _i * 8192), 16, 0, 0); } while (0)
; #define PG8_LDA(dst, b, h) do { _Pragma("unroll") for (int m = 0; m < 4; ++m) _Pragma("unroll") for (int k = 0; k < 2; ++k) dst[m][k] = *(const LAS bf16x8*)(lds + PG8_SA(b, h) + aoff + m * 2048 + k * 1024); } while (0)
; #define PG8_LDB(dst, b, h) do { _Pragma("unroll") for (int n = 0; n < 2; ++n) _Pragma("unroll") for (int k = 0; k < 2; ++k) dst[n][k] = *(const LAS bf16x8*)(lds + PG8_SB(b, h) + boff + n * 2048 + k * 1024); } while (0)
; #define PG8_MMA(ai, bj, At, Bt) do { __builtin_amdgcn_s_setprio(1); _Pragma("unroll") for (int m = 0; m < 4; ++m) _Pragma("unroll") for (int n = 0; n < 2; ++n) _Pragma("unroll") for (int k = 0; k < 2; ++k) \
;         acc[ai][bj][m][n] = __builtin_amdgcn_mfma_f32_16x16x32_bf16(Bt[n][k], At[m][k], acc[ai][bj][m][n], 0, 0, 0); __builtin_amdgcn_s_setprio(0); } while (0)
; #define PG8_BAR __builtin_amdgcn_s_barrier()
; template <class Epi>
; __device__ __forceinline__ void gemm_phase(LAS unsigned char* lds, const Gemm g, const StaticOrder& S, const Epi& E) {
;     ...
;         const bool has_next = S.next(ui + 1, nxt);
;         const char* nA = has_next ? (const char*)g.A + (size_t)nxt.pm * tstepA : cA; const char* nB = has_next ? (const char*)g.Bt + (size_t)nxt.pn * tstepB : cB;
; #pragma nounroll
;         for (int t = 0; t < nt; t += 2) {
;             const bool last = (t == nt - 2);
;             const char* a1 = cA + (size_t)(t + 1) * kstep;
;             const char* a2 = last ? nA : cA + (size_t)(t + 2) * kstep; const char* b2 = last ? nB : cB + (size_t)(t + 2) * kstep;
;             const char* a3 = a2 + kstep; const char* b3 = b2 + kstep;
;             PG8_LDB(B0, 0, 0); PG8_LDB(B1, 0, 1); PG8_SCHED; PG8_LDA(At, 0, 0); PG8_STAGE(PG8_SA(1, 1), a1 + hstepA, voffA);
;             PG8_WAIT_V(8); PG8_WAIT_L(0); PG8_BAR; PG8_MMA(0, 0, At, B0); PG8_MMA(0, 1, At, B1); PG8_BAR; PG8_SCHED;
;             PG8_LDA(At, 0, 1); PG8_STAGE(PG8_SB(0, 0), b2, voffB); PG8_STAGE(PG8_SB(0, 1), b2 + hstepB, voffB); PG8_STAGE(PG8_SA(0, 0), a2, voffA);
;             PG8_WAIT_V(8); PG8_WAIT_L(0); PG8_BAR; PG8_MMA(1, 0, At, B0); PG8_MMA(1, 1, At, B1); PG8_BAR; PG8_SCHED;
.LBB0_1745:
	s_ashr_i32 s35, s34, 31
	s_lshl_b64 s[36:37], s[34:35], 19
	s_add_u32 s36, s30, s36
	s_addc_u32 s37, s31, s37
	s_and_b64 s[38:39], s[4:5], exec
	s_cselect_b32 s7, s37, s43
	s_cselect_b32 s9, s36, s42
	s_ashr_i32 s29, s28, 31
	s_lshl_b64 s[38:39], s[28:29], 19
	s_add_u32 s38, s3, s38
	s_addc_u32 s39, s33, s39
	s_and_b64 s[44:45], s[4:5], exec
	s_cselect_b32 s29, s39, s53
	s_cselect_b32 s35, s38, s52
	s_add_u32 s42, s42, 0x40080
	s_addc_u32 s43, s43, 0
	s_add_u32 s69, s52, 0x100
	s_addc_u32 s70, s53, 0
	s_mov_b32 s71, -2
	s_waitcnt lgkmcnt(0)
	ds_read_b128 v[40:43], v208
	ds_read_b128 v[44:47], v208 offset:1024
	ds_read_b128 v[56:59], v208 offset:2048
	ds_read_b128 v[60:63], v208 offset:3072
	ds_read_b128 v[144:147], v209
	ds_read_b128 v[148:151], v209 offset:1024
	ds_read_b128 v[152:155], v209 offset:2048
	ds_read_b128 v[156:159], v209 offset:3072
	s_add_u32 s44, s42, 0xfffc0080
	s_addc_u32 s45, s43, -1
	s_cmp_eq_u32 s71, 12
	s_cselect_b32 s53, s7, s45
	s_cselect_b32 s52, s9, s44
	s_cselect_b32 s45, s29, s70
	s_cselect_b32 s44, s35, s69
	s_add_i32 m0, s55, 0xc000
	ds_read_b128 v[160:163], v210
	ds_read_b128 v[164:167], v210 offset:1024
	ds_read_b128 v[186:189], v210 offset:2048
	ds_read_b128 v[190:193], v210 offset:3072
	ds_read_b128 v[194:197], v210 offset:4096
	ds_read_b128 v[198:201], v210 offset:5120
	ds_read_b128 v[202:205], v210 offset:6144
	ds_read_b128 v[214:217], v210 offset:7168
	global_load_lds_dwordx4 v178, s[42:43]
	s_add_i32 m0, s55, 0xe000
	s_nop 0
	global_load_lds_dwordx4 v180, s[42:43]
	s_waitcnt vmcnt(8)
	s_waitcnt lgkmcnt(0)
	s_barrier
	s_waitcnt lgkmcnt(0)
	v_mfma_f32_16x16x32_bf16 v[140:143], v[40:43], v[160:163], 0
	v_mfma_f32_16x16x32_bf16 v[136:139], v[56:59], v[160:163], 0
	v_mfma_f32_16x16x32_bf16 v[124:127], v[40:43], v[186:189], 0
	v_mfma_f32_16x16x32_bf16 v[120:123], v[56:59], v[186:189], 0
	v_mfma_f32_16x16x32_bf16 v[108:111], v[40:43], v[194:197], 0
	v_mfma_f32_16x16x32_bf16 v[104:107], v[56:59], v[194:197], 0
	v_mfma_f32_16x16x32_bf16 v[92:95], v[40:43], v[202:205], 0
	v_mfma_f32_16x16x32_bf16 v[88:91], v[56:59], v[202:205], 0
	v_mfma_f32_16x16x32_bf16 v[140:143], v[44:47], v[164:167], v[140:143]
	v_mfma_f32_16x16x32_bf16 v[136:139], v[60:63], v[164:167], v[136:139]
	v_mfma_f32_16x16x32_bf16 v[124:127], v[44:47], v[190:193], v[124:127]
	v_mfma_f32_16x16x32_bf16 v[120:123], v[60:63], v[190:193], v[120:123]
	v_mfma_f32_16x16x32_bf16 v[108:111], v[44:47], v[198:201], v[108:111]
	v_mfma_f32_16x16x32_bf16 v[104:107], v[60:63], v[198:201], v[104:107]
	v_mfma_f32_16x16x32_bf16 v[92:95], v[44:47], v[214:217], v[92:95]
	v_mfma_f32_16x16x32_bf16 v[88:91], v[60:63], v[214:217], v[88:91]
	v_mfma_f32_16x16x32_bf16 v[132:135], v[144:147], v[160:163], 0
	v_mfma_f32_16x16x32_bf16 v[128:131], v[152:155], v[160:163], 0
	v_mfma_f32_16x16x32_bf16 v[116:119], v[144:147], v[186:189], 0
	v_mfma_f32_16x16x32_bf16 v[112:115], v[152:155], v[186:189], 0
	v_mfma_f32_16x16x32_bf16 v[100:103], v[144:147], v[194:197], 0
	v_mfma_f32_16x16x32_bf16 v[96:99], v[152:155], v[194:197], 0
	v_mfma_f32_16x16x32_bf16 v[84:87], v[144:147], v[202:205], 0
	v_mfma_f32_16x16x32_bf16 v[80:83], v[152:155], v[202:205], 0
	v_mfma_f32_16x16x32_bf16 v[132:135], v[148:151], v[164:167], v[132:135]
	v_mfma_f32_16x16x32_bf16 v[128:131], v[156:159], v[164:167], v[128:131]
	v_mfma_f32_16x16x32_bf16 v[116:119], v[148:151], v[190:193], v[116:119]
	v_mfma_f32_16x16x32_bf16 v[112:115], v[156:159], v[190:193], v[112:115]
	v_mfma_f32_16x16x32_bf16 v[100:103], v[148:151], v[198:201], v[100:103]
	v_mfma_f32_16x16x32_bf16 v[96:99], v[156:159], v[198:201], v[96:99]
	v_mfma_f32_16x16x32_bf16 v[84:87], v[148:151], v[214:217], v[84:87]
	v_mfma_f32_16x16x32_bf16 v[80:83], v[156:159], v[214:217], v[80:83]
	s_barrier
	s_add_i32 s72, s67, s54
	v_lshl_add_u64 v[218:219], s[44:45], 0, v[170:171]
	s_mov_b32 m0, s72
	ds_read_b128 v[160:163], v210 offset:16384
	ds_read_b128 v[164:167], v210 offset:17408
	ds_read_b128 v[186:189], v210 offset:18432
	ds_read_b128 v[190:193], v210 offset:19456
	ds_read_b128 v[194:197], v210 offset:20480
	ds_read_b128 v[198:201], v210 offset:21504
	ds_read_b128 v[202:205], v210 offset:22528
	ds_read_b128 v[214:217], v210 offset:23552
	global_load_lds_dwordx4 v[218:219], off
	s_add_i32 m0, s72, 0x2000
	s_add_u32 s72, s44, 0x40000
	v_lshl_add_u64 v[220:221], s[44:45], 0, v[174:175]
	s_addc_u32 s73, s45, 0
	s_add_i32 s74, s68, s54
	global_load_lds_dwordx4 v[220:221], off
	s_mov_b32 m0, s74
	v_lshl_add_u64 v[224:225], s[52:53], 0, v[172:173]
	global_load_lds_dwordx4 v170, s[72:73]
	s_add_i32 m0, s74, 0x2000
	s_nop 0
	global_load_lds_dwordx4 v174, s[72:73]
	v_lshl_add_u64 v[222:223], s[52:53], 0, v[168:169]
	s_mov_b32 m0, s55
	s_nop 0
	global_load_lds_dwordx4 v[222:223], off
	s_mov_b32 m0, s56
	s_nop 0
	global_load_lds_dwordx4 v[224:225], off
	s_waitcnt vmcnt(8)
	s_waitcnt lgkmcnt(0)
	s_barrier
; #define PG8_STAGE(bufoff, gbase, voff) do { _Pragma("unroll") for (int _i = 0; _i < 2; ++_i) \
;         __builtin_amdgcn_global_load_lds((const unsigned*)((const char*)(gbase) + (voff)[_i]), (LAS unsigned*)(lds + (bufoff) + ldsw + _i * 8192), 16, 0, 0); } while (0)
; #define PG8_LDA(dst, b, h) do { _Pragma("unroll") for (int m = 0; m < 4; ++m) _Pragma("unroll") for (int k = 0; k < 2; ++k) dst[m][k] = *(const LAS bf16x8*)(lds + PG8_SA(b, h) + aoff + m * 2048 + k * 1024); } while (0)
; #define PG8_LDB(dst, b, h) do { _Pragma("unroll") for (int n = 0; n < 2; ++n) _Pragma("unroll") for (int k = 0; k < 2; ++k) dst[n][k] = *(const LAS bf16x8*)(lds + PG8_SB(b, h) + boff + n * 2048 + k * 1024); } while (0)
; #define PG8_MMA(ai, bj, At, Bt) do { __builtin_amdgcn_s_setprio(1); _Pragma("unroll") for (int m = 0; m < 4; ++m) _Pragma("unroll") for (int n = 0; n < 2; ++n) _Pragma("unroll") for (int k = 0; k < 2; ++k) \
;         acc[ai][bj][m][n] = __builtin_amdgcn_mfma_f32_16x16x32_bf16(Bt[n][k], At[m][k], acc[ai][bj][m][n], 0, 0, 0); __builtin_amdgcn_s_setprio(0); } while (0)
; #define PG8_WAIT_V(n) asm volatile("s_waitcnt vmcnt(" #n ")" ::: "memory")
; #define PG8_WAIT_L(n) asm volatile("s_waitcnt lgkmcnt(" #n ")" ::: "memory")
; #define PG8_BAR __builtin_amdgcn_s_barrier()
; #define PG8_SCHED __builtin_amdgcn_sched_barrier(0)
; template <class Epi>
; __device__ __forceinline__ void gemm_phase(LAS unsigned char* lds, const Gemm g, const StaticOrder& S, const Epi& E) {
;     ...
;             PG8_WAIT_V(8); PG8_WAIT_L(0); PG8_BAR; PG8_MMA(1, 0, At, B0); PG8_MMA(1, 1, At, B1); PG8_BAR; PG8_SCHED;
;             PG8_LDB(B0, 1, 0); PG8_LDB(B1, 1, 1); PG8_SCHED; PG8_LDA(At, 1, 0); PG8_STAGE(PG8_SA(0, 1), a2 + hstepA, voffA);
;             PG8_WAIT_V(8); PG8_WAIT_L(0); PG8_BAR; PG8_MMA(0, 0, At, B0); PG8_MMA(0, 1, At, B1); PG8_BAR; PG8_SCHED;
	s_waitcnt lgkmcnt(0)
	v_mfma_f32_16x16x32_bf16 v[76:79], v[40:43], v[160:163], 0
	v_mfma_f32_16x16x32_bf16 v[72:75], v[56:59], v[160:163], 0
	v_mfma_f32_16x16x32_bf16 v[52:55], v[40:43], v[186:189], 0
	v_mfma_f32_16x16x32_bf16 v[48:51], v[56:59], v[186:189], 0
	v_mfma_f32_16x16x32_bf16 v[28:31], v[40:43], v[194:197], 0
	v_mfma_f32_16x16x32_bf16 v[24:27], v[56:59], v[194:197], 0
	v_mfma_f32_16x16x32_bf16 v[12:15], v[40:43], v[202:205], 0
	v_mfma_f32_16x16x32_bf16 v[8:11], v[56:59], v[202:205], 0
	v_mfma_f32_16x16x32_bf16 v[76:79], v[44:47], v[164:167], v[76:79]
	v_mfma_f32_16x16x32_bf16 v[72:75], v[60:63], v[164:167], v[72:75]
	v_mfma_f32_16x16x32_bf16 v[52:55], v[44:47], v[190:193], v[52:55]
	v_mfma_f32_16x16x32_bf16 v[48:51], v[60:63], v[190:193], v[48:51]
	v_mfma_f32_16x16x32_bf16 v[28:31], v[44:47], v[198:201], v[28:31]
	v_mfma_f32_16x16x32_bf16 v[24:27], v[60:63], v[198:201], v[24:27]
	v_mfma_f32_16x16x32_bf16 v[12:15], v[44:47], v[214:217], v[12:15]
	v_mfma_f32_16x16x32_bf16 v[8:11], v[60:63], v[214:217], v[8:11]
	v_mfma_f32_16x16x32_bf16 v[36:39], v[144:147], v[186:189], 0
	v_mfma_f32_16x16x32_bf16 v[32:35], v[152:155], v[186:189], 0
	v_mfma_f32_16x16x32_bf16 v[20:23], v[144:147], v[194:197], 0
	v_mfma_f32_16x16x32_bf16 v[16:19], v[152:155], v[194:197], 0
	v_mfma_f32_16x16x32_bf16 v[4:7], v[144:147], v[202:205], 0
	v_mfma_f32_16x16x32_bf16 v[0:3], v[152:155], v[202:205], 0
	v_mfma_f32_16x16x32_bf16 v[40:43], v[144:147], v[160:163], 0
	v_mfma_f32_16x16x32_bf16 v[44:47], v[152:155], v[160:163], 0
	v_mfma_f32_16x16x32_bf16 v[36:39], v[148:151], v[190:193], v[36:39]
	v_mfma_f32_16x16x32_bf16 v[32:35], v[156:159], v[190:193], v[32:35]
	v_mfma_f32_16x16x32_bf16 v[20:23], v[148:151], v[198:201], v[20:23]
	v_mfma_f32_16x16x32_bf16 v[16:19], v[156:159], v[198:201], v[16:19]
	v_mfma_f32_16x16x32_bf16 v[4:7], v[148:151], v[214:217], v[4:7]
	v_mfma_f32_16x16x32_bf16 v[0:3], v[156:159], v[214:217], v[0:3]
	v_mfma_f32_16x16x32_bf16 v[40:43], v[148:151], v[164:167], v[40:43]
	v_mfma_f32_16x16x32_bf16 v[44:47], v[156:159], v[164:167], v[44:47]
	s_barrier
	s_add_i32 s72, 0, 0x18000
	s_add_i32 s73, 0, 0x1c000
	v_add_u32_e32 v68, s72, v207
	v_add_u32_e32 v156, s73, v207
	ds_read_b128 v[56:59], v68
	ds_read_b128 v[60:63], v68 offset:1024
	ds_read_b128 v[64:67], v68 offset:2048
	ds_read_b128 v[68:71], v68 offset:3072
	ds_read_b128 v[144:147], v156
	ds_read_b128 v[148:151], v156 offset:1024
	ds_read_b128 v[152:155], v156 offset:2048
	ds_read_b128 v[156:159], v156 offset:3072
	s_add_u32 s52, s52, 0x40000
	s_addc_u32 s53, s53, 0
	s_mov_b32 m0, s57
	ds_read_b128 v[160:163], v210 offset:32768
	ds_read_b128 v[164:167], v210 offset:33792
	ds_read_b128 v[186:189], v210 offset:34816
	ds_read_b128 v[190:193], v210 offset:35840
	ds_read_b128 v[194:197], v210 offset:36864
	ds_read_b128 v[198:201], v210 offset:37888
	ds_read_b128 v[202:205], v210 offset:38912
	ds_read_b128 v[214:217], v210 offset:39936
	global_load_lds_dwordx4 v168, s[52:53]
	s_mov_b32 m0, s58
	s_nop 0
	global_load_lds_dwordx4 v172, s[52:53]
	s_waitcnt vmcnt(8)
	s_waitcnt lgkmcnt(0)
	s_barrier
	s_waitcnt lgkmcnt(0)
	v_mfma_f32_16x16x32_bf16 v[140:143], v[56:59], v[160:163], v[140:143]
	v_mfma_f32_16x16x32_bf16 v[136:139], v[64:67], v[160:163], v[136:139]
	v_mfma_f32_16x16x32_bf16 v[124:127], v[56:59], v[186:189], v[124:127]
	v_mfma_f32_16x16x32_bf16 v[120:123], v[64:67], v[186:189], v[120:123]
	v_mfma_f32_16x16x32_bf16 v[108:111], v[56:59], v[194:197], v[108:111]
	v_mfma_f32_16x16x32_bf16 v[104:107], v[64:67], v[194:197], v[104:107]
	v_mfma_f32_16x16x32_bf16 v[92:95], v[56:59], v[202:205], v[92:95]
	v_mfma_f32_16x16x32_bf16 v[88:91], v[64:67], v[202:205], v[88:91]
	v_mfma_f32_16x16x32_bf16 v[140:143], v[60:63], v[164:167], v[140:143]
	v_mfma_f32_16x16x32_bf16 v[136:139], v[68:71], v[164:167], v[136:139]
	v_mfma_f32_16x16x32_bf16 v[124:127], v[60:63], v[190:193], v[124:127]
	v_mfma_f32_16x16x32_bf16 v[120:123], v[68:71], v[190:193], v[120:123]
	v_mfma_f32_16x16x32_bf16 v[108:111], v[60:63], v[198:201], v[108:111]
	v_mfma_f32_16x16x32_bf16 v[104:107], v[68:71], v[198:201], v[104:107]
	v_mfma_f32_16x16x32_bf16 v[92:95], v[60:63], v[214:217], v[92:95]
	v_mfma_f32_16x16x32_bf16 v[88:91], v[68:71], v[214:217], v[88:91]
	v_mfma_f32_16x16x32_bf16 v[132:135], v[144:147], v[160:163], v[132:135]
	v_mfma_f32_16x16x32_bf16 v[128:131], v[152:155], v[160:163], v[128:131]
	v_mfma_f32_16x16x32_bf16 v[116:119], v[144:147], v[186:189], v[116:119]
	v_mfma_f32_16x16x32_bf16 v[112:115], v[152:155], v[186:189], v[112:115]
	v_mfma_f32_16x16x32_bf16 v[100:103], v[144:147], v[194:197], v[100:103]
	v_mfma_f32_16x16x32_bf16 v[96:99], v[152:155], v[194:197], v[96:99]
	v_mfma_f32_16x16x32_bf16 v[84:87], v[144:147], v[202:205], v[84:87]
	v_mfma_f32_16x16x32_bf16 v[80:83], v[152:155], v[202:205], v[80:83]
	v_mfma_f32_16x16x32_bf16 v[132:135], v[148:151], v[164:167], v[132:135]
	v_mfma_f32_16x16x32_bf16 v[128:131], v[156:159], v[164:167], v[128:131]
	v_mfma_f32_16x16x32_bf16 v[116:119], v[148:151], v[190:193], v[116:119]
	v_mfma_f32_16x16x32_bf16 v[112:115], v[156:159], v[190:193], v[112:115]
	v_mfma_f32_16x16x32_bf16 v[100:103], v[148:151], v[198:201], v[100:103]
	v_mfma_f32_16x16x32_bf16 v[96:99], v[156:159], v[198:201], v[96:99]
	v_mfma_f32_16x16x32_bf16 v[84:87], v[148:151], v[214:217], v[84:87]
	v_mfma_f32_16x16x32_bf16 v[80:83], v[156:159], v[214:217], v[80:83]
	s_barrier
; #define PG8_STAGE(bufoff, gbase, voff) do { _Pragma("unroll") for (int _i = 0; _i < 2; ++_i) \
;         __builtin_amdgcn_global_load_lds((const unsigned*)((const char*)(gbase) + (voff)[_i]), (LAS unsigned*)(lds + (bufoff) + ldsw + _i * 8192), 16, 0, 0); } while (0)
; #define PG8_LDA(dst, b, h) do { _Pragma("unroll") for (int m = 0; m < 4; ++m) _Pragma("unroll") for (int k = 0; k < 2; ++k) dst[m][k] = *(const LAS bf16x8*)(lds + PG8_SA(b, h) + aoff + m * 2048 + k * 1024); } while (0)
; #define PG8_LDB(dst, b, h) do { _Pragma("unroll") for (int n = 0; n < 2; ++n) _Pragma("unroll") for (int k = 0; k < 2; ++k) dst[n][k] = *(const LAS bf16x8*)(lds + PG8_SB(b, h) + boff + n * 2048 + k * 1024); } while (0)
; #define PG8_MMA(ai, bj, At, Bt) do { __builtin_amdgcn_s_setprio(1); _Pragma("unroll") for (int m = 0; m < 4; ++m) _Pragma("unroll") for (int n = 0; n < 2; ++n) _Pragma("unroll") for (int k = 0; k < 2; ++k) \
;         acc[ai][bj][m][n] = __builtin_amdgcn_mfma_f32_16x16x32_bf16(Bt[n][k], At[m][k], acc[ai][bj][m][n], 0, 0, 0); __builtin_amdgcn_s_setprio(0); } while (0)
; #define PG8_WAIT_V(n) asm volatile("s_waitcnt vmcnt(" #n ")" ::: "memory")
; #define PG8_WAIT_L(n) asm volatile("s_waitcnt lgkmcnt(" #n ")" ::: "memory")
; #define PG8_BAR __builtin_amdgcn_s_barrier()
; #define PG8_SCHED __builtin_amdgcn_sched_barrier(0)
; template <class Epi>
; __device__ __forceinline__ void gemm_phase(LAS unsigned char* lds, const Gemm g, const StaticOrder& S, const Epi& E) {
;     ...
;             PG8_LDB(B0, 0, 0); PG8_LDB(B1, 0, 1); PG8_SCHED; PG8_LDA(At, 0, 0); PG8_STAGE(PG8_SA(1, 1), a1 + hstepA, voffA);
;             PG8_WAIT_V(8); PG8_WAIT_L(0); PG8_BAR; PG8_MMA(0, 0, At, B0); PG8_MMA(0, 1, At, B1); PG8_BAR; PG8_SCHED;
;     ...
;             PG8_LDA(At, 1, 1); PG8_STAGE(PG8_SB(1, 0), b3, voffB); PG8_STAGE(PG8_SB(1, 1), b3 + hstepB, voffB); PG8_STAGE(PG8_SA(1, 0), a3, voffA);
;             PG8_WAIT_V(8); PG8_WAIT_L(0); PG8_BAR; PG8_MMA(1, 0, At, B0); PG8_MMA(1, 1, At, B1); PG8_BAR; PG8_SCHED;
	s_add_i32 s52, s72, s54
	v_lshl_add_u64 v[218:219], v[218:219], 0, s[20:21]
	s_mov_b32 m0, s52
	ds_read_b128 v[160:163], v210 offset:49152
	ds_read_b128 v[164:167], v210 offset:50176
	ds_read_b128 v[186:189], v210 offset:51200
	ds_read_b128 v[190:193], v210 offset:52224
	ds_read_b128 v[194:197], v210 offset:53248
	ds_read_b128 v[198:201], v210 offset:54272
	ds_read_b128 v[202:205], v210 offset:55296
	ds_read_b128 v[214:217], v210 offset:56320
	global_load_lds_dwordx4 v[218:219], off
	s_add_i32 m0, s52, 0x2000
	s_add_u32 s44, s44, 0x40080
	v_lshl_add_u64 v[218:219], v[220:221], 0, s[20:21]
	s_addc_u32 s45, s45, 0
	s_add_i32 s52, s73, s54
	global_load_lds_dwordx4 v[218:219], off
	s_mov_b32 m0, s52
	s_nop 0
	global_load_lds_dwordx4 v170, s[44:45]
	s_add_i32 m0, s52, 0x2000
	s_nop 0
	global_load_lds_dwordx4 v174, s[44:45]
	v_lshl_add_u64 v[218:219], v[222:223], 0, s[20:21]
	s_mov_b32 m0, s62
	s_nop 0
	global_load_lds_dwordx4 v[218:219], off
	v_lshl_add_u64 v[218:219], v[224:225], 0, s[20:21]
	s_mov_b32 m0, s63
	s_nop 0
	global_load_lds_dwordx4 v[218:219], off
	s_waitcnt vmcnt(8)
	s_waitcnt lgkmcnt(0)
	s_barrier
	s_waitcnt lgkmcnt(0)
	v_mfma_f32_16x16x32_bf16 v[76:79], v[56:59], v[160:163], v[76:79]
	v_mfma_f32_16x16x32_bf16 v[72:75], v[64:67], v[160:163], v[72:75]
	v_mfma_f32_16x16x32_bf16 v[52:55], v[56:59], v[186:189], v[52:55]
	v_mfma_f32_16x16x32_bf16 v[48:51], v[64:67], v[186:189], v[48:51]
	v_mfma_f32_16x16x32_bf16 v[28:31], v[56:59], v[194:197], v[28:31]
	v_mfma_f32_16x16x32_bf16 v[24:27], v[64:67], v[194:197], v[24:27]
	v_mfma_f32_16x16x32_bf16 v[12:15], v[56:59], v[202:205], v[12:15]
	v_mfma_f32_16x16x32_bf16 v[8:11], v[64:67], v[202:205], v[8:11]
	v_mfma_f32_16x16x32_bf16 v[76:79], v[60:63], v[164:167], v[76:79]
	v_mfma_f32_16x16x32_bf16 v[72:75], v[68:71], v[164:167], v[72:75]
	v_mfma_f32_16x16x32_bf16 v[52:55], v[60:63], v[190:193], v[52:55]
	v_mfma_f32_16x16x32_bf16 v[48:51], v[68:71], v[190:193], v[48:51]
	v_mfma_f32_16x16x32_bf16 v[28:31], v[60:63], v[198:201], v[28:31]
	v_mfma_f32_16x16x32_bf16 v[24:27], v[68:71], v[198:201], v[24:27]
	v_mfma_f32_16x16x32_bf16 v[12:15], v[60:63], v[214:217], v[12:15]
	v_mfma_f32_16x16x32_bf16 v[8:11], v[68:71], v[214:217], v[8:11]
	v_mfma_f32_16x16x32_bf16 v[40:43], v[144:147], v[160:163], v[40:43]
	v_mfma_f32_16x16x32_bf16 v[68:71], v[148:151], v[164:167], v[40:43]
	v_mfma_f32_16x16x32_bf16 v[40:43], v[152:155], v[160:163], v[44:47]
	v_mfma_f32_16x16x32_bf16 v[36:39], v[144:147], v[186:189], v[36:39]
	v_mfma_f32_16x16x32_bf16 v[32:35], v[152:155], v[186:189], v[32:35]
	v_mfma_f32_16x16x32_bf16 v[20:23], v[144:147], v[194:197], v[20:23]
	v_mfma_f32_16x16x32_bf16 v[16:19], v[152:155], v[194:197], v[16:19]
	v_mfma_f32_16x16x32_bf16 v[4:7], v[144:147], v[202:205], v[4:7]
	v_mfma_f32_16x16x32_bf16 v[0:3], v[152:155], v[202:205], v[0:3]
	v_mfma_f32_16x16x32_bf16 v[64:67], v[156:159], v[164:167], v[40:43]
	v_mfma_f32_16x16x32_bf16 v[36:39], v[148:151], v[190:193], v[36:39]
	v_mfma_f32_16x16x32_bf16 v[32:35], v[156:159], v[190:193], v[32:35]
	v_mfma_f32_16x16x32_bf16 v[20:23], v[148:151], v[198:201], v[20:23]
	v_mfma_f32_16x16x32_bf16 v[16:19], v[156:159], v[198:201], v[16:19]
	v_mfma_f32_16x16x32_bf16 v[4:7], v[148:151], v[214:217], v[4:7]
	v_mfma_f32_16x16x32_bf16 v[0:3], v[156:159], v[214:217], v[0:3]
	s_barrier
	s_add_i32 s71, s71, 2
	s_add_u32 s42, s42, 0x100
	s_addc_u32 s43, s43, 0
	s_add_u32 s69, s69, 0x100
	s_addc_u32 s70, s70, 0
	s_cmp_gt_u32 s71, 13
.LBB0_1746:
	ds_read_b128 v[40:43], v208
	ds_read_b128 v[44:47], v208 offset:1024
	ds_read_b128 v[56:59], v208 offset:2048
	ds_read_b128 v[60:63], v208 offset:3072
	ds_read_b128 v[144:147], v209
	ds_read_b128 v[148:151], v209 offset:1024
	ds_read_b128 v[152:155], v209 offset:2048
	ds_read_b128 v[156:159], v209 offset:3072
	s_add_u32 s44, s42, 0xfffc0080
	s_addc_u32 s45, s43, -1
	s_cmp_eq_u32 s71, 12
	s_cselect_b32 s53, s7, s45
	s_cselect_b32 s52, s9, s44
	s_cselect_b32 s45, s29, s70
	s_cselect_b32 s44, s35, s69
	s_add_i32 m0, s55, 0xc000
	ds_read_b128 v[160:163], v210
	ds_read_b128 v[164:167], v210 offset:1024
	ds_read_b128 v[186:189], v210 offset:2048
	ds_read_b128 v[190:193], v210 offset:3072
	ds_read_b128 v[194:197], v210 offset:4096
	ds_read_b128 v[198:201], v210 offset:5120
	ds_read_b128 v[202:205], v210 offset:6144
	ds_read_b128 v[214:217], v210 offset:7168
	global_load_lds_dwordx4 v178, s[42:43]
	s_add_i32 m0, s55, 0xe000
	s_nop 0
	global_load_lds_dwordx4 v180, s[42:43]
	s_waitcnt vmcnt(8)
	s_waitcnt lgkmcnt(0)
	s_barrier
; #define PG8_STAGE(bufoff, gbase, voff) do { _Pragma("unroll") for (int _i = 0; _i < 2; ++_i) \
;         __builtin_amdgcn_global_load_lds((const unsigned*)((const char*)(gbase) + (voff)[_i]), (LAS unsigned*)(lds + (bufoff) + ldsw + _i * 8192), 16, 0, 0); } while (0)
; #define PG8_LDA(dst, b, h) do { _Pragma("unroll") for (int m = 0; m < 4; ++m) _Pragma("unroll") for (int k = 0; k < 2; ++k) dst[m][k] = *(const LAS bf16x8*)(lds + PG8_SA(b, h) + aoff + m * 2048 + k * 1024); } while (0)
; #define PG8_LDB(dst, b, h) do { _Pragma("unroll") for (int n = 0; n < 2; ++n) _Pragma("unroll") for (int k = 0; k < 2; ++k) dst[n][k] = *(const LAS bf16x8*)(lds + PG8_SB(b, h) + boff + n * 2048 + k * 1024); } while (0)
; #define PG8_MMA(ai, bj, At, Bt) do { __builtin_amdgcn_s_setprio(1); _Pragma("unroll") for (int m = 0; m < 4; ++m) _Pragma("unroll") for (int n = 0; n < 2; ++n) _Pragma("unroll") for (int k = 0; k < 2; ++k) \
;         acc[ai][bj][m][n] = __builtin_amdgcn_mfma_f32_16x16x32_bf16(Bt[n][k], At[m][k], acc[ai][bj][m][n], 0, 0, 0); __builtin_amdgcn_s_setprio(0); } while (0)
; #define PG8_WAIT_V(n) asm volatile("s_waitcnt vmcnt(" #n ")" ::: "memory")
; #define PG8_WAIT_L(n) asm volatile("s_waitcnt lgkmcnt(" #n ")" ::: "memory")
; #define PG8_BAR __builtin_amdgcn_s_barrier()
; #define PG8_SCHED __builtin_amdgcn_sched_barrier(0)
; template <class Epi>
; __device__ __forceinline__ void gemm_phase(LAS unsigned char* lds, const Gemm g, const StaticOrder& S, const Epi& E) {
;     ...
;             PG8_LDB(B0, 0, 0); PG8_LDB(B1, 0, 1); PG8_SCHED; PG8_LDA(At, 0, 0); PG8_STAGE(PG8_SA(1, 1), a1 + hstepA, voffA);
;             PG8_WAIT_V(8); PG8_WAIT_L(0); PG8_BAR; PG8_MMA(0, 0, At, B0); PG8_MMA(0, 1, At, B1); PG8_BAR; PG8_SCHED;
;             PG8_LDA(At, 0, 1); PG8_STAGE(PG8_SB(0, 0), b2, voffB); PG8_STAGE(PG8_SB(0, 1), b2 + hstepB, voffB); PG8_STAGE(PG8_SA(0, 0), a2, voffA);
;             PG8_WAIT_V(8); PG8_WAIT_L(0); PG8_BAR; PG8_MMA(1, 0, At, B0); PG8_MMA(1, 1, At, B1); PG8_BAR; PG8_SCHED;
	s_waitcnt lgkmcnt(0)
	v_mfma_f32_16x16x32_bf16 v[140:143], v[40:43], v[160:163], v[140:143]
	v_mfma_f32_16x16x32_bf16 v[136:139], v[56:59], v[160:163], v[136:139]
	v_mfma_f32_16x16x32_bf16 v[124:127], v[40:43], v[186:189], v[124:127]
	v_mfma_f32_16x16x32_bf16 v[120:123], v[56:59], v[186:189], v[120:123]
	v_mfma_f32_16x16x32_bf16 v[108:111], v[40:43], v[194:197], v[108:111]
	v_mfma_f32_16x16x32_bf16 v[104:107], v[56:59], v[194:197], v[104:107]
	v_mfma_f32_16x16x32_bf16 v[92:95], v[40:43], v[202:205], v[92:95]
	v_mfma_f32_16x16x32_bf16 v[88:91], v[56:59], v[202:205], v[88:91]
	v_mfma_f32_16x16x32_bf16 v[140:143], v[44:47], v[164:167], v[140:143]
	v_mfma_f32_16x16x32_bf16 v[136:139], v[60:63], v[164:167], v[136:139]
	v_mfma_f32_16x16x32_bf16 v[124:127], v[44:47], v[190:193], v[124:127]
	v_mfma_f32_16x16x32_bf16 v[120:123], v[60:63], v[190:193], v[120:123]
	v_mfma_f32_16x16x32_bf16 v[108:111], v[44:47], v[198:201], v[108:111]
	v_mfma_f32_16x16x32_bf16 v[104:107], v[60:63], v[198:201], v[104:107]
	v_mfma_f32_16x16x32_bf16 v[92:95], v[44:47], v[214:217], v[92:95]
	v_mfma_f32_16x16x32_bf16 v[88:91], v[60:63], v[214:217], v[88:91]
	v_mfma_f32_16x16x32_bf16 v[132:135], v[144:147], v[160:163], v[132:135]
	v_mfma_f32_16x16x32_bf16 v[128:131], v[152:155], v[160:163], v[128:131]
	v_mfma_f32_16x16x32_bf16 v[116:119], v[144:147], v[186:189], v[116:119]
	v_mfma_f32_16x16x32_bf16 v[112:115], v[152:155], v[186:189], v[112:115]
	v_mfma_f32_16x16x32_bf16 v[100:103], v[144:147], v[194:197], v[100:103]
	v_mfma_f32_16x16x32_bf16 v[96:99], v[152:155], v[194:197], v[96:99]
	v_mfma_f32_16x16x32_bf16 v[84:87], v[144:147], v[202:205], v[84:87]
	v_mfma_f32_16x16x32_bf16 v[80:83], v[152:155], v[202:205], v[80:83]
	v_mfma_f32_16x16x32_bf16 v[132:135], v[148:151], v[164:167], v[132:135]
	v_mfma_f32_16x16x32_bf16 v[128:131], v[156:159], v[164:167], v[128:131]
	v_mfma_f32_16x16x32_bf16 v[116:119], v[148:151], v[190:193], v[116:119]
	v_mfma_f32_16x16x32_bf16 v[112:115], v[156:159], v[190:193], v[112:115]
	v_mfma_f32_16x16x32_bf16 v[100:103], v[148:151], v[198:201], v[100:103]
	v_mfma_f32_16x16x32_bf16 v[96:99], v[156:159], v[198:201], v[96:99]
	v_mfma_f32_16x16x32_bf16 v[84:87], v[148:151], v[214:217], v[84:87]
	v_mfma_f32_16x16x32_bf16 v[80:83], v[156:159], v[214:217], v[80:83]
	s_barrier
	s_add_i32 s72, s67, s54
	v_lshl_add_u64 v[218:219], s[44:45], 0, v[170:171]
	s_mov_b32 m0, s72
	ds_read_b128 v[160:163], v210 offset:16384
	ds_read_b128 v[164:167], v210 offset:17408
	ds_read_b128 v[186:189], v210 offset:18432
	ds_read_b128 v[190:193], v210 offset:19456
	ds_read_b128 v[194:197], v210 offset:20480
	ds_read_b128 v[198:201], v210 offset:21504
	ds_read_b128 v[202:205], v210 offset:22528
	ds_read_b128 v[214:217], v210 offset:23552
	global_load_lds_dwordx4 v[218:219], off
	s_add_i32 m0, s72, 0x2000
	s_add_u32 s72, s44, 0x40000
	v_lshl_add_u64 v[220:221], s[44:45], 0, v[174:175]
	s_addc_u32 s73, s45, 0
	s_add_i32 s74, s68, s54
	global_load_lds_dwordx4 v[220:221], off
	s_mov_b32 m0, s74
	v_lshl_add_u64 v[224:225], s[52:53], 0, v[172:173]
	global_load_lds_dwordx4 v170, s[72:73]
	s_add_i32 m0, s74, 0x2000
	s_nop 0
	global_load_lds_dwordx4 v174, s[72:73]
	v_lshl_add_u64 v[222:223], s[52:53], 0, v[168:169]
	s_mov_b32 m0, s55
	s_nop 0
	global_load_lds_dwordx4 v[222:223], off
	s_mov_b32 m0, s56
	s_nop 0
	global_load_lds_dwordx4 v[224:225], off
	s_waitcnt vmcnt(8)
	s_waitcnt lgkmcnt(0)
	s_barrier
	s_waitcnt lgkmcnt(0)
	v_mfma_f32_16x16x32_bf16 v[76:79], v[40:43], v[160:163], v[76:79]
	v_mfma_f32_16x16x32_bf16 v[72:75], v[56:59], v[160:163], v[72:75]
	v_mfma_f32_16x16x32_bf16 v[52:55], v[40:43], v[186:189], v[52:55]
	v_mfma_f32_16x16x32_bf16 v[48:51], v[56:59], v[186:189], v[48:51]
	v_mfma_f32_16x16x32_bf16 v[28:31], v[40:43], v[194:197], v[28:31]
	v_mfma_f32_16x16x32_bf16 v[24:27], v[56:59], v[194:197], v[24:27]
	v_mfma_f32_16x16x32_bf16 v[12:15], v[40:43], v[202:205], v[12:15]
	v_mfma_f32_16x16x32_bf16 v[8:11], v[56:59], v[202:205], v[8:11]
	v_mfma_f32_16x16x32_bf16 v[76:79], v[44:47], v[164:167], v[76:79]
	v_mfma_f32_16x16x32_bf16 v[72:75], v[60:63], v[164:167], v[72:75]
	v_mfma_f32_16x16x32_bf16 v[52:55], v[44:47], v[190:193], v[52:55]
	v_mfma_f32_16x16x32_bf16 v[48:51], v[60:63], v[190:193], v[48:51]
	v_mfma_f32_16x16x32_bf16 v[28:31], v[44:47], v[198:201], v[28:31]
	v_mfma_f32_16x16x32_bf16 v[24:27], v[60:63], v[198:201], v[24:27]
	v_mfma_f32_16x16x32_bf16 v[12:15], v[44:47], v[214:217], v[12:15]
	v_mfma_f32_16x16x32_bf16 v[8:11], v[60:63], v[214:217], v[8:11]
	v_mfma_f32_16x16x32_bf16 v[36:39], v[144:147], v[186:189], v[36:39]
	v_mfma_f32_16x16x32_bf16 v[32:35], v[152:155], v[186:189], v[32:35]
	v_mfma_f32_16x16x32_bf16 v[20:23], v[144:147], v[194:197], v[20:23]
	v_mfma_f32_16x16x32_bf16 v[16:19], v[152:155], v[194:197], v[16:19]
	v_mfma_f32_16x16x32_bf16 v[4:7], v[144:147], v[202:205], v[4:7]
	v_mfma_f32_16x16x32_bf16 v[0:3], v[152:155], v[202:205], v[0:3]
	v_mfma_f32_16x16x32_bf16 v[40:43], v[144:147], v[160:163], v[68:71]
	v_mfma_f32_16x16x32_bf16 v[44:47], v[152:155], v[160:163], v[64:67]
	v_mfma_f32_16x16x32_bf16 v[36:39], v[148:151], v[190:193], v[36:39]
	v_mfma_f32_16x16x32_bf16 v[32:35], v[156:159], v[190:193], v[32:35]
	v_mfma_f32_16x16x32_bf16 v[20:23], v[148:151], v[198:201], v[20:23]
	v_mfma_f32_16x16x32_bf16 v[16:19], v[156:159], v[198:201], v[16:19]
	v_mfma_f32_16x16x32_bf16 v[4:7], v[148:151], v[214:217], v[4:7]
	v_mfma_f32_16x16x32_bf16 v[0:3], v[156:159], v[214:217], v[0:3]
	v_mfma_f32_16x16x32_bf16 v[40:43], v[148:151], v[164:167], v[40:43]
	v_mfma_f32_16x16x32_bf16 v[44:47], v[156:159], v[164:167], v[44:47]
	s_barrier
; #define PG8_STAGE(bufoff, gbase, voff) do { _Pragma("unroll") for (int _i = 0; _i < 2; ++_i) \
;         __builtin_amdgcn_global_load_lds((const unsigned*)((const char*)(gbase) + (voff)[_i]), (LAS unsigned*)(lds + (bufoff) + ldsw + _i * 8192), 16, 0, 0); } while (0)
; #define PG8_LDA(dst, b, h) do { _Pragma("unroll") for (int m = 0; m < 4; ++m) _Pragma("unroll") for (int k = 0; k < 2; ++k) dst[m][k] = *(const LAS bf16x8*)(lds + PG8_SA(b, h) + aoff + m * 2048 + k * 1024); } while (0)
; #define PG8_LDB(dst, b, h) do { _Pragma("unroll") for (int n = 0; n < 2; ++n) _Pragma("unroll") for (int k = 0; k < 2; ++k) dst[n][k] = *(const LAS bf16x8*)(lds + PG8_SB(b, h) + boff + n * 2048 + k * 1024); } while (0)
; #define PG8_MMA(ai, bj, At, Bt) do { __builtin_amdgcn_s_setprio(1); _Pragma("unroll") for (int m = 0; m < 4; ++m) _Pragma("unroll") for (int n = 0; n < 2; ++n) _Pragma("unroll") for (int k = 0; k < 2; ++k) \
;         acc[ai][bj][m][n] = __builtin_amdgcn_mfma_f32_16x16x32_bf16(Bt[n][k], At[m][k], acc[ai][bj][m][n], 0, 0, 0); __builtin_amdgcn_s_setprio(0); } while (0)
; #define PG8_WAIT_V(n) asm volatile("s_waitcnt vmcnt(" #n ")" ::: "memory")
; #define PG8_WAIT_L(n) asm volatile("s_waitcnt lgkmcnt(" #n ")" ::: "memory")
; #define PG8_BAR __builtin_amdgcn_s_barrier()
; #define PG8_SCHED __builtin_amdgcn_sched_barrier(0)
; template <class Epi>
; __device__ __forceinline__ void gemm_phase(LAS unsigned char* lds, const Gemm g, const StaticOrder& S, const Epi& E) {
;     ...
;             PG8_LDB(B0, 1, 0); PG8_LDB(B1, 1, 1); PG8_SCHED; PG8_LDA(At, 1, 0); PG8_STAGE(PG8_SA(0, 1), a2 + hstepA, voffA);
;             PG8_WAIT_V(8); PG8_WAIT_L(0); PG8_BAR; PG8_MMA(0, 0, At, B0); PG8_MMA(0, 1, At, B1); PG8_BAR; PG8_SCHED;
;             PG8_LDA(At, 1, 1); PG8_STAGE(PG8_SB(1, 0), b3, voffB); PG8_STAGE(PG8_SB(1, 1), b3 + hstepB, voffB); PG8_STAGE(PG8_SA(1, 0), a3, voffA);
;             PG8_WAIT_V(8); PG8_WAIT_L(0); PG8_BAR; PG8_MMA(1, 0, At, B0); PG8_MMA(1, 1, At, B1); PG8_BAR; PG8_SCHED;
;         }
;         if (wr == 0) PG8_BAR;
	s_add_i32 s72, 0, 0x18000
	s_add_i32 s73, 0, 0x1c000
	v_add_u32_e32 v68, s72, v207
	v_add_u32_e32 v156, s73, v207
	ds_read_b128 v[56:59], v68
	ds_read_b128 v[60:63], v68 offset:1024
	ds_read_b128 v[64:67], v68 offset:2048
	ds_read_b128 v[68:71], v68 offset:3072
	ds_read_b128 v[144:147], v156
	ds_read_b128 v[148:151], v156 offset:1024
	ds_read_b128 v[152:155], v156 offset:2048
	ds_read_b128 v[156:159], v156 offset:3072
	s_add_u32 s52, s52, 0x40000
	s_addc_u32 s53, s53, 0
	s_mov_b32 m0, s57
	ds_read_b128 v[160:163], v210 offset:32768
	ds_read_b128 v[164:167], v210 offset:33792
	ds_read_b128 v[186:189], v210 offset:34816
	ds_read_b128 v[190:193], v210 offset:35840
	ds_read_b128 v[194:197], v210 offset:36864
	ds_read_b128 v[198:201], v210 offset:37888
	ds_read_b128 v[202:205], v210 offset:38912
	ds_read_b128 v[214:217], v210 offset:39936
	global_load_lds_dwordx4 v168, s[52:53]
	v_lshl_add_u64 v[226:227], s[52:53], 0, v[172:173]
	s_mov_b32 m0, s58
	s_nop 0
	global_load_lds_dwordx4 v[226:227], off
	s_waitcnt vmcnt(8)
	s_waitcnt lgkmcnt(0)
	s_barrier
	s_waitcnt lgkmcnt(0)
	v_mfma_f32_16x16x32_bf16 v[140:143], v[56:59], v[160:163], v[140:143]
	v_mfma_f32_16x16x32_bf16 v[136:139], v[64:67], v[160:163], v[136:139]
	v_mfma_f32_16x16x32_bf16 v[124:127], v[56:59], v[186:189], v[124:127]
	v_mfma_f32_16x16x32_bf16 v[120:123], v[64:67], v[186:189], v[120:123]
	v_mfma_f32_16x16x32_bf16 v[108:111], v[56:59], v[194:197], v[108:111]
	v_mfma_f32_16x16x32_bf16 v[104:107], v[64:67], v[194:197], v[104:107]
	v_mfma_f32_16x16x32_bf16 v[92:95], v[56:59], v[202:205], v[92:95]
	v_mfma_f32_16x16x32_bf16 v[88:91], v[64:67], v[202:205], v[88:91]
	v_mfma_f32_16x16x32_bf16 v[140:143], v[60:63], v[164:167], v[140:143]
	v_mfma_f32_16x16x32_bf16 v[136:139], v[68:71], v[164:167], v[136:139]
	v_mfma_f32_16x16x32_bf16 v[124:127], v[60:63], v[190:193], v[124:127]
	v_mfma_f32_16x16x32_bf16 v[120:123], v[68:71], v[190:193], v[120:123]
	v_mfma_f32_16x16x32_bf16 v[108:111], v[60:63], v[198:201], v[108:111]
	v_mfma_f32_16x16x32_bf16 v[104:107], v[68:71], v[198:201], v[104:107]
	v_mfma_f32_16x16x32_bf16 v[92:95], v[60:63], v[214:217], v[92:95]
	v_mfma_f32_16x16x32_bf16 v[88:91], v[68:71], v[214:217], v[88:91]
	v_mfma_f32_16x16x32_bf16 v[132:135], v[144:147], v[160:163], v[132:135]
	v_mfma_f32_16x16x32_bf16 v[128:131], v[152:155], v[160:163], v[128:131]
	v_mfma_f32_16x16x32_bf16 v[116:119], v[144:147], v[186:189], v[116:119]
	v_mfma_f32_16x16x32_bf16 v[112:115], v[152:155], v[186:189], v[112:115]
	v_mfma_f32_16x16x32_bf16 v[100:103], v[144:147], v[194:197], v[100:103]
	v_mfma_f32_16x16x32_bf16 v[96:99], v[152:155], v[194:197], v[96:99]
	v_mfma_f32_16x16x32_bf16 v[84:87], v[144:147], v[202:205], v[84:87]
	v_mfma_f32_16x16x32_bf16 v[80:83], v[152:155], v[202:205], v[80:83]
	v_mfma_f32_16x16x32_bf16 v[132:135], v[148:151], v[164:167], v[132:135]
	v_mfma_f32_16x16x32_bf16 v[128:131], v[156:159], v[164:167], v[128:131]
	v_mfma_f32_16x16x32_bf16 v[116:119], v[148:151], v[190:193], v[116:119]
	v_mfma_f32_16x16x32_bf16 v[112:115], v[156:159], v[190:193], v[112:115]
	v_mfma_f32_16x16x32_bf16 v[100:103], v[148:151], v[198:201], v[100:103]
	v_mfma_f32_16x16x32_bf16 v[96:99], v[156:159], v[198:201], v[96:99]
	v_mfma_f32_16x16x32_bf16 v[84:87], v[148:151], v[214:217], v[84:87]
	v_mfma_f32_16x16x32_bf16 v[80:83], v[156:159], v[214:217], v[80:83]
	s_barrier
	s_add_i32 s52, s72, s54
	v_lshl_add_u64 v[218:219], v[218:219], 0, s[20:21]
	s_mov_b32 m0, s52
	ds_read_b128 v[160:163], v210 offset:49152
	ds_read_b128 v[164:167], v210 offset:50176
	ds_read_b128 v[186:189], v210 offset:51200
	ds_read_b128 v[190:193], v210 offset:52224
	ds_read_b128 v[194:197], v210 offset:53248
	ds_read_b128 v[198:201], v210 offset:54272
	ds_read_b128 v[202:205], v210 offset:55296
	ds_read_b128 v[214:217], v210 offset:56320
	global_load_lds_dwordx4 v[218:219], off
	s_add_i32 m0, s52, 0x2000
	s_add_u32 s44, s44, 0x40080
	v_lshl_add_u64 v[218:219], v[220:221], 0, s[20:21]
	s_addc_u32 s45, s45, 0
	s_add_i32 s52, s73, s54
	global_load_lds_dwordx4 v[218:219], off
	s_mov_b32 m0, s52
	s_nop 0
	global_load_lds_dwordx4 v170, s[44:45]
	s_add_i32 m0, s52, 0x2000
	s_nop 0
	global_load_lds_dwordx4 v174, s[44:45]
	v_lshl_add_u64 v[218:219], v[222:223], 0, s[20:21]
	s_mov_b32 m0, s62
	s_nop 0
	global_load_lds_dwordx4 v[218:219], off
	v_lshl_add_u64 v[218:219], v[224:225], 0, s[20:21]
	s_mov_b32 m0, s63
	s_nop 0
	global_load_lds_dwordx4 v[218:219], off
	s_waitcnt vmcnt(8)
	s_waitcnt lgkmcnt(0)
	s_barrier
	s_waitcnt lgkmcnt(0)
	v_mfma_f32_16x16x32_bf16 v[76:79], v[56:59], v[160:163], v[76:79]
	v_mfma_f32_16x16x32_bf16 v[72:75], v[64:67], v[160:163], v[72:75]
	v_mfma_f32_16x16x32_bf16 v[52:55], v[56:59], v[186:189], v[52:55]
	v_mfma_f32_16x16x32_bf16 v[48:51], v[64:67], v[186:189], v[48:51]
	v_mfma_f32_16x16x32_bf16 v[28:31], v[56:59], v[194:197], v[28:31]
	v_mfma_f32_16x16x32_bf16 v[24:27], v[64:67], v[194:197], v[24:27]
	v_mfma_f32_16x16x32_bf16 v[12:15], v[56:59], v[202:205], v[12:15]
	v_mfma_f32_16x16x32_bf16 v[8:11], v[64:67], v[202:205], v[8:11]
	v_mfma_f32_16x16x32_bf16 v[76:79], v[60:63], v[164:167], v[76:79]
	v_mfma_f32_16x16x32_bf16 v[72:75], v[68:71], v[164:167], v[72:75]
	v_mfma_f32_16x16x32_bf16 v[52:55], v[60:63], v[190:193], v[52:55]
	v_mfma_f32_16x16x32_bf16 v[48:51], v[68:71], v[190:193], v[48:51]
	v_mfma_f32_16x16x32_bf16 v[28:31], v[60:63], v[198:201], v[28:31]
	v_mfma_f32_16x16x32_bf16 v[24:27], v[68:71], v[198:201], v[24:27]
	v_mfma_f32_16x16x32_bf16 v[12:15], v[60:63], v[214:217], v[12:15]
	v_mfma_f32_16x16x32_bf16 v[8:11], v[68:71], v[214:217], v[8:11]
	v_mfma_f32_16x16x32_bf16 v[40:43], v[144:147], v[160:163], v[40:43]
	v_mfma_f32_16x16x32_bf16 v[68:71], v[148:151], v[164:167], v[40:43]
	v_mfma_f32_16x16x32_bf16 v[40:43], v[152:155], v[160:163], v[44:47]
	v_mfma_f32_16x16x32_bf16 v[36:39], v[144:147], v[186:189], v[36:39]
	v_mfma_f32_16x16x32_bf16 v[32:35], v[152:155], v[186:189], v[32:35]
	v_mfma_f32_16x16x32_bf16 v[20:23], v[144:147], v[194:197], v[20:23]
	v_mfma_f32_16x16x32_bf16 v[16:19], v[152:155], v[194:197], v[16:19]
	v_mfma_f32_16x16x32_bf16 v[4:7], v[144:147], v[202:205], v[4:7]
	v_mfma_f32_16x16x32_bf16 v[0:3], v[152:155], v[202:205], v[0:3]
	v_mfma_f32_16x16x32_bf16 v[64:67], v[156:159], v[164:167], v[40:43]
	v_mfma_f32_16x16x32_bf16 v[36:39], v[148:151], v[190:193], v[36:39]
	v_mfma_f32_16x16x32_bf16 v[32:35], v[156:159], v[190:193], v[32:35]
	v_mfma_f32_16x16x32_bf16 v[20:23], v[148:151], v[198:201], v[20:23]
	v_mfma_f32_16x16x32_bf16 v[16:19], v[156:159], v[198:201], v[16:19]
	v_mfma_f32_16x16x32_bf16 v[4:7], v[148:151], v[214:217], v[4:7]
	v_mfma_f32_16x16x32_bf16 v[0:3], v[156:159], v[214:217], v[0:3]
	s_barrier
	s_add_i32 s71, s71, 2
	s_add_u32 s42, s42, 0x100
	s_addc_u32 s43, s43, 0
	s_add_u32 s69, s69, 0x100
	s_addc_u32 s70, s70, 0
	s_cmp_gt_u32 s71, 13
	s_cbranch_scc0 .LBB0_1746
	s_and_b64 vcc, exec, s[22:23]
	s_cbranch_vccz .LBB0_1749
	s_barrier
